# PEER pass1/pass2 patches (dot8 zero-init, load hoisting, integer reduction network, pre-shifted indices) applied to the second (other-layer) code copy too
# speedup vs baseline: 1.0234x; 1.0031x over previous
.LBB0_668:
	v_cmp_gt_i32_e32 vcc, s33, v2
	s_or_b64 s[16:17], s[16:17], exec
	s_and_saveexec_b64 s[18:19], vcc
	s_cbranch_execz .LBB0_667
	v_ashrrev_i32_e32 v3, 31, v2
	v_lshlrev_b64 v[4:5], 11, v[2:3]
	v_lshl_add_u64 v[8:9], v[60:61], 0, v[4:5]
	global_load_dwordx4 v[4:7], v[8:9], off offset:16
	s_nop 0
	global_load_dwordx4 v[8:11], v[8:9], off
	v_lshlrev_b64 v[110:111], 9, v[2:3]
	v_lshl_add_u64 v[110:111], v[62:63], 0, v[110:111]
	global_load_dword v112, v[110:111], off
	global_load_dword v113, v[110:111], off offset:64
	global_load_dword v114, v[110:111], off offset:128
	global_load_dword v115, v[110:111], off offset:192
	global_load_dword v116, v[110:111], off offset:256
	global_load_dword v117, v[110:111], off offset:320
	global_load_dword v118, v[110:111], off offset:384
	global_load_dword v119, v[110:111], off offset:448
	v_add_u32_e32 v109, s20, v193
	s_waitcnt vmcnt(9)
	v_lshlrev_b32_e32 v13, 16, v4
	s_waitcnt vmcnt(8)
	v_lshlrev_b32_e32 v12, 16, v8
	v_and_b32_e32 v8, 0xffff0000, v8
	v_lshlrev_b32_e32 v14, 16, v9
	v_and_b32_e32 v15, 0xffff0000, v9
	s_waitcnt lgkmcnt(0)
	v_max3_f32 v0, |v12|, 0, |v8|
	v_lshlrev_b32_e32 v17, 16, v10
	v_and_b32_e32 v10, 0xffff0000, v10
	v_max3_f32 v0, v0, |v14|, |v15|
	v_lshlrev_b32_e32 v19, 16, v11
	v_and_b32_e32 v11, 0xffff0000, v11
	v_max3_f32 v0, v0, |v17|, |v10|
	v_and_b32_e32 v4, 0xffff0000, v4
	v_max3_f32 v0, v0, |v19|, |v11|
	v_lshlrev_b32_e32 v16, 16, v5
	v_and_b32_e32 v5, 0xffff0000, v5
	v_max3_f32 v0, v0, |v13|, |v4|
	v_lshlrev_b32_e32 v18, 16, v6
	v_and_b32_e32 v6, 0xffff0000, v6
	v_max3_f32 v0, v0, |v16|, |v5|
	v_lshlrev_b32_e32 v20, 16, v7
	v_and_b32_e32 v7, 0xffff0000, v7
	v_max3_f32 v0, v0, |v18|, |v6|
	v_max3_f32 v9, v0, |v20|, |v7|
	v_and_b32_e32 v0, 64, v219
	v_add_u32_e32 v21, 64, v0
	v_xor_b32_e32 v0, 32, v219
	v_cmp_lt_i32_e32 vcc, v0, v21
	s_nop 1
	v_cndmask_b32_e32 v0, v219, v0, vcc
	v_lshlrev_b32_e32 v0, 2, v0
	ds_bpermute_b32 v22, v0, v9
	s_waitcnt lgkmcnt(0)
	v_max_f32_e32 v22, v22, v22
	v_max_f32_e32 v9, v9, v22
	v_xor_b32_e32 v22, 16, v219
	v_cmp_lt_i32_e32 vcc, v22, v21
	s_nop 1
	v_cndmask_b32_e32 v22, v219, v22, vcc
	v_lshlrev_b32_e32 v22, 2, v22
	ds_bpermute_b32 v22, v22, v9
	s_waitcnt lgkmcnt(0)
	v_max_f32_e32 v22, v22, v22
	v_max_f32_e32 v9, v9, v22
	v_xor_b32_e32 v22, 8, v219
	v_cmp_lt_i32_e32 vcc, v22, v21
	s_nop 1
	v_cndmask_b32_e32 v22, v219, v22, vcc
	v_lshlrev_b32_e32 v22, 2, v22
	ds_bpermute_b32 v22, v22, v9
	s_waitcnt lgkmcnt(0)
	v_max_f32_e32 v22, v22, v22
	v_max_f32_e32 v9, v9, v22
	v_xor_b32_e32 v22, 4, v219
	v_cmp_lt_i32_e32 vcc, v22, v21
	s_nop 1
	v_cndmask_b32_e32 v22, v219, v22, vcc
	v_lshlrev_b32_e32 v22, 2, v22
	ds_bpermute_b32 v22, v22, v9
	s_waitcnt lgkmcnt(0)
	v_max_f32_e32 v22, v22, v22
	v_max_f32_e32 v9, v9, v22
	v_xor_b32_e32 v22, 2, v219
	v_cmp_lt_i32_e32 vcc, v22, v21
	s_nop 1
	v_cndmask_b32_e32 v22, v219, v22, vcc
	v_lshlrev_b32_e32 v22, 2, v22
	ds_bpermute_b32 v22, v22, v9
	s_waitcnt lgkmcnt(0)
	v_max_f32_e32 v22, v22, v22
	v_max_f32_e32 v9, v9, v22
	v_xor_b32_e32 v22, 1, v219
	v_cmp_lt_i32_e32 vcc, v22, v21
	s_nop 1
	v_cndmask_b32_e32 v21, v219, v22, vcc
	v_lshlrev_b32_e32 v21, 2, v21
	ds_bpermute_b32 v21, v21, v9
	s_waitcnt lgkmcnt(0)
	v_max_f32_e32 v21, v21, v21
	v_max_f32_e32 v9, v9, v21
	v_div_scale_f32 v21, s[22:23], v9, v9, s69
	v_rcp_f32_e32 v22, v21
	v_cmp_lt_f32_e64 s[0:1], 0, v9
	v_fma_f32 v23, -v21, v22, 1.0
	v_fmac_f32_e32 v22, v23, v22
	v_div_scale_f32 v23, vcc, s69, v9, s69
	v_mul_f32_e32 v24, v23, v22
	v_fma_f32 v25, -v21, v24, v23
	v_fmac_f32_e32 v24, v25, v22
	v_fma_f32 v21, -v21, v24, v23
	v_div_fmas_f32 v21, v21, v22, v24
	v_div_fixup_f32 v21, v21, v9, s69
	v_cndmask_b32_e64 v21, 0, v21, s[0:1]
	v_mul_f32_e32 v12, v21, v12
	v_mul_f32_e32 v8, v21, v8
	v_rndne_f32_e32 v12, v12
	v_rndne_f32_e32 v8, v8
	v_cvt_i32_f32_e32 v12, v12
	v_cvt_i32_f32_e32 v8, v8
	v_mul_f32_e32 v14, v21, v14
	v_mul_f32_e32 v15, v21, v15
	v_rndne_f32_e32 v14, v14
	v_rndne_f32_e32 v15, v15
	v_cvt_i32_f32_e32 v14, v14
	v_cvt_i32_f32_e32 v15, v15
	v_mul_f32_e32 v17, v21, v17
	v_mul_f32_e32 v10, v21, v10
	v_rndne_f32_e32 v17, v17
	v_rndne_f32_e32 v10, v10
	v_add_u32_e32 v22, 8, v12
	v_add_u32_e32 v23, 8, v8
	v_cvt_i32_f32_e32 v17, v17
	v_cvt_i32_f32_e32 v10, v10
	v_mul_f32_e32 v11, v21, v11
	v_lshrrev_b32_e32 v22, 4, v22
	v_and_b32_e32 v23, 0xf0, v23
	v_mul_f32_e32 v19, v21, v19
	v_rndne_f32_e32 v11, v11
	v_and_or_b32 v22, v22, 15, v23
	v_lshl_add_u32 v23, v14, 4, v222
	v_lshl_add_u32 v24, v15, 8, v223
	v_rndne_f32_e32 v19, v19
	v_cvt_i32_f32_e32 v11, v11
	v_and_b32_e32 v23, 0xf00, v23
	v_and_b32_e32 v24, 0xf000, v24
	v_cvt_i32_f32_e32 v19, v19
	v_or3_b32 v22, v22, v23, v24
	v_lshl_add_u32 v23, v17, 12, v224
	v_lshl_add_u32 v24, v10, 16, v225
	v_and_b32_e32 v12, 15, v12
	v_lshlrev_b32_e32 v8, 4, v8
	v_lshlrev_b32_e32 v14, 8, v14
	v_and_b32_e32 v23, 0xf0000, v23
	v_and_b32_e32 v24, 0xf00000, v24
	v_and_b32_e32 v8, 0xf0, v8
	v_and_b32_e32 v14, 0xf00, v14
	v_lshlrev_b32_e32 v15, 12, v15
	v_lshlrev_b32_e32 v17, 16, v17
	v_or3_b32 v22, v22, v23, v24
	v_lshl_add_u32 v24, v11, 24, v227
	v_lshl_or_b32 v11, v11, 28, v12
	v_and_b32_e32 v15, 0xf000, v15
	v_and_b32_e32 v17, 0xf0000, v17
	v_lshlrev_b32_e32 v10, 20, v10
	v_lshl_add_u32 v23, v19, 20, v226
	v_lshlrev_b32_e32 v19, 24, v19
	v_or3_b32 v8, v11, v8, v14
	v_and_b32_e32 v10, 0xf00000, v10
	v_and_b32_e32 v19, 0xf000000, v19
	v_or3_b32 v8, v8, v15, v17
	v_or3_b32 v75, v8, v10, v19
	v_mul_f32_e32 v8, v21, v13
	v_mul_f32_e32 v4, v21, v4
	v_rndne_f32_e32 v8, v8
	v_rndne_f32_e32 v4, v4
	v_cvt_i32_f32_e32 v8, v8
	v_cvt_i32_f32_e32 v4, v4
	v_mul_f32_e32 v5, v21, v5
	v_rndne_f32_e32 v5, v5
	v_add_u32_e32 v10, 8, v8
	v_add_u32_e32 v11, 8, v4
	v_lshrrev_b32_e32 v10, 4, v10
	v_and_b32_e32 v11, 0xf0, v11
	v_and_or_b32 v10, v10, 15, v11
	v_mul_f32_e32 v11, v21, v16
	v_rndne_f32_e32 v11, v11
	v_cvt_i32_f32_e32 v11, v11
	v_cvt_i32_f32_e32 v5, v5
	v_mul_f32_e32 v6, v21, v6
	v_rndne_f32_e32 v6, v6
	v_lshl_add_u32 v12, v11, 4, v222
	v_lshl_add_u32 v13, v5, 8, v223
	v_and_b32_e32 v12, 0xf00, v12
	v_and_b32_e32 v13, 0xf000, v13
	v_or3_b32 v10, v10, v12, v13
	v_mul_f32_e32 v12, v21, v18
	v_rndne_f32_e32 v12, v12
	v_cvt_i32_f32_e32 v12, v12
	v_cvt_i32_f32_e32 v6, v6
	v_mul_f32_e32 v7, v21, v7
	v_rndne_f32_e32 v7, v7
	v_lshl_add_u32 v13, v12, 12, v224
	v_lshl_add_u32 v14, v6, 16, v225
	v_and_b32_e32 v13, 0xf0000, v13
	v_and_b32_e32 v14, 0xf00000, v14
	v_or3_b32 v10, v10, v13, v14
	v_mul_f32_e32 v13, v21, v20
	v_rndne_f32_e32 v13, v13
	v_cvt_i32_f32_e32 v7, v7
	v_cvt_i32_f32_e32 v13, v13
	v_and_b32_e32 v8, 15, v8
	v_lshlrev_b32_e32 v4, 4, v4
	v_lshlrev_b32_e32 v11, 8, v11
	v_and_b32_e32 v4, 0xf0, v4
	v_and_b32_e32 v11, 0xf00, v11
	v_lshlrev_b32_e32 v5, 12, v5
	v_lshlrev_b32_e32 v12, 16, v12
	v_lshl_add_u32 v15, v7, 24, v227
	v_lshl_or_b32 v7, v7, 28, v8
	v_and_b32_e32 v5, 0xf000, v5
	v_and_b32_e32 v12, 0xf0000, v12
	v_lshlrev_b32_e32 v6, 20, v6
	v_lshl_add_u32 v14, v13, 20, v226
	v_lshlrev_b32_e32 v13, 24, v13
	v_or3_b32 v4, v7, v4, v11
	v_and_b32_e32 v6, 0xf00000, v6
	v_and_b32_e32 v13, 0xf000000, v13
	v_or3_b32 v4, v4, v5, v12
	v_or3_b32 v108, v4, v6, v13
	v_lshlrev_b64 v[6:7], 9, v[2:3]
	v_and_b32_e32 v14, 0xf000000, v14
	v_and_b32_e32 v15, 0xf0000000, v15
	v_lshl_add_u64 v[4:5], v[62:63], 0, v[6:7]
	v_or3_b32 v77, v10, v14, v15
	s_waitcnt vmcnt(7)
	v_mov_b32_e32 v20, v112
	s_waitcnt vmcnt(6)
	v_mov_b32_e32 v18, v113
	s_waitcnt vmcnt(5)
	v_mov_b32_e32 v16, v114
	s_waitcnt vmcnt(4)
	v_mov_b32_e32 v14, v115
	s_waitcnt vmcnt(3)
	v_mov_b32_e32 v12, v116
	s_waitcnt vmcnt(2)
	v_mov_b32_e32 v10, v117
	s_waitcnt vmcnt(1)
	v_mov_b32_e32 v8, v118
	s_nop 0
	s_waitcnt vmcnt(0)
	v_mov_b32_e32 v4, v119
	v_and_b32_e32 v23, 0xf000000, v23
	v_and_b32_e32 v24, 0xf0000000, v24
	v_or3_b32 v73, v22, v23, v24
	v_mul_f32_e32 v3, 0x3c09ae41, v9
	v_lshl_add_u64 v[6:7], v[64:65], 0, v[6:7]
	v_lshlrev_b32_e32 v120, 2, v20
	v_lshlrev_b32_e32 v121, 2, v18
	v_lshlrev_b32_e32 v122, 2, v16
	v_lshlrev_b32_e32 v123, 2, v14
	v_lshlrev_b32_e32 v124, 2, v12
	v_lshlrev_b32_e32 v125, 2, v10
	v_lshlrev_b32_e32 v126, 2, v8
	v_lshlrev_b32_e32 v127, 2, v4
	v_lshlrev_b32_e32 v20, 9, v20
	v_lshlrev_b32_e32 v18, 9, v18
	v_lshlrev_b32_e32 v16, 9, v16
	v_lshlrev_b32_e32 v14, 9, v14
	v_lshlrev_b32_e32 v12, 9, v12
	v_lshlrev_b32_e32 v10, 9, v10
	v_lshlrev_b32_e32 v8, 9, v8
	v_lshlrev_b32_e32 v4, 9, v4
	s_nop 0
	v_readlane_b32 s0, v20, 0
	s_nop 4
	buffer_load_dwordx2 v[100:101], v192, s[52:55], s0 offen
	v_readlane_b32 s0, v20, 1
	s_nop 4
	buffer_load_dwordx2 v[102:103], v192, s[52:55], s0 offen
	v_readlane_b32 s0, v20, 2
	s_nop 4
	buffer_load_dwordx2 v[98:99], v192, s[52:55], s0 offen
	v_readlane_b32 s0, v20, 3
	s_nop 4
	buffer_load_dwordx2 v[104:105], v192, s[52:55], s0 offen
	v_readlane_b32 s0, v20, 4
	s_nop 4
	buffer_load_dwordx2 v[94:95], v192, s[52:55], s0 offen
	v_readlane_b32 s0, v20, 5
	s_nop 4
	buffer_load_dwordx2 v[86:87], v192, s[52:55], s0 offen
	v_readlane_b32 s0, v20, 6
	s_nop 4
	buffer_load_dwordx2 v[84:85], v192, s[52:55], s0 offen
	v_readlane_b32 s0, v20, 7
	s_nop 4
	buffer_load_dwordx2 v[90:91], v192, s[52:55], s0 offen
	v_readlane_b32 s0, v20, 8
	s_nop 4
	buffer_load_dwordx2 v[78:79], v192, s[52:55], s0 offen
	v_readlane_b32 s0, v20, 9
	s_nop 4
	buffer_load_dwordx2 v[50:51], v192, s[52:55], s0 offen
	v_readlane_b32 s0, v20, 10
	s_nop 4
	buffer_load_dwordx2 v[48:49], v192, s[52:55], s0 offen
	v_readlane_b32 s0, v20, 11
	s_nop 4
	buffer_load_dwordx2 v[54:55], v192, s[52:55], s0 offen
	v_readlane_b32 s0, v20, 12
	s_nop 4
	buffer_load_dwordx2 v[42:43], v192, s[52:55], s0 offen
	v_readlane_b32 s0, v20, 13
	s_nop 4
	buffer_load_dwordx2 v[34:35], v192, s[52:55], s0 offen
	v_readlane_b32 s0, v20, 14
	s_nop 4
	buffer_load_dwordx2 v[32:33], v192, s[52:55], s0 offen
	v_readlane_b32 s0, v20, 15
	s_nop 4
	buffer_load_dwordx2 v[38:39], v192, s[52:55], s0 offen
	global_load_dword v128, v120, s[8:9]
	global_load_dword v136, v120, s[10:11]
	global_load_dword v144, v[6:7], off
	global_load_dword v129, v121, s[8:9]
	global_load_dword v137, v121, s[10:11]
	global_load_dword v145, v[6:7], off offset:64
	global_load_dword v130, v122, s[8:9]
	global_load_dword v138, v122, s[10:11]
	global_load_dword v146, v[6:7], off offset:128
	global_load_dword v131, v123, s[8:9]
	global_load_dword v139, v123, s[10:11]
	global_load_dword v147, v[6:7], off offset:192
	global_load_dword v132, v124, s[8:9]
	global_load_dword v140, v124, s[10:11]
	global_load_dword v148, v[6:7], off offset:256
	global_load_dword v133, v125, s[8:9]
	global_load_dword v141, v125, s[10:11]
	global_load_dword v149, v[6:7], off offset:320
	global_load_dword v134, v126, s[8:9]
	global_load_dword v142, v126, s[10:11]
	global_load_dword v150, v[6:7], off offset:384
	global_load_dword v135, v127, s[8:9]
	global_load_dword v143, v127, s[10:11]
	global_load_dword v151, v[6:7], off offset:448
	s_nop 3
	s_waitcnt vmcnt(39)
	v_dot8_i32_i4 v5, v100, v73, 0
	s_nop 1
	v_dot8_i32_i4 v9, v100, v75, 0
	v_dot8_i32_i4 v5, v101, v77, v5
	v_dot8_i32_i4 v9, v101, v108, v9
	s_waitcnt vmcnt(38)
	v_dot8_i32_i4 v11, v102, v75, 0
	s_nop 0
	v_lshl_add_u32 v5, v5, 4, v9
	v_dot8_i32_i4 v9, v102, v73, 0
	v_dot8_i32_i4 v9, v103, v77, v9
	v_dot8_i32_i4 v11, v103, v108, v11
	s_waitcnt vmcnt(37)
	v_dot8_i32_i4 v13, v98, v75, 0
	s_nop 0
	v_lshl_add_u32 v9, v9, 4, v11
	v_dot8_i32_i4 v11, v98, v73, 0
	v_dot8_i32_i4 v11, v99, v77, v11
	v_dot8_i32_i4 v13, v99, v108, v13
	s_waitcnt vmcnt(36)
	v_dot8_i32_i4 v15, v104, v75, 0
	v_dot8_i32_i4 v15, v105, v108, v15
	v_lshl_add_u32 v11, v11, 4, v13
	v_dot8_i32_i4 v13, v104, v73, 0
	v_dot8_i32_i4 v13, v105, v77, v13
	s_nop 1
	s_nop 0
	v_lshl_add_u32 v13, v13, 4, v15
	s_nop 0
	s_waitcnt vmcnt(35)
	v_dot8_i32_i4 v15, v94, v73, 0
	s_nop 1
	v_dot8_i32_i4 v17, v94, v75, 0
	v_dot8_i32_i4 v15, v95, v77, v15
	v_dot8_i32_i4 v17, v95, v108, v17
	s_waitcnt vmcnt(34)
	v_dot8_i32_i4 v19, v86, v75, 0
	s_nop 0
	v_lshl_add_u32 v15, v15, 4, v17
	v_dot8_i32_i4 v17, v86, v73, 0
	v_dot8_i32_i4 v17, v87, v77, v17
	v_dot8_i32_i4 v19, v87, v108, v19
	s_waitcnt vmcnt(33)
	v_dot8_i32_i4 v21, v84, v75, 0
	v_dot8_i32_i4 v21, v85, v108, v21
	v_lshl_add_u32 v17, v17, 4, v19
	v_dot8_i32_i4 v19, v84, v73, 0
	v_dot8_i32_i4 v19, v85, v77, v19
	s_nop 1
	s_nop 0
	v_lshl_add_u32 v19, v19, 4, v21
	s_waitcnt vmcnt(32)
	v_dot8_i32_i4 v21, v90, v73, 0
	v_dot8_i32_i4 v84, v90, v75, 0
	v_dot8_i32_i4 v21, v91, v77, v21
	v_dot8_i32_i4 v84, v91, v108, v84
	v_readlane_b32 s0, v18, 0
	s_nop 0
	s_nop 0
	v_lshl_add_u32 v21, v21, 4, v84
	s_waitcnt vmcnt(31)
	v_dot8_i32_i4 v84, v78, v73, 0
	v_dot8_i32_i4 v85, v78, v75, 0
	s_nop 0
	buffer_load_dwordx2 v[96:97], v192, s[52:55], s0 offen
	v_readlane_b32 s0, v18, 1
	v_dot8_i32_i4 v84, v79, v77, v84
	v_dot8_i32_i4 v85, v79, v108, v85
	s_nop 1
	s_nop 0
	buffer_load_dwordx2 v[88:89], v192, s[52:55], s0 offen
	v_readlane_b32 s0, v18, 2
	v_lshl_add_u32 v78, v84, 4, v85
	s_nop 1
	s_nop 1
	buffer_load_dwordx2 v[82:83], v192, s[52:55], s0 offen
	v_readlane_b32 s0, v18, 3
	s_waitcnt vmcnt(33)
	v_dot8_i32_i4 v79, v50, v73, 0
	s_nop 0
	s_nop 0
	s_nop 0
	buffer_load_dwordx2 v[92:93], v192, s[52:55], s0 offen
	v_readlane_b32 s0, v18, 4
	v_dot8_i32_i4 v84, v50, v75, 0
	v_dot8_i32_i4 v79, v51, v77, v79
	v_dot8_i32_i4 v84, v51, v108, v84
	s_nop 1
	buffer_load_dwordx2 v[80:81], v192, s[52:55], s0 offen
	v_readlane_b32 s0, v18, 5
	s_nop 0
	v_lshl_add_u32 v50, v79, 4, v84
	s_waitcnt vmcnt(34)
	v_dot8_i32_i4 v51, v48, v73, 0
	v_dot8_i32_i4 v79, v48, v75, 0
	s_nop 0
	buffer_load_dwordx2 v[52:53], v192, s[52:55], s0 offen
	v_readlane_b32 s0, v18, 6
	v_dot8_i32_i4 v51, v49, v77, v51
	v_dot8_i32_i4 v79, v49, v108, v79
	s_waitcnt vmcnt(34)
	v_dot8_i32_i4 v49, v54, v73, 0
	s_nop 0
	buffer_load_dwordx2 v[46:47], v192, s[52:55], s0 offen
	v_readlane_b32 s0, v18, 7
	v_lshl_add_u32 v48, v51, 4, v79
	v_dot8_i32_i4 v51, v54, v75, 0
	v_dot8_i32_i4 v49, v55, v77, v49
	s_nop 1
	buffer_load_dwordx2 v[56:57], v192, s[52:55], s0 offen
	v_readlane_b32 s0, v18, 8
	v_dot8_i32_i4 v51, v55, v108, v51
	s_waitcnt vmcnt(35)
	v_dot8_i32_i4 v54, v42, v75, 0
	v_dot8_i32_i4 v54, v43, v108, v54
	s_nop 0
	buffer_load_dwordx2 v[44:45], v192, s[52:55], s0 offen
	v_readlane_b32 s0, v18, 9
	v_lshl_add_u32 v49, v49, 4, v51
	v_dot8_i32_i4 v51, v42, v73, 0
	v_dot8_i32_i4 v51, v43, v77, v51
	s_nop 1
	buffer_load_dwordx2 v[36:37], v192, s[52:55], s0 offen
	v_readlane_b32 s0, v18, 10
	s_nop 0
	v_lshl_add_u32 v42, v51, 4, v54
	s_waitcnt vmcnt(36)
	v_dot8_i32_i4 v43, v34, v73, 0
	s_nop 1
	buffer_load_dwordx2 v[30:31], v192, s[52:55], s0 offen
	v_readlane_b32 s0, v18, 11
	v_dot8_i32_i4 v51, v34, v75, 0
	v_dot8_i32_i4 v43, v35, v77, v43
	v_dot8_i32_i4 v51, v35, v108, v51
	s_nop 1
	buffer_load_dwordx2 v[40:41], v192, s[52:55], s0 offen
	v_readlane_b32 s0, v18, 12
	s_nop 0
	v_lshl_add_u32 v34, v43, 4, v51
	s_waitcnt vmcnt(37)
	v_dot8_i32_i4 v35, v32, v73, 0
	v_dot8_i32_i4 v43, v32, v75, 0
	s_nop 0
	buffer_load_dwordx2 v[28:29], v192, s[52:55], s0 offen
	v_readlane_b32 s0, v18, 13
	v_dot8_i32_i4 v35, v33, v77, v35
	v_dot8_i32_i4 v43, v33, v108, v43
	s_waitcnt vmcnt(37)
	v_dot8_i32_i4 v33, v38, v73, 0
	s_nop 0
	buffer_load_dwordx2 v[24:25], v192, s[52:55], s0 offen
	v_readlane_b32 s0, v18, 14
	v_lshl_add_u32 v32, v35, 4, v43
	v_dot8_i32_i4 v35, v38, v75, 0
	v_dot8_i32_i4 v33, v39, v77, v33
	s_nop 1
	buffer_load_dwordx2 v[22:23], v192, s[52:55], s0 offen
	v_readlane_b32 s0, v18, 15
	v_dot8_i32_i4 v35, v39, v108, v35
	s_nop 0
	s_nop 2
	buffer_load_dwordx2 v[26:27], v192, s[52:55], s0 offen
	s_nop 0
	v_lshl_add_u32 v33, v33, 4, v35
	v_cndmask_b32_e64 v35, v9, v5, s[40:41]
	v_cndmask_b32_e64 v5, v5, v9, s[40:41]
	v_cndmask_b32_e64 v9, v13, v11, s[40:41]
	v_cndmask_b32_e64 v11, v11, v13, s[40:41]
	ds_swizzle_b32 v11, v11 offset:swizzle(SWAP,1)
	v_cndmask_b32_e64 v13, v15, v17, s[40:41]
	ds_swizzle_b32 v13, v13 offset:swizzle(SWAP,1)
	s_waitcnt lgkmcnt(1)
	v_add_u32_e32 v9, v9, v11
	v_cndmask_b32_e64 v11, v17, v15, s[40:41]
	v_cndmask_b32_e64 v15, v19, v21, s[40:41]
	ds_swizzle_b32 v15, v15 offset:swizzle(SWAP,1)
	v_cndmask_b32_e64 v17, v78, v50, s[40:41]
	s_waitcnt lgkmcnt(1)
	v_add_u32_e32 v11, v11, v13
	v_cndmask_b32_e64 v13, v21, v19, s[40:41]
	ds_swizzle_b32 v17, v17 offset:swizzle(SWAP,1)
	v_cndmask_b32_e64 v19, v48, v49, s[40:41]
	ds_swizzle_b32 v19, v19 offset:swizzle(SWAP,1)
	v_cndmask_b32_e64 v21, v42, v34, s[40:41]
	ds_swizzle_b32 v21, v21 offset:swizzle(SWAP,1)
	s_waitcnt lgkmcnt(3)
	v_add_u32_e32 v13, v13, v15
	v_cndmask_b32_e64 v15, v50, v78, s[40:41]
	s_waitcnt lgkmcnt(2)
	v_add_u32_e32 v15, v15, v17
	v_cndmask_b32_e64 v17, v49, v48, s[40:41]
	s_waitcnt lgkmcnt(1)
	v_add_u32_e32 v17, v17, v19
	v_cndmask_b32_e64 v19, v34, v42, s[40:41]
	ds_swizzle_b32 v5, v5 offset:swizzle(SWAP,1)
	s_waitcnt lgkmcnt(1)
	v_add_u32_e32 v19, v19, v21
	v_cndmask_b32_e64 v21, v33, v32, s[40:41]
	v_cndmask_b32_e64 v32, v32, v33, s[40:41]
	ds_swizzle_b32 v32, v32 offset:swizzle(SWAP,1)
	s_waitcnt lgkmcnt(1)
	v_add_u32_e32 v5, v35, v5
	s_waitcnt lgkmcnt(0)
	v_add_u32_e32 v21, v21, v32
	v_cndmask_b32_e64 v32, v9, v5, s[42:43]
	v_cndmask_b32_e64 v5, v5, v9, s[42:43]
	v_cndmask_b32_e64 v9, v13, v11, s[42:43]
	v_cndmask_b32_e64 v11, v11, v13, s[42:43]
	ds_swizzle_b32 v11, v11 offset:swizzle(SWAP,2)
	v_cndmask_b32_e64 v13, v15, v17, s[42:43]
	ds_swizzle_b32 v13, v13 offset:swizzle(SWAP,2)
	ds_swizzle_b32 v5, v5 offset:swizzle(SWAP,2)
	s_waitcnt lgkmcnt(2)
	v_add_u32_e32 v9, v9, v11
	v_cndmask_b32_e64 v11, v17, v15, s[42:43]
	v_cndmask_b32_e64 v15, v19, v21, s[42:43]
	ds_swizzle_b32 v15, v15 offset:swizzle(SWAP,2)
	s_waitcnt lgkmcnt(2)
	v_add_u32_e32 v11, v11, v13
	v_cndmask_b32_e64 v13, v21, v19, s[42:43]
	s_waitcnt lgkmcnt(1)
	v_add_u32_e32 v5, v32, v5
	s_waitcnt lgkmcnt(0)
	v_add_u32_e32 v13, v13, v15
	v_cndmask_b32_e64 v15, v9, v5, s[44:45]
	v_cndmask_b32_e64 v5, v5, v9, s[44:45]
	v_cndmask_b32_e64 v9, v13, v11, s[44:45]
	v_cndmask_b32_e64 v11, v11, v13, s[44:45]
	ds_swizzle_b32 v5, v5 offset:swizzle(SWAP,4)
	ds_swizzle_b32 v11, v11 offset:swizzle(SWAP,4)
	s_waitcnt lgkmcnt(1)
	v_add_u32_e32 v5, v15, v5
	s_waitcnt lgkmcnt(0)
	v_add_u32_e32 v9, v9, v11
	v_cndmask_b32_e64 v11, v9, v5, s[46:47]
	v_cndmask_b32_e64 v5, v5, v9, s[46:47]
	ds_swizzle_b32 v5, v5 offset:swizzle(SWAP,8)
	s_waitcnt lgkmcnt(0)
	v_add_u32_e32 v5, v11, v5
	ds_swizzle_b32 v9, v5 offset:swizzle(SWAP,16)
	s_waitcnt lgkmcnt(0)
	v_add_u32_e32 v5, v5, v9
	ds_bpermute_b32 v9, v0, v5
	s_and_saveexec_b64 s[0:1], s[48:49]
	s_cbranch_execz .LBB0_671
	v_ashrrev_i32_e32 v21, 31, v20
	v_lshlrev_b64 v[20:21], 2, v[20:21]
	v_lshl_add_u64 v[32:33], s[8:9], 0, v[20:21]
	s_waitcnt vmcnt(39)
	v_mov_b32_e32 v11, v128
	v_lshl_add_u64 v[20:21], s[10:11], 0, v[20:21]
	s_waitcnt vmcnt(37)
	v_mov_b32_e32 v13, v144
	v_mov_b32_e32 v15, v136
	s_waitcnt lgkmcnt(0)
	v_add_u32_e32 v5, v5, v9
	v_cvt_f32_i32_e32 v5, v5
	v_mul_f32_e32 v5, v5, v11
	v_mul_f32_e32 v5, v3, v5
	v_mul_f32_e32 v11, 0x3d372713, v5
	v_mul_f32_e32 v11, v5, v11
	v_mul_f32_e32 v9, 0.5, v5
	v_fmac_f32_e32 v5, v5, v11
	v_mul_f32_e32 v5, 0x3f4c422a, v5
	v_add_f32_e32 v5, v5, v5
	v_mul_f32_e32 v5, 0x3fb8aa3b, v5
	v_exp_f32_e32 v5, v5
	s_nop 0
	v_add_f32_e32 v5, 1.0, v5
	v_rcp_f32_e32 v5, v5
	s_nop 0
	v_fma_f32 v5, v5, -2.0, 1.0
	v_add_f32_e32 v5, 1.0, v5
	v_mul_f32_e32 v5, v9, v5
	v_mul_f32_e32 v5, v13, v5
	v_mul_f32_e32 v5, v15, v5
	ds_write_b32 v109, v5
.LBB0_671:
	s_or_b64 exec, exec, s[0:1]
	v_readlane_b32 s0, v16, 0
	s_waitcnt lgkmcnt(0)
	s_waitcnt vmcnt(15)
	v_dot8_i32_i4 v5, v96, v73, 0
	v_dot8_i32_i4 v9, v96, v75, 0
	s_nop 0
	buffer_load_dwordx2 v[102:103], v192, s[52:55], s0 offen
	v_readlane_b32 s0, v16, 1
	v_dot8_i32_i4 v5, v97, v77, v5
	v_dot8_i32_i4 v9, v97, v108, v9
	s_waitcnt vmcnt(15)
	v_dot8_i32_i4 v11, v88, v75, 0
	s_nop 0
	buffer_load_dwordx2 v[98:99], v192, s[52:55], s0 offen
	v_readlane_b32 s0, v16, 2
	v_lshl_add_u32 v5, v5, 4, v9
	v_dot8_i32_i4 v9, v88, v73, 0
	v_dot8_i32_i4 v9, v89, v77, v9
	s_nop 1
	buffer_load_dwordx2 v[94:95], v192, s[52:55], s0 offen
	v_readlane_b32 s0, v16, 3
	v_dot8_i32_i4 v11, v89, v108, v11
	s_waitcnt vmcnt(16)
	v_dot8_i32_i4 v13, v82, v75, 0
	v_dot8_i32_i4 v13, v83, v108, v13
	s_nop 0
	buffer_load_dwordx2 v[100:101], v192, s[52:55], s0 offen
	v_readlane_b32 s0, v16, 4
	v_lshl_add_u32 v9, v9, 4, v11
	v_dot8_i32_i4 v11, v82, v73, 0
	v_dot8_i32_i4 v11, v83, v77, v11
	s_nop 1
	buffer_load_dwordx2 v[90:91], v192, s[52:55], s0 offen
	v_readlane_b32 s0, v16, 5
	s_nop 0
	v_lshl_add_u32 v11, v11, 4, v13
	s_waitcnt vmcnt(17)
	v_dot8_i32_i4 v13, v92, v73, 0
	s_nop 1
	buffer_load_dwordx2 v[84:85], v192, s[52:55], s0 offen
	v_readlane_b32 s0, v16, 6
	v_dot8_i32_i4 v15, v92, v75, 0
	v_dot8_i32_i4 v13, v93, v77, v13
	v_dot8_i32_i4 v15, v93, v108, v15
	s_nop 1
	buffer_load_dwordx2 v[78:79], v192, s[52:55], s0 offen
	v_readlane_b32 s0, v16, 7
	s_nop 0
	v_lshl_add_u32 v13, v13, 4, v15
	s_waitcnt vmcnt(18)
	v_dot8_i32_i4 v15, v80, v73, 0
	v_dot8_i32_i4 v17, v80, v75, 0
	s_nop 0
	buffer_load_dwordx2 v[86:87], v192, s[52:55], s0 offen
	v_readlane_b32 s0, v16, 8
	v_dot8_i32_i4 v15, v81, v77, v15
	v_dot8_i32_i4 v17, v81, v108, v17
	s_waitcnt vmcnt(18)
	v_dot8_i32_i4 v19, v52, v75, 0
	s_nop 0
	buffer_load_dwordx2 v[54:55], v192, s[52:55], s0 offen
	v_readlane_b32 s0, v16, 9
	v_lshl_add_u32 v15, v15, 4, v17
	v_dot8_i32_i4 v17, v52, v73, 0
	v_dot8_i32_i4 v17, v53, v77, v17
	s_nop 1
	buffer_load_dwordx2 v[48:49], v192, s[52:55], s0 offen
	v_readlane_b32 s0, v16, 10
	v_dot8_i32_i4 v19, v53, v108, v19
	s_waitcnt vmcnt(19)
	v_dot8_i32_i4 v52, v46, v75, 0
	v_dot8_i32_i4 v52, v47, v108, v52
	s_nop 0
	buffer_load_dwordx2 v[42:43], v192, s[52:55], s0 offen
	v_readlane_b32 s0, v16, 11
	v_lshl_add_u32 v17, v17, 4, v19
	v_dot8_i32_i4 v19, v46, v73, 0
	v_dot8_i32_i4 v19, v47, v77, v19
	s_nop 1
	buffer_load_dwordx2 v[50:51], v192, s[52:55], s0 offen
	v_readlane_b32 s0, v16, 12
	s_waitcnt vmcnt(20)
	v_dot8_i32_i4 v46, v56, v73, 0
	v_dot8_i32_i4 v47, v56, v75, 0
	s_nop 1
	buffer_load_dwordx2 v[38:39], v192, s[52:55], s0 offen
	v_readlane_b32 s0, v16, 13
	v_dot8_i32_i4 v46, v57, v77, v46
	v_dot8_i32_i4 v47, v57, v108, v47
	v_lshl_add_u32 v19, v19, 4, v52
	s_nop 1
	buffer_load_dwordx2 v[32:33], v192, s[52:55], s0 offen
	v_readlane_b32 s0, v16, 14
	v_lshl_add_u32 v46, v46, 4, v47
	s_waitcnt vmcnt(21)
	v_dot8_i32_i4 v47, v44, v73, 0
	v_dot8_i32_i4 v52, v44, v75, 0
	s_nop 0
	buffer_load_dwordx2 v[20:21], v192, s[52:55], s0 offen
	v_readlane_b32 s0, v16, 15
	v_dot8_i32_i4 v47, v45, v77, v47
	v_dot8_i32_i4 v52, v45, v108, v52
	s_waitcnt vmcnt(21)
	v_dot8_i32_i4 v45, v36, v73, 0
	s_nop 0
	buffer_load_dwordx2 v[34:35], v192, s[52:55], s0 offen
	v_lshl_add_u32 v44, v47, 4, v52
	v_dot8_i32_i4 v47, v36, v75, 0
	v_dot8_i32_i4 v45, v37, v77, v45
	v_dot8_i32_i4 v47, v37, v108, v47
	s_waitcnt vmcnt(21)
	v_dot8_i32_i4 v37, v30, v73, 0
	v_dot8_i32_i4 v37, v31, v77, v37
	v_lshl_add_u32 v36, v45, 4, v47
	v_dot8_i32_i4 v45, v30, v75, 0
	v_dot8_i32_i4 v45, v31, v108, v45
	s_waitcnt vmcnt(20)
	v_dot8_i32_i4 v31, v40, v73, 0
	v_dot8_i32_i4 v31, v41, v77, v31
	v_lshl_add_u32 v30, v37, 4, v45
	v_dot8_i32_i4 v37, v40, v75, 0
	v_dot8_i32_i4 v37, v41, v108, v37
	s_waitcnt vmcnt(19)
	v_dot8_i32_i4 v40, v28, v75, 0
	v_dot8_i32_i4 v40, v29, v108, v40
	v_lshl_add_u32 v31, v31, 4, v37
	v_dot8_i32_i4 v37, v28, v73, 0
	v_dot8_i32_i4 v37, v29, v77, v37
	s_waitcnt vmcnt(18)
	v_dot8_i32_i4 v29, v24, v73, 0
	v_dot8_i32_i4 v29, v25, v77, v29
	v_lshl_add_u32 v28, v37, 4, v40
	v_dot8_i32_i4 v37, v24, v75, 0
	v_dot8_i32_i4 v37, v25, v108, v37
	s_waitcnt vmcnt(17)
	v_dot8_i32_i4 v25, v22, v73, 0
	s_nop 0
	v_lshl_add_u32 v24, v29, 4, v37
	v_dot8_i32_i4 v29, v22, v75, 0
	v_dot8_i32_i4 v25, v23, v77, v25
	v_dot8_i32_i4 v29, v23, v108, v29
	s_nop 0
	s_nop 0
	s_nop 0
	v_lshl_add_u32 v22, v25, 4, v29
	s_waitcnt vmcnt(16)
	v_dot8_i32_i4 v23, v26, v73, 0
	v_dot8_i32_i4 v25, v26, v75, 0
	v_dot8_i32_i4 v23, v27, v77, v23
	v_dot8_i32_i4 v25, v27, v108, v25
	s_nop 0
	s_nop 0
	s_nop 0
	v_lshl_add_u32 v23, v23, 4, v25
	s_nop 1
	v_cndmask_b32_e64 v25, v9, v5, s[40:41]
	v_cndmask_b32_e64 v5, v5, v9, s[40:41]
	v_cndmask_b32_e64 v9, v13, v11, s[40:41]
	v_cndmask_b32_e64 v11, v11, v13, s[40:41]
	ds_swizzle_b32 v11, v11 offset:swizzle(SWAP,1)
	v_cndmask_b32_e64 v13, v15, v17, s[40:41]
	ds_swizzle_b32 v13, v13 offset:swizzle(SWAP,1)
	s_waitcnt lgkmcnt(1)
	v_add_u32_e32 v9, v9, v11
	v_cndmask_b32_e64 v11, v17, v15, s[40:41]
	v_cndmask_b32_e64 v15, v19, v46, s[40:41]
	ds_swizzle_b32 v15, v15 offset:swizzle(SWAP,1)
	v_cndmask_b32_e64 v17, v44, v36, s[40:41]
	s_waitcnt lgkmcnt(1)
	v_add_u32_e32 v11, v11, v13
	v_cndmask_b32_e64 v13, v46, v19, s[40:41]
	ds_swizzle_b32 v17, v17 offset:swizzle(SWAP,1)
	v_cndmask_b32_e64 v19, v30, v31, s[40:41]
	ds_swizzle_b32 v19, v19 offset:swizzle(SWAP,1)
	s_waitcnt lgkmcnt(2)
	v_add_u32_e32 v13, v13, v15
	v_cndmask_b32_e64 v15, v36, v44, s[40:41]
	s_waitcnt lgkmcnt(1)
	v_add_u32_e32 v15, v15, v17
	v_cndmask_b32_e64 v17, v31, v30, s[40:41]
	s_waitcnt lgkmcnt(0)
	v_add_u32_e32 v17, v17, v19
	v_cndmask_b32_e64 v19, v24, v28, s[40:41]
	v_cndmask_b32_e64 v24, v28, v24, s[40:41]
	ds_swizzle_b32 v5, v5 offset:swizzle(SWAP,1)
	ds_swizzle_b32 v24, v24 offset:swizzle(SWAP,1)
	s_waitcnt lgkmcnt(1)
	v_add_u32_e32 v5, v25, v5
	s_waitcnt lgkmcnt(0)
	v_add_u32_e32 v19, v19, v24
	v_cndmask_b32_e64 v24, v23, v22, s[40:41]
	v_cndmask_b32_e64 v22, v22, v23, s[40:41]
	ds_swizzle_b32 v22, v22 offset:swizzle(SWAP,1)
	v_cndmask_b32_e64 v23, v9, v5, s[42:43]
	v_cndmask_b32_e64 v5, v5, v9, s[42:43]
	v_cndmask_b32_e64 v9, v13, v11, s[42:43]
	v_cndmask_b32_e64 v11, v11, v13, s[42:43]
	ds_swizzle_b32 v11, v11 offset:swizzle(SWAP,2)
	s_waitcnt lgkmcnt(1)
	v_add_u32_e32 v22, v24, v22
	v_cndmask_b32_e64 v13, v15, v17, s[42:43]
	ds_swizzle_b32 v13, v13 offset:swizzle(SWAP,2)
	ds_swizzle_b32 v5, v5 offset:swizzle(SWAP,2)
	s_waitcnt lgkmcnt(2)
	v_add_u32_e32 v9, v9, v11
	v_cndmask_b32_e64 v11, v17, v15, s[42:43]
	v_cndmask_b32_e64 v15, v19, v22, s[42:43]
	ds_swizzle_b32 v15, v15 offset:swizzle(SWAP,2)
	s_waitcnt lgkmcnt(2)
	v_add_u32_e32 v11, v11, v13
	v_cndmask_b32_e64 v13, v22, v19, s[42:43]
	s_waitcnt lgkmcnt(1)
	v_add_u32_e32 v5, v23, v5
	s_waitcnt lgkmcnt(0)
	v_add_u32_e32 v13, v13, v15
	v_cndmask_b32_e64 v15, v9, v5, s[44:45]
	v_cndmask_b32_e64 v5, v5, v9, s[44:45]
	v_cndmask_b32_e64 v9, v13, v11, s[44:45]
	v_cndmask_b32_e64 v11, v11, v13, s[44:45]
	ds_swizzle_b32 v5, v5 offset:swizzle(SWAP,4)
	ds_swizzle_b32 v11, v11 offset:swizzle(SWAP,4)
	s_waitcnt lgkmcnt(1)
	v_add_u32_e32 v5, v15, v5
	s_waitcnt lgkmcnt(0)
	v_add_u32_e32 v9, v9, v11
	v_cndmask_b32_e64 v11, v9, v5, s[46:47]
	v_cndmask_b32_e64 v5, v5, v9, s[46:47]
	ds_swizzle_b32 v5, v5 offset:swizzle(SWAP,8)
	s_waitcnt lgkmcnt(0)
	v_add_u32_e32 v5, v11, v5
	ds_swizzle_b32 v9, v5 offset:swizzle(SWAP,16)
	s_waitcnt lgkmcnt(0)
	v_add_u32_e32 v5, v5, v9
	ds_bpermute_b32 v9, v0, v5
	s_and_saveexec_b64 s[0:1], s[48:49]
	s_cbranch_execz .LBB0_673
	v_ashrrev_i32_e32 v19, 31, v18
	v_lshlrev_b64 v[18:19], 2, v[18:19]
	v_lshl_add_u64 v[22:23], s[8:9], 0, v[18:19]
	v_mov_b32_e32 v11, v129
	v_lshl_add_u64 v[18:19], s[10:11], 0, v[18:19]
	v_mov_b32_e32 v13, v145
	v_mov_b32_e32 v15, v137
	s_waitcnt lgkmcnt(0)
	v_add_u32_e32 v5, v5, v9
	v_cvt_f32_i32_e32 v5, v5
	v_mul_f32_e32 v5, v5, v11
	v_mul_f32_e32 v5, v3, v5
	v_mul_f32_e32 v11, 0x3d372713, v5
	v_mul_f32_e32 v11, v5, v11
	v_mul_f32_e32 v9, 0.5, v5
	v_fmac_f32_e32 v5, v5, v11
	v_mul_f32_e32 v5, 0x3f4c422a, v5
	v_add_f32_e32 v5, v5, v5
	v_mul_f32_e32 v5, 0x3fb8aa3b, v5
	v_exp_f32_e32 v5, v5
	s_nop 0
	v_add_f32_e32 v5, 1.0, v5
	v_rcp_f32_e32 v5, v5
	s_nop 0
	v_fma_f32 v5, v5, -2.0, 1.0
	v_add_f32_e32 v5, 1.0, v5
	v_mul_f32_e32 v5, v9, v5
	v_mul_f32_e32 v5, v13, v5
	v_mul_f32_e32 v5, v15, v5
	ds_write_b32 v109, v5 offset:64
.LBB0_673:
	s_or_b64 exec, exec, s[0:1]
	v_readlane_b32 s0, v14, 0
	s_waitcnt lgkmcnt(0)
	s_waitcnt vmcnt(15)
	v_dot8_i32_i4 v5, v102, v73, 0
	v_dot8_i32_i4 v9, v102, v75, 0
	s_nop 0
	buffer_load_dwordx2 v[96:97], v192, s[52:55], s0 offen
	v_readlane_b32 s0, v14, 1
	v_dot8_i32_i4 v5, v103, v77, v5
	v_dot8_i32_i4 v9, v103, v108, v9
	s_waitcnt vmcnt(15)
	v_dot8_i32_i4 v11, v98, v75, 0
	s_nop 0
	buffer_load_dwordx2 v[104:105], v192, s[52:55], s0 offen
	v_readlane_b32 s0, v14, 2
	v_lshl_add_u32 v5, v5, 4, v9
	v_dot8_i32_i4 v9, v98, v73, 0
	v_dot8_i32_i4 v9, v99, v77, v9
	s_nop 1
	buffer_load_dwordx2 v[92:93], v192, s[52:55], s0 offen
	v_readlane_b32 s0, v14, 3
	v_dot8_i32_i4 v11, v99, v108, v11
	s_waitcnt vmcnt(16)
	v_dot8_i32_i4 v13, v94, v75, 0
	v_dot8_i32_i4 v13, v95, v108, v13
	s_nop 0
	buffer_load_dwordx2 v[106:107], v192, s[52:55], s0 offen
	v_readlane_b32 s0, v14, 4
	v_lshl_add_u32 v9, v9, 4, v11
	v_dot8_i32_i4 v11, v94, v73, 0
	v_dot8_i32_i4 v11, v95, v77, v11
	s_nop 1
	buffer_load_dwordx2 v[88:89], v192, s[52:55], s0 offen
	v_readlane_b32 s0, v14, 5
	s_nop 0
	v_lshl_add_u32 v11, v11, 4, v13
	s_waitcnt vmcnt(17)
	v_dot8_i32_i4 v13, v100, v73, 0
	s_nop 1
	buffer_load_dwordx2 v[80:81], v192, s[52:55], s0 offen
	v_readlane_b32 s0, v14, 6
	v_dot8_i32_i4 v15, v100, v75, 0
	v_dot8_i32_i4 v13, v101, v77, v13
	v_dot8_i32_i4 v15, v101, v108, v15
	s_nop 1
	buffer_load_dwordx2 v[56:57], v192, s[52:55], s0 offen
	v_readlane_b32 s0, v14, 7
	s_nop 0
	v_lshl_add_u32 v13, v13, 4, v15
	s_waitcnt vmcnt(18)
	v_dot8_i32_i4 v15, v90, v73, 0
	v_dot8_i32_i4 v17, v90, v75, 0
	s_nop 0
	buffer_load_dwordx2 v[82:83], v192, s[52:55], s0 offen
	v_readlane_b32 s0, v14, 8
	v_dot8_i32_i4 v15, v91, v77, v15
	v_dot8_i32_i4 v17, v91, v108, v17
	s_waitcnt vmcnt(18)
	v_dot8_i32_i4 v22, v84, v75, 0
	s_nop 0
	buffer_load_dwordx2 v[52:53], v192, s[52:55], s0 offen
	v_readlane_b32 s0, v14, 9
	v_lshl_add_u32 v15, v15, 4, v17
	v_dot8_i32_i4 v17, v84, v73, 0
	v_dot8_i32_i4 v17, v85, v77, v17
	s_nop 1
	buffer_load_dwordx2 v[44:45], v192, s[52:55], s0 offen
	v_readlane_b32 s0, v14, 10
	v_dot8_i32_i4 v22, v85, v108, v22
	s_waitcnt vmcnt(19)
	v_dot8_i32_i4 v23, v78, v75, 0
	v_dot8_i32_i4 v23, v79, v108, v23
	s_nop 0
	buffer_load_dwordx2 v[40:41], v192, s[52:55], s0 offen
	v_readlane_b32 s0, v14, 11
	v_lshl_add_u32 v17, v17, 4, v22
	v_dot8_i32_i4 v22, v78, v73, 0
	v_dot8_i32_i4 v22, v79, v77, v22
	s_nop 1
	buffer_load_dwordx2 v[46:47], v192, s[52:55], s0 offen
	v_readlane_b32 s0, v14, 12
	s_nop 0
	v_lshl_add_u32 v22, v22, 4, v23
	s_waitcnt vmcnt(20)
	v_dot8_i32_i4 v23, v86, v73, 0
	s_nop 1
	buffer_load_dwordx2 v[36:37], v192, s[52:55], s0 offen
	v_readlane_b32 s0, v14, 13
	v_dot8_i32_i4 v26, v86, v75, 0
	v_dot8_i32_i4 v23, v87, v77, v23
	v_dot8_i32_i4 v26, v87, v108, v26
	s_nop 1
	buffer_load_dwordx2 v[24:25], v192, s[52:55], s0 offen
	v_readlane_b32 s0, v14, 14
	s_nop 0
	v_lshl_add_u32 v23, v23, 4, v26
	s_waitcnt vmcnt(21)
	v_dot8_i32_i4 v26, v54, v73, 0
	v_dot8_i32_i4 v27, v54, v75, 0
	s_nop 0
	buffer_load_dwordx2 v[18:19], v192, s[52:55], s0 offen
	v_readlane_b32 s0, v14, 15
	v_dot8_i32_i4 v26, v55, v77, v26
	v_dot8_i32_i4 v27, v55, v108, v27
	s_waitcnt vmcnt(21)
	v_dot8_i32_i4 v30, v48, v75, 0
	s_nop 0
	buffer_load_dwordx2 v[28:29], v192, s[52:55], s0 offen
	v_lshl_add_u32 v26, v26, 4, v27
	v_dot8_i32_i4 v27, v48, v73, 0
	v_dot8_i32_i4 v27, v49, v77, v27
	v_dot8_i32_i4 v30, v49, v108, v30
	s_waitcnt vmcnt(21)
	v_dot8_i32_i4 v31, v42, v75, 0
	v_dot8_i32_i4 v31, v43, v108, v31
	v_lshl_add_u32 v27, v27, 4, v30
	v_dot8_i32_i4 v30, v42, v73, 0
	v_dot8_i32_i4 v30, v43, v77, v30
	s_waitcnt vmcnt(20)
	v_dot8_i32_i4 v42, v50, v75, 0
	v_dot8_i32_i4 v42, v51, v108, v42
	v_lshl_add_u32 v30, v30, 4, v31
	v_dot8_i32_i4 v31, v50, v73, 0
	v_dot8_i32_i4 v31, v51, v77, v31
	s_waitcnt vmcnt(19)
	v_dot8_i32_i4 v43, v38, v75, 0
	v_dot8_i32_i4 v43, v39, v108, v43
	v_lshl_add_u32 v31, v31, 4, v42
	v_dot8_i32_i4 v42, v38, v73, 0
	v_dot8_i32_i4 v42, v39, v77, v42
	s_waitcnt vmcnt(18)
	v_dot8_i32_i4 v39, v32, v73, 0
	v_dot8_i32_i4 v39, v33, v77, v39
	v_lshl_add_u32 v38, v42, 4, v43
	v_dot8_i32_i4 v42, v32, v75, 0
	v_dot8_i32_i4 v42, v33, v108, v42
	s_waitcnt vmcnt(17)
	v_dot8_i32_i4 v33, v20, v73, 0
	s_nop 0
	v_lshl_add_u32 v32, v39, 4, v42
	v_dot8_i32_i4 v39, v20, v75, 0
	v_dot8_i32_i4 v33, v21, v77, v33
	v_dot8_i32_i4 v39, v21, v108, v39
	s_nop 0
	s_nop 0
	s_nop 0
	v_lshl_add_u32 v20, v33, 4, v39
	s_waitcnt vmcnt(16)
	v_dot8_i32_i4 v21, v34, v73, 0
	v_dot8_i32_i4 v33, v34, v75, 0
	v_dot8_i32_i4 v21, v35, v77, v21
	v_dot8_i32_i4 v33, v35, v108, v33
	s_nop 0
	s_nop 0
	s_nop 0
	v_lshl_add_u32 v21, v21, 4, v33
	s_nop 1
	v_cndmask_b32_e64 v33, v9, v5, s[40:41]
	v_cndmask_b32_e64 v5, v5, v9, s[40:41]
	v_cndmask_b32_e64 v9, v13, v11, s[40:41]
	v_cndmask_b32_e64 v11, v11, v13, s[40:41]
	ds_swizzle_b32 v11, v11 offset:swizzle(SWAP,1)
	v_cndmask_b32_e64 v13, v15, v17, s[40:41]
	ds_swizzle_b32 v13, v13 offset:swizzle(SWAP,1)
	s_waitcnt lgkmcnt(1)
	v_add_u32_e32 v9, v9, v11
	v_cndmask_b32_e64 v11, v17, v15, s[40:41]
	v_cndmask_b32_e64 v15, v22, v23, s[40:41]
	ds_swizzle_b32 v15, v15 offset:swizzle(SWAP,1)
	v_cndmask_b32_e64 v17, v26, v27, s[40:41]
	s_waitcnt lgkmcnt(1)
	v_add_u32_e32 v11, v11, v13
	v_cndmask_b32_e64 v13, v23, v22, s[40:41]
	ds_swizzle_b32 v17, v17 offset:swizzle(SWAP,1)
	v_cndmask_b32_e64 v22, v30, v31, s[40:41]
	ds_swizzle_b32 v22, v22 offset:swizzle(SWAP,1)
	v_cndmask_b32_e64 v23, v38, v32, s[40:41]
	ds_swizzle_b32 v5, v5 offset:swizzle(SWAP,1)
	ds_swizzle_b32 v23, v23 offset:swizzle(SWAP,1)
	s_waitcnt lgkmcnt(4)
	v_add_u32_e32 v13, v13, v15
	v_cndmask_b32_e64 v15, v27, v26, s[40:41]
	s_waitcnt lgkmcnt(3)
	v_add_u32_e32 v15, v15, v17
	v_cndmask_b32_e64 v17, v31, v30, s[40:41]
	s_waitcnt lgkmcnt(2)
	v_add_u32_e32 v17, v17, v22
	v_cndmask_b32_e64 v22, v32, v38, s[40:41]
	s_waitcnt lgkmcnt(1)
	v_add_u32_e32 v5, v33, v5
	s_waitcnt lgkmcnt(0)
	v_add_u32_e32 v22, v22, v23
	v_cndmask_b32_e64 v23, v21, v20, s[40:41]
	v_cndmask_b32_e64 v20, v20, v21, s[40:41]
	ds_swizzle_b32 v20, v20 offset:swizzle(SWAP,1)
	v_cndmask_b32_e64 v21, v9, v5, s[42:43]
	v_cndmask_b32_e64 v5, v5, v9, s[42:43]
	v_cndmask_b32_e64 v9, v13, v11, s[42:43]
	v_cndmask_b32_e64 v11, v11, v13, s[42:43]
	ds_swizzle_b32 v11, v11 offset:swizzle(SWAP,2)
	s_waitcnt lgkmcnt(1)
	v_add_u32_e32 v20, v23, v20
	v_cndmask_b32_e64 v13, v15, v17, s[42:43]
	ds_swizzle_b32 v13, v13 offset:swizzle(SWAP,2)
	ds_swizzle_b32 v5, v5 offset:swizzle(SWAP,2)
	s_waitcnt lgkmcnt(2)
	v_add_u32_e32 v9, v9, v11
	v_cndmask_b32_e64 v11, v17, v15, s[42:43]
	v_cndmask_b32_e64 v15, v22, v20, s[42:43]
	ds_swizzle_b32 v15, v15 offset:swizzle(SWAP,2)
	s_waitcnt lgkmcnt(2)
	v_add_u32_e32 v11, v11, v13
	v_cndmask_b32_e64 v13, v20, v22, s[42:43]
	s_waitcnt lgkmcnt(1)
	v_add_u32_e32 v5, v21, v5
	s_waitcnt lgkmcnt(0)
	v_add_u32_e32 v13, v13, v15
	v_cndmask_b32_e64 v15, v9, v5, s[44:45]
	v_cndmask_b32_e64 v5, v5, v9, s[44:45]
	v_cndmask_b32_e64 v9, v13, v11, s[44:45]
	v_cndmask_b32_e64 v11, v11, v13, s[44:45]
	ds_swizzle_b32 v5, v5 offset:swizzle(SWAP,4)
	ds_swizzle_b32 v11, v11 offset:swizzle(SWAP,4)
	s_waitcnt lgkmcnt(1)
	v_add_u32_e32 v5, v15, v5
	s_waitcnt lgkmcnt(0)
	v_add_u32_e32 v9, v9, v11
	v_cndmask_b32_e64 v11, v9, v5, s[46:47]
	v_cndmask_b32_e64 v5, v5, v9, s[46:47]
	ds_swizzle_b32 v5, v5 offset:swizzle(SWAP,8)
	s_waitcnt lgkmcnt(0)
	v_add_u32_e32 v5, v11, v5
	ds_swizzle_b32 v9, v5 offset:swizzle(SWAP,16)
	s_waitcnt lgkmcnt(0)
	v_add_u32_e32 v5, v5, v9
	ds_bpermute_b32 v9, v0, v5
	s_and_saveexec_b64 s[0:1], s[48:49]
	s_cbranch_execz .LBB0_675
	v_ashrrev_i32_e32 v17, 31, v16
	v_lshlrev_b64 v[16:17], 2, v[16:17]
	v_lshl_add_u64 v[20:21], s[8:9], 0, v[16:17]
	v_mov_b32_e32 v11, v130
	v_lshl_add_u64 v[16:17], s[10:11], 0, v[16:17]
	v_mov_b32_e32 v13, v146
	v_mov_b32_e32 v15, v138
	s_waitcnt lgkmcnt(0)
	v_add_u32_e32 v5, v5, v9
	v_cvt_f32_i32_e32 v5, v5
	v_mul_f32_e32 v5, v5, v11
	v_mul_f32_e32 v5, v3, v5
	v_mul_f32_e32 v11, 0x3d372713, v5
	v_mul_f32_e32 v11, v5, v11
	v_mul_f32_e32 v9, 0.5, v5
	v_fmac_f32_e32 v5, v5, v11
	v_mul_f32_e32 v5, 0x3f4c422a, v5
	v_add_f32_e32 v5, v5, v5
	v_mul_f32_e32 v5, 0x3fb8aa3b, v5
	v_exp_f32_e32 v5, v5
	s_nop 0
	v_add_f32_e32 v5, 1.0, v5
	v_rcp_f32_e32 v5, v5
	s_nop 0
	v_fma_f32 v5, v5, -2.0, 1.0
	v_add_f32_e32 v5, 1.0, v5
	v_mul_f32_e32 v5, v9, v5
	v_mul_f32_e32 v5, v13, v5
	v_mul_f32_e32 v5, v15, v5
	ds_write_b32 v109, v5 offset:128
.LBB0_675:
	s_or_b64 exec, exec, s[0:1]
	v_readlane_b32 s0, v12, 0
	s_waitcnt lgkmcnt(0)
	s_waitcnt vmcnt(15)
	v_dot8_i32_i4 v5, v96, v73, 0
	v_dot8_i32_i4 v9, v96, v75, 0
	s_nop 0
	buffer_load_dwordx2 v[94:95], v192, s[52:55], s0 offen
	v_readlane_b32 s0, v12, 1
	v_dot8_i32_i4 v5, v97, v77, v5
	v_dot8_i32_i4 v9, v97, v108, v9
	s_waitcnt vmcnt(15)
	v_dot8_i32_i4 v11, v104, v75, 0
	s_nop 0
	buffer_load_dwordx2 v[86:87], v192, s[52:55], s0 offen
	v_readlane_b32 s0, v12, 2
	v_lshl_add_u32 v5, v5, 4, v9
	v_dot8_i32_i4 v9, v104, v73, 0
	v_dot8_i32_i4 v9, v105, v77, v9
	s_nop 1
	buffer_load_dwordx2 v[84:85], v192, s[52:55], s0 offen
	v_readlane_b32 s0, v12, 3
	v_dot8_i32_i4 v11, v105, v108, v11
	s_waitcnt vmcnt(16)
	v_dot8_i32_i4 v13, v92, v75, 0
	v_dot8_i32_i4 v13, v93, v108, v13
	s_nop 0
	buffer_load_dwordx2 v[90:91], v192, s[52:55], s0 offen
	v_readlane_b32 s0, v12, 4
	v_lshl_add_u32 v9, v9, 4, v11
	v_dot8_i32_i4 v11, v92, v73, 0
	v_dot8_i32_i4 v11, v93, v77, v11
	s_nop 1
	buffer_load_dwordx2 v[78:79], v192, s[52:55], s0 offen
	v_readlane_b32 s0, v12, 5
	s_nop 0
	v_lshl_add_u32 v11, v11, 4, v13
	s_waitcnt vmcnt(17)
	v_dot8_i32_i4 v13, v106, v73, 0
	s_nop 1
	buffer_load_dwordx2 v[50:51], v192, s[52:55], s0 offen
	v_readlane_b32 s0, v12, 6
	v_dot8_i32_i4 v15, v106, v75, 0
	v_dot8_i32_i4 v13, v107, v77, v13
	v_dot8_i32_i4 v15, v107, v108, v15
	s_nop 1
	buffer_load_dwordx2 v[48:49], v192, s[52:55], s0 offen
	v_readlane_b32 s0, v12, 7
	s_nop 0
	v_lshl_add_u32 v13, v13, 4, v15
	s_waitcnt vmcnt(18)
	v_dot8_i32_i4 v15, v88, v73, 0
	v_dot8_i32_i4 v32, v88, v75, 0
	s_nop 0
	buffer_load_dwordx2 v[54:55], v192, s[52:55], s0 offen
	v_readlane_b32 s0, v12, 8
	v_dot8_i32_i4 v15, v89, v77, v15
	v_dot8_i32_i4 v32, v89, v108, v32
	s_waitcnt vmcnt(18)
	v_dot8_i32_i4 v33, v80, v75, 0
	s_nop 0
	buffer_load_dwordx2 v[42:43], v192, s[52:55], s0 offen
	v_readlane_b32 s0, v12, 9
	v_lshl_add_u32 v15, v15, 4, v32
	v_dot8_i32_i4 v32, v80, v73, 0
	v_dot8_i32_i4 v32, v81, v77, v32
	s_nop 1
	buffer_load_dwordx2 v[34:35], v192, s[52:55], s0 offen
	v_readlane_b32 s0, v12, 10
	v_dot8_i32_i4 v33, v81, v108, v33
	s_waitcnt vmcnt(19)
	v_dot8_i32_i4 v80, v56, v75, 0
	v_dot8_i32_i4 v80, v57, v108, v80
	s_nop 0
	buffer_load_dwordx2 v[30:31], v192, s[52:55], s0 offen
	v_readlane_b32 s0, v12, 11
	v_lshl_add_u32 v32, v32, 4, v33
	v_dot8_i32_i4 v33, v56, v73, 0
	v_dot8_i32_i4 v33, v57, v77, v33
	s_nop 1
	buffer_load_dwordx2 v[38:39], v192, s[52:55], s0 offen
	v_readlane_b32 s0, v12, 12
	s_waitcnt vmcnt(20)
	v_dot8_i32_i4 v56, v82, v73, 0
	v_dot8_i32_i4 v57, v82, v75, 0
	s_nop 1
	buffer_load_dwordx2 v[26:27], v192, s[52:55], s0 offen
	v_readlane_b32 s0, v12, 13
	v_dot8_i32_i4 v56, v83, v77, v56
	v_dot8_i32_i4 v57, v83, v108, v57
	v_lshl_add_u32 v33, v33, 4, v80
	s_nop 1
	buffer_load_dwordx2 v[20:21], v192, s[52:55], s0 offen
	v_readlane_b32 s0, v12, 14
	v_lshl_add_u32 v56, v56, 4, v57
	s_waitcnt vmcnt(21)
	v_dot8_i32_i4 v57, v52, v73, 0
	v_dot8_i32_i4 v80, v52, v75, 0
	s_nop 0
	buffer_load_dwordx2 v[16:17], v192, s[52:55], s0 offen
	v_readlane_b32 s0, v12, 15
	v_dot8_i32_i4 v57, v53, v77, v57
	v_dot8_i32_i4 v80, v53, v108, v80
	s_waitcnt vmcnt(21)
	v_dot8_i32_i4 v53, v44, v73, 0
	s_nop 0
	buffer_load_dwordx2 v[22:23], v192, s[52:55], s0 offen
	v_lshl_add_u32 v52, v57, 4, v80
	v_dot8_i32_i4 v57, v44, v75, 0
	v_dot8_i32_i4 v53, v45, v77, v53
	v_dot8_i32_i4 v57, v45, v108, v57
	s_waitcnt vmcnt(21)
	v_dot8_i32_i4 v45, v40, v73, 0
	v_dot8_i32_i4 v45, v41, v77, v45
	v_lshl_add_u32 v44, v53, 4, v57
	v_dot8_i32_i4 v53, v40, v75, 0
	v_dot8_i32_i4 v53, v41, v108, v53
	s_waitcnt vmcnt(20)
	v_dot8_i32_i4 v41, v46, v73, 0
	v_dot8_i32_i4 v41, v47, v77, v41
	v_lshl_add_u32 v40, v45, 4, v53
	v_dot8_i32_i4 v45, v46, v75, 0
	v_dot8_i32_i4 v45, v47, v108, v45
	s_waitcnt vmcnt(19)
	v_dot8_i32_i4 v46, v36, v75, 0
	v_dot8_i32_i4 v46, v37, v108, v46
	v_lshl_add_u32 v41, v41, 4, v45
	v_dot8_i32_i4 v45, v36, v73, 0
	v_dot8_i32_i4 v45, v37, v77, v45
	s_waitcnt vmcnt(18)
	v_dot8_i32_i4 v37, v24, v73, 0
	v_dot8_i32_i4 v37, v25, v77, v37
	v_lshl_add_u32 v36, v45, 4, v46
	v_dot8_i32_i4 v45, v24, v75, 0
	v_dot8_i32_i4 v45, v25, v108, v45
	s_waitcnt vmcnt(17)
	v_dot8_i32_i4 v25, v18, v73, 0
	s_nop 0
	v_lshl_add_u32 v24, v37, 4, v45
	v_dot8_i32_i4 v37, v18, v75, 0
	v_dot8_i32_i4 v25, v19, v77, v25
	v_dot8_i32_i4 v37, v19, v108, v37
	s_waitcnt vmcnt(16)
	v_dot8_i32_i4 v19, v28, v73, 0
	v_dot8_i32_i4 v19, v29, v77, v19
	v_lshl_add_u32 v18, v25, 4, v37
	v_dot8_i32_i4 v25, v28, v75, 0
	v_dot8_i32_i4 v25, v29, v108, v25
	s_nop 1
	s_nop 0
	v_lshl_add_u32 v19, v19, 4, v25
	s_nop 0
	v_cndmask_b32_e64 v25, v9, v5, s[40:41]
	v_cndmask_b32_e64 v5, v5, v9, s[40:41]
	v_cndmask_b32_e64 v9, v13, v11, s[40:41]
	v_cndmask_b32_e64 v11, v11, v13, s[40:41]
	ds_swizzle_b32 v11, v11 offset:swizzle(SWAP,1)
	ds_swizzle_b32 v5, v5 offset:swizzle(SWAP,1)
	v_cndmask_b32_e64 v13, v15, v32, s[40:41]
	s_waitcnt lgkmcnt(1)
	v_add_u32_e32 v9, v9, v11
	v_cndmask_b32_e64 v11, v32, v15, s[40:41]
	ds_swizzle_b32 v13, v13 offset:swizzle(SWAP,1)
	v_cndmask_b32_e64 v15, v33, v56, s[40:41]
	s_waitcnt lgkmcnt(1)
	v_add_u32_e32 v5, v25, v5
	ds_swizzle_b32 v15, v15 offset:swizzle(SWAP,1)
	v_cndmask_b32_e64 v25, v52, v44, s[40:41]
	ds_swizzle_b32 v25, v25 offset:swizzle(SWAP,1)
	v_cndmask_b32_e64 v28, v40, v41, s[40:41]
	ds_swizzle_b32 v28, v28 offset:swizzle(SWAP,1)
	s_waitcnt lgkmcnt(3)
	v_add_u32_e32 v11, v11, v13
	v_cndmask_b32_e64 v13, v56, v33, s[40:41]
	s_waitcnt lgkmcnt(2)
	v_add_u32_e32 v13, v13, v15
	v_cndmask_b32_e64 v15, v44, v52, s[40:41]
	s_waitcnt lgkmcnt(1)
	v_add_u32_e32 v15, v15, v25
	v_cndmask_b32_e64 v25, v41, v40, s[40:41]
	s_waitcnt lgkmcnt(0)
	v_add_u32_e32 v25, v25, v28
	v_cndmask_b32_e64 v28, v24, v36, s[40:41]
	v_cndmask_b32_e64 v24, v36, v24, s[40:41]
	ds_swizzle_b32 v24, v24 offset:swizzle(SWAP,1)
	s_waitcnt lgkmcnt(0)
	v_add_u32_e32 v24, v28, v24
	v_cndmask_b32_e64 v28, v19, v18, s[40:41]
	v_cndmask_b32_e64 v18, v18, v19, s[40:41]
	ds_swizzle_b32 v18, v18 offset:swizzle(SWAP,1)
	v_cndmask_b32_e64 v19, v9, v5, s[42:43]
	v_cndmask_b32_e64 v5, v5, v9, s[42:43]
	v_cndmask_b32_e64 v9, v13, v11, s[42:43]
	v_cndmask_b32_e64 v11, v11, v13, s[42:43]
	ds_swizzle_b32 v11, v11 offset:swizzle(SWAP,2)
	s_waitcnt lgkmcnt(1)
	v_add_u32_e32 v18, v28, v18
	v_cndmask_b32_e64 v13, v15, v25, s[42:43]
	ds_swizzle_b32 v13, v13 offset:swizzle(SWAP,2)
	ds_swizzle_b32 v5, v5 offset:swizzle(SWAP,2)
	s_waitcnt lgkmcnt(2)
	v_add_u32_e32 v9, v9, v11
	v_cndmask_b32_e64 v11, v25, v15, s[42:43]
	v_cndmask_b32_e64 v15, v24, v18, s[42:43]
	ds_swizzle_b32 v15, v15 offset:swizzle(SWAP,2)
	s_waitcnt lgkmcnt(2)
	v_add_u32_e32 v11, v11, v13
	v_cndmask_b32_e64 v13, v18, v24, s[42:43]
	s_waitcnt lgkmcnt(1)
	v_add_u32_e32 v5, v19, v5
	s_waitcnt lgkmcnt(0)
	v_add_u32_e32 v13, v13, v15
	v_cndmask_b32_e64 v15, v9, v5, s[44:45]
	v_cndmask_b32_e64 v5, v5, v9, s[44:45]
	v_cndmask_b32_e64 v9, v13, v11, s[44:45]
	v_cndmask_b32_e64 v11, v11, v13, s[44:45]
	ds_swizzle_b32 v5, v5 offset:swizzle(SWAP,4)
	ds_swizzle_b32 v11, v11 offset:swizzle(SWAP,4)
	s_waitcnt lgkmcnt(1)
	v_add_u32_e32 v5, v15, v5
	s_waitcnt lgkmcnt(0)
	v_add_u32_e32 v9, v9, v11
	v_cndmask_b32_e64 v11, v9, v5, s[46:47]
	v_cndmask_b32_e64 v5, v5, v9, s[46:47]
	ds_swizzle_b32 v5, v5 offset:swizzle(SWAP,8)
	s_waitcnt lgkmcnt(0)
	v_add_u32_e32 v5, v11, v5
	ds_swizzle_b32 v9, v5 offset:swizzle(SWAP,16)
	s_waitcnt lgkmcnt(0)
	v_add_u32_e32 v5, v5, v9
	ds_bpermute_b32 v9, v0, v5
	s_and_saveexec_b64 s[0:1], s[48:49]
	s_cbranch_execz .LBB0_677
	v_ashrrev_i32_e32 v15, 31, v14
	v_lshlrev_b64 v[14:15], 2, v[14:15]
	v_lshl_add_u64 v[18:19], s[8:9], 0, v[14:15]
	v_mov_b32_e32 v11, v131
	v_lshl_add_u64 v[14:15], s[10:11], 0, v[14:15]
	v_mov_b32_e32 v13, v147
	s_nop 0
	v_mov_b32_e32 v14, v139
	s_waitcnt lgkmcnt(0)
	v_add_u32_e32 v5, v5, v9
	v_cvt_f32_i32_e32 v5, v5
	v_mul_f32_e32 v5, v5, v11
	v_mul_f32_e32 v5, v3, v5
	v_mul_f32_e32 v11, 0x3d372713, v5
	v_mul_f32_e32 v11, v5, v11
	v_mul_f32_e32 v9, 0.5, v5
	v_fmac_f32_e32 v5, v5, v11
	v_mul_f32_e32 v5, 0x3f4c422a, v5
	v_add_f32_e32 v5, v5, v5
	v_mul_f32_e32 v5, 0x3fb8aa3b, v5
	v_exp_f32_e32 v5, v5
	s_nop 0
	v_add_f32_e32 v5, 1.0, v5
	v_rcp_f32_e32 v5, v5
	s_nop 0
	v_fma_f32 v5, v5, -2.0, 1.0
	v_add_f32_e32 v5, 1.0, v5
	v_mul_f32_e32 v5, v9, v5
	v_mul_f32_e32 v5, v13, v5
	v_mul_f32_e32 v5, v14, v5
	ds_write_b32 v109, v5 offset:192
.LBB0_677:
	s_or_b64 exec, exec, s[0:1]
	v_readlane_b32 s0, v10, 0
	s_waitcnt lgkmcnt(0)
	s_waitcnt vmcnt(15)
	v_dot8_i32_i4 v5, v94, v73, 0
	v_dot8_i32_i4 v9, v94, v75, 0
	s_nop 0
	buffer_load_dwordx2 v[92:93], v192, s[52:55], s0 offen
	v_readlane_b32 s0, v10, 1
	v_dot8_i32_i4 v5, v95, v77, v5
	v_dot8_i32_i4 v9, v95, v108, v9
	s_waitcnt vmcnt(15)
	v_dot8_i32_i4 v11, v86, v75, 0
	s_nop 0
	buffer_load_dwordx2 v[96:97], v192, s[52:55], s0 offen
	v_readlane_b32 s0, v10, 2
	v_lshl_add_u32 v5, v5, 4, v9
	v_dot8_i32_i4 v9, v86, v73, 0
	v_dot8_i32_i4 v9, v87, v77, v9
	s_nop 1
	buffer_load_dwordx2 v[88:89], v192, s[52:55], s0 offen
	v_readlane_b32 s0, v10, 3
	v_dot8_i32_i4 v11, v87, v108, v11
	s_waitcnt vmcnt(16)
	v_dot8_i32_i4 v13, v84, v75, 0
	v_dot8_i32_i4 v13, v85, v108, v13
	s_nop 0
	buffer_load_dwordx2 v[98:99], v192, s[52:55], s0 offen
	v_readlane_b32 s0, v10, 4
	v_lshl_add_u32 v9, v9, 4, v11
	v_dot8_i32_i4 v11, v84, v73, 0
	v_dot8_i32_i4 v11, v85, v77, v11
	s_nop 1
	buffer_load_dwordx2 v[82:83], v192, s[52:55], s0 offen
	v_readlane_b32 s0, v10, 5
	s_nop 0
	v_lshl_add_u32 v11, v11, 4, v13
	s_waitcnt vmcnt(17)
	v_dot8_i32_i4 v13, v90, v73, 0
	s_nop 1
	buffer_load_dwordx2 v[56:57], v192, s[52:55], s0 offen
	v_readlane_b32 s0, v10, 6
	v_dot8_i32_i4 v18, v90, v75, 0
	v_dot8_i32_i4 v13, v91, v77, v13
	v_dot8_i32_i4 v18, v91, v108, v18
	s_nop 1
	buffer_load_dwordx2 v[52:53], v192, s[52:55], s0 offen
	v_readlane_b32 s0, v10, 7
	s_nop 0
	v_lshl_add_u32 v13, v13, 4, v18
	s_waitcnt vmcnt(18)
	v_dot8_i32_i4 v18, v78, v73, 0
	v_dot8_i32_i4 v19, v78, v75, 0
	s_nop 0
	buffer_load_dwordx2 v[80:81], v192, s[52:55], s0 offen
	v_readlane_b32 s0, v10, 8
	v_dot8_i32_i4 v18, v79, v77, v18
	v_dot8_i32_i4 v19, v79, v108, v19
	s_waitcnt vmcnt(18)
	v_dot8_i32_i4 v78, v50, v75, 0
	s_nop 0
	buffer_load_dwordx2 v[46:47], v192, s[52:55], s0 offen
	v_readlane_b32 s0, v10, 9
	v_lshl_add_u32 v18, v18, 4, v19
	v_dot8_i32_i4 v19, v50, v73, 0
	v_dot8_i32_i4 v19, v51, v77, v19
	s_nop 1
	buffer_load_dwordx2 v[40:41], v192, s[52:55], s0 offen
	v_readlane_b32 s0, v10, 10
	v_dot8_i32_i4 v78, v51, v108, v78
	s_waitcnt vmcnt(19)
	v_dot8_i32_i4 v50, v48, v73, 0
	s_nop 1
	buffer_load_dwordx2 v[36:37], v192, s[52:55], s0 offen
	v_readlane_b32 s0, v10, 11
	v_dot8_i32_i4 v51, v48, v75, 0
	v_dot8_i32_i4 v50, v49, v77, v50
	v_dot8_i32_i4 v51, v49, v108, v51
	s_nop 1
	buffer_load_dwordx2 v[44:45], v192, s[52:55], s0 offen
	v_readlane_b32 s0, v10, 12
	s_nop 0
	v_lshl_add_u32 v48, v50, 4, v51
	s_waitcnt vmcnt(20)
	v_dot8_i32_i4 v49, v54, v73, 0
	v_dot8_i32_i4 v50, v54, v75, 0
	s_nop 0
	buffer_load_dwordx2 v[32:33], v192, s[52:55], s0 offen
	v_readlane_b32 s0, v10, 13
	v_dot8_i32_i4 v49, v55, v77, v49
	v_dot8_i32_i4 v50, v55, v108, v50
	s_waitcnt vmcnt(20)
	v_dot8_i32_i4 v51, v42, v75, 0
	s_nop 0
	buffer_load_dwordx2 v[24:25], v192, s[52:55], s0 offen
	v_readlane_b32 s0, v10, 14
	v_lshl_add_u32 v49, v49, 4, v50
	v_dot8_i32_i4 v50, v42, v73, 0
	v_dot8_i32_i4 v50, v43, v77, v50
	s_nop 1
	buffer_load_dwordx2 v[14:15], v192, s[52:55], s0 offen
	v_readlane_b32 s0, v10, 15
	v_dot8_i32_i4 v51, v43, v108, v51
	s_waitcnt vmcnt(21)
	v_dot8_i32_i4 v43, v34, v73, 0
	v_dot8_i32_i4 v43, v35, v77, v43
	s_nop 0
	buffer_load_dwordx2 v[28:29], v192, s[52:55], s0 offen
	v_lshl_add_u32 v42, v50, 4, v51
	v_dot8_i32_i4 v50, v34, v75, 0
	v_dot8_i32_i4 v50, v35, v108, v50
	s_waitcnt vmcnt(21)
	v_dot8_i32_i4 v35, v30, v73, 0
	v_dot8_i32_i4 v35, v31, v77, v35
	v_lshl_add_u32 v34, v43, 4, v50
	v_dot8_i32_i4 v43, v30, v75, 0
	v_dot8_i32_i4 v43, v31, v108, v43
	s_waitcnt vmcnt(20)
	v_dot8_i32_i4 v31, v38, v73, 0
	v_dot8_i32_i4 v31, v39, v77, v31
	v_lshl_add_u32 v30, v35, 4, v43
	v_dot8_i32_i4 v35, v38, v75, 0
	v_dot8_i32_i4 v35, v39, v108, v35
	s_waitcnt vmcnt(19)
	v_dot8_i32_i4 v38, v26, v75, 0
	v_dot8_i32_i4 v38, v27, v108, v38
	v_lshl_add_u32 v31, v31, 4, v35
	v_dot8_i32_i4 v35, v26, v73, 0
	v_dot8_i32_i4 v35, v27, v77, v35
	s_waitcnt vmcnt(18)
	v_dot8_i32_i4 v27, v20, v73, 0
	v_dot8_i32_i4 v27, v21, v77, v27
	v_lshl_add_u32 v26, v35, 4, v38
	v_dot8_i32_i4 v35, v20, v75, 0
	v_dot8_i32_i4 v35, v21, v108, v35
	s_waitcnt vmcnt(17)
	v_dot8_i32_i4 v21, v16, v73, 0
	s_nop 0
	v_lshl_add_u32 v20, v27, 4, v35
	v_dot8_i32_i4 v27, v16, v75, 0
	v_dot8_i32_i4 v21, v17, v77, v21
	v_dot8_i32_i4 v27, v17, v108, v27
	s_waitcnt vmcnt(16)
	v_dot8_i32_i4 v17, v22, v73, 0
	v_dot8_i32_i4 v17, v23, v77, v17
	v_lshl_add_u32 v16, v21, 4, v27
	v_dot8_i32_i4 v21, v22, v75, 0
	v_dot8_i32_i4 v21, v23, v108, v21
	v_lshl_add_u32 v19, v19, 4, v78
	s_nop 0
	s_nop 0
	v_lshl_add_u32 v17, v17, 4, v21
	s_nop 0
	v_cndmask_b32_e64 v21, v9, v5, s[40:41]
	v_cndmask_b32_e64 v5, v5, v9, s[40:41]
	v_cndmask_b32_e64 v9, v13, v11, s[40:41]
	v_cndmask_b32_e64 v11, v11, v13, s[40:41]
	ds_swizzle_b32 v11, v11 offset:swizzle(SWAP,1)
	ds_swizzle_b32 v5, v5 offset:swizzle(SWAP,1)
	v_cndmask_b32_e64 v13, v18, v19, s[40:41]
	s_waitcnt lgkmcnt(1)
	v_add_u32_e32 v9, v9, v11
	v_cndmask_b32_e64 v11, v19, v18, s[40:41]
	ds_swizzle_b32 v13, v13 offset:swizzle(SWAP,1)
	v_cndmask_b32_e64 v18, v48, v49, s[40:41]
	ds_swizzle_b32 v18, v18 offset:swizzle(SWAP,1)
	v_cndmask_b32_e64 v19, v42, v34, s[40:41]
	s_waitcnt lgkmcnt(2)
	v_add_u32_e32 v5, v21, v5
	ds_swizzle_b32 v19, v19 offset:swizzle(SWAP,1)
	v_cndmask_b32_e64 v21, v30, v31, s[40:41]
	ds_swizzle_b32 v21, v21 offset:swizzle(SWAP,1)
	s_waitcnt lgkmcnt(3)
	v_add_u32_e32 v11, v11, v13
	v_cndmask_b32_e64 v13, v49, v48, s[40:41]
	s_waitcnt lgkmcnt(2)
	v_add_u32_e32 v13, v13, v18
	v_cndmask_b32_e64 v18, v34, v42, s[40:41]
	s_waitcnt lgkmcnt(1)
	v_add_u32_e32 v18, v18, v19
	v_cndmask_b32_e64 v19, v31, v30, s[40:41]
	s_waitcnt lgkmcnt(0)
	v_add_u32_e32 v19, v19, v21
	v_cndmask_b32_e64 v21, v20, v26, s[40:41]
	v_cndmask_b32_e64 v20, v26, v20, s[40:41]
	ds_swizzle_b32 v20, v20 offset:swizzle(SWAP,1)
	s_waitcnt lgkmcnt(0)
	v_add_u32_e32 v20, v21, v20
	v_cndmask_b32_e64 v21, v17, v16, s[40:41]
	v_cndmask_b32_e64 v16, v16, v17, s[40:41]
	v_cndmask_b32_e64 v17, v9, v5, s[42:43]
	v_cndmask_b32_e64 v5, v5, v9, s[42:43]
	v_cndmask_b32_e64 v9, v13, v11, s[42:43]
	v_cndmask_b32_e64 v11, v11, v13, s[42:43]
	ds_swizzle_b32 v16, v16 offset:swizzle(SWAP,1)
	ds_swizzle_b32 v11, v11 offset:swizzle(SWAP,2)
	v_cndmask_b32_e64 v13, v18, v19, s[42:43]
	ds_swizzle_b32 v13, v13 offset:swizzle(SWAP,2)
	ds_swizzle_b32 v5, v5 offset:swizzle(SWAP,2)
	s_waitcnt lgkmcnt(3)
	v_add_u32_e32 v16, v21, v16
	s_waitcnt lgkmcnt(2)
	v_add_u32_e32 v9, v9, v11
	v_cndmask_b32_e64 v11, v19, v18, s[42:43]
	s_waitcnt lgkmcnt(1)
	v_add_u32_e32 v11, v11, v13
	v_cndmask_b32_e64 v13, v16, v20, s[42:43]
	v_cndmask_b32_e64 v16, v20, v16, s[42:43]
	ds_swizzle_b32 v16, v16 offset:swizzle(SWAP,2)
	s_waitcnt lgkmcnt(1)
	v_add_u32_e32 v5, v17, v5
	s_waitcnt lgkmcnt(0)
	v_add_u32_e32 v13, v13, v16
	v_cndmask_b32_e64 v16, v9, v5, s[44:45]
	v_cndmask_b32_e64 v5, v5, v9, s[44:45]
	v_cndmask_b32_e64 v9, v13, v11, s[44:45]
	v_cndmask_b32_e64 v11, v11, v13, s[44:45]
	ds_swizzle_b32 v5, v5 offset:swizzle(SWAP,4)
	ds_swizzle_b32 v11, v11 offset:swizzle(SWAP,4)
	s_waitcnt lgkmcnt(1)
	v_add_u32_e32 v5, v16, v5
	s_waitcnt lgkmcnt(0)
	v_add_u32_e32 v9, v9, v11
	v_cndmask_b32_e64 v11, v9, v5, s[46:47]
	v_cndmask_b32_e64 v5, v5, v9, s[46:47]
	ds_swizzle_b32 v5, v5 offset:swizzle(SWAP,8)
	s_waitcnt lgkmcnt(0)
	v_add_u32_e32 v5, v11, v5
	ds_swizzle_b32 v9, v5 offset:swizzle(SWAP,16)
	s_waitcnt lgkmcnt(0)
	v_add_u32_e32 v5, v5, v9
	ds_bpermute_b32 v9, v0, v5
	s_and_saveexec_b64 s[0:1], s[48:49]
	s_cbranch_execz .LBB0_679
	v_ashrrev_i32_e32 v13, 31, v12
	v_lshlrev_b64 v[12:13], 2, v[12:13]
	v_lshl_add_u64 v[16:17], s[8:9], 0, v[12:13]
	v_mov_b32_e32 v11, v132
	v_lshl_add_u64 v[12:13], s[10:11], 0, v[12:13]
	v_mov_b32_e32 v16, v148
	s_nop 0
	v_mov_b32_e32 v12, v140
	s_waitcnt lgkmcnt(0)
	v_add_u32_e32 v5, v5, v9
	v_cvt_f32_i32_e32 v5, v5
	v_mul_f32_e32 v5, v5, v11
	v_mul_f32_e32 v5, v3, v5
	v_mul_f32_e32 v11, 0x3d372713, v5
	v_mul_f32_e32 v11, v5, v11
	v_mul_f32_e32 v9, 0.5, v5
	v_fmac_f32_e32 v5, v5, v11
	v_mul_f32_e32 v5, 0x3f4c422a, v5
	v_add_f32_e32 v5, v5, v5
	v_mul_f32_e32 v5, 0x3fb8aa3b, v5
	v_exp_f32_e32 v5, v5
	s_nop 0
	v_add_f32_e32 v5, 1.0, v5
	v_rcp_f32_e32 v5, v5
	s_nop 0
	v_fma_f32 v5, v5, -2.0, 1.0
	v_add_f32_e32 v5, 1.0, v5
	v_mul_f32_e32 v5, v9, v5
	v_mul_f32_e32 v5, v16, v5
	v_mul_f32_e32 v5, v12, v5
	ds_write_b32 v109, v5 offset:256
.LBB0_679:
	s_or_b64 exec, exec, s[0:1]
	v_readlane_b32 s0, v8, 0
	s_waitcnt lgkmcnt(0)
	s_waitcnt vmcnt(15)
	v_dot8_i32_i4 v5, v92, v73, 0
	v_dot8_i32_i4 v9, v92, v75, 0
	s_nop 0
	buffer_load_dwordx2 v[86:87], v192, s[52:55], s0 offen
	v_readlane_b32 s0, v8, 1
	v_dot8_i32_i4 v5, v93, v77, v5
	v_dot8_i32_i4 v9, v93, v108, v9
	s_waitcnt vmcnt(15)
	v_dot8_i32_i4 v11, v96, v75, 0
	s_nop 0
	buffer_load_dwordx2 v[78:79], v192, s[52:55], s0 offen
	v_readlane_b32 s0, v8, 2
	v_lshl_add_u32 v5, v5, 4, v9
	v_dot8_i32_i4 v9, v96, v73, 0
	v_dot8_i32_i4 v9, v97, v77, v9
	s_nop 1
	buffer_load_dwordx2 v[54:55], v192, s[52:55], s0 offen
	v_readlane_b32 s0, v8, 3
	v_dot8_i32_i4 v11, v97, v108, v11
	s_waitcnt vmcnt(16)
	v_dot8_i32_i4 v90, v88, v75, 0
	v_dot8_i32_i4 v90, v89, v108, v90
	s_nop 0
	buffer_load_dwordx2 v[84:85], v192, s[52:55], s0 offen
	v_readlane_b32 s0, v8, 4
	v_lshl_add_u32 v9, v9, 4, v11
	v_dot8_i32_i4 v11, v88, v73, 0
	v_dot8_i32_i4 v11, v89, v77, v11
	s_nop 1
	buffer_load_dwordx2 v[50:51], v192, s[52:55], s0 offen
	v_readlane_b32 s0, v8, 5
	s_waitcnt vmcnt(17)
	v_dot8_i32_i4 v88, v98, v73, 0
	v_dot8_i32_i4 v89, v98, v75, 0
	s_nop 1
	buffer_load_dwordx2 v[42:43], v192, s[52:55], s0 offen
	v_readlane_b32 s0, v8, 6
	v_dot8_i32_i4 v88, v99, v77, v88
	v_dot8_i32_i4 v89, v99, v108, v89
	v_lshl_add_u32 v11, v11, 4, v90
	s_nop 1
	buffer_load_dwordx2 v[38:39], v192, s[52:55], s0 offen
	v_readlane_b32 s0, v8, 7
	v_lshl_add_u32 v88, v88, 4, v89
	s_waitcnt vmcnt(18)
	v_dot8_i32_i4 v89, v82, v73, 0
	v_dot8_i32_i4 v90, v82, v75, 0
	s_nop 0
	buffer_load_dwordx2 v[48:49], v192, s[52:55], s0 offen
	v_readlane_b32 s0, v8, 8
	v_dot8_i32_i4 v89, v83, v77, v89
	v_dot8_i32_i4 v90, v83, v108, v90
	s_waitcnt vmcnt(18)
	v_dot8_i32_i4 v83, v56, v73, 0
	s_nop 0
	buffer_load_dwordx2 v[34:35], v192, s[52:55], s0 offen
	v_readlane_b32 s0, v8, 9
	v_lshl_add_u32 v82, v89, 4, v90
	v_dot8_i32_i4 v89, v56, v75, 0
	v_dot8_i32_i4 v83, v57, v77, v83
	s_nop 1
	buffer_load_dwordx2 v[26:27], v192, s[52:55], s0 offen
	v_readlane_b32 s0, v8, 10
	v_dot8_i32_i4 v89, v57, v108, v89
	s_waitcnt vmcnt(19)
	v_dot8_i32_i4 v57, v52, v73, 0
	v_dot8_i32_i4 v57, v53, v77, v57
	s_nop 0
	buffer_load_dwordx2 v[22:23], v192, s[52:55], s0 offen
	v_readlane_b32 s0, v8, 11
	v_lshl_add_u32 v56, v83, 4, v89
	v_dot8_i32_i4 v83, v52, v75, 0
	v_dot8_i32_i4 v83, v53, v108, v83
	s_nop 1
	buffer_load_dwordx2 v[30:31], v192, s[52:55], s0 offen
	v_readlane_b32 s0, v8, 12
	s_nop 0
	v_lshl_add_u32 v52, v57, 4, v83
	s_waitcnt vmcnt(20)
	v_dot8_i32_i4 v53, v80, v73, 0
	s_nop 1
	buffer_load_dwordx2 v[20:21], v192, s[52:55], s0 offen
	v_readlane_b32 s0, v8, 13
	v_dot8_i32_i4 v57, v80, v75, 0
	v_dot8_i32_i4 v53, v81, v77, v53
	v_dot8_i32_i4 v57, v81, v108, v57
	s_nop 1
	buffer_load_dwordx2 v[16:17], v192, s[52:55], s0 offen
	v_readlane_b32 s0, v8, 14
	s_nop 0
	v_lshl_add_u32 v53, v53, 4, v57
	s_waitcnt vmcnt(21)
	v_dot8_i32_i4 v57, v46, v73, 0
	v_dot8_i32_i4 v80, v46, v75, 0
	s_nop 0
	buffer_load_dwordx2 v[12:13], v192, s[52:55], s0 offen
	v_readlane_b32 s0, v8, 15
	v_dot8_i32_i4 v57, v47, v77, v57
	v_dot8_i32_i4 v80, v47, v108, v80
	s_waitcnt vmcnt(21)
	v_dot8_i32_i4 v47, v40, v73, 0
	s_nop 0
	buffer_load_dwordx2 v[18:19], v192, s[52:55], s0 offen
	v_lshl_add_u32 v46, v57, 4, v80
	v_dot8_i32_i4 v57, v40, v75, 0
	v_dot8_i32_i4 v47, v41, v77, v47
	v_dot8_i32_i4 v57, v41, v108, v57
	s_waitcnt vmcnt(21)
	v_dot8_i32_i4 v41, v36, v73, 0
	v_dot8_i32_i4 v41, v37, v77, v41
	v_lshl_add_u32 v40, v47, 4, v57
	v_dot8_i32_i4 v47, v36, v75, 0
	v_dot8_i32_i4 v47, v37, v108, v47
	s_waitcnt vmcnt(20)
	v_dot8_i32_i4 v37, v44, v73, 0
	v_dot8_i32_i4 v37, v45, v77, v37
	v_lshl_add_u32 v36, v41, 4, v47
	v_dot8_i32_i4 v41, v44, v75, 0
	v_dot8_i32_i4 v41, v45, v108, v41
	s_waitcnt vmcnt(19)
	v_dot8_i32_i4 v44, v32, v75, 0
	v_dot8_i32_i4 v44, v33, v108, v44
	v_lshl_add_u32 v37, v37, 4, v41
	v_dot8_i32_i4 v41, v32, v73, 0
	v_dot8_i32_i4 v41, v33, v77, v41
	s_waitcnt vmcnt(18)
	v_dot8_i32_i4 v33, v24, v73, 0
	v_dot8_i32_i4 v33, v25, v77, v33
	v_lshl_add_u32 v32, v41, 4, v44
	v_dot8_i32_i4 v41, v24, v75, 0
	v_dot8_i32_i4 v41, v25, v108, v41
	s_waitcnt vmcnt(17)
	v_dot8_i32_i4 v25, v14, v73, 0
	s_nop 0
	v_lshl_add_u32 v24, v33, 4, v41
	v_dot8_i32_i4 v33, v14, v75, 0
	v_dot8_i32_i4 v25, v15, v77, v25
	v_dot8_i32_i4 v33, v15, v108, v33
	s_waitcnt vmcnt(16)
	v_dot8_i32_i4 v15, v28, v73, 0
	v_dot8_i32_i4 v15, v29, v77, v15
	v_lshl_add_u32 v14, v25, 4, v33
	v_dot8_i32_i4 v25, v28, v75, 0
	v_dot8_i32_i4 v25, v29, v108, v25
	s_nop 1
	s_nop 0
	v_lshl_add_u32 v15, v15, 4, v25
	s_nop 0
	v_cndmask_b32_e64 v25, v9, v5, s[40:41]
	v_cndmask_b32_e64 v5, v5, v9, s[40:41]
	ds_swizzle_b32 v5, v5 offset:swizzle(SWAP,1)
	v_cndmask_b32_e64 v9, v88, v11, s[40:41]
	v_cndmask_b32_e64 v11, v11, v88, s[40:41]
	s_waitcnt lgkmcnt(0)
	v_add_u32_e32 v5, v25, v5
	ds_swizzle_b32 v11, v11 offset:swizzle(SWAP,1)
	v_cndmask_b32_e64 v25, v82, v56, s[40:41]
	ds_swizzle_b32 v25, v25 offset:swizzle(SWAP,1)
	v_cndmask_b32_e64 v28, v52, v53, s[40:41]
	ds_swizzle_b32 v28, v28 offset:swizzle(SWAP,1)
	v_cndmask_b32_e64 v29, v46, v40, s[40:41]
	ds_swizzle_b32 v29, v29 offset:swizzle(SWAP,1)
	v_cndmask_b32_e64 v33, v36, v37, s[40:41]
	ds_swizzle_b32 v33, v33 offset:swizzle(SWAP,1)
	s_waitcnt lgkmcnt(4)
	v_add_u32_e32 v9, v9, v11
	v_cndmask_b32_e64 v11, v56, v82, s[40:41]
	s_waitcnt lgkmcnt(3)
	v_add_u32_e32 v11, v11, v25
	v_cndmask_b32_e64 v25, v53, v52, s[40:41]
	s_waitcnt lgkmcnt(2)
	v_add_u32_e32 v25, v25, v28
	v_cndmask_b32_e64 v28, v40, v46, s[40:41]
	s_waitcnt lgkmcnt(1)
	v_add_u32_e32 v28, v28, v29
	v_cndmask_b32_e64 v29, v37, v36, s[40:41]
	s_waitcnt lgkmcnt(0)
	v_add_u32_e32 v29, v29, v33
	v_cndmask_b32_e64 v33, v24, v32, s[40:41]
	v_cndmask_b32_e64 v24, v32, v24, s[40:41]
	v_cndmask_b32_e64 v32, v15, v14, s[40:41]
	v_cndmask_b32_e64 v14, v14, v15, s[40:41]
	v_cndmask_b32_e64 v15, v9, v5, s[42:43]
	v_cndmask_b32_e64 v5, v5, v9, s[42:43]
	ds_swizzle_b32 v5, v5 offset:swizzle(SWAP,2)
	v_cndmask_b32_e64 v9, v25, v11, s[42:43]
	v_cndmask_b32_e64 v11, v11, v25, s[42:43]
	ds_swizzle_b32 v24, v24 offset:swizzle(SWAP,1)
	ds_swizzle_b32 v14, v14 offset:swizzle(SWAP,1)
	s_waitcnt lgkmcnt(2)
	v_add_u32_e32 v5, v15, v5
	ds_swizzle_b32 v11, v11 offset:swizzle(SWAP,2)
	v_cndmask_b32_e64 v15, v28, v29, s[42:43]
	ds_swizzle_b32 v15, v15 offset:swizzle(SWAP,2)
	s_waitcnt lgkmcnt(3)
	v_add_u32_e32 v24, v33, v24
	s_waitcnt lgkmcnt(2)
	v_add_u32_e32 v14, v32, v14
	s_waitcnt lgkmcnt(1)
	v_add_u32_e32 v9, v9, v11
	v_cndmask_b32_e64 v11, v29, v28, s[42:43]
	s_waitcnt lgkmcnt(0)
	v_add_u32_e32 v11, v11, v15
	v_cndmask_b32_e64 v15, v14, v24, s[42:43]
	v_cndmask_b32_e64 v14, v24, v14, s[42:43]
	ds_swizzle_b32 v14, v14 offset:swizzle(SWAP,2)
	s_waitcnt lgkmcnt(0)
	v_add_u32_e32 v14, v15, v14
	v_cndmask_b32_e64 v15, v9, v5, s[44:45]
	v_cndmask_b32_e64 v5, v5, v9, s[44:45]
	v_cndmask_b32_e64 v9, v14, v11, s[44:45]
	v_cndmask_b32_e64 v11, v11, v14, s[44:45]
	ds_swizzle_b32 v5, v5 offset:swizzle(SWAP,4)
	ds_swizzle_b32 v11, v11 offset:swizzle(SWAP,4)
	s_waitcnt lgkmcnt(1)
	v_add_u32_e32 v5, v15, v5
	s_waitcnt lgkmcnt(0)
	v_add_u32_e32 v9, v9, v11
	v_cndmask_b32_e64 v11, v9, v5, s[46:47]
	v_cndmask_b32_e64 v5, v5, v9, s[46:47]
	ds_swizzle_b32 v5, v5 offset:swizzle(SWAP,8)
	s_waitcnt lgkmcnt(0)
	v_add_u32_e32 v5, v11, v5
	ds_swizzle_b32 v9, v5 offset:swizzle(SWAP,16)
	s_waitcnt lgkmcnt(0)
	v_add_u32_e32 v5, v5, v9
	ds_bpermute_b32 v9, v0, v5
	s_and_saveexec_b64 s[0:1], s[48:49]
	s_cbranch_execz .LBB0_681
	v_ashrrev_i32_e32 v11, 31, v10
	v_lshlrev_b64 v[10:11], 2, v[10:11]
	v_lshl_add_u64 v[14:15], s[8:9], 0, v[10:11]
	v_mov_b32_e32 v14, v133
	v_lshl_add_u64 v[10:11], s[10:11], 0, v[10:11]
	v_mov_b32_e32 v15, v149
	s_nop 0
	v_mov_b32_e32 v10, v141
	s_waitcnt lgkmcnt(0)
	v_add_u32_e32 v5, v5, v9
	v_cvt_f32_i32_e32 v5, v5
	v_mul_f32_e32 v5, v5, v14
	v_mul_f32_e32 v5, v3, v5
	v_mul_f32_e32 v11, 0x3d372713, v5
	v_mul_f32_e32 v11, v5, v11
	v_mul_f32_e32 v9, 0.5, v5
	v_fmac_f32_e32 v5, v5, v11
	v_mul_f32_e32 v5, 0x3f4c422a, v5
	v_add_f32_e32 v5, v5, v5
	v_mul_f32_e32 v5, 0x3fb8aa3b, v5
	v_exp_f32_e32 v5, v5
	s_nop 0
	v_add_f32_e32 v5, 1.0, v5
	v_rcp_f32_e32 v5, v5
	s_nop 0
	v_fma_f32 v5, v5, -2.0, 1.0
	v_add_f32_e32 v5, 1.0, v5
	v_mul_f32_e32 v5, v9, v5
	v_mul_f32_e32 v5, v15, v5
	v_mul_f32_e32 v5, v10, v5
	ds_write_b32 v109, v5 offset:320
.LBB0_681:
	s_or_b64 exec, exec, s[0:1]
	s_waitcnt lgkmcnt(0)
	v_readlane_b32 s0, v4, 0
	s_waitcnt vmcnt(15)
	v_dot8_i32_i4 v5, v86, v73, 0
	v_dot8_i32_i4 v9, v86, v75, 0
	v_dot8_i32_i4 v5, v87, v77, v5
	v_dot8_i32_i4 v9, v87, v108, v9
	buffer_load_dwordx2 v[88:89], v192, s[52:55], s0 offen
	v_readlane_b32 s0, v4, 1
	s_nop 0
	v_lshl_add_u32 v5, v5, 4, v9
	s_waitcnt vmcnt(15)
	v_dot8_i32_i4 v9, v78, v73, 0
	v_dot8_i32_i4 v86, v78, v75, 0
	buffer_load_dwordx2 v[90:91], v192, s[52:55], s0 offen
	v_readlane_b32 s0, v4, 2
	v_dot8_i32_i4 v9, v79, v77, v9
	v_dot8_i32_i4 v86, v79, v108, v86
	s_waitcnt vmcnt(15)
	v_dot8_i32_i4 v78, v54, v73, 0
	v_dot8_i32_i4 v79, v54, v75, 0
	buffer_load_dwordx2 v[82:83], v192, s[52:55], s0 offen
	v_readlane_b32 s0, v4, 3
	v_dot8_i32_i4 v78, v55, v77, v78
	v_dot8_i32_i4 v79, v55, v108, v79
	s_waitcnt vmcnt(15)
	v_dot8_i32_i4 v55, v84, v73, 0
	s_nop 0
	v_lshl_add_u32 v54, v78, 4, v79
	buffer_load_dwordx2 v[92:93], v192, s[52:55], s0 offen
	v_readlane_b32 s0, v4, 4
	v_dot8_i32_i4 v78, v84, v75, 0
	v_dot8_i32_i4 v55, v85, v77, v55
	v_dot8_i32_i4 v78, v85, v108, v78
	s_nop 1
	buffer_load_dwordx2 v[80:81], v192, s[52:55], s0 offen
	v_readlane_b32 s0, v4, 5
	s_nop 0
	v_lshl_add_u32 v55, v55, 4, v78
	s_waitcnt vmcnt(16)
	v_dot8_i32_i4 v78, v50, v73, 0
	v_dot8_i32_i4 v79, v50, v75, 0
	buffer_load_dwordx2 v[52:53], v192, s[52:55], s0 offen
	v_readlane_b32 s0, v4, 6
	v_dot8_i32_i4 v78, v51, v77, v78
	v_dot8_i32_i4 v79, v51, v108, v79
	s_waitcnt vmcnt(16)
	v_dot8_i32_i4 v51, v42, v73, 0
	s_nop 0
	v_lshl_add_u32 v50, v78, 4, v79
	buffer_load_dwordx2 v[46:47], v192, s[52:55], s0 offen
	v_readlane_b32 s0, v4, 7
	v_dot8_i32_i4 v78, v42, v75, 0
	v_dot8_i32_i4 v51, v43, v77, v51
	v_dot8_i32_i4 v78, v43, v108, v78
	s_nop 1
	buffer_load_dwordx2 v[56:57], v192, s[52:55], s0 offen
	v_readlane_b32 s0, v4, 8
	s_nop 0
	v_lshl_add_u32 v42, v51, 4, v78
	s_waitcnt vmcnt(17)
	v_dot8_i32_i4 v43, v38, v73, 0
	v_dot8_i32_i4 v51, v38, v75, 0
	buffer_load_dwordx2 v[44:45], v192, s[52:55], s0 offen
	v_readlane_b32 s0, v4, 9
	v_dot8_i32_i4 v43, v39, v77, v43
	v_dot8_i32_i4 v51, v39, v108, v51
	s_waitcnt vmcnt(17)
	v_dot8_i32_i4 v39, v48, v73, 0
	s_nop 0
	v_lshl_add_u32 v38, v43, 4, v51
	buffer_load_dwordx2 v[36:37], v192, s[52:55], s0 offen
	v_readlane_b32 s0, v4, 10
	v_dot8_i32_i4 v43, v48, v75, 0
	v_dot8_i32_i4 v39, v49, v77, v39
	v_dot8_i32_i4 v43, v49, v108, v43
	s_nop 1
	buffer_load_dwordx2 v[32:33], v192, s[52:55], s0 offen
	v_readlane_b32 s0, v4, 11
	s_nop 0
	v_lshl_add_u32 v39, v39, 4, v43
	s_waitcnt vmcnt(18)
	v_dot8_i32_i4 v43, v34, v73, 0
	v_dot8_i32_i4 v48, v34, v75, 0
	buffer_load_dwordx2 v[40:41], v192, s[52:55], s0 offen
	v_readlane_b32 s0, v4, 12
	v_dot8_i32_i4 v43, v35, v77, v43
	v_dot8_i32_i4 v48, v35, v108, v48
	s_waitcnt vmcnt(18)
	v_dot8_i32_i4 v35, v26, v73, 0
	s_nop 0
	v_lshl_add_u32 v34, v43, 4, v48
	buffer_load_dwordx2 v[28:29], v192, s[52:55], s0 offen
	v_readlane_b32 s0, v4, 13
	v_dot8_i32_i4 v43, v26, v75, 0
	v_dot8_i32_i4 v35, v27, v77, v35
	v_dot8_i32_i4 v43, v27, v108, v43
	s_nop 1
	buffer_load_dwordx2 v[14:15], v192, s[52:55], s0 offen
	v_readlane_b32 s0, v4, 14
	s_nop 0
	v_lshl_add_u32 v26, v35, 4, v43
	s_waitcnt vmcnt(19)
	v_dot8_i32_i4 v27, v22, v73, 0
	v_dot8_i32_i4 v35, v22, v75, 0
	buffer_load_dwordx2 v[10:11], v192, s[52:55], s0 offen
	v_readlane_b32 s0, v4, 15
	v_dot8_i32_i4 v27, v23, v77, v27
	v_dot8_i32_i4 v35, v23, v108, v35
	s_waitcnt vmcnt(19)
	v_dot8_i32_i4 v23, v30, v73, 0
	s_nop 0
	v_lshl_add_u32 v22, v27, 4, v35
	buffer_load_dwordx2 v[24:25], v192, s[52:55], s0 offen
	v_dot8_i32_i4 v27, v30, v75, 0
	v_dot8_i32_i4 v23, v31, v77, v23
	v_dot8_i32_i4 v27, v31, v108, v27
	s_waitcnt vmcnt(19)
	v_dot8_i32_i4 v30, v20, v75, 0
	v_dot8_i32_i4 v30, v21, v108, v30
	v_lshl_add_u32 v23, v23, 4, v27
	v_dot8_i32_i4 v27, v20, v73, 0
	v_dot8_i32_i4 v27, v21, v77, v27
	s_waitcnt vmcnt(18)
	v_dot8_i32_i4 v21, v16, v73, 0
	v_dot8_i32_i4 v21, v17, v77, v21
	v_lshl_add_u32 v20, v27, 4, v30
	v_dot8_i32_i4 v27, v16, v75, 0
	v_dot8_i32_i4 v27, v17, v108, v27
	v_lshl_add_u32 v9, v9, 4, v86
	s_waitcnt vmcnt(17)
	v_dot8_i32_i4 v17, v12, v73, 0
	v_lshl_add_u32 v16, v21, 4, v27
	v_dot8_i32_i4 v21, v12, v75, 0
	v_dot8_i32_i4 v17, v13, v77, v17
	v_dot8_i32_i4 v21, v13, v108, v21
	s_waitcnt vmcnt(16)
	v_dot8_i32_i4 v13, v18, v73, 0
	v_dot8_i32_i4 v13, v19, v77, v13
	v_lshl_add_u32 v12, v17, 4, v21
	v_dot8_i32_i4 v17, v18, v75, 0
	v_dot8_i32_i4 v17, v19, v108, v17
	s_nop 1
	s_nop 0
	v_lshl_add_u32 v13, v13, 4, v17
	s_nop 0
	v_cndmask_b32_e64 v17, v9, v5, s[40:41]
	v_cndmask_b32_e64 v5, v5, v9, s[40:41]
	ds_swizzle_b32 v5, v5 offset:swizzle(SWAP,1)
	s_waitcnt lgkmcnt(0)
	v_add_u32_e32 v5, v17, v5
	v_cndmask_b32_e64 v17, v54, v55, s[40:41]
	ds_swizzle_b32 v17, v17 offset:swizzle(SWAP,1)
	v_cndmask_b32_e64 v18, v50, v42, s[40:41]
	ds_swizzle_b32 v18, v18 offset:swizzle(SWAP,1)
	v_cndmask_b32_e64 v19, v38, v39, s[40:41]
	ds_swizzle_b32 v19, v19 offset:swizzle(SWAP,1)
	v_cndmask_b32_e64 v21, v34, v26, s[40:41]
	ds_swizzle_b32 v21, v21 offset:swizzle(SWAP,1)
	v_cndmask_b32_e64 v9, v55, v54, s[40:41]
	s_waitcnt lgkmcnt(3)
	v_add_u32_e32 v9, v9, v17
	v_cndmask_b32_e64 v17, v42, v50, s[40:41]
	s_waitcnt lgkmcnt(2)
	v_add_u32_e32 v17, v17, v18
	v_cndmask_b32_e64 v18, v39, v38, s[40:41]
	s_waitcnt lgkmcnt(1)
	v_add_u32_e32 v18, v18, v19
	v_cndmask_b32_e64 v19, v26, v34, s[40:41]
	s_waitcnt lgkmcnt(0)
	v_add_u32_e32 v19, v19, v21
	v_cndmask_b32_e64 v21, v23, v22, s[40:41]
	v_cndmask_b32_e64 v22, v22, v23, s[40:41]
	ds_swizzle_b32 v22, v22 offset:swizzle(SWAP,1)
	s_waitcnt lgkmcnt(0)
	v_add_u32_e32 v21, v21, v22
	v_cndmask_b32_e64 v22, v16, v20, s[40:41]
	v_cndmask_b32_e64 v16, v20, v16, s[40:41]
	v_cndmask_b32_e64 v20, v13, v12, s[40:41]
	v_cndmask_b32_e64 v12, v12, v13, s[40:41]
	v_cndmask_b32_e64 v13, v9, v5, s[42:43]
	v_cndmask_b32_e64 v5, v5, v9, s[42:43]
	ds_swizzle_b32 v5, v5 offset:swizzle(SWAP,2)
	ds_swizzle_b32 v16, v16 offset:swizzle(SWAP,1)
	ds_swizzle_b32 v12, v12 offset:swizzle(SWAP,1)
	v_cndmask_b32_e64 v9, v18, v17, s[42:43]
	s_waitcnt lgkmcnt(2)
	v_add_u32_e32 v5, v13, v5
	v_cndmask_b32_e64 v13, v17, v18, s[42:43]
	ds_swizzle_b32 v13, v13 offset:swizzle(SWAP,2)
	v_cndmask_b32_e64 v17, v19, v21, s[42:43]
	ds_swizzle_b32 v17, v17 offset:swizzle(SWAP,2)
	s_waitcnt lgkmcnt(3)
	v_add_u32_e32 v16, v22, v16
	s_waitcnt lgkmcnt(2)
	v_add_u32_e32 v12, v20, v12
	s_waitcnt lgkmcnt(1)
	v_add_u32_e32 v9, v9, v13
	v_cndmask_b32_e64 v13, v21, v19, s[42:43]
	s_waitcnt lgkmcnt(0)
	v_add_u32_e32 v13, v13, v17
	v_cndmask_b32_e64 v17, v12, v16, s[42:43]
	v_cndmask_b32_e64 v12, v16, v12, s[42:43]
	ds_swizzle_b32 v12, v12 offset:swizzle(SWAP,2)
	v_cndmask_b32_e64 v16, v9, v5, s[44:45]
	v_cndmask_b32_e64 v5, v5, v9, s[44:45]
	ds_swizzle_b32 v5, v5 offset:swizzle(SWAP,4)
	s_waitcnt lgkmcnt(1)
	v_add_u32_e32 v12, v17, v12
	v_cndmask_b32_e64 v9, v12, v13, s[44:45]
	v_cndmask_b32_e64 v12, v13, v12, s[44:45]
	ds_swizzle_b32 v12, v12 offset:swizzle(SWAP,4)
	s_waitcnt lgkmcnt(1)
	v_add_u32_e32 v5, v16, v5
	s_waitcnt lgkmcnt(0)
	v_add_u32_e32 v9, v9, v12
	v_cndmask_b32_e64 v12, v9, v5, s[46:47]
	v_cndmask_b32_e64 v5, v5, v9, s[46:47]
	ds_swizzle_b32 v5, v5 offset:swizzle(SWAP,8)
	s_waitcnt lgkmcnt(0)
	v_add_u32_e32 v5, v12, v5
	ds_swizzle_b32 v9, v5 offset:swizzle(SWAP,16)
	s_waitcnt lgkmcnt(0)
	v_add_u32_e32 v5, v5, v9
	ds_bpermute_b32 v12, v0, v5
	s_and_saveexec_b64 s[0:1], s[48:49]
	s_cbranch_execz .LBB0_683
	v_ashrrev_i32_e32 v9, 31, v8
	v_lshlrev_b64 v[8:9], 2, v[8:9]
	v_lshl_add_u64 v[16:17], s[8:9], 0, v[8:9]
	v_mov_b32_e32 v13, v134
	v_lshl_add_u64 v[8:9], s[10:11], 0, v[8:9]
	v_mov_b32_e32 v16, v150
	s_nop 0
	v_mov_b32_e32 v8, v142
	s_waitcnt lgkmcnt(0)
	v_add_u32_e32 v5, v5, v12
	v_cvt_f32_i32_e32 v5, v5
	v_mul_f32_e32 v5, v5, v13
	v_mul_f32_e32 v5, v3, v5
	v_mul_f32_e32 v12, 0x3d372713, v5
	v_mul_f32_e32 v12, v5, v12
	v_mul_f32_e32 v9, 0.5, v5
	v_fmac_f32_e32 v5, v5, v12
	v_mul_f32_e32 v5, 0x3f4c422a, v5
	v_add_f32_e32 v5, v5, v5
	v_mul_f32_e32 v5, 0x3fb8aa3b, v5
	v_exp_f32_e32 v5, v5
	s_nop 0
	v_add_f32_e32 v5, 1.0, v5
	v_rcp_f32_e32 v5, v5
	s_nop 0
	v_fma_f32 v5, v5, -2.0, 1.0
	v_add_f32_e32 v5, 1.0, v5
	v_mul_f32_e32 v5, v9, v5
	v_mul_f32_e32 v5, v16, v5
	v_mul_f32_e32 v5, v8, v5
	ds_write_b32 v109, v5 offset:384
.LBB0_683:
	s_or_b64 exec, exec, s[0:1]
	s_waitcnt vmcnt(15)
	v_dot8_i32_i4 v5, v88, v73, 0
	v_dot8_i32_i4 v8, v88, v75, 0
	v_dot8_i32_i4 v5, v89, v77, v5
	v_dot8_i32_i4 v8, v89, v108, v8
	s_waitcnt vmcnt(14)
	v_dot8_i32_i4 v9, v90, v75, 0
	v_dot8_i32_i4 v9, v91, v108, v9
	v_lshl_add_u32 v5, v5, 4, v8
	v_dot8_i32_i4 v8, v90, v73, 0
	v_dot8_i32_i4 v8, v91, v77, v8
	s_waitcnt lgkmcnt(0)
	s_waitcnt vmcnt(13)
	v_dot8_i32_i4 v12, v82, v75, 0
	v_dot8_i32_i4 v12, v83, v108, v12
	v_lshl_add_u32 v8, v8, 4, v9
	v_dot8_i32_i4 v9, v82, v73, 0
	v_dot8_i32_i4 v9, v83, v77, v9
	s_waitcnt vmcnt(12)
	v_dot8_i32_i4 v13, v92, v75, 0
	v_dot8_i32_i4 v13, v93, v108, v13
	v_lshl_add_u32 v9, v9, 4, v12
	v_dot8_i32_i4 v12, v92, v73, 0
	v_dot8_i32_i4 v12, v93, v77, v12
	s_waitcnt vmcnt(11)
	v_dot8_i32_i4 v16, v80, v75, 0
	v_dot8_i32_i4 v16, v81, v108, v16
	v_lshl_add_u32 v12, v12, 4, v13
	v_dot8_i32_i4 v13, v80, v73, 0
	v_dot8_i32_i4 v13, v81, v77, v13
	s_waitcnt vmcnt(10)
	v_dot8_i32_i4 v17, v52, v75, 0
	v_dot8_i32_i4 v17, v53, v108, v17
	v_lshl_add_u32 v13, v13, 4, v16
	v_dot8_i32_i4 v16, v52, v73, 0
	v_dot8_i32_i4 v16, v53, v77, v16
	s_waitcnt vmcnt(9)
	v_dot8_i32_i4 v18, v46, v75, 0
	v_dot8_i32_i4 v18, v47, v108, v18
	v_lshl_add_u32 v16, v16, 4, v17
	v_dot8_i32_i4 v17, v46, v73, 0
	v_dot8_i32_i4 v17, v47, v77, v17
	s_waitcnt vmcnt(8)
	v_dot8_i32_i4 v19, v56, v75, 0
	v_dot8_i32_i4 v19, v57, v108, v19
	v_lshl_add_u32 v17, v17, 4, v18
	v_dot8_i32_i4 v18, v56, v73, 0
	v_dot8_i32_i4 v18, v57, v77, v18
	s_waitcnt vmcnt(7)
	v_dot8_i32_i4 v20, v44, v75, 0
	v_dot8_i32_i4 v20, v45, v108, v20
	v_lshl_add_u32 v18, v18, 4, v19
	v_dot8_i32_i4 v19, v44, v73, 0
	v_dot8_i32_i4 v19, v45, v77, v19
	s_waitcnt vmcnt(6)
	v_dot8_i32_i4 v21, v36, v75, 0
	v_dot8_i32_i4 v21, v37, v108, v21
	v_lshl_add_u32 v19, v19, 4, v20
	v_dot8_i32_i4 v20, v36, v73, 0
	v_dot8_i32_i4 v20, v37, v77, v20
	s_waitcnt vmcnt(5)
	v_dot8_i32_i4 v22, v32, v75, 0
	v_dot8_i32_i4 v22, v33, v108, v22
	v_lshl_add_u32 v20, v20, 4, v21
	v_dot8_i32_i4 v21, v32, v73, 0
	v_dot8_i32_i4 v21, v33, v77, v21
	s_waitcnt vmcnt(4)
	v_dot8_i32_i4 v23, v40, v75, 0
	v_dot8_i32_i4 v23, v41, v108, v23
	v_lshl_add_u32 v21, v21, 4, v22
	v_dot8_i32_i4 v22, v40, v73, 0
	v_dot8_i32_i4 v22, v41, v77, v22
	s_waitcnt vmcnt(3)
	v_dot8_i32_i4 v26, v28, v75, 0
	v_dot8_i32_i4 v26, v29, v108, v26
	v_lshl_add_u32 v22, v22, 4, v23
	v_dot8_i32_i4 v23, v28, v73, 0
	v_dot8_i32_i4 v23, v29, v77, v23
	s_waitcnt vmcnt(2)
	v_dot8_i32_i4 v27, v14, v75, 0
	v_dot8_i32_i4 v27, v15, v108, v27
	v_lshl_add_u32 v23, v23, 4, v26
	v_dot8_i32_i4 v26, v14, v73, 0
	v_dot8_i32_i4 v26, v15, v77, v26
	s_waitcnt vmcnt(1)
	v_dot8_i32_i4 v15, v10, v73, 0
	s_nop 0
	v_lshl_add_u32 v14, v26, 4, v27
	v_dot8_i32_i4 v26, v10, v75, 0
	v_dot8_i32_i4 v15, v11, v77, v15
	v_dot8_i32_i4 v26, v11, v108, v26
	s_waitcnt vmcnt(0)
	v_dot8_i32_i4 v11, v24, v73, 0
	v_dot8_i32_i4 v11, v25, v77, v11
	v_lshl_add_u32 v10, v15, 4, v26
	v_dot8_i32_i4 v15, v24, v75, 0
	v_dot8_i32_i4 v15, v25, v108, v15
	s_nop 1
	s_nop 0
	v_lshl_add_u32 v11, v11, 4, v15
	v_cndmask_b32_e64 v15, v8, v5, s[40:41]
	v_cndmask_b32_e64 v5, v5, v8, s[40:41]
	v_cndmask_b32_e64 v8, v9, v12, s[40:41]
	ds_swizzle_b32 v8, v8 offset:swizzle(SWAP,1)
	ds_swizzle_b32 v5, v5 offset:swizzle(SWAP,1)
	v_cndmask_b32_e64 v9, v12, v9, s[40:41]
	v_cndmask_b32_e64 v24, v13, v16, s[40:41]
	s_waitcnt lgkmcnt(1)
	v_add_u32_e32 v8, v9, v8
	v_cndmask_b32_e64 v9, v16, v13, s[40:41]
	v_cndmask_b32_e64 v13, v17, v18, s[40:41]
	s_waitcnt lgkmcnt(0)
	v_add_u32_e32 v5, v15, v5
	ds_swizzle_b32 v13, v13 offset:swizzle(SWAP,1)
	v_cndmask_b32_e64 v15, v19, v20, s[40:41]
	ds_swizzle_b32 v15, v15 offset:swizzle(SWAP,1)
	v_cndmask_b32_e64 v16, v21, v22, s[40:41]
	ds_swizzle_b32 v16, v16 offset:swizzle(SWAP,1)
	v_cndmask_b32_e64 v12, v18, v17, s[40:41]
	s_waitcnt lgkmcnt(2)
	v_add_u32_e32 v12, v12, v13
	v_cndmask_b32_e64 v13, v20, v19, s[40:41]
	s_waitcnt lgkmcnt(1)
	v_add_u32_e32 v13, v13, v15
	v_cndmask_b32_e64 v15, v22, v21, s[40:41]
	ds_swizzle_b32 v24, v24 offset:swizzle(SWAP,1)
	s_waitcnt lgkmcnt(1)
	v_add_u32_e32 v15, v15, v16
	v_cndmask_b32_e64 v16, v14, v23, s[40:41]
	v_cndmask_b32_e64 v14, v23, v14, s[40:41]
	v_cndmask_b32_e64 v17, v10, v11, s[40:41]
	ds_swizzle_b32 v14, v14 offset:swizzle(SWAP,1)
	ds_swizzle_b32 v17, v17 offset:swizzle(SWAP,1)
	s_waitcnt lgkmcnt(2)
	v_add_u32_e32 v9, v9, v24
	v_cndmask_b32_e64 v10, v11, v10, s[40:41]
	v_cndmask_b32_e64 v18, v5, v8, s[42:43]
	s_waitcnt lgkmcnt(1)
	v_add_u32_e32 v14, v16, v14
	s_waitcnt lgkmcnt(0)
	v_add_u32_e32 v10, v10, v17
	v_cndmask_b32_e64 v5, v8, v5, s[42:43]
	v_cndmask_b32_e64 v8, v12, v9, s[42:43]
	v_cndmask_b32_e64 v9, v9, v12, s[42:43]
	ds_swizzle_b32 v9, v9 offset:swizzle(SWAP,2)
	v_cndmask_b32_e64 v11, v13, v15, s[42:43]
	v_cndmask_b32_e64 v12, v14, v10, s[42:43]
	ds_swizzle_b32 v18, v18 offset:swizzle(SWAP,2)
	ds_swizzle_b32 v11, v11 offset:swizzle(SWAP,2)
	ds_swizzle_b32 v12, v12 offset:swizzle(SWAP,2)
	s_waitcnt lgkmcnt(3)
	v_add_u32_e32 v8, v8, v9
	v_cndmask_b32_e64 v9, v15, v13, s[42:43]
	v_cndmask_b32_e64 v10, v10, v14, s[42:43]
	s_waitcnt lgkmcnt(2)
	v_add_u32_e32 v5, v5, v18
	s_waitcnt lgkmcnt(1)
	v_add_u32_e32 v9, v9, v11
	s_waitcnt lgkmcnt(0)
	v_add_u32_e32 v10, v10, v12
	v_cndmask_b32_e64 v11, v5, v8, s[44:45]
	v_cndmask_b32_e64 v12, v9, v10, s[44:45]
	ds_swizzle_b32 v11, v11 offset:swizzle(SWAP,4)
	ds_swizzle_b32 v12, v12 offset:swizzle(SWAP,4)
	v_cndmask_b32_e64 v5, v8, v5, s[44:45]
	v_cndmask_b32_e64 v8, v10, v9, s[44:45]
	s_waitcnt lgkmcnt(1)
	v_add_u32_e32 v5, v5, v11
	s_waitcnt lgkmcnt(0)
	v_add_u32_e32 v8, v8, v12
	v_cndmask_b32_e64 v9, v5, v8, s[46:47]
	ds_swizzle_b32 v9, v9 offset:swizzle(SWAP,8)
	v_cndmask_b32_e64 v5, v8, v5, s[46:47]
	s_waitcnt lgkmcnt(0)
	v_add_u32_e32 v5, v5, v9
	ds_swizzle_b32 v8, v5 offset:swizzle(SWAP,16)
	s_waitcnt lgkmcnt(0)
	v_add_u32_e32 v8, v5, v8
	ds_bpermute_b32 v0, v0, v8
	s_and_saveexec_b64 s[0:1], s[48:49]
	s_cbranch_execz .LBB0_666
	v_ashrrev_i32_e32 v5, 31, v4
	v_lshlrev_b64 v[4:5], 2, v[4:5]
	v_lshl_add_u64 v[10:11], s[8:9], 0, v[4:5]
	v_mov_b32_e32 v9, v135
	v_lshl_add_u64 v[4:5], s[10:11], 0, v[4:5]
	v_mov_b32_e32 v6, v151
	s_nop 0
	v_mov_b32_e32 v4, v143
	s_waitcnt lgkmcnt(0)
	v_add_u32_e32 v0, v8, v0
	v_cvt_f32_i32_e32 v0, v0
	v_mul_f32_e32 v0, v0, v9
	v_mul_f32_e32 v0, v3, v0
	v_mul_f32_e32 v5, 0x3d372713, v0
	v_mul_f32_e32 v5, v0, v5
	v_mul_f32_e32 v3, 0.5, v0
	v_fmac_f32_e32 v0, v0, v5
	v_mul_f32_e32 v0, 0x3f4c422a, v0
	v_add_f32_e32 v0, v0, v0
	v_mul_f32_e32 v0, 0x3fb8aa3b, v0
	v_exp_f32_e32 v0, v0
	s_nop 0
	v_add_f32_e32 v0, 1.0, v0
	v_rcp_f32_e32 v0, v0
	s_nop 0
	v_fma_f32 v0, v0, -2.0, 1.0
	v_add_f32_e32 v0, 1.0, v0
	v_mul_f32_e32 v0, v3, v0
	v_mul_f32_e32 v0, v6, v0
	v_mul_f32_e32 v0, v4, v0
	ds_write_b32 v109, v0 offset:448
	s_branch .LBB0_666

.LBB0_688:
	v_cmp_gt_i32_e32 vcc, s33, v78
	s_or_b64 s[16:17], s[16:17], exec
	s_and_saveexec_b64 s[18:19], vcc
	s_cbranch_execz .LBB0_687
	v_ashrrev_i32_e32 v79, 31, v78
	v_lshlrev_b64 v[2:3], 9, v[78:79]
	v_lshl_add_u64 v[2:3], v[62:63], 0, v[2:3]
	global_load_dword v4, v[2:3], off
	s_mov_b32 s6, s54
	s_mov_b32 s7, s55
	global_load_dword v73, v[2:3], off offset:64
	global_load_dword v51, v[2:3], off offset:128
	global_load_dword v50, v[2:3], off offset:192
	global_load_dword v49, v[2:3], off offset:256
	global_load_dword v48, v[2:3], off offset:320
	global_load_dword v46, v[2:3], off offset:384
	s_waitcnt lgkmcnt(0)
	global_load_dword v0, v[2:3], off offset:448
	v_add_u32_e32 v47, s23, v194
	ds_read2_b32 v[2:3], v47 offset1:16
	v_mov_b32_e32 v75, v1
	v_mov_b32_e32 v77, v1
	s_waitcnt lgkmcnt(0)
	v_readlane_b32 s38, v2, 0
	v_readlane_b32 s56, v2, 1
	v_readlane_b32 s24, v2, 3
	v_readlane_b32 s28, v2, 4
	v_readlane_b32 s34, v2, 5
	v_readlane_b32 s36, v2, 6
	v_readlane_b32 s26, v2, 8
	v_readlane_b32 s30, v2, 9
	v_readlane_b32 s60, v2, 12
	s_waitcnt vmcnt(0)
	v_lshlrev_b32_e32 v4, 9, v4
	v_lshlrev_b32_e32 v73, 9, v73
	v_lshlrev_b32_e32 v51, 9, v51
	v_lshlrev_b32_e32 v50, 9, v50
	v_lshlrev_b32_e32 v49, 9, v49
	v_lshlrev_b32_e32 v48, 9, v48
	v_lshlrev_b32_e32 v46, 9, v46
	v_lshlrev_b32_e32 v0, 9, v0
	s_nop 0
	v_readlane_b32 s20, v4, 0
	v_readlane_b32 s22, v4, 6
	s_nop 1
	s_nop 1
	buffer_load_dwordx2 v[8:9], v192, s[4:7], s20 offen
	v_readlane_b32 s25, v4, 7
	s_nop 0
	buffer_load_dwordx2 v[22:23], v192, s[4:7], s22 offen
	v_readlane_b32 s20, v4, 1
	v_readlane_b32 s27, v4, 8
	s_nop 1
	buffer_load_dwordx2 v[24:25], v192, s[4:7], s25 offen
	v_readlane_b32 s25, v4, 9
	s_nop 1
	buffer_load_dwordx2 v[12:13], v192, s[4:7], s20 offen
	v_readlane_b32 s20, v4, 2
	s_nop 2
	buffer_load_dwordx2 v[28:29], v192, s[4:7], s25 offen
	buffer_load_dwordx2 v[26:27], v192, s[4:7], s27 offen
	v_readlane_b32 s29, v4, 10
	s_nop 1
	buffer_load_dwordx2 v[14:15], v192, s[4:7], s20 offen
	v_readlane_b32 s20, v4, 3
	v_readlane_b32 s31, v4, 11
	v_readlane_b32 s35, v4, 12
	v_readlane_b32 s37, v4, 13
	v_readlane_b32 s39, v4, 14
	s_nop 0
	buffer_load_dwordx2 v[16:17], v192, s[4:7], s20 offen
	v_readlane_b32 s20, v4, 4
	v_readlane_b32 s27, v4, 15
	s_nop 3
	buffer_load_dwordx2 v[18:19], v192, s[4:7], s20 offen
	v_readlane_b32 s20, v4, 5
	s_mov_b32 s25, s27
	v_readlane_b32 s22, v2, 7
	s_nop 2
	buffer_load_dwordx2 v[20:21], v192, s[4:7], s20 offen
	buffer_load_dwordx2 v[30:31], v192, s[4:7], s29 offen
	buffer_load_dwordx2 v[32:33], v192, s[4:7], s31 offen
	buffer_load_dwordx2 v[34:35], v192, s[4:7], s35 offen
	buffer_load_dwordx2 v[10:11], v192, s[4:7], s37 offen
	buffer_load_dwordx2 v[6:7], v192, s[4:7], s39 offen
	buffer_load_dwordx2 v[4:5], v192, s[4:7], s25 offen
	v_readlane_b32 s20, v2, 2
	s_waitcnt vmcnt(15)
	v_cvt_scalef32_pk_f32_fp4 v[36:37], v8, 1.0
	v_cvt_scalef32_pk_f32_fp4 v[44:45], v9, 1.0
	v_pk_fma_f32 v[36:37], v[36:37], s[38:39], 0 op_sel_hi:[1,0,0]
	v_pk_fma_f32 v[44:45], v[44:45], s[38:39], 0 op_sel_hi:[1,0,0]
	s_waitcnt vmcnt(14)
	v_cvt_scalef32_pk_f32_fp4 v[156:157], v23, 1.0
	v_cvt_scalef32_pk_f32_fp4 v[42:43], v8, 1.0 op_sel:[1,1,0]
	v_cvt_scalef32_pk_f32_fp4 v[38:39], v8, 1.0 op_sel:[1,0,0]
	s_waitcnt vmcnt(13)
	v_cvt_scalef32_pk_f32_fp4 v[170:171], v25, 1.0
	v_cvt_scalef32_pk_f32_fp4 v[40:41], v8, 1.0 op_sel:[0,1,0]
	v_cvt_scalef32_pk_f32_fp4 v[52:53], v9, 1.0 op_sel:[1,0,0]
	s_waitcnt vmcnt(12)
	v_cvt_scalef32_pk_f32_fp4 v[56:57], v12, 1.0
	v_cvt_scalef32_pk_f32_fp4 v[86:87], v13, 1.0
	v_pk_fma_f32 v[36:37], v[56:57], s[56:57], v[36:37] op_sel_hi:[1,0,1]
	v_pk_fma_f32 v[44:45], v[86:87], s[56:57], v[44:45] op_sel_hi:[1,0,1]
	v_cvt_scalef32_pk_f32_fp4 v[54:55], v9, 1.0 op_sel:[0,1,0]
	s_waitcnt vmcnt(10)
	v_cvt_scalef32_pk_f32_fp4 v[184:185], v27, 1.0
	v_cvt_scalef32_pk_f32_fp4 v[8:9], v9, 1.0 op_sel:[1,1,0]
	s_waitcnt vmcnt(9)
	v_cvt_scalef32_pk_f32_fp4 v[92:93], v14, 1.0
	v_cvt_scalef32_pk_f32_fp4 v[94:95], v14, 1.0 op_sel:[1,0,0]
	v_cvt_scalef32_pk_f32_fp4 v[96:97], v14, 1.0 op_sel:[0,1,0]
	v_cvt_scalef32_pk_f32_fp4 v[98:99], v14, 1.0 op_sel:[1,1,0]
	v_cvt_scalef32_pk_f32_fp4 v[100:101], v15, 1.0
	v_cvt_scalef32_pk_f32_fp4 v[102:103], v15, 1.0 op_sel:[1,0,0]
	v_cvt_scalef32_pk_f32_fp4 v[104:105], v15, 1.0 op_sel:[0,1,0]
	v_cvt_scalef32_pk_f32_fp4 v[106:107], v15, 1.0 op_sel:[1,1,0]
	s_waitcnt vmcnt(8)
	v_cvt_scalef32_pk_f32_fp4 v[14:15], v16, 1.0
	v_pk_fma_f32 v[36:37], v[92:93], s[20:21], v[36:37] op_sel_hi:[1,0,1]
	v_cvt_scalef32_pk_f32_fp4 v[114:115], v17, 1.0
	v_pk_fma_f32 v[14:15], v[14:15], s[24:25], v[36:37] op_sel_hi:[1,0,1]
	v_pk_fma_f32 v[36:37], v[100:101], s[20:21], v[44:45] op_sel_hi:[1,0,1]
	v_cvt_scalef32_pk_f32_fp4 v[84:85], v12, 1.0 op_sel:[1,1,0]
	s_waitcnt vmcnt(7)
	v_cvt_scalef32_pk_f32_fp4 v[128:129], v19, 1.0
	v_pk_fma_f32 v[36:37], v[114:115], s[24:25], v[36:37] op_sel_hi:[1,0,1]
	v_cvt_scalef32_pk_f32_fp4 v[202:203], v29, 1.0
	v_pk_fma_f32 v[36:37], v[128:129], s[28:29], v[36:37] op_sel_hi:[1,0,1]
	v_pk_fma_f32 v[42:43], v[42:43], s[38:39], 0 op_sel_hi:[1,0,0]
	v_cvt_scalef32_pk_f32_fp4 v[80:81], v12, 1.0 op_sel:[1,0,0]
	v_cvt_scalef32_pk_f32_fp4 v[82:83], v12, 1.0 op_sel:[0,1,0]
	s_waitcnt vmcnt(6)
	v_cvt_scalef32_pk_f32_fp4 v[142:143], v21, 1.0
	v_pk_fma_f32 v[36:37], v[142:143], s[34:35], v[36:37] op_sel_hi:[1,0,1]
	v_cvt_scalef32_pk_f32_fp4 v[88:89], v13, 1.0 op_sel:[1,0,0]
	v_pk_fma_f32 v[36:37], v[156:157], s[36:37], v[36:37] op_sel_hi:[1,0,1]
	v_cvt_scalef32_pk_f32_fp4 v[90:91], v13, 1.0 op_sel:[0,1,0]
	v_pk_fma_f32 v[36:37], v[170:171], s[22:23], v[36:37] op_sel_hi:[1,0,1]
	v_cvt_scalef32_pk_f32_fp4 v[12:13], v13, 1.0 op_sel:[1,1,0]
	v_pk_fma_f32 v[36:37], v[184:185], s[26:27], v[36:37] op_sel_hi:[1,0,1]
	v_pk_fma_f32 v[38:39], v[38:39], s[38:39], 0 op_sel_hi:[1,0,0]
	v_pk_fma_f32 v[40:41], v[40:41], s[38:39], 0 op_sel_hi:[1,0,0]
	v_pk_fma_f32 v[52:53], v[52:53], s[38:39], 0 op_sel_hi:[1,0,0]
	v_pk_fma_f32 v[54:55], v[54:55], s[38:39], 0 op_sel_hi:[1,0,0]
	v_pk_fma_f32 v[8:9], v[8:9], s[38:39], 0 op_sel_hi:[1,0,0]
	v_pk_fma_f32 v[42:43], v[84:85], s[56:57], v[42:43] op_sel_hi:[1,0,1]
	v_readlane_b32 s38, v2, 10
	s_waitcnt vmcnt(5)
	v_cvt_scalef32_pk_f32_fp4 v[84:85], v31, 1.0
	v_pk_fma_f32 v[36:37], v[202:203], s[30:31], v[36:37] op_sel_hi:[1,0,1]
	v_cvt_scalef32_pk_f32_fp4 v[108:109], v16, 1.0 op_sel:[1,0,0]
	v_cvt_scalef32_pk_f32_fp4 v[110:111], v16, 1.0 op_sel:[0,1,0]
	v_cvt_scalef32_pk_f32_fp4 v[112:113], v16, 1.0 op_sel:[1,1,0]
	v_cvt_scalef32_pk_f32_fp4 v[116:117], v17, 1.0 op_sel:[1,0,0]
	v_cvt_scalef32_pk_f32_fp4 v[118:119], v17, 1.0 op_sel:[0,1,0]
	v_cvt_scalef32_pk_f32_fp4 v[120:121], v17, 1.0 op_sel:[1,1,0]
	v_cvt_scalef32_pk_f32_fp4 v[16:17], v18, 1.0
	v_pk_fma_f32 v[38:39], v[80:81], s[56:57], v[38:39] op_sel_hi:[1,0,1]
	v_pk_fma_f32 v[40:41], v[82:83], s[56:57], v[40:41] op_sel_hi:[1,0,1]
	v_pk_fma_f32 v[52:53], v[88:89], s[56:57], v[52:53] op_sel_hi:[1,0,1]
	v_pk_fma_f32 v[54:55], v[90:91], s[56:57], v[54:55] op_sel_hi:[1,0,1]
	v_pk_fma_f32 v[56:57], v[12:13], s[56:57], v[8:9] op_sel_hi:[1,0,1]
	v_readlane_b32 s56, v2, 11
	s_waitcnt vmcnt(4)
	v_cvt_scalef32_pk_f32_fp4 v[216:217], v33, 1.0
	v_pk_fma_f32 v[36:37], v[84:85], s[38:39], v[36:37] op_sel_hi:[1,0,1]
	v_pk_fma_f32 v[14:15], v[16:17], s[28:29], v[14:15] op_sel_hi:[1,0,1]
	s_waitcnt vmcnt(3)
	v_cvt_scalef32_pk_f32_fp4 v[16:17], v35, 1.0
	v_pk_fma_f32 v[36:37], v[216:217], s[56:57], v[36:37] op_sel_hi:[1,0,1]
	v_cvt_scalef32_pk_f32_fp4 v[130:131], v19, 1.0 op_sel:[1,0,0]
	v_pk_fma_f32 v[16:17], v[16:17], s[60:61], v[36:37] op_sel_hi:[1,0,1]
	v_pk_fma_f32 v[36:37], v[102:103], s[20:21], v[52:53] op_sel_hi:[1,0,1]
	v_cvt_scalef32_pk_f32_fp4 v[144:145], v21, 1.0 op_sel:[1,0,0]
	v_pk_fma_f32 v[36:37], v[116:117], s[24:25], v[36:37] op_sel_hi:[1,0,1]
	v_cvt_scalef32_pk_f32_fp4 v[158:159], v23, 1.0 op_sel:[1,0,0]
	v_pk_fma_f32 v[36:37], v[130:131], s[28:29], v[36:37] op_sel_hi:[1,0,1]
	v_cvt_scalef32_pk_f32_fp4 v[122:123], v18, 1.0 op_sel:[1,0,0]
	v_pk_fma_f32 v[36:37], v[144:145], s[34:35], v[36:37] op_sel_hi:[1,0,1]
	v_cvt_scalef32_pk_f32_fp4 v[124:125], v18, 1.0 op_sel:[0,1,0]
	v_cvt_scalef32_pk_f32_fp4 v[126:127], v18, 1.0 op_sel:[1,1,0]
	v_cvt_scalef32_pk_f32_fp4 v[132:133], v19, 1.0 op_sel:[0,1,0]
	v_cvt_scalef32_pk_f32_fp4 v[134:135], v19, 1.0 op_sel:[1,1,0]
	v_cvt_scalef32_pk_f32_fp4 v[18:19], v20, 1.0
	v_cvt_scalef32_pk_f32_fp4 v[172:173], v25, 1.0 op_sel:[1,0,0]
	v_pk_fma_f32 v[36:37], v[158:159], s[36:37], v[36:37] op_sel_hi:[1,0,1]
	v_cvt_scalef32_pk_f32_fp4 v[136:137], v20, 1.0 op_sel:[1,0,0]
	v_cvt_scalef32_pk_f32_fp4 v[138:139], v20, 1.0 op_sel:[0,1,0]
	v_cvt_scalef32_pk_f32_fp4 v[140:141], v20, 1.0 op_sel:[1,1,0]
	v_cvt_scalef32_pk_f32_fp4 v[146:147], v21, 1.0 op_sel:[0,1,0]
	v_cvt_scalef32_pk_f32_fp4 v[148:149], v21, 1.0 op_sel:[1,1,0]
	v_cvt_scalef32_pk_f32_fp4 v[20:21], v22, 1.0
	v_cvt_scalef32_pk_f32_fp4 v[186:187], v27, 1.0 op_sel:[1,0,0]
	v_pk_fma_f32 v[14:15], v[18:19], s[34:35], v[14:15] op_sel_hi:[1,0,1]
	v_pk_fma_f32 v[36:37], v[172:173], s[22:23], v[36:37] op_sel_hi:[1,0,1]
	v_cvt_scalef32_pk_f32_fp4 v[150:151], v22, 1.0 op_sel:[1,0,0]
	v_cvt_scalef32_pk_f32_fp4 v[152:153], v22, 1.0 op_sel:[0,1,0]
	v_cvt_scalef32_pk_f32_fp4 v[154:155], v22, 1.0 op_sel:[1,1,0]
	v_cvt_scalef32_pk_f32_fp4 v[160:161], v23, 1.0 op_sel:[0,1,0]
	v_cvt_scalef32_pk_f32_fp4 v[162:163], v23, 1.0 op_sel:[1,1,0]
	v_cvt_scalef32_pk_f32_fp4 v[22:23], v24, 1.0
	v_cvt_scalef32_pk_f32_fp4 v[204:205], v29, 1.0 op_sel:[1,0,0]
	v_pk_fma_f32 v[14:15], v[20:21], s[36:37], v[14:15] op_sel_hi:[1,0,1]
	v_pk_fma_f32 v[36:37], v[186:187], s[26:27], v[36:37] op_sel_hi:[1,0,1]
	v_cvt_scalef32_pk_f32_fp4 v[176:177], v26, 1.0
	v_cvt_scalef32_pk_f32_fp4 v[86:87], v31, 1.0 op_sel:[1,0,0]
	v_pk_fma_f32 v[14:15], v[22:23], s[22:23], v[14:15] op_sel_hi:[1,0,1]
	v_pk_fma_f32 v[36:37], v[204:205], s[30:31], v[36:37] op_sel_hi:[1,0,1]
	v_cvt_scalef32_pk_f32_fp4 v[190:191], v28, 1.0
	v_cvt_scalef32_pk_f32_fp4 v[228:229], v33, 1.0 op_sel:[1,0,0]
	v_pk_fma_f32 v[14:15], v[176:177], s[26:27], v[14:15] op_sel_hi:[1,0,1]
	v_pk_fma_f32 v[36:37], v[86:87], s[38:39], v[36:37] op_sel_hi:[1,0,1]
	v_cvt_scalef32_pk_f32_fp4 v[8:9], v30, 1.0
	v_pk_fma_f32 v[14:15], v[190:191], s[30:31], v[14:15] op_sel_hi:[1,0,1]
	v_cvt_scalef32_pk_f32_fp4 v[18:19], v35, 1.0 op_sel:[1,0,0]
	v_pk_fma_f32 v[36:37], v[228:229], s[56:57], v[36:37] op_sel_hi:[1,0,1]
	v_cvt_scalef32_pk_f32_fp4 v[90:91], v32, 1.0
	v_pk_fma_f32 v[8:9], v[8:9], s[38:39], v[14:15] op_sel_hi:[1,0,1]
	v_pk_fma_f32 v[18:19], v[18:19], s[60:61], v[36:37] op_sel_hi:[1,0,1]
	v_pk_fma_f32 v[36:37], v[104:105], s[20:21], v[54:55] op_sel_hi:[1,0,1]
	v_cvt_scalef32_pk_f32_fp4 v[232:233], v34, 1.0
	v_pk_fma_f32 v[8:9], v[90:91], s[56:57], v[8:9] op_sel_hi:[1,0,1]
	v_pk_fma_f32 v[36:37], v[118:119], s[24:25], v[36:37] op_sel_hi:[1,0,1]
	v_pk_fma_f32 v[22:23], v[232:233], s[60:61], v[8:9] op_sel_hi:[1,0,1]
	v_pk_fma_f32 v[8:9], v[94:95], s[20:21], v[38:39] op_sel_hi:[1,0,1]
	v_pk_fma_f32 v[36:37], v[132:133], s[28:29], v[36:37] op_sel_hi:[1,0,1]
	v_pk_fma_f32 v[8:9], v[108:109], s[24:25], v[8:9] op_sel_hi:[1,0,1]
	v_pk_fma_f32 v[36:37], v[146:147], s[34:35], v[36:37] op_sel_hi:[1,0,1]
	v_cvt_scalef32_pk_f32_fp4 v[174:175], v25, 1.0 op_sel:[0,1,0]
	v_pk_fma_f32 v[8:9], v[122:123], s[28:29], v[8:9] op_sel_hi:[1,0,1]
	v_pk_fma_f32 v[36:37], v[160:161], s[36:37], v[36:37] op_sel_hi:[1,0,1]
	v_cvt_scalef32_pk_f32_fp4 v[188:189], v27, 1.0 op_sel:[0,1,0]
	v_pk_fma_f32 v[8:9], v[136:137], s[34:35], v[8:9] op_sel_hi:[1,0,1]
	v_pk_fma_f32 v[36:37], v[174:175], s[22:23], v[36:37] op_sel_hi:[1,0,1]
	v_cvt_scalef32_pk_f32_fp4 v[164:165], v24, 1.0 op_sel:[1,0,0]
	v_cvt_scalef32_pk_f32_fp4 v[206:207], v29, 1.0 op_sel:[0,1,0]
	v_pk_fma_f32 v[8:9], v[150:151], s[36:37], v[8:9] op_sel_hi:[1,0,1]
	v_pk_fma_f32 v[36:37], v[188:189], s[26:27], v[36:37] op_sel_hi:[1,0,1]
	v_cvt_scalef32_pk_f32_fp4 v[178:179], v26, 1.0 op_sel:[1,0,0]
	v_cvt_scalef32_pk_f32_fp4 v[88:89], v31, 1.0 op_sel:[0,1,0]
	v_pk_fma_f32 v[8:9], v[164:165], s[22:23], v[8:9] op_sel_hi:[1,0,1]
	v_pk_fma_f32 v[36:37], v[206:207], s[30:31], v[36:37] op_sel_hi:[1,0,1]
	v_cvt_scalef32_pk_f32_fp4 v[196:197], v28, 1.0 op_sel:[1,0,0]
	v_cvt_scalef32_pk_f32_fp4 v[230:231], v33, 1.0 op_sel:[0,1,0]
	v_pk_fma_f32 v[8:9], v[178:179], s[26:27], v[8:9] op_sel_hi:[1,0,1]
	v_pk_fma_f32 v[36:37], v[88:89], s[38:39], v[36:37] op_sel_hi:[1,0,1]
	v_cvt_scalef32_pk_f32_fp4 v[12:13], v30, 1.0 op_sel:[1,0,0]
	v_pk_fma_f32 v[8:9], v[196:197], s[30:31], v[8:9] op_sel_hi:[1,0,1]
	v_cvt_scalef32_pk_f32_fp4 v[20:21], v35, 1.0 op_sel:[0,1,0]
	v_pk_fma_f32 v[36:37], v[230:231], s[56:57], v[36:37] op_sel_hi:[1,0,1]
	v_pk_fma_f32 v[8:9], v[12:13], s[38:39], v[8:9] op_sel_hi:[1,0,1]
	v_pk_fma_f32 v[12:13], v[96:97], s[20:21], v[40:41] op_sel_hi:[1,0,1]
	v_pk_fma_f32 v[14:15], v[98:99], s[20:21], v[42:43] op_sel_hi:[1,0,1]
	v_pk_fma_f32 v[20:21], v[20:21], s[60:61], v[36:37] op_sel_hi:[1,0,1]
	v_pk_fma_f32 v[36:37], v[106:107], s[20:21], v[56:57] op_sel_hi:[1,0,1]
	v_pk_fma_f32 v[12:13], v[110:111], s[24:25], v[12:13] op_sel_hi:[1,0,1]
	v_pk_fma_f32 v[14:15], v[112:113], s[24:25], v[14:15] op_sel_hi:[1,0,1]
	v_pk_fma_f32 v[36:37], v[120:121], s[24:25], v[36:37] op_sel_hi:[1,0,1]
	v_pk_fma_f32 v[12:13], v[124:125], s[28:29], v[12:13] op_sel_hi:[1,0,1]
	v_pk_fma_f32 v[14:15], v[126:127], s[28:29], v[14:15] op_sel_hi:[1,0,1]
	v_pk_fma_f32 v[36:37], v[134:135], s[28:29], v[36:37] op_sel_hi:[1,0,1]
	v_pk_fma_f32 v[12:13], v[138:139], s[34:35], v[12:13] op_sel_hi:[1,0,1]
	v_pk_fma_f32 v[14:15], v[140:141], s[34:35], v[14:15] op_sel_hi:[1,0,1]
	v_pk_fma_f32 v[36:37], v[148:149], s[34:35], v[36:37] op_sel_hi:[1,0,1]
	v_cvt_scalef32_pk_f32_fp4 v[166:167], v24, 1.0 op_sel:[0,1,0]
	v_cvt_scalef32_pk_f32_fp4 v[168:169], v24, 1.0 op_sel:[1,1,0]
	v_cvt_scalef32_pk_f32_fp4 v[24:25], v25, 1.0 op_sel:[1,1,0]
	v_pk_fma_f32 v[12:13], v[152:153], s[36:37], v[12:13] op_sel_hi:[1,0,1]
	v_pk_fma_f32 v[14:15], v[154:155], s[36:37], v[14:15] op_sel_hi:[1,0,1]
	v_pk_fma_f32 v[36:37], v[162:163], s[36:37], v[36:37] op_sel_hi:[1,0,1]
	v_pk_fma_f32 v[12:13], v[166:167], s[22:23], v[12:13] op_sel_hi:[1,0,1]
	v_pk_fma_f32 v[14:15], v[168:169], s[22:23], v[14:15] op_sel_hi:[1,0,1]
	v_readlane_b32 s20, v73, 0
	v_pk_fma_f32 v[24:25], v[24:25], s[22:23], v[36:37] op_sel_hi:[1,0,1]
	v_readlane_b32 s22, v73, 2
	v_readlane_b32 s25, v73, 5
	v_cvt_scalef32_pk_f32_fp4 v[182:183], v26, 1.0 op_sel:[1,1,0]
	s_nop 0
	buffer_load_dwordx2 v[38:39], v192, s[4:7], s20 offen
	s_nop 1
	buffer_load_dwordx2 v[44:45], v192, s[4:7], s22 offen
	s_nop 1
	buffer_load_dwordx2 v[108:109], v192, s[4:7], s25 offen
	v_readlane_b32 s20, v73, 1
	v_cvt_scalef32_pk_f32_fp4 v[180:181], v26, 1.0 op_sel:[0,1,0]
	v_cvt_scalef32_pk_f32_fp4 v[26:27], v27, 1.0 op_sel:[1,1,0]
	v_cvt_scalef32_pk_f32_fp4 v[200:201], v28, 1.0 op_sel:[1,1,0]
	v_pk_fma_f32 v[14:15], v[182:183], s[26:27], v[14:15] op_sel_hi:[1,0,1]
	v_readlane_b32 s24, v73, 3
	v_cvt_scalef32_pk_f32_fp4 v[82:83], v30, 1.0 op_sel:[1,1,0]
	v_pk_fma_f32 v[14:15], v[200:201], s[30:31], v[14:15] op_sel_hi:[1,0,1]
	v_pk_fma_f32 v[24:25], v[26:27], s[26:27], v[24:25] op_sel_hi:[1,0,1]
	buffer_load_dwordx2 v[26:27], v192, s[4:7], s20 offen
	v_pk_fma_f32 v[14:15], v[82:83], s[38:39], v[14:15] op_sel_hi:[1,0,1]
	buffer_load_dwordx2 v[82:83], v192, s[4:7], s24 offen
	v_readlane_b32 s24, v73, 4
	v_readlane_b32 s25, v73, 6
	v_pk_fma_f32 v[12:13], v[180:181], s[26:27], v[12:13] op_sel_hi:[1,0,1]
	v_readlane_b32 s26, v73, 7
	s_nop 1
	buffer_load_dwordx2 v[96:97], v192, s[4:7], s24 offen
	s_nop 1
	buffer_load_dwordx2 v[116:117], v192, s[4:7], s25 offen
	s_nop 1
	s_nop 0
	buffer_load_dwordx2 v[118:119], v192, s[4:7], s26 offen
	v_cvt_scalef32_pk_f32_fp4 v[198:199], v28, 1.0 op_sel:[0,1,0]
	v_cvt_scalef32_pk_f32_fp4 v[28:29], v29, 1.0 op_sel:[1,1,0]
	v_readlane_b32 s25, v73, 8
	v_cvt_scalef32_pk_f32_fp4 v[80:81], v30, 1.0 op_sel:[0,1,0]
	v_cvt_scalef32_pk_f32_fp4 v[30:31], v31, 1.0 op_sel:[1,1,0]
	v_pk_fma_f32 v[24:25], v[28:29], s[30:31], v[24:25] op_sel_hi:[1,0,1]
	v_readlane_b32 s26, v73, 9
	v_readlane_b32 s27, v73, 10
	v_readlane_b32 s28, v73, 11
	v_cvt_scalef32_pk_f32_fp4 v[208:209], v32, 1.0 op_sel:[1,0,0]
	v_cvt_scalef32_pk_f32_fp4 v[210:211], v32, 1.0 op_sel:[0,1,0]
	v_cvt_scalef32_pk_f32_fp4 v[214:215], v32, 1.0 op_sel:[1,1,0]
	v_cvt_scalef32_pk_f32_fp4 v[32:33], v33, 1.0 op_sel:[1,1,0]
	v_pk_fma_f32 v[24:25], v[30:31], s[38:39], v[24:25] op_sel_hi:[1,0,1]
	buffer_load_dwordx2 v[120:121], v192, s[4:7], s25 offen
	buffer_load_dwordx2 v[122:123], v192, s[4:7], s26 offen
	buffer_load_dwordx2 v[124:125], v192, s[4:7], s27 offen
	buffer_load_dwordx2 v[126:127], v192, s[4:7], s28 offen
	v_readlane_b32 s25, v73, 12
	v_cvt_scalef32_pk_f32_fp4 v[234:235], v34, 1.0 op_sel:[1,0,0]
	v_cvt_scalef32_pk_f32_fp4 v[236:237], v34, 1.0 op_sel:[0,1,0]
	v_cvt_scalef32_pk_f32_fp4 v[238:239], v34, 1.0 op_sel:[1,1,0]
	v_pk_fma_f32 v[12:13], v[198:199], s[30:31], v[12:13] op_sel_hi:[1,0,1]
	v_cvt_scalef32_pk_f32_fp4 v[34:35], v35, 1.0 op_sel:[1,1,0]
	v_pk_fma_f32 v[24:25], v[32:33], s[56:57], v[24:25] op_sel_hi:[1,0,1]
	v_readlane_b32 s26, v73, 13
	v_readlane_b32 s27, v73, 14
	v_readlane_b32 s28, v73, 15
	v_pk_fma_f32 v[12:13], v[80:81], s[38:39], v[12:13] op_sel_hi:[1,0,1]
	v_pk_fma_f32 v[24:25], v[34:35], s[60:61], v[24:25] op_sel_hi:[1,0,1]
	s_waitcnt vmcnt(14)
	v_cvt_scalef32_pk_f32_fp4 v[28:29], v10, 1.0
	v_cvt_scalef32_pk_f32_fp4 v[32:33], v10, 1.0 op_sel:[1,0,0]
	v_cvt_scalef32_pk_f32_fp4 v[34:35], v10, 1.0 op_sel:[0,1,0]
	v_cvt_scalef32_pk_f32_fp4 v[36:37], v10, 1.0 op_sel:[1,1,0]
	v_cvt_scalef32_pk_f32_fp4 v[42:43], v11, 1.0
	v_cvt_scalef32_pk_f32_fp4 v[52:53], v11, 1.0 op_sel:[1,0,0]
	v_cvt_scalef32_pk_f32_fp4 v[54:55], v11, 1.0 op_sel:[0,1,0]
	v_cvt_scalef32_pk_f32_fp4 v[56:57], v11, 1.0 op_sel:[1,1,0]
	s_waitcnt vmcnt(13)
	v_cvt_scalef32_pk_f32_fp4 v[10:11], v6, 1.0
	v_cvt_scalef32_pk_f32_fp4 v[80:81], v6, 1.0 op_sel:[1,0,0]
	v_cvt_scalef32_pk_f32_fp4 v[84:85], v6, 1.0 op_sel:[0,1,0]
	v_cvt_scalef32_pk_f32_fp4 v[86:87], v6, 1.0 op_sel:[1,1,0]
	v_cvt_scalef32_pk_f32_fp4 v[88:89], v7, 1.0
	v_cvt_scalef32_pk_f32_fp4 v[90:91], v7, 1.0 op_sel:[1,0,0]
	v_cvt_scalef32_pk_f32_fp4 v[92:93], v7, 1.0 op_sel:[0,1,0]
	v_cvt_scalef32_pk_f32_fp4 v[94:95], v7, 1.0 op_sel:[1,1,0]
	s_waitcnt vmcnt(12)
	v_cvt_scalef32_pk_f32_fp4 v[98:99], v4, 1.0
	v_cvt_scalef32_pk_f32_fp4 v[100:101], v4, 1.0 op_sel:[1,0,0]
	v_cvt_scalef32_pk_f32_fp4 v[102:103], v4, 1.0 op_sel:[0,1,0]
	v_cvt_scalef32_pk_f32_fp4 v[104:105], v4, 1.0 op_sel:[1,1,0]
	v_cvt_scalef32_pk_f32_fp4 v[106:107], v5, 1.0
	v_cvt_scalef32_pk_f32_fp4 v[110:111], v5, 1.0 op_sel:[1,0,0]
	v_cvt_scalef32_pk_f32_fp4 v[112:113], v5, 1.0 op_sel:[0,1,0]
	v_cvt_scalef32_pk_f32_fp4 v[114:115], v5, 1.0 op_sel:[1,1,0]
	buffer_load_dwordx2 v[40:41], v192, s[4:7], s25 offen
	buffer_load_dwordx2 v[30:31], v192, s[4:7], s26 offen
	buffer_load_dwordx2 v[6:7], v192, s[4:7], s27 offen
	buffer_load_dwordx2 v[4:5], v192, s[4:7], s28 offen
	v_pk_fma_f32 v[8:9], v[208:209], s[56:57], v[8:9] op_sel_hi:[1,0,1]
	v_readlane_b32 s20, v2, 13
	v_pk_fma_f32 v[8:9], v[234:235], s[60:61], v[8:9] op_sel_hi:[1,0,1]
	v_readlane_b32 s22, v2, 14
	v_pk_fma_f32 v[22:23], v[28:29], s[20:21], v[22:23] op_sel_hi:[1,0,1]
	v_pk_fma_f32 v[8:9], v[32:33], s[20:21], v[8:9] op_sel_hi:[1,0,1]
	v_readlane_b32 s24, v2, 15
	v_pk_fma_f32 v[10:11], v[10:11], s[22:23], v[22:23] op_sel_hi:[1,0,1]
	v_pk_fma_f32 v[8:9], v[80:81], s[22:23], v[8:9] op_sel_hi:[1,0,1]
	v_readlane_b32 s26, v3, 0
	s_waitcnt vmcnt(15)
	v_cvt_scalef32_pk_f32_fp4 v[128:129], v38, 1.0
	v_cvt_scalef32_pk_f32_fp4 v[130:131], v38, 1.0 op_sel:[1,0,0]
	v_pk_fma_f32 v[10:11], v[98:99], s[24:25], v[10:11] op_sel_hi:[1,0,1]
	v_pk_fma_f32 v[8:9], v[100:101], s[24:25], v[8:9] op_sel_hi:[1,0,1]
	v_readlane_b32 s28, v3, 1
	s_waitcnt vmcnt(12)
	v_cvt_scalef32_pk_f32_fp4 v[142:143], v26, 1.0
	v_cvt_scalef32_pk_f32_fp4 v[144:145], v26, 1.0 op_sel:[1,0,0]
	v_pk_fma_f32 v[10:11], v[128:129], s[26:27], v[10:11] op_sel_hi:[1,0,1]
	v_pk_fma_f32 v[8:9], v[130:131], s[26:27], v[8:9] op_sel_hi:[1,0,1]
	v_cvt_scalef32_pk_f32_fp4 v[146:147], v26, 1.0 op_sel:[0,1,0]
	v_cvt_scalef32_pk_f32_fp4 v[148:149], v26, 1.0 op_sel:[1,1,0]
	v_cvt_scalef32_pk_f32_fp4 v[150:151], v27, 1.0
	v_cvt_scalef32_pk_f32_fp4 v[152:153], v27, 1.0 op_sel:[1,0,0]
	v_cvt_scalef32_pk_f32_fp4 v[154:155], v27, 1.0 op_sel:[0,1,0]
	v_cvt_scalef32_pk_f32_fp4 v[156:157], v27, 1.0 op_sel:[1,1,0]
	v_readlane_b32 s30, v3, 2
	v_cvt_scalef32_pk_f32_fp4 v[26:27], v44, 1.0
	v_cvt_scalef32_pk_f32_fp4 v[158:159], v44, 1.0 op_sel:[1,0,0]
	v_pk_fma_f32 v[10:11], v[142:143], s[28:29], v[10:11] op_sel_hi:[1,0,1]
	v_pk_fma_f32 v[8:9], v[144:145], s[28:29], v[8:9] op_sel_hi:[1,0,1]
	v_readlane_b32 s34, v3, 3
	s_waitcnt vmcnt(11)
	v_cvt_scalef32_pk_f32_fp4 v[170:171], v82, 1.0
	v_cvt_scalef32_pk_f32_fp4 v[172:173], v82, 1.0 op_sel:[1,0,0]
	v_pk_fma_f32 v[10:11], v[26:27], s[30:31], v[10:11] op_sel_hi:[1,0,1]
	v_pk_fma_f32 v[8:9], v[158:159], s[30:31], v[8:9] op_sel_hi:[1,0,1]
	v_readlane_b32 s36, v3, 4
	s_waitcnt vmcnt(10)
	v_cvt_scalef32_pk_f32_fp4 v[184:185], v96, 1.0
	v_cvt_scalef32_pk_f32_fp4 v[186:187], v96, 1.0 op_sel:[1,0,0]
	v_pk_fma_f32 v[10:11], v[170:171], s[34:35], v[10:11] op_sel_hi:[1,0,1]
	v_pk_fma_f32 v[8:9], v[172:173], s[34:35], v[8:9] op_sel_hi:[1,0,1]
	v_readlane_b32 s38, v3, 5
	v_cvt_scalef32_pk_f32_fp4 v[202:203], v108, 1.0
	v_cvt_scalef32_pk_f32_fp4 v[204:205], v108, 1.0 op_sel:[1,0,0]
	v_pk_fma_f32 v[10:11], v[184:185], s[36:37], v[10:11] op_sel_hi:[1,0,1]
	v_pk_fma_f32 v[8:9], v[186:187], s[36:37], v[8:9] op_sel_hi:[1,0,1]
	v_pk_fma_f32 v[12:13], v[210:211], s[56:57], v[12:13] op_sel_hi:[1,0,1]
	v_pk_fma_f32 v[14:15], v[214:215], s[56:57], v[14:15] op_sel_hi:[1,0,1]
	v_readlane_b32 s56, v3, 6
	s_waitcnt vmcnt(9)
	v_cvt_scalef32_pk_f32_fp4 v[228:229], v116, 1.0
	v_cvt_scalef32_pk_f32_fp4 v[230:231], v116, 1.0 op_sel:[1,0,0]
	v_pk_fma_f32 v[10:11], v[202:203], s[38:39], v[10:11] op_sel_hi:[1,0,1]
	v_pk_fma_f32 v[8:9], v[204:205], s[38:39], v[8:9] op_sel_hi:[1,0,1]
	v_pk_fma_f32 v[12:13], v[236:237], s[60:61], v[12:13] op_sel_hi:[1,0,1]
	v_pk_fma_f32 v[14:15], v[238:239], s[60:61], v[14:15] op_sel_hi:[1,0,1]
	v_readlane_b32 s60, v3, 7
	s_waitcnt vmcnt(8)
	v_cvt_scalef32_pk_f32_fp4 v[242:243], v118, 1.0
	v_cvt_scalef32_pk_f32_fp4 v[244:245], v118, 1.0 op_sel:[1,0,0]
	v_pk_fma_f32 v[10:11], v[228:229], s[56:57], v[10:11] op_sel_hi:[1,0,1]
	v_pk_fma_f32 v[8:9], v[230:231], s[56:57], v[8:9] op_sel_hi:[1,0,1]
	v_pk_fma_f32 v[26:27], v[242:243], s[60:61], v[10:11] op_sel_hi:[1,0,1]
	v_pk_fma_f32 v[10:11], v[244:245], s[60:61], v[8:9] op_sel_hi:[1,0,1]
	v_pk_fma_f32 v[8:9], v[34:35], s[20:21], v[12:13] op_sel_hi:[1,0,1]
	v_cvt_scalef32_pk_f32_fp4 v[132:133], v38, 1.0 op_sel:[0,1,0]
	v_pk_fma_f32 v[8:9], v[84:85], s[22:23], v[8:9] op_sel_hi:[1,0,1]
	v_cvt_scalef32_pk_f32_fp4 v[160:161], v44, 1.0 op_sel:[0,1,0]
	v_pk_fma_f32 v[8:9], v[102:103], s[24:25], v[8:9] op_sel_hi:[1,0,1]
	v_cvt_scalef32_pk_f32_fp4 v[174:175], v82, 1.0 op_sel:[0,1,0]
	v_pk_fma_f32 v[8:9], v[132:133], s[26:27], v[8:9] op_sel_hi:[1,0,1]
	v_cvt_scalef32_pk_f32_fp4 v[188:189], v96, 1.0 op_sel:[0,1,0]
	v_pk_fma_f32 v[8:9], v[146:147], s[28:29], v[8:9] op_sel_hi:[1,0,1]
	v_cvt_scalef32_pk_f32_fp4 v[206:207], v108, 1.0 op_sel:[0,1,0]
	v_pk_fma_f32 v[8:9], v[160:161], s[30:31], v[8:9] op_sel_hi:[1,0,1]
	v_cvt_scalef32_pk_f32_fp4 v[232:233], v116, 1.0 op_sel:[0,1,0]
	v_pk_fma_f32 v[8:9], v[174:175], s[34:35], v[8:9] op_sel_hi:[1,0,1]
	v_cvt_scalef32_pk_f32_fp4 v[246:247], v118, 1.0 op_sel:[0,1,0]
	v_pk_fma_f32 v[8:9], v[188:189], s[36:37], v[8:9] op_sel_hi:[1,0,1]
	v_pk_fma_f32 v[16:17], v[42:43], s[20:21], v[16:17] op_sel_hi:[1,0,1]
	v_pk_fma_f32 v[8:9], v[206:207], s[38:39], v[8:9] op_sel_hi:[1,0,1]
	v_cvt_scalef32_pk_f32_fp4 v[134:135], v38, 1.0 op_sel:[1,1,0]
	v_pk_fma_f32 v[8:9], v[232:233], s[56:57], v[8:9] op_sel_hi:[1,0,1]
	v_pk_fma_f32 v[16:17], v[88:89], s[22:23], v[16:17] op_sel_hi:[1,0,1]
	v_pk_fma_f32 v[12:13], v[246:247], s[60:61], v[8:9] op_sel_hi:[1,0,1]
	v_pk_fma_f32 v[8:9], v[36:37], s[20:21], v[14:15] op_sel_hi:[1,0,1]
	v_cvt_scalef32_pk_f32_fp4 v[136:137], v39, 1.0
	v_pk_fma_f32 v[8:9], v[86:87], s[22:23], v[8:9] op_sel_hi:[1,0,1]
	v_pk_fma_f32 v[16:17], v[106:107], s[24:25], v[16:17] op_sel_hi:[1,0,1]
	v_pk_fma_f32 v[8:9], v[104:105], s[24:25], v[8:9] op_sel_hi:[1,0,1]
	v_cvt_scalef32_pk_f32_fp4 v[162:163], v44, 1.0 op_sel:[1,1,0]
	v_pk_fma_f32 v[8:9], v[134:135], s[26:27], v[8:9] op_sel_hi:[1,0,1]
	v_pk_fma_f32 v[16:17], v[136:137], s[26:27], v[16:17] op_sel_hi:[1,0,1]
	v_pk_fma_f32 v[8:9], v[148:149], s[28:29], v[8:9] op_sel_hi:[1,0,1]
	v_cvt_scalef32_pk_f32_fp4 v[164:165], v45, 1.0
	v_cvt_scalef32_pk_f32_fp4 v[176:177], v82, 1.0 op_sel:[1,1,0]
	v_pk_fma_f32 v[8:9], v[162:163], s[30:31], v[8:9] op_sel_hi:[1,0,1]
	v_pk_fma_f32 v[16:17], v[150:151], s[28:29], v[16:17] op_sel_hi:[1,0,1]
	v_cvt_scalef32_pk_f32_fp4 v[178:179], v83, 1.0
	v_cvt_scalef32_pk_f32_fp4 v[190:191], v96, 1.0 op_sel:[1,1,0]
	v_pk_fma_f32 v[8:9], v[176:177], s[34:35], v[8:9] op_sel_hi:[1,0,1]
	v_pk_fma_f32 v[16:17], v[164:165], s[30:31], v[16:17] op_sel_hi:[1,0,1]
	v_cvt_scalef32_pk_f32_fp4 v[196:197], v97, 1.0
	v_cvt_scalef32_pk_f32_fp4 v[208:209], v108, 1.0 op_sel:[1,1,0]
	v_pk_fma_f32 v[8:9], v[190:191], s[36:37], v[8:9] op_sel_hi:[1,0,1]
	v_pk_fma_f32 v[16:17], v[178:179], s[34:35], v[16:17] op_sel_hi:[1,0,1]
	v_cvt_scalef32_pk_f32_fp4 v[210:211], v109, 1.0
	v_cvt_scalef32_pk_f32_fp4 v[234:235], v116, 1.0 op_sel:[1,1,0]
	v_pk_fma_f32 v[8:9], v[208:209], s[38:39], v[8:9] op_sel_hi:[1,0,1]
	v_pk_fma_f32 v[16:17], v[196:197], s[36:37], v[16:17] op_sel_hi:[1,0,1]
	v_cvt_scalef32_pk_f32_fp4 v[236:237], v117, 1.0
	v_cvt_scalef32_pk_f32_fp4 v[248:249], v118, 1.0 op_sel:[1,1,0]
	v_pk_fma_f32 v[8:9], v[234:235], s[56:57], v[8:9] op_sel_hi:[1,0,1]
	v_pk_fma_f32 v[16:17], v[210:211], s[38:39], v[16:17] op_sel_hi:[1,0,1]
	v_pk_fma_f32 v[14:15], v[248:249], s[60:61], v[8:9] op_sel_hi:[1,0,1]
	v_cvt_scalef32_pk_f32_fp4 v[8:9], v119, 1.0
	v_pk_fma_f32 v[16:17], v[236:237], s[56:57], v[16:17] op_sel_hi:[1,0,1]
	v_cvt_scalef32_pk_f32_fp4 v[138:139], v39, 1.0 op_sel:[1,0,0]
	v_pk_fma_f32 v[16:17], v[8:9], s[60:61], v[16:17] op_sel_hi:[1,0,1]
	v_pk_fma_f32 v[8:9], v[52:53], s[20:21], v[18:19] op_sel_hi:[1,0,1]
	v_cvt_scalef32_pk_f32_fp4 v[166:167], v45, 1.0 op_sel:[1,0,0]
	v_pk_fma_f32 v[8:9], v[90:91], s[22:23], v[8:9] op_sel_hi:[1,0,1]
	v_cvt_scalef32_pk_f32_fp4 v[180:181], v83, 1.0 op_sel:[1,0,0]
	v_pk_fma_f32 v[8:9], v[110:111], s[24:25], v[8:9] op_sel_hi:[1,0,1]
	v_cvt_scalef32_pk_f32_fp4 v[198:199], v97, 1.0 op_sel:[1,0,0]
	v_pk_fma_f32 v[8:9], v[138:139], s[26:27], v[8:9] op_sel_hi:[1,0,1]
	v_cvt_scalef32_pk_f32_fp4 v[214:215], v109, 1.0 op_sel:[1,0,0]
	v_pk_fma_f32 v[8:9], v[152:153], s[28:29], v[8:9] op_sel_hi:[1,0,1]
	v_cvt_scalef32_pk_f32_fp4 v[238:239], v117, 1.0 op_sel:[1,0,0]
	v_pk_fma_f32 v[8:9], v[166:167], s[30:31], v[8:9] op_sel_hi:[1,0,1]
	v_cvt_scalef32_pk_f32_fp4 v[22:23], v119, 1.0 op_sel:[1,0,0]
	v_pk_fma_f32 v[8:9], v[180:181], s[34:35], v[8:9] op_sel_hi:[1,0,1]
	v_cvt_scalef32_pk_f32_fp4 v[140:141], v39, 1.0 op_sel:[0,1,0]
	v_pk_fma_f32 v[8:9], v[198:199], s[36:37], v[8:9] op_sel_hi:[1,0,1]
	v_cvt_scalef32_pk_f32_fp4 v[168:169], v45, 1.0 op_sel:[0,1,0]
	v_pk_fma_f32 v[8:9], v[214:215], s[38:39], v[8:9] op_sel_hi:[1,0,1]
	v_cvt_scalef32_pk_f32_fp4 v[182:183], v83, 1.0 op_sel:[0,1,0]
	v_pk_fma_f32 v[8:9], v[238:239], s[56:57], v[8:9] op_sel_hi:[1,0,1]
	v_cvt_scalef32_pk_f32_fp4 v[200:201], v97, 1.0 op_sel:[0,1,0]
	v_pk_fma_f32 v[18:19], v[22:23], s[60:61], v[8:9] op_sel_hi:[1,0,1]
	v_pk_fma_f32 v[8:9], v[54:55], s[20:21], v[20:21] op_sel_hi:[1,0,1]
	v_cvt_scalef32_pk_f32_fp4 v[216:217], v109, 1.0 op_sel:[0,1,0]
	v_pk_fma_f32 v[8:9], v[92:93], s[22:23], v[8:9] op_sel_hi:[1,0,1]
	v_cvt_scalef32_pk_f32_fp4 v[240:241], v117, 1.0 op_sel:[0,1,0]
	v_pk_fma_f32 v[8:9], v[112:113], s[24:25], v[8:9] op_sel_hi:[1,0,1]
	v_cvt_scalef32_pk_f32_fp4 v[28:29], v119, 1.0 op_sel:[0,1,0]
	v_pk_fma_f32 v[8:9], v[140:141], s[26:27], v[8:9] op_sel_hi:[1,0,1]
	v_cvt_scalef32_pk_f32_fp4 v[38:39], v39, 1.0 op_sel:[1,1,0]
	v_pk_fma_f32 v[8:9], v[154:155], s[28:29], v[8:9] op_sel_hi:[1,0,1]
	v_cvt_scalef32_pk_f32_fp4 v[44:45], v45, 1.0 op_sel:[1,1,0]
	v_pk_fma_f32 v[8:9], v[168:169], s[30:31], v[8:9] op_sel_hi:[1,0,1]
	v_cvt_scalef32_pk_f32_fp4 v[82:83], v83, 1.0 op_sel:[1,1,0]
	v_pk_fma_f32 v[8:9], v[182:183], s[34:35], v[8:9] op_sel_hi:[1,0,1]
	v_cvt_scalef32_pk_f32_fp4 v[96:97], v97, 1.0 op_sel:[1,1,0]
	v_pk_fma_f32 v[8:9], v[200:201], s[36:37], v[8:9] op_sel_hi:[1,0,1]
	v_cvt_scalef32_pk_f32_fp4 v[108:109], v109, 1.0 op_sel:[1,1,0]
	v_pk_fma_f32 v[8:9], v[216:217], s[38:39], v[8:9] op_sel_hi:[1,0,1]
	v_cvt_scalef32_pk_f32_fp4 v[116:117], v117, 1.0 op_sel:[1,1,0]
	v_pk_fma_f32 v[8:9], v[240:241], s[56:57], v[8:9] op_sel_hi:[1,0,1]
	v_cvt_scalef32_pk_f32_fp4 v[32:33], v119, 1.0 op_sel:[1,1,0]
	v_pk_fma_f32 v[20:21], v[28:29], s[60:61], v[8:9] op_sel_hi:[1,0,1]
	v_pk_fma_f32 v[8:9], v[56:57], s[20:21], v[24:25] op_sel_hi:[1,0,1]
	v_readlane_b32 s20, v3, 8
	v_pk_fma_f32 v[8:9], v[94:95], s[22:23], v[8:9] op_sel_hi:[1,0,1]
	v_readlane_b32 s22, v3, 9
	v_pk_fma_f32 v[8:9], v[114:115], s[24:25], v[8:9] op_sel_hi:[1,0,1]
	v_readlane_b32 s25, v51, 0
	v_pk_fma_f32 v[8:9], v[38:39], s[26:27], v[8:9] op_sel_hi:[1,0,1]
	v_readlane_b32 s27, v51, 5
	v_pk_fma_f32 v[8:9], v[156:157], s[28:29], v[8:9] op_sel_hi:[1,0,1]
	v_readlane_b32 s29, v51, 6
	s_nop 0
	buffer_load_dwordx2 v[128:129], v192, s[4:7], s25 offen
	v_readlane_b32 s25, v51, 1
	v_pk_fma_f32 v[8:9], v[44:45], s[30:31], v[8:9] op_sel_hi:[1,0,1]
	v_readlane_b32 s31, v51, 7
	s_nop 2
	buffer_load_dwordx2 v[138:139], v192, s[4:7], s25 offen
	v_readlane_b32 s25, v51, 2
	v_pk_fma_f32 v[8:9], v[82:83], s[34:35], v[8:9] op_sel_hi:[1,0,1]
	v_readlane_b32 s24, v3, 10
	v_pk_fma_f32 v[8:9], v[96:97], s[36:37], v[8:9] op_sel_hi:[1,0,1]
	s_nop 1
	buffer_load_dwordx2 v[152:153], v192, s[4:7], s25 offen
	v_readlane_b32 s25, v51, 3
	v_pk_fma_f32 v[8:9], v[108:109], s[38:39], v[8:9] op_sel_hi:[1,0,1]
	v_readlane_b32 s26, v3, 11
	v_pk_fma_f32 v[8:9], v[116:117], s[56:57], v[8:9] op_sel_hi:[1,0,1]
	v_readlane_b32 s28, v3, 12
	s_nop 0
	buffer_load_dwordx2 v[188:189], v192, s[4:7], s25 offen
	v_readlane_b32 s25, v51, 4
	s_nop 3
	s_nop 0
	buffer_load_dwordx2 v[190:191], v192, s[4:7], s25 offen
	buffer_load_dwordx2 v[196:197], v192, s[4:7], s27 offen
	buffer_load_dwordx2 v[198:199], v192, s[4:7], s29 offen
	buffer_load_dwordx2 v[200:201], v192, s[4:7], s31 offen
	v_readlane_b32 s25, v51, 8
	v_readlane_b32 s27, v51, 9
	v_readlane_b32 s29, v51, 10
	v_readlane_b32 s31, v51, 11
	s_nop 1
	buffer_load_dwordx2 v[202:203], v192, s[4:7], s25 offen
	s_nop 1
	buffer_load_dwordx2 v[204:205], v192, s[4:7], s27 offen
	s_nop 1
	buffer_load_dwordx2 v[206:207], v192, s[4:7], s29 offen
	s_nop 1
	buffer_load_dwordx2 v[208:209], v192, s[4:7], s31 offen
	v_readlane_b32 s25, v51, 12
	v_readlane_b32 s27, v51, 13
	v_readlane_b32 s29, v51, 14
	v_readlane_b32 s31, v51, 15
	v_pk_fma_f32 v[22:23], v[32:33], s[60:61], v[8:9] op_sel_hi:[1,0,1]
	v_readlane_b32 s30, v3, 13
	v_readlane_b32 s34, v3, 14
	s_waitcnt vmcnt(13)
	v_cvt_scalef32_pk_f32_fp4 v[156:157], v6, 1.0
	v_cvt_scalef32_pk_f32_fp4 v[158:159], v6, 1.0 op_sel:[1,0,0]
	v_cvt_scalef32_pk_f32_fp4 v[160:161], v6, 1.0 op_sel:[0,1,0]
	v_cvt_scalef32_pk_f32_fp4 v[162:163], v6, 1.0 op_sel:[1,1,0]
	v_cvt_scalef32_pk_f32_fp4 v[164:165], v7, 1.0
	v_cvt_scalef32_pk_f32_fp4 v[166:167], v7, 1.0 op_sel:[1,0,0]
	v_cvt_scalef32_pk_f32_fp4 v[168:169], v7, 1.0 op_sel:[0,1,0]
	v_cvt_scalef32_pk_f32_fp4 v[170:171], v7, 1.0 op_sel:[1,1,0]
	v_readlane_b32 s36, v3, 15
	s_waitcnt vmcnt(12)
	v_cvt_scalef32_pk_f32_fp4 v[172:173], v4, 1.0
	v_cvt_scalef32_pk_f32_fp4 v[174:175], v4, 1.0 op_sel:[1,0,0]
	v_cvt_scalef32_pk_f32_fp4 v[176:177], v4, 1.0 op_sel:[0,1,0]
	v_cvt_scalef32_pk_f32_fp4 v[178:179], v4, 1.0 op_sel:[1,1,0]
	v_cvt_scalef32_pk_f32_fp4 v[180:181], v5, 1.0
	v_cvt_scalef32_pk_f32_fp4 v[182:183], v5, 1.0 op_sel:[1,0,0]
	v_cvt_scalef32_pk_f32_fp4 v[184:185], v5, 1.0 op_sel:[0,1,0]
	v_cvt_scalef32_pk_f32_fp4 v[186:187], v5, 1.0 op_sel:[1,1,0]
	ds_read2_b32 v[2:3], v47 offset0:32 offset1:48
	buffer_load_dwordx2 v[210:211], v192, s[4:7], s25 offen
	buffer_load_dwordx2 v[8:9], v192, s[4:7], s27 offen
	buffer_load_dwordx2 v[6:7], v192, s[4:7], s29 offen
	buffer_load_dwordx2 v[4:5], v192, s[4:7], s31 offen
	v_cvt_scalef32_pk_f32_fp4 v[32:33], v121, 1.0 op_sel:[0,1,0]
	v_cvt_scalef32_pk_f32_fp4 v[36:37], v123, 1.0 op_sel:[0,1,0]
	v_pk_fma_f32 v[20:21], v[32:33], s[20:21], v[20:21] op_sel_hi:[1,0,1]
	v_cvt_scalef32_pk_f32_fp4 v[82:83], v121, 1.0
	v_cvt_scalef32_pk_f32_fp4 v[44:45], v125, 1.0 op_sel:[0,1,0]
	v_pk_fma_f32 v[20:21], v[36:37], s[22:23], v[20:21] op_sel_hi:[1,0,1]
	v_cvt_scalef32_pk_f32_fp4 v[52:53], v120, 1.0
	v_cvt_scalef32_pk_f32_fp4 v[54:55], v120, 1.0 op_sel:[1,0,0]
	v_cvt_scalef32_pk_f32_fp4 v[56:57], v120, 1.0 op_sel:[0,1,0]
	v_cvt_scalef32_pk_f32_fp4 v[80:81], v120, 1.0 op_sel:[1,1,0]
	v_cvt_scalef32_pk_f32_fp4 v[38:39], v121, 1.0 op_sel:[1,0,0]
	v_cvt_scalef32_pk_f32_fp4 v[24:25], v121, 1.0 op_sel:[1,1,0]
	v_cvt_scalef32_pk_f32_fp4 v[92:93], v123, 1.0
	v_cvt_scalef32_pk_f32_fp4 v[120:121], v127, 1.0 op_sel:[0,1,0]
	v_pk_fma_f32 v[16:17], v[82:83], s[20:21], v[16:17] op_sel_hi:[1,0,1]
	v_pk_fma_f32 v[20:21], v[44:45], s[24:25], v[20:21] op_sel_hi:[1,0,1]
	v_cvt_scalef32_pk_f32_fp4 v[94:95], v123, 1.0 op_sel:[1,0,0]
	v_cvt_scalef32_pk_f32_fp4 v[104:105], v125, 1.0
	v_cvt_scalef32_pk_f32_fp4 v[136:137], v41, 1.0 op_sel:[0,1,0]
	v_pk_fma_f32 v[16:17], v[92:93], s[22:23], v[16:17] op_sel_hi:[1,0,1]
	v_pk_fma_f32 v[18:19], v[38:39], s[20:21], v[18:19] op_sel_hi:[1,0,1]
	v_pk_fma_f32 v[20:21], v[120:121], s[26:27], v[20:21] op_sel_hi:[1,0,1]
	v_cvt_scalef32_pk_f32_fp4 v[106:107], v125, 1.0 op_sel:[1,0,0]
	v_cvt_scalef32_pk_f32_fp4 v[116:117], v127, 1.0
	v_cvt_scalef32_pk_f32_fp4 v[154:155], v31, 1.0 op_sel:[0,1,0]
	v_pk_fma_f32 v[16:17], v[104:105], s[24:25], v[16:17] op_sel_hi:[1,0,1]
	v_pk_fma_f32 v[18:19], v[94:95], s[22:23], v[18:19] op_sel_hi:[1,0,1]
	v_pk_fma_f32 v[20:21], v[136:137], s[28:29], v[20:21] op_sel_hi:[1,0,1]
	v_cvt_scalef32_pk_f32_fp4 v[118:119], v127, 1.0 op_sel:[1,0,0]
	v_cvt_scalef32_pk_f32_fp4 v[132:133], v41, 1.0
	v_pk_fma_f32 v[16:17], v[116:117], s[26:27], v[16:17] op_sel_hi:[1,0,1]
	v_pk_fma_f32 v[18:19], v[106:107], s[24:25], v[18:19] op_sel_hi:[1,0,1]
	v_pk_fma_f32 v[20:21], v[154:155], s[30:31], v[20:21] op_sel_hi:[1,0,1]
	v_cvt_scalef32_pk_f32_fp4 v[134:135], v41, 1.0 op_sel:[1,0,0]
	v_cvt_scalef32_pk_f32_fp4 v[148:149], v31, 1.0
	v_pk_fma_f32 v[16:17], v[132:133], s[28:29], v[16:17] op_sel_hi:[1,0,1]
	v_pk_fma_f32 v[18:19], v[118:119], s[26:27], v[18:19] op_sel_hi:[1,0,1]
	v_pk_fma_f32 v[20:21], v[168:169], s[34:35], v[20:21] op_sel_hi:[1,0,1]
	v_cvt_scalef32_pk_f32_fp4 v[150:151], v31, 1.0 op_sel:[1,0,0]
	s_waitcnt lgkmcnt(0)
	v_readlane_b32 s38, v2, 0
	s_waitcnt vmcnt(15)
	v_cvt_scalef32_pk_f32_fp4 v[236:237], v129, 1.0 op_sel:[0,1,0]
	v_pk_fma_f32 v[16:17], v[148:149], s[30:31], v[16:17] op_sel_hi:[1,0,1]
	v_pk_fma_f32 v[18:19], v[134:135], s[28:29], v[18:19] op_sel_hi:[1,0,1]
	v_pk_fma_f32 v[20:21], v[184:185], s[36:37], v[20:21] op_sel_hi:[1,0,1]
	v_readlane_b32 s56, v2, 1
	v_pk_fma_f32 v[26:27], v[52:53], s[20:21], v[26:27] op_sel_hi:[1,0,1]
	s_waitcnt vmcnt(14)
	v_cvt_scalef32_pk_f32_fp4 v[52:53], v139, 1.0 op_sel:[0,1,0]
	v_pk_fma_f32 v[16:17], v[164:165], s[34:35], v[16:17] op_sel_hi:[1,0,1]
	v_pk_fma_f32 v[18:19], v[150:151], s[30:31], v[18:19] op_sel_hi:[1,0,1]
	v_pk_fma_f32 v[20:21], v[236:237], s[38:39], v[20:21] op_sel_hi:[1,0,1]
	v_cvt_scalef32_pk_f32_fp4 v[84:85], v122, 1.0
	v_cvt_scalef32_pk_f32_fp4 v[232:233], v129, 1.0
	v_readlane_b32 s60, v2, 2
	v_pk_fma_f32 v[14:15], v[80:81], s[20:21], v[14:15] op_sel_hi:[1,0,1]
	s_waitcnt vmcnt(13)
	v_cvt_scalef32_pk_f32_fp4 v[80:81], v153, 1.0 op_sel:[0,1,0]
	v_pk_fma_f32 v[16:17], v[180:181], s[36:37], v[16:17] op_sel_hi:[1,0,1]
	v_pk_fma_f32 v[18:19], v[166:167], s[34:35], v[18:19] op_sel_hi:[1,0,1]
	v_pk_fma_f32 v[20:21], v[52:53], s[56:57], v[20:21] op_sel_hi:[1,0,1]
	v_cvt_scalef32_pk_f32_fp4 v[28:29], v123, 1.0 op_sel:[1,1,0]
	v_cvt_scalef32_pk_f32_fp4 v[96:97], v124, 1.0
	v_cvt_scalef32_pk_f32_fp4 v[234:235], v129, 1.0 op_sel:[1,0,0]
	v_cvt_scalef32_pk_f32_fp4 v[246:247], v139, 1.0
	v_pk_fma_f32 v[26:27], v[84:85], s[22:23], v[26:27] op_sel_hi:[1,0,1]
	v_pk_fma_f32 v[16:17], v[232:233], s[38:39], v[16:17] op_sel_hi:[1,0,1]
	v_pk_fma_f32 v[18:19], v[182:183], s[36:37], v[18:19] op_sel_hi:[1,0,1]
	v_pk_fma_f32 v[32:33], v[80:81], s[60:61], v[20:21] op_sel_hi:[1,0,1]
	v_pk_fma_f32 v[20:21], v[24:25], s[20:21], v[22:23] op_sel_hi:[1,0,1]
	v_cvt_scalef32_pk_f32_fp4 v[86:87], v122, 1.0 op_sel:[1,0,0]
	v_cvt_scalef32_pk_f32_fp4 v[34:35], v125, 1.0 op_sel:[1,1,0]
	v_cvt_scalef32_pk_f32_fp4 v[108:109], v126, 1.0
	v_cvt_scalef32_pk_f32_fp4 v[248:249], v139, 1.0 op_sel:[1,0,0]
	v_pk_fma_f32 v[26:27], v[96:97], s[24:25], v[26:27] op_sel_hi:[1,0,1]
	v_pk_fma_f32 v[10:11], v[54:55], s[20:21], v[10:11] op_sel_hi:[1,0,1]
	v_cvt_scalef32_pk_f32_fp4 v[54:55], v153, 1.0
	v_pk_fma_f32 v[16:17], v[246:247], s[56:57], v[16:17] op_sel_hi:[1,0,1]
	v_pk_fma_f32 v[18:19], v[234:235], s[38:39], v[18:19] op_sel_hi:[1,0,1]
	v_pk_fma_f32 v[20:21], v[28:29], s[22:23], v[20:21] op_sel_hi:[1,0,1]
	v_cvt_scalef32_pk_f32_fp4 v[88:89], v122, 1.0 op_sel:[0,1,0]
	v_cvt_scalef32_pk_f32_fp4 v[90:91], v122, 1.0 op_sel:[1,1,0]
	v_cvt_scalef32_pk_f32_fp4 v[98:99], v124, 1.0 op_sel:[1,0,0]
	v_cvt_scalef32_pk_f32_fp4 v[42:43], v127, 1.0 op_sel:[1,1,0]
	v_cvt_scalef32_pk_f32_fp4 v[122:123], v40, 1.0
	v_pk_fma_f32 v[26:27], v[108:109], s[26:27], v[26:27] op_sel_hi:[1,0,1]
	v_pk_fma_f32 v[10:11], v[86:87], s[22:23], v[10:11] op_sel_hi:[1,0,1]
	v_pk_fma_f32 v[12:13], v[56:57], s[20:21], v[12:13] op_sel_hi:[1,0,1]
	v_cvt_scalef32_pk_f32_fp4 v[56:57], v153, 1.0 op_sel:[1,0,0]
	v_pk_fma_f32 v[16:17], v[54:55], s[60:61], v[16:17] op_sel_hi:[1,0,1]
	v_pk_fma_f32 v[18:19], v[248:249], s[56:57], v[18:19] op_sel_hi:[1,0,1]
	v_pk_fma_f32 v[20:21], v[34:35], s[24:25], v[20:21] op_sel_hi:[1,0,1]
	v_readlane_b32 s20, v2, 3
	s_waitcnt vmcnt(12)
	v_cvt_scalef32_pk_f32_fp4 v[34:35], v189, 1.0
	v_cvt_scalef32_pk_f32_fp4 v[100:101], v124, 1.0 op_sel:[0,1,0]
	v_cvt_scalef32_pk_f32_fp4 v[102:103], v124, 1.0 op_sel:[1,1,0]
	v_cvt_scalef32_pk_f32_fp4 v[110:111], v126, 1.0 op_sel:[1,0,0]
	v_cvt_scalef32_pk_f32_fp4 v[112:113], v126, 1.0 op_sel:[0,1,0]
	v_cvt_scalef32_pk_f32_fp4 v[114:115], v126, 1.0 op_sel:[1,1,0]
	v_cvt_scalef32_pk_f32_fp4 v[124:125], v40, 1.0 op_sel:[1,0,0]
	v_cvt_scalef32_pk_f32_fp4 v[126:127], v40, 1.0 op_sel:[0,1,0]
	v_cvt_scalef32_pk_f32_fp4 v[130:131], v40, 1.0 op_sel:[1,1,0]
	v_cvt_scalef32_pk_f32_fp4 v[40:41], v41, 1.0 op_sel:[1,1,0]
	v_cvt_scalef32_pk_f32_fp4 v[140:141], v30, 1.0
	v_pk_fma_f32 v[26:27], v[122:123], s[28:29], v[26:27] op_sel_hi:[1,0,1]
	v_pk_fma_f32 v[10:11], v[98:99], s[24:25], v[10:11] op_sel_hi:[1,0,1]
	v_pk_fma_f32 v[12:13], v[88:89], s[22:23], v[12:13] op_sel_hi:[1,0,1]
	v_pk_fma_f32 v[14:15], v[90:91], s[22:23], v[14:15] op_sel_hi:[1,0,1]
	v_pk_fma_f32 v[18:19], v[56:57], s[60:61], v[18:19] op_sel_hi:[1,0,1]
	v_pk_fma_f32 v[20:21], v[42:43], s[26:27], v[20:21] op_sel_hi:[1,0,1]
	v_readlane_b32 s22, v2, 4
	s_waitcnt vmcnt(11)
	v_cvt_scalef32_pk_f32_fp4 v[56:57], v191, 1.0
	v_pk_fma_f32 v[16:17], v[34:35], s[20:21], v[16:17] op_sel_hi:[1,0,1]
	v_cvt_scalef32_pk_f32_fp4 v[142:143], v30, 1.0 op_sel:[1,0,0]
	v_cvt_scalef32_pk_f32_fp4 v[144:145], v30, 1.0 op_sel:[0,1,0]
	v_cvt_scalef32_pk_f32_fp4 v[146:147], v30, 1.0 op_sel:[1,1,0]
	v_cvt_scalef32_pk_f32_fp4 v[30:31], v31, 1.0 op_sel:[1,1,0]
	v_pk_fma_f32 v[26:27], v[140:141], s[30:31], v[26:27] op_sel_hi:[1,0,1]
	v_pk_fma_f32 v[10:11], v[110:111], s[26:27], v[10:11] op_sel_hi:[1,0,1]
	v_pk_fma_f32 v[12:13], v[100:101], s[24:25], v[12:13] op_sel_hi:[1,0,1]
	v_pk_fma_f32 v[14:15], v[102:103], s[24:25], v[14:15] op_sel_hi:[1,0,1]
	v_pk_fma_f32 v[20:21], v[40:41], s[28:29], v[20:21] op_sel_hi:[1,0,1]
	v_readlane_b32 s24, v2, 5
	s_waitcnt vmcnt(10)
	v_cvt_scalef32_pk_f32_fp4 v[94:95], v197, 1.0
	v_pk_fma_f32 v[16:17], v[56:57], s[22:23], v[16:17] op_sel_hi:[1,0,1]
	v_pk_fma_f32 v[26:27], v[156:157], s[34:35], v[26:27] op_sel_hi:[1,0,1]
	v_pk_fma_f32 v[10:11], v[124:125], s[28:29], v[10:11] op_sel_hi:[1,0,1]
	v_pk_fma_f32 v[12:13], v[112:113], s[26:27], v[12:13] op_sel_hi:[1,0,1]
	v_pk_fma_f32 v[14:15], v[114:115], s[26:27], v[14:15] op_sel_hi:[1,0,1]
	v_pk_fma_f32 v[20:21], v[30:31], s[30:31], v[20:21] op_sel_hi:[1,0,1]
	v_readlane_b32 s26, v2, 6
	s_waitcnt vmcnt(9)
	v_cvt_scalef32_pk_f32_fp4 v[110:111], v199, 1.0
	v_pk_fma_f32 v[16:17], v[94:95], s[24:25], v[16:17] op_sel_hi:[1,0,1]
	v_cvt_scalef32_pk_f32_fp4 v[214:215], v128, 1.0
	v_pk_fma_f32 v[26:27], v[172:173], s[36:37], v[26:27] op_sel_hi:[1,0,1]
	v_pk_fma_f32 v[10:11], v[142:143], s[30:31], v[10:11] op_sel_hi:[1,0,1]
	v_pk_fma_f32 v[12:13], v[126:127], s[28:29], v[12:13] op_sel_hi:[1,0,1]
	v_pk_fma_f32 v[14:15], v[130:131], s[28:29], v[14:15] op_sel_hi:[1,0,1]
	v_pk_fma_f32 v[20:21], v[170:171], s[34:35], v[20:21] op_sel_hi:[1,0,1]
	v_readlane_b32 s28, v2, 7
	s_waitcnt vmcnt(8)
	v_cvt_scalef32_pk_f32_fp4 v[126:127], v201, 1.0
	v_pk_fma_f32 v[16:17], v[110:111], s[26:27], v[16:17] op_sel_hi:[1,0,1]
	v_cvt_scalef32_pk_f32_fp4 v[216:217], v128, 1.0 op_sel:[1,0,0]
	v_cvt_scalef32_pk_f32_fp4 v[228:229], v128, 1.0 op_sel:[0,1,0]
	v_cvt_scalef32_pk_f32_fp4 v[230:231], v128, 1.0 op_sel:[1,1,0]
	v_cvt_scalef32_pk_f32_fp4 v[128:129], v129, 1.0 op_sel:[1,1,0]
	v_cvt_scalef32_pk_f32_fp4 v[238:239], v138, 1.0
	v_pk_fma_f32 v[26:27], v[214:215], s[38:39], v[26:27] op_sel_hi:[1,0,1]
	v_pk_fma_f32 v[10:11], v[158:159], s[34:35], v[10:11] op_sel_hi:[1,0,1]
	v_pk_fma_f32 v[12:13], v[144:145], s[30:31], v[12:13] op_sel_hi:[1,0,1]
	v_pk_fma_f32 v[14:15], v[146:147], s[30:31], v[14:15] op_sel_hi:[1,0,1]
	v_pk_fma_f32 v[20:21], v[186:187], s[36:37], v[20:21] op_sel_hi:[1,0,1]
	v_readlane_b32 s30, v2, 8
	s_waitcnt vmcnt(7)
	v_cvt_scalef32_pk_f32_fp4 v[142:143], v203, 1.0
	v_pk_fma_f32 v[16:17], v[126:127], s[28:29], v[16:17] op_sel_hi:[1,0,1]
	v_cvt_scalef32_pk_f32_fp4 v[240:241], v138, 1.0 op_sel:[1,0,0]
	v_cvt_scalef32_pk_f32_fp4 v[242:243], v138, 1.0 op_sel:[0,1,0]
	v_cvt_scalef32_pk_f32_fp4 v[244:245], v138, 1.0 op_sel:[1,1,0]
	v_cvt_scalef32_pk_f32_fp4 v[138:139], v139, 1.0 op_sel:[1,1,0]
	v_cvt_scalef32_pk_f32_fp4 v[84:85], v152, 1.0
	v_pk_fma_f32 v[26:27], v[238:239], s[56:57], v[26:27] op_sel_hi:[1,0,1]
	v_pk_fma_f32 v[10:11], v[174:175], s[36:37], v[10:11] op_sel_hi:[1,0,1]
	v_pk_fma_f32 v[12:13], v[160:161], s[34:35], v[12:13] op_sel_hi:[1,0,1]
	v_pk_fma_f32 v[14:15], v[162:163], s[34:35], v[14:15] op_sel_hi:[1,0,1]
	v_pk_fma_f32 v[20:21], v[128:129], s[38:39], v[20:21] op_sel_hi:[1,0,1]
	v_readlane_b32 s34, v2, 9
	s_waitcnt vmcnt(6)
	v_cvt_scalef32_pk_f32_fp4 v[158:159], v205, 1.0
	v_pk_fma_f32 v[16:17], v[142:143], s[30:31], v[16:17] op_sel_hi:[1,0,1]
	v_pk_fma_f32 v[26:27], v[84:85], s[60:61], v[26:27] op_sel_hi:[1,0,1]
	v_pk_fma_f32 v[10:11], v[216:217], s[38:39], v[10:11] op_sel_hi:[1,0,1]
	v_pk_fma_f32 v[12:13], v[176:177], s[36:37], v[12:13] op_sel_hi:[1,0,1]
	v_pk_fma_f32 v[14:15], v[178:179], s[36:37], v[14:15] op_sel_hi:[1,0,1]
	v_cvt_scalef32_pk_f32_fp4 v[84:85], v153, 1.0 op_sel:[1,1,0]
	v_pk_fma_f32 v[20:21], v[138:139], s[56:57], v[20:21] op_sel_hi:[1,0,1]
	v_readlane_b32 s36, v2, 10
	s_waitcnt vmcnt(5)
	v_cvt_scalef32_pk_f32_fp4 v[174:175], v207, 1.0
	v_pk_fma_f32 v[16:17], v[158:159], s[34:35], v[16:17] op_sel_hi:[1,0,1]
	v_cvt_scalef32_pk_f32_fp4 v[96:97], v152, 1.0 op_sel:[1,0,0]
	v_pk_fma_f32 v[10:11], v[240:241], s[56:57], v[10:11] op_sel_hi:[1,0,1]
	v_pk_fma_f32 v[12:13], v[228:229], s[38:39], v[12:13] op_sel_hi:[1,0,1]
	v_pk_fma_f32 v[14:15], v[230:231], s[38:39], v[14:15] op_sel_hi:[1,0,1]
	v_pk_fma_f32 v[22:23], v[84:85], s[60:61], v[20:21] op_sel_hi:[1,0,1]
	v_cvt_scalef32_pk_f32_fp4 v[42:43], v190, 1.0
	v_cvt_scalef32_pk_f32_fp4 v[44:45], v190, 1.0 op_sel:[1,0,0]
	v_cvt_scalef32_pk_f32_fp4 v[52:53], v190, 1.0 op_sel:[0,1,0]
	v_cvt_scalef32_pk_f32_fp4 v[54:55], v190, 1.0 op_sel:[1,1,0]
	v_cvt_scalef32_pk_f32_fp4 v[80:81], v191, 1.0 op_sel:[1,0,0]
	v_cvt_scalef32_pk_f32_fp4 v[82:83], v191, 1.0 op_sel:[0,1,0]
	v_cvt_scalef32_pk_f32_fp4 v[84:85], v191, 1.0 op_sel:[1,1,0]
	v_readlane_b32 s38, v2, 11
	s_waitcnt vmcnt(4)
	v_cvt_scalef32_pk_f32_fp4 v[190:191], v209, 1.0
	v_pk_fma_f32 v[16:17], v[174:175], s[36:37], v[16:17] op_sel_hi:[1,0,1]
	v_cvt_scalef32_pk_f32_fp4 v[108:109], v152, 1.0 op_sel:[0,1,0]
	v_cvt_scalef32_pk_f32_fp4 v[122:123], v152, 1.0 op_sel:[1,1,0]
	v_pk_fma_f32 v[10:11], v[96:97], s[60:61], v[10:11] op_sel_hi:[1,0,1]
	v_pk_fma_f32 v[12:13], v[242:243], s[56:57], v[12:13] op_sel_hi:[1,0,1]
	v_pk_fma_f32 v[14:15], v[244:245], s[56:57], v[14:15] op_sel_hi:[1,0,1]
	v_cvt_scalef32_pk_f32_fp4 v[24:25], v188, 1.0 op_sel:[1,0,0]
	v_readlane_b32 s56, v2, 12
	s_waitcnt vmcnt(3)
	v_cvt_scalef32_pk_f32_fp4 v[214:215], v211, 1.0
	v_pk_fma_f32 v[16:17], v[190:191], s[38:39], v[16:17] op_sel_hi:[1,0,1]
	v_pk_fma_f32 v[12:13], v[108:109], s[60:61], v[12:13] op_sel_hi:[1,0,1]
	v_pk_fma_f32 v[14:15], v[122:123], s[60:61], v[14:15] op_sel_hi:[1,0,1]
	v_cvt_scalef32_pk_f32_fp4 v[38:39], v189, 1.0 op_sel:[0,1,0]
	v_readlane_b32 s60, v2, 13
	v_pk_fma_f32 v[10:11], v[24:25], s[20:21], v[10:11] op_sel_hi:[1,0,1]
	s_waitcnt vmcnt(2)
	v_cvt_scalef32_pk_f32_fp4 v[24:25], v9, 1.0
	v_pk_fma_f32 v[16:17], v[214:215], s[56:57], v[16:17] op_sel_hi:[1,0,1]
	v_cvt_scalef32_pk_f32_fp4 v[98:99], v197, 1.0 op_sel:[0,1,0]
	v_pk_fma_f32 v[16:17], v[24:25], s[60:61], v[16:17] op_sel_hi:[1,0,1]
	v_pk_fma_f32 v[24:25], v[38:39], s[20:21], v[32:33] op_sel_hi:[1,0,1]
	v_cvt_scalef32_pk_f32_fp4 v[114:115], v199, 1.0 op_sel:[0,1,0]
	v_pk_fma_f32 v[24:25], v[82:83], s[22:23], v[24:25] op_sel_hi:[1,0,1]
	v_cvt_scalef32_pk_f32_fp4 v[20:21], v188, 1.0
	v_pk_fma_f32 v[24:25], v[98:99], s[24:25], v[24:25] op_sel_hi:[1,0,1]
	v_cvt_scalef32_pk_f32_fp4 v[28:29], v188, 1.0 op_sel:[0,1,0]
	v_cvt_scalef32_pk_f32_fp4 v[30:31], v188, 1.0 op_sel:[1,1,0]
	v_cvt_scalef32_pk_f32_fp4 v[36:37], v189, 1.0 op_sel:[1,0,0]
	v_cvt_scalef32_pk_f32_fp4 v[130:131], v201, 1.0 op_sel:[0,1,0]
	v_pk_fma_f32 v[24:25], v[114:115], s[26:27], v[24:25] op_sel_hi:[1,0,1]
	v_cvt_scalef32_pk_f32_fp4 v[146:147], v203, 1.0 op_sel:[0,1,0]
	v_pk_fma_f32 v[20:21], v[20:21], s[20:21], v[26:27] op_sel_hi:[1,0,1]
	v_pk_fma_f32 v[12:13], v[28:29], s[20:21], v[12:13] op_sel_hi:[1,0,1]
	v_pk_fma_f32 v[14:15], v[30:31], s[20:21], v[14:15] op_sel_hi:[1,0,1]
	v_pk_fma_f32 v[18:19], v[36:37], s[20:21], v[18:19] op_sel_hi:[1,0,1]
	v_pk_fma_f32 v[24:25], v[130:131], s[28:29], v[24:25] op_sel_hi:[1,0,1]
	v_cvt_scalef32_pk_f32_fp4 v[40:41], v189, 1.0 op_sel:[1,1,0]
	v_cvt_scalef32_pk_f32_fp4 v[86:87], v196, 1.0
	v_cvt_scalef32_pk_f32_fp4 v[88:89], v196, 1.0 op_sel:[1,0,0]
	v_cvt_scalef32_pk_f32_fp4 v[90:91], v196, 1.0 op_sel:[0,1,0]
	v_cvt_scalef32_pk_f32_fp4 v[92:93], v196, 1.0 op_sel:[1,1,0]
	v_cvt_scalef32_pk_f32_fp4 v[96:97], v197, 1.0 op_sel:[1,0,0]
	v_cvt_scalef32_pk_f32_fp4 v[162:163], v205, 1.0 op_sel:[0,1,0]
	v_pk_fma_f32 v[20:21], v[42:43], s[22:23], v[20:21] op_sel_hi:[1,0,1]
	v_pk_fma_f32 v[10:11], v[44:45], s[22:23], v[10:11] op_sel_hi:[1,0,1]
	v_pk_fma_f32 v[12:13], v[52:53], s[22:23], v[12:13] op_sel_hi:[1,0,1]
	v_pk_fma_f32 v[14:15], v[54:55], s[22:23], v[14:15] op_sel_hi:[1,0,1]
	v_pk_fma_f32 v[18:19], v[80:81], s[22:23], v[18:19] op_sel_hi:[1,0,1]
	v_pk_fma_f32 v[24:25], v[146:147], s[30:31], v[24:25] op_sel_hi:[1,0,1]
	v_cvt_scalef32_pk_f32_fp4 v[178:179], v207, 1.0 op_sel:[0,1,0]
	v_pk_fma_f32 v[20:21], v[86:87], s[24:25], v[20:21] op_sel_hi:[1,0,1]
	v_pk_fma_f32 v[10:11], v[88:89], s[24:25], v[10:11] op_sel_hi:[1,0,1]
	v_pk_fma_f32 v[12:13], v[90:91], s[24:25], v[12:13] op_sel_hi:[1,0,1]
	v_pk_fma_f32 v[14:15], v[92:93], s[24:25], v[14:15] op_sel_hi:[1,0,1]
	v_pk_fma_f32 v[18:19], v[96:97], s[24:25], v[18:19] op_sel_hi:[1,0,1]
	v_pk_fma_f32 v[24:25], v[162:163], s[34:35], v[24:25] op_sel_hi:[1,0,1]
	v_readlane_b32 s25, v50, 0
	v_pk_fma_f32 v[22:23], v[40:41], s[20:21], v[22:23] op_sel_hi:[1,0,1]
	v_cvt_scalef32_pk_f32_fp4 v[100:101], v197, 1.0 op_sel:[1,1,0]
	v_cvt_scalef32_pk_f32_fp4 v[102:103], v198, 1.0
	v_cvt_scalef32_pk_f32_fp4 v[104:105], v198, 1.0 op_sel:[1,0,0]
	v_cvt_scalef32_pk_f32_fp4 v[106:107], v198, 1.0 op_sel:[0,1,0]
	v_cvt_scalef32_pk_f32_fp4 v[108:109], v198, 1.0 op_sel:[1,1,0]
	v_cvt_scalef32_pk_f32_fp4 v[112:113], v199, 1.0 op_sel:[1,0,0]
	v_cvt_scalef32_pk_f32_fp4 v[116:117], v199, 1.0 op_sel:[1,1,0]
	v_cvt_scalef32_pk_f32_fp4 v[198:199], v209, 1.0 op_sel:[0,1,0]
	v_pk_fma_f32 v[24:25], v[178:179], s[36:37], v[24:25] op_sel_hi:[1,0,1]
	v_pk_fma_f32 v[22:23], v[84:85], s[22:23], v[22:23] op_sel_hi:[1,0,1]
	v_cvt_scalef32_pk_f32_fp4 v[228:229], v211, 1.0 op_sel:[0,1,0]
	v_pk_fma_f32 v[24:25], v[198:199], s[38:39], v[24:25] op_sel_hi:[1,0,1]
	v_readlane_b32 s20, v50, 1
	v_pk_fma_f32 v[22:23], v[100:101], s[24:25], v[22:23] op_sel_hi:[1,0,1]
	v_readlane_b32 s22, v50, 3
	v_readlane_b32 s24, v50, 5
	v_cvt_scalef32_pk_f32_fp4 v[28:29], v9, 1.0 op_sel:[0,1,0]
	v_pk_fma_f32 v[24:25], v[228:229], s[56:57], v[24:25] op_sel_hi:[1,0,1]
	buffer_load_dwordx2 v[30:31], v192, s[4:7], s25 offen
	v_pk_fma_f32 v[28:29], v[28:29], s[60:61], v[24:25] op_sel_hi:[1,0,1]
	buffer_load_dwordx2 v[24:25], v192, s[4:7], s20 offen
	buffer_load_dwordx2 v[38:39], v192, s[4:7], s22 offen
	buffer_load_dwordx2 v[92:93], v192, s[4:7], s24 offen
	v_readlane_b32 s20, v50, 2
	v_readlane_b32 s22, v50, 4
	v_readlane_b32 s24, v50, 6
	s_nop 2
	buffer_load_dwordx2 v[32:33], v192, s[4:7], s20 offen
	v_pk_fma_f32 v[20:21], v[102:103], s[26:27], v[20:21] op_sel_hi:[1,0,1]
	s_nop 1
	buffer_load_dwordx2 v[80:81], v192, s[4:7], s22 offen
	v_readlane_b32 s25, v50, 7
	s_nop 0
	buffer_load_dwordx2 v[100:101], v192, s[4:7], s24 offen
	s_nop 2
	s_nop 0
	buffer_load_dwordx2 v[102:103], v192, s[4:7], s25 offen
	v_readlane_b32 s24, v50, 8
	v_pk_fma_f32 v[10:11], v[104:105], s[26:27], v[10:11] op_sel_hi:[1,0,1]
	v_pk_fma_f32 v[12:13], v[106:107], s[26:27], v[12:13] op_sel_hi:[1,0,1]
	v_pk_fma_f32 v[14:15], v[108:109], s[26:27], v[14:15] op_sel_hi:[1,0,1]
	v_pk_fma_f32 v[18:19], v[112:113], s[26:27], v[18:19] op_sel_hi:[1,0,1]
	v_pk_fma_f32 v[22:23], v[116:117], s[26:27], v[22:23] op_sel_hi:[1,0,1]
	v_readlane_b32 s25, v50, 9
	v_readlane_b32 s26, v50, 10
	v_readlane_b32 s27, v50, 11
	buffer_load_dwordx2 v[104:105], v192, s[4:7], s24 offen
	s_nop 1
	buffer_load_dwordx2 v[106:107], v192, s[4:7], s25 offen
	s_nop 1
	buffer_load_dwordx2 v[108:109], v192, s[4:7], s26 offen
	s_nop 1
	buffer_load_dwordx2 v[110:111], v192, s[4:7], s27 offen
	v_cvt_scalef32_pk_f32_fp4 v[128:129], v201, 1.0 op_sel:[1,0,0]
	v_cvt_scalef32_pk_f32_fp4 v[132:133], v201, 1.0 op_sel:[1,1,0]
	v_cvt_scalef32_pk_f32_fp4 v[144:145], v203, 1.0 op_sel:[1,0,0]
	v_cvt_scalef32_pk_f32_fp4 v[148:149], v203, 1.0 op_sel:[1,1,0]
	v_pk_fma_f32 v[18:19], v[128:129], s[28:29], v[18:19] op_sel_hi:[1,0,1]
	v_pk_fma_f32 v[22:23], v[132:133], s[28:29], v[22:23] op_sel_hi:[1,0,1]
	v_cvt_scalef32_pk_f32_fp4 v[160:161], v205, 1.0 op_sel:[1,0,0]
	v_cvt_scalef32_pk_f32_fp4 v[164:165], v205, 1.0 op_sel:[1,1,0]
	v_pk_fma_f32 v[18:19], v[144:145], s[30:31], v[18:19] op_sel_hi:[1,0,1]
	v_pk_fma_f32 v[22:23], v[148:149], s[30:31], v[22:23] op_sel_hi:[1,0,1]
	v_cvt_scalef32_pk_f32_fp4 v[176:177], v207, 1.0 op_sel:[1,0,0]
	v_cvt_scalef32_pk_f32_fp4 v[180:181], v207, 1.0 op_sel:[1,1,0]
	v_pk_fma_f32 v[18:19], v[160:161], s[34:35], v[18:19] op_sel_hi:[1,0,1]
	v_pk_fma_f32 v[22:23], v[164:165], s[34:35], v[22:23] op_sel_hi:[1,0,1]
	v_cvt_scalef32_pk_f32_fp4 v[118:119], v200, 1.0
	v_cvt_scalef32_pk_f32_fp4 v[120:121], v200, 1.0 op_sel:[1,0,0]
	v_cvt_scalef32_pk_f32_fp4 v[122:123], v200, 1.0 op_sel:[0,1,0]
	v_cvt_scalef32_pk_f32_fp4 v[124:125], v200, 1.0 op_sel:[1,1,0]
	v_cvt_scalef32_pk_f32_fp4 v[196:197], v209, 1.0 op_sel:[1,0,0]
	v_cvt_scalef32_pk_f32_fp4 v[200:201], v209, 1.0 op_sel:[1,1,0]
	v_pk_fma_f32 v[18:19], v[176:177], s[36:37], v[18:19] op_sel_hi:[1,0,1]
	v_pk_fma_f32 v[22:23], v[180:181], s[36:37], v[22:23] op_sel_hi:[1,0,1]
	v_cvt_scalef32_pk_f32_fp4 v[134:135], v202, 1.0
	v_cvt_scalef32_pk_f32_fp4 v[136:137], v202, 1.0 op_sel:[1,0,0]
	v_cvt_scalef32_pk_f32_fp4 v[138:139], v202, 1.0 op_sel:[0,1,0]
	v_cvt_scalef32_pk_f32_fp4 v[140:141], v202, 1.0 op_sel:[1,1,0]
	v_cvt_scalef32_pk_f32_fp4 v[150:151], v204, 1.0
	v_cvt_scalef32_pk_f32_fp4 v[152:153], v204, 1.0 op_sel:[1,0,0]
	v_cvt_scalef32_pk_f32_fp4 v[154:155], v204, 1.0 op_sel:[0,1,0]
	v_cvt_scalef32_pk_f32_fp4 v[156:157], v204, 1.0 op_sel:[1,1,0]
	v_cvt_scalef32_pk_f32_fp4 v[166:167], v206, 1.0
	v_cvt_scalef32_pk_f32_fp4 v[168:169], v206, 1.0 op_sel:[1,0,0]
	v_cvt_scalef32_pk_f32_fp4 v[170:171], v206, 1.0 op_sel:[0,1,0]
	v_cvt_scalef32_pk_f32_fp4 v[172:173], v206, 1.0 op_sel:[1,1,0]
	v_cvt_scalef32_pk_f32_fp4 v[182:183], v208, 1.0
	v_cvt_scalef32_pk_f32_fp4 v[184:185], v208, 1.0 op_sel:[1,0,0]
	v_cvt_scalef32_pk_f32_fp4 v[186:187], v208, 1.0 op_sel:[0,1,0]
	v_cvt_scalef32_pk_f32_fp4 v[188:189], v208, 1.0 op_sel:[1,1,0]
	v_cvt_scalef32_pk_f32_fp4 v[202:203], v210, 1.0
	v_cvt_scalef32_pk_f32_fp4 v[204:205], v210, 1.0 op_sel:[1,0,0]
	v_cvt_scalef32_pk_f32_fp4 v[206:207], v210, 1.0 op_sel:[0,1,0]
	v_cvt_scalef32_pk_f32_fp4 v[208:209], v210, 1.0 op_sel:[1,1,0]
	v_cvt_scalef32_pk_f32_fp4 v[216:217], v211, 1.0 op_sel:[1,0,0]
	v_cvt_scalef32_pk_f32_fp4 v[210:211], v211, 1.0 op_sel:[1,1,0]
	v_pk_fma_f32 v[18:19], v[196:197], s[38:39], v[18:19] op_sel_hi:[1,0,1]
	v_pk_fma_f32 v[22:23], v[200:201], s[38:39], v[22:23] op_sel_hi:[1,0,1]
	v_readlane_b32 s24, v50, 12
	v_cvt_scalef32_pk_f32_fp4 v[230:231], v8, 1.0
	v_cvt_scalef32_pk_f32_fp4 v[232:233], v8, 1.0 op_sel:[1,0,0]
	v_cvt_scalef32_pk_f32_fp4 v[234:235], v8, 1.0 op_sel:[0,1,0]
	v_cvt_scalef32_pk_f32_fp4 v[236:237], v8, 1.0 op_sel:[1,1,0]
	v_cvt_scalef32_pk_f32_fp4 v[26:27], v9, 1.0 op_sel:[1,0,0]
	v_cvt_scalef32_pk_f32_fp4 v[8:9], v9, 1.0 op_sel:[1,1,0]
	v_pk_fma_f32 v[18:19], v[216:217], s[56:57], v[18:19] op_sel_hi:[1,0,1]
	v_pk_fma_f32 v[22:23], v[210:211], s[56:57], v[22:23] op_sel_hi:[1,0,1]
	v_readlane_b32 s25, v50, 13
	v_readlane_b32 s26, v50, 14
	v_readlane_b32 s27, v50, 15
	v_pk_fma_f32 v[18:19], v[26:27], s[60:61], v[18:19] op_sel_hi:[1,0,1]
	v_pk_fma_f32 v[22:23], v[8:9], s[60:61], v[22:23] op_sel_hi:[1,0,1]
	s_waitcnt vmcnt(13)
	v_cvt_scalef32_pk_f32_fp4 v[8:9], v6, 1.0
	v_cvt_scalef32_pk_f32_fp4 v[36:37], v6, 1.0 op_sel:[1,0,0]
	v_cvt_scalef32_pk_f32_fp4 v[40:41], v6, 1.0 op_sel:[0,1,0]
	v_cvt_scalef32_pk_f32_fp4 v[42:43], v6, 1.0 op_sel:[1,1,0]
	v_cvt_scalef32_pk_f32_fp4 v[44:45], v7, 1.0
	v_cvt_scalef32_pk_f32_fp4 v[52:53], v7, 1.0 op_sel:[1,0,0]
	v_cvt_scalef32_pk_f32_fp4 v[54:55], v7, 1.0 op_sel:[0,1,0]
	v_cvt_scalef32_pk_f32_fp4 v[56:57], v7, 1.0 op_sel:[1,1,0]
	s_waitcnt vmcnt(12)
	v_cvt_scalef32_pk_f32_fp4 v[82:83], v4, 1.0
	v_cvt_scalef32_pk_f32_fp4 v[84:85], v4, 1.0 op_sel:[1,0,0]
	v_cvt_scalef32_pk_f32_fp4 v[86:87], v4, 1.0 op_sel:[0,1,0]
	v_cvt_scalef32_pk_f32_fp4 v[88:89], v4, 1.0 op_sel:[1,1,0]
	v_cvt_scalef32_pk_f32_fp4 v[90:91], v5, 1.0
	v_cvt_scalef32_pk_f32_fp4 v[94:95], v5, 1.0 op_sel:[1,0,0]
	v_cvt_scalef32_pk_f32_fp4 v[96:97], v5, 1.0 op_sel:[0,1,0]
	v_cvt_scalef32_pk_f32_fp4 v[98:99], v5, 1.0 op_sel:[1,1,0]
	buffer_load_dwordx2 v[34:35], v192, s[4:7], s24 offen
	buffer_load_dwordx2 v[26:27], v192, s[4:7], s25 offen
	buffer_load_dwordx2 v[6:7], v192, s[4:7], s26 offen
	buffer_load_dwordx2 v[4:5], v192, s[4:7], s27 offen
	v_pk_fma_f32 v[20:21], v[118:119], s[28:29], v[20:21] op_sel_hi:[1,0,1]
	v_readlane_b32 s20, v2, 14
	v_pk_fma_f32 v[20:21], v[134:135], s[30:31], v[20:21] op_sel_hi:[1,0,1]
	v_readlane_b32 s22, v2, 15
	v_pk_fma_f32 v[20:21], v[150:151], s[34:35], v[20:21] op_sel_hi:[1,0,1]
	v_readlane_b32 s24, v3, 0
	v_pk_fma_f32 v[20:21], v[166:167], s[36:37], v[20:21] op_sel_hi:[1,0,1]
	s_waitcnt vmcnt(15)
	v_cvt_scalef32_pk_f32_fp4 v[50:51], v30, 1.0
	v_pk_fma_f32 v[20:21], v[182:183], s[38:39], v[20:21] op_sel_hi:[1,0,1]
	v_pk_fma_f32 v[16:17], v[44:45], s[20:21], v[16:17] op_sel_hi:[1,0,1]
	v_pk_fma_f32 v[20:21], v[202:203], s[56:57], v[20:21] op_sel_hi:[1,0,1]
	v_pk_fma_f32 v[10:11], v[120:121], s[28:29], v[10:11] op_sel_hi:[1,0,1]
	v_pk_fma_f32 v[20:21], v[230:231], s[60:61], v[20:21] op_sel_hi:[1,0,1]
	v_pk_fma_f32 v[12:13], v[122:123], s[28:29], v[12:13] op_sel_hi:[1,0,1]
	v_pk_fma_f32 v[8:9], v[8:9], s[20:21], v[20:21] op_sel_hi:[1,0,1]
	v_pk_fma_f32 v[14:15], v[124:125], s[28:29], v[14:15] op_sel_hi:[1,0,1]
	v_pk_fma_f32 v[8:9], v[82:83], s[22:23], v[8:9] op_sel_hi:[1,0,1]
	v_cvt_scalef32_pk_f32_fp4 v[118:119], v31, 1.0
	v_readlane_b32 s26, v3, 1
	s_waitcnt vmcnt(14)
	v_cvt_scalef32_pk_f32_fp4 v[124:125], v24, 1.0
	v_pk_fma_f32 v[8:9], v[50:51], s[24:25], v[8:9] op_sel_hi:[1,0,1]
	v_pk_fma_f32 v[16:17], v[90:91], s[22:23], v[16:17] op_sel_hi:[1,0,1]
	v_pk_fma_f32 v[10:11], v[136:137], s[30:31], v[10:11] op_sel_hi:[1,0,1]
	v_pk_fma_f32 v[12:13], v[138:139], s[30:31], v[12:13] op_sel_hi:[1,0,1]
	v_cvt_scalef32_pk_f32_fp4 v[126:127], v24, 1.0 op_sel:[1,0,0]
	v_cvt_scalef32_pk_f32_fp4 v[128:129], v24, 1.0 op_sel:[0,1,0]
	v_cvt_scalef32_pk_f32_fp4 v[130:131], v24, 1.0 op_sel:[1,1,0]
	v_cvt_scalef32_pk_f32_fp4 v[132:133], v25, 1.0
	v_cvt_scalef32_pk_f32_fp4 v[134:135], v25, 1.0 op_sel:[1,0,0]
	v_cvt_scalef32_pk_f32_fp4 v[136:137], v25, 1.0 op_sel:[0,1,0]
	v_cvt_scalef32_pk_f32_fp4 v[138:139], v25, 1.0 op_sel:[1,1,0]
	v_readlane_b32 s28, v3, 2
	s_waitcnt vmcnt(11)
	v_cvt_scalef32_pk_f32_fp4 v[24:25], v32, 1.0
	v_pk_fma_f32 v[8:9], v[124:125], s[26:27], v[8:9] op_sel_hi:[1,0,1]
	v_pk_fma_f32 v[16:17], v[118:119], s[24:25], v[16:17] op_sel_hi:[1,0,1]
	v_pk_fma_f32 v[10:11], v[152:153], s[34:35], v[10:11] op_sel_hi:[1,0,1]
	v_pk_fma_f32 v[14:15], v[140:141], s[30:31], v[14:15] op_sel_hi:[1,0,1]
	v_cvt_scalef32_pk_f32_fp4 v[146:147], v33, 1.0
	v_readlane_b32 s30, v3, 3
	v_cvt_scalef32_pk_f32_fp4 v[152:153], v38, 1.0
	v_pk_fma_f32 v[8:9], v[24:25], s[28:29], v[8:9] op_sel_hi:[1,0,1]
	v_pk_fma_f32 v[16:17], v[132:133], s[26:27], v[16:17] op_sel_hi:[1,0,1]
	v_pk_fma_f32 v[12:13], v[154:155], s[34:35], v[12:13] op_sel_hi:[1,0,1]
	v_pk_fma_f32 v[14:15], v[156:157], s[34:35], v[14:15] op_sel_hi:[1,0,1]
	v_cvt_scalef32_pk_f32_fp4 v[160:161], v39, 1.0
	v_readlane_b32 s34, v3, 4
	s_waitcnt vmcnt(10)
	v_cvt_scalef32_pk_f32_fp4 v[166:167], v80, 1.0
	v_pk_fma_f32 v[8:9], v[152:153], s[30:31], v[8:9] op_sel_hi:[1,0,1]
	v_pk_fma_f32 v[16:17], v[146:147], s[28:29], v[16:17] op_sel_hi:[1,0,1]
	v_pk_fma_f32 v[10:11], v[168:169], s[36:37], v[10:11] op_sel_hi:[1,0,1]
	v_pk_fma_f32 v[12:13], v[170:171], s[36:37], v[12:13] op_sel_hi:[1,0,1]
	v_pk_fma_f32 v[14:15], v[172:173], s[36:37], v[14:15] op_sel_hi:[1,0,1]
	v_cvt_scalef32_pk_f32_fp4 v[174:175], v81, 1.0
	v_readlane_b32 s36, v3, 5
	v_cvt_scalef32_pk_f32_fp4 v[180:181], v92, 1.0
	v_pk_fma_f32 v[8:9], v[166:167], s[34:35], v[8:9] op_sel_hi:[1,0,1]
	v_pk_fma_f32 v[16:17], v[160:161], s[30:31], v[16:17] op_sel_hi:[1,0,1]
	v_pk_fma_f32 v[10:11], v[184:185], s[38:39], v[10:11] op_sel_hi:[1,0,1]
	v_pk_fma_f32 v[12:13], v[186:187], s[38:39], v[12:13] op_sel_hi:[1,0,1]
	v_pk_fma_f32 v[14:15], v[188:189], s[38:39], v[14:15] op_sel_hi:[1,0,1]
	v_cvt_scalef32_pk_f32_fp4 v[188:189], v93, 1.0
	v_readlane_b32 s38, v3, 6
	s_waitcnt vmcnt(9)
	v_cvt_scalef32_pk_f32_fp4 v[198:199], v100, 1.0
	v_pk_fma_f32 v[8:9], v[180:181], s[36:37], v[8:9] op_sel_hi:[1,0,1]
	v_pk_fma_f32 v[16:17], v[174:175], s[34:35], v[16:17] op_sel_hi:[1,0,1]
	v_pk_fma_f32 v[10:11], v[204:205], s[56:57], v[10:11] op_sel_hi:[1,0,1]
	v_pk_fma_f32 v[12:13], v[206:207], s[56:57], v[12:13] op_sel_hi:[1,0,1]
	v_pk_fma_f32 v[14:15], v[208:209], s[56:57], v[14:15] op_sel_hi:[1,0,1]
	v_cvt_scalef32_pk_f32_fp4 v[206:207], v101, 1.0
	v_readlane_b32 s56, v3, 7
	s_waitcnt vmcnt(8)
	v_cvt_scalef32_pk_f32_fp4 v[214:215], v102, 1.0
	v_pk_fma_f32 v[8:9], v[198:199], s[38:39], v[8:9] op_sel_hi:[1,0,1]
	v_pk_fma_f32 v[16:17], v[188:189], s[36:37], v[16:17] op_sel_hi:[1,0,1]
	v_pk_fma_f32 v[10:11], v[232:233], s[60:61], v[10:11] op_sel_hi:[1,0,1]
	v_pk_fma_f32 v[12:13], v[234:235], s[60:61], v[12:13] op_sel_hi:[1,0,1]
	v_pk_fma_f32 v[14:15], v[236:237], s[60:61], v[14:15] op_sel_hi:[1,0,1]
	v_cvt_scalef32_pk_f32_fp4 v[232:233], v103, 1.0
	v_readlane_b32 s60, v3, 8
	s_waitcnt vmcnt(7)
	v_cvt_scalef32_pk_f32_fp4 v[238:239], v104, 1.0
	v_pk_fma_f32 v[8:9], v[214:215], s[56:57], v[8:9] op_sel_hi:[1,0,1]
	v_pk_fma_f32 v[16:17], v[206:207], s[38:39], v[16:17] op_sel_hi:[1,0,1]
	v_pk_fma_f32 v[24:25], v[238:239], s[60:61], v[8:9] op_sel_hi:[1,0,1]
	v_pk_fma_f32 v[8:9], v[36:37], s[20:21], v[10:11] op_sel_hi:[1,0,1]
	v_pk_fma_f32 v[10:11], v[40:41], s[20:21], v[12:13] op_sel_hi:[1,0,1]
	v_pk_fma_f32 v[12:13], v[42:43], s[20:21], v[14:15] op_sel_hi:[1,0,1]
	v_cvt_scalef32_pk_f32_fp4 v[14:15], v105, 1.0
	v_pk_fma_f32 v[16:17], v[232:233], s[56:57], v[16:17] op_sel_hi:[1,0,1]
	v_cvt_scalef32_pk_f32_fp4 v[120:121], v31, 1.0 op_sel:[1,0,0]
	v_pk_fma_f32 v[14:15], v[14:15], s[60:61], v[16:17] op_sel_hi:[1,0,1]
	v_pk_fma_f32 v[16:17], v[52:53], s[20:21], v[18:19] op_sel_hi:[1,0,1]
	v_cvt_scalef32_pk_f32_fp4 v[148:149], v33, 1.0 op_sel:[1,0,0]
	v_pk_fma_f32 v[16:17], v[94:95], s[22:23], v[16:17] op_sel_hi:[1,0,1]
	v_cvt_scalef32_pk_f32_fp4 v[162:163], v39, 1.0 op_sel:[1,0,0]
	v_pk_fma_f32 v[16:17], v[120:121], s[24:25], v[16:17] op_sel_hi:[1,0,1]
	v_cvt_scalef32_pk_f32_fp4 v[176:177], v81, 1.0 op_sel:[1,0,0]
	v_pk_fma_f32 v[16:17], v[134:135], s[26:27], v[16:17] op_sel_hi:[1,0,1]
	v_cvt_scalef32_pk_f32_fp4 v[190:191], v93, 1.0 op_sel:[1,0,0]
	v_pk_fma_f32 v[16:17], v[148:149], s[28:29], v[16:17] op_sel_hi:[1,0,1]
	v_pk_fma_f32 v[18:19], v[54:55], s[20:21], v[28:29] op_sel_hi:[1,0,1]
	v_pk_fma_f32 v[16:17], v[162:163], s[30:31], v[16:17] op_sel_hi:[1,0,1]
	v_cvt_scalef32_pk_f32_fp4 v[122:123], v31, 1.0 op_sel:[0,1,0]
	v_pk_fma_f32 v[16:17], v[176:177], s[34:35], v[16:17] op_sel_hi:[1,0,1]
	v_cvt_scalef32_pk_f32_fp4 v[208:209], v101, 1.0 op_sel:[1,0,0]
	v_pk_fma_f32 v[16:17], v[190:191], s[36:37], v[16:17] op_sel_hi:[1,0,1]
	v_pk_fma_f32 v[18:19], v[96:97], s[22:23], v[18:19] op_sel_hi:[1,0,1]
	v_cvt_scalef32_pk_f32_fp4 v[234:235], v103, 1.0 op_sel:[1,0,0]
	v_pk_fma_f32 v[16:17], v[208:209], s[38:39], v[16:17] op_sel_hi:[1,0,1]
	v_pk_fma_f32 v[18:19], v[122:123], s[24:25], v[18:19] op_sel_hi:[1,0,1]
	v_cvt_scalef32_pk_f32_fp4 v[150:151], v33, 1.0 op_sel:[0,1,0]
	v_cvt_scalef32_pk_f32_fp4 v[20:21], v105, 1.0 op_sel:[1,0,0]
	v_pk_fma_f32 v[16:17], v[234:235], s[56:57], v[16:17] op_sel_hi:[1,0,1]
	v_pk_fma_f32 v[18:19], v[136:137], s[26:27], v[18:19] op_sel_hi:[1,0,1]
	v_cvt_scalef32_pk_f32_fp4 v[164:165], v39, 1.0 op_sel:[0,1,0]
	v_pk_fma_f32 v[16:17], v[20:21], s[60:61], v[16:17] op_sel_hi:[1,0,1]
	v_pk_fma_f32 v[18:19], v[150:151], s[28:29], v[18:19] op_sel_hi:[1,0,1]
	v_pk_fma_f32 v[20:21], v[56:57], s[20:21], v[22:23] op_sel_hi:[1,0,1]
	v_cvt_scalef32_pk_f32_fp4 v[112:113], v30, 1.0 op_sel:[1,0,0]
	v_cvt_scalef32_pk_f32_fp4 v[114:115], v30, 1.0 op_sel:[0,1,0]
	v_cvt_scalef32_pk_f32_fp4 v[116:117], v30, 1.0 op_sel:[1,1,0]
	v_cvt_scalef32_pk_f32_fp4 v[30:31], v31, 1.0 op_sel:[1,1,0]
	v_cvt_scalef32_pk_f32_fp4 v[178:179], v81, 1.0 op_sel:[0,1,0]
	v_pk_fma_f32 v[18:19], v[164:165], s[30:31], v[18:19] op_sel_hi:[1,0,1]
	v_pk_fma_f32 v[20:21], v[98:99], s[22:23], v[20:21] op_sel_hi:[1,0,1]
	v_cvt_scalef32_pk_f32_fp4 v[196:197], v93, 1.0 op_sel:[0,1,0]
	v_pk_fma_f32 v[18:19], v[178:179], s[34:35], v[18:19] op_sel_hi:[1,0,1]
	v_pk_fma_f32 v[20:21], v[30:31], s[24:25], v[20:21] op_sel_hi:[1,0,1]
	v_cvt_scalef32_pk_f32_fp4 v[140:141], v32, 1.0 op_sel:[1,0,0]
	v_cvt_scalef32_pk_f32_fp4 v[142:143], v32, 1.0 op_sel:[0,1,0]
	v_cvt_scalef32_pk_f32_fp4 v[144:145], v32, 1.0 op_sel:[1,1,0]
	v_cvt_scalef32_pk_f32_fp4 v[32:33], v33, 1.0 op_sel:[1,1,0]
	v_cvt_scalef32_pk_f32_fp4 v[210:211], v101, 1.0 op_sel:[0,1,0]
	v_pk_fma_f32 v[8:9], v[84:85], s[22:23], v[8:9] op_sel_hi:[1,0,1]
	v_pk_fma_f32 v[10:11], v[86:87], s[22:23], v[10:11] op_sel_hi:[1,0,1]
	v_pk_fma_f32 v[12:13], v[88:89], s[22:23], v[12:13] op_sel_hi:[1,0,1]
	v_pk_fma_f32 v[18:19], v[196:197], s[36:37], v[18:19] op_sel_hi:[1,0,1]
	v_pk_fma_f32 v[20:21], v[138:139], s[26:27], v[20:21] op_sel_hi:[1,0,1]
	v_cvt_scalef32_pk_f32_fp4 v[154:155], v38, 1.0 op_sel:[1,0,0]
	v_cvt_scalef32_pk_f32_fp4 v[156:157], v38, 1.0 op_sel:[0,1,0]
	v_cvt_scalef32_pk_f32_fp4 v[158:159], v38, 1.0 op_sel:[1,1,0]
	v_cvt_scalef32_pk_f32_fp4 v[38:39], v39, 1.0 op_sel:[1,1,0]
	v_cvt_scalef32_pk_f32_fp4 v[236:237], v103, 1.0 op_sel:[0,1,0]
	v_pk_fma_f32 v[8:9], v[112:113], s[24:25], v[8:9] op_sel_hi:[1,0,1]
	v_pk_fma_f32 v[10:11], v[114:115], s[24:25], v[10:11] op_sel_hi:[1,0,1]
	v_pk_fma_f32 v[12:13], v[116:117], s[24:25], v[12:13] op_sel_hi:[1,0,1]
	v_pk_fma_f32 v[18:19], v[210:211], s[38:39], v[18:19] op_sel_hi:[1,0,1]
	v_pk_fma_f32 v[20:21], v[32:33], s[28:29], v[20:21] op_sel_hi:[1,0,1]
	v_readlane_b32 s25, v49, 0
	v_cvt_scalef32_pk_f32_fp4 v[168:169], v80, 1.0 op_sel:[1,0,0]
	v_cvt_scalef32_pk_f32_fp4 v[170:171], v80, 1.0 op_sel:[0,1,0]
	v_cvt_scalef32_pk_f32_fp4 v[172:173], v80, 1.0 op_sel:[1,1,0]
	v_cvt_scalef32_pk_f32_fp4 v[80:81], v81, 1.0 op_sel:[1,1,0]
	v_cvt_scalef32_pk_f32_fp4 v[36:37], v105, 1.0 op_sel:[0,1,0]
	v_pk_fma_f32 v[18:19], v[236:237], s[56:57], v[18:19] op_sel_hi:[1,0,1]
	v_pk_fma_f32 v[20:21], v[38:39], s[30:31], v[20:21] op_sel_hi:[1,0,1]
	v_pk_fma_f32 v[18:19], v[36:37], s[60:61], v[18:19] op_sel_hi:[1,0,1]
	v_pk_fma_f32 v[20:21], v[80:81], s[34:35], v[20:21] op_sel_hi:[1,0,1]
	s_waitcnt vmcnt(5)
	v_cvt_scalef32_pk_f32_fp4 v[54:55], v108, 1.0
	v_cvt_scalef32_pk_f32_fp4 v[56:57], v108, 1.0 op_sel:[1,0,0]
	v_cvt_scalef32_pk_f32_fp4 v[80:81], v108, 1.0 op_sel:[0,1,0]
	v_cvt_scalef32_pk_f32_fp4 v[82:83], v108, 1.0 op_sel:[1,1,0]
	v_cvt_scalef32_pk_f32_fp4 v[84:85], v109, 1.0
	v_cvt_scalef32_pk_f32_fp4 v[86:87], v109, 1.0 op_sel:[1,0,0]
	v_cvt_scalef32_pk_f32_fp4 v[36:37], v109, 1.0 op_sel:[0,1,0]
	v_cvt_scalef32_pk_f32_fp4 v[28:29], v109, 1.0 op_sel:[1,1,0]
	buffer_load_dwordx2 v[108:109], v192, s[4:7], s25 offen
	v_readlane_b32 s25, v49, 1
	v_pk_fma_f32 v[10:11], v[128:129], s[26:27], v[10:11] op_sel_hi:[1,0,1]
	v_pk_fma_f32 v[8:9], v[126:127], s[26:27], v[8:9] op_sel_hi:[1,0,1]
	v_pk_fma_f32 v[10:11], v[142:143], s[28:29], v[10:11] op_sel_hi:[1,0,1]
	v_pk_fma_f32 v[12:13], v[130:131], s[26:27], v[12:13] op_sel_hi:[1,0,1]
	s_nop 0
	buffer_load_dwordx2 v[118:119], v192, s[4:7], s25 offen
	v_readlane_b32 s25, v49, 2
	v_pk_fma_f32 v[8:9], v[140:141], s[28:29], v[8:9] op_sel_hi:[1,0,1]
	v_pk_fma_f32 v[12:13], v[144:145], s[28:29], v[12:13] op_sel_hi:[1,0,1]
	v_pk_fma_f32 v[8:9], v[154:155], s[30:31], v[8:9] op_sel_hi:[1,0,1]
	v_pk_fma_f32 v[10:11], v[156:157], s[30:31], v[10:11] op_sel_hi:[1,0,1]
	s_nop 0
	buffer_load_dwordx2 v[132:133], v192, s[4:7], s25 offen
	v_readlane_b32 s25, v49, 3
	v_pk_fma_f32 v[12:13], v[158:159], s[30:31], v[12:13] op_sel_hi:[1,0,1]
	v_readlane_b32 s27, v49, 5
	v_readlane_b32 s29, v49, 6
	v_readlane_b32 s31, v49, 7
	s_nop 0
	buffer_load_dwordx2 v[142:143], v192, s[4:7], s25 offen
	v_readlane_b32 s25, v49, 4
	v_pk_fma_f32 v[10:11], v[170:171], s[34:35], v[10:11] op_sel_hi:[1,0,1]
	v_pk_fma_f32 v[12:13], v[172:173], s[34:35], v[12:13] op_sel_hi:[1,0,1]
	s_nop 2
	buffer_load_dwordx2 v[170:171], v192, s[4:7], s25 offen
	buffer_load_dwordx2 v[172:173], v192, s[4:7], s27 offen
	buffer_load_dwordx2 v[174:175], v192, s[4:7], s29 offen
	buffer_load_dwordx2 v[176:177], v192, s[4:7], s31 offen
	v_readlane_b32 s25, v49, 8
	v_cvt_scalef32_pk_f32_fp4 v[182:183], v92, 1.0 op_sel:[1,0,0]
	v_cvt_scalef32_pk_f32_fp4 v[184:185], v92, 1.0 op_sel:[0,1,0]
	v_pk_fma_f32 v[8:9], v[168:169], s[34:35], v[8:9] op_sel_hi:[1,0,1]
	v_readlane_b32 s27, v49, 9
	v_readlane_b32 s29, v49, 10
	v_readlane_b32 s31, v49, 11
	v_pk_fma_f32 v[8:9], v[182:183], s[36:37], v[8:9] op_sel_hi:[1,0,1]
	v_pk_fma_f32 v[10:11], v[184:185], s[36:37], v[10:11] op_sel_hi:[1,0,1]
	buffer_load_dwordx2 v[178:179], v192, s[4:7], s25 offen
	buffer_load_dwordx2 v[180:181], v192, s[4:7], s27 offen
	buffer_load_dwordx2 v[182:183], v192, s[4:7], s29 offen
	buffer_load_dwordx2 v[184:185], v192, s[4:7], s31 offen
	v_readlane_b32 s25, v49, 12
	v_cvt_scalef32_pk_f32_fp4 v[186:187], v92, 1.0 op_sel:[1,1,0]
	v_readlane_b32 s27, v49, 13
	v_readlane_b32 s29, v49, 14
	v_readlane_b32 s31, v49, 15
	v_pk_fma_f32 v[12:13], v[186:187], s[36:37], v[12:13] op_sel_hi:[1,0,1]
	v_readlane_b32 s20, v3, 9
	v_readlane_b32 s22, v3, 10
	v_readlane_b32 s24, v3, 11
	v_readlane_b32 s26, v3, 12
	v_readlane_b32 s28, v3, 13
	v_readlane_b32 s30, v3, 14
	s_waitcnt vmcnt(13)
	v_cvt_scalef32_pk_f32_fp4 v[136:137], v6, 1.0
	v_cvt_scalef32_pk_f32_fp4 v[138:139], v6, 1.0 op_sel:[1,0,0]
	v_cvt_scalef32_pk_f32_fp4 v[140:141], v6, 1.0 op_sel:[0,1,0]
	v_cvt_scalef32_pk_f32_fp4 v[144:145], v6, 1.0 op_sel:[1,1,0]
	v_cvt_scalef32_pk_f32_fp4 v[146:147], v7, 1.0
	v_cvt_scalef32_pk_f32_fp4 v[148:149], v7, 1.0 op_sel:[1,0,0]
	v_cvt_scalef32_pk_f32_fp4 v[150:151], v7, 1.0 op_sel:[0,1,0]
	v_cvt_scalef32_pk_f32_fp4 v[152:153], v7, 1.0 op_sel:[1,1,0]
	v_readlane_b32 s34, v3, 15
	s_waitcnt vmcnt(12)
	v_cvt_scalef32_pk_f32_fp4 v[154:155], v4, 1.0
	v_cvt_scalef32_pk_f32_fp4 v[156:157], v4, 1.0 op_sel:[1,0,0]
	v_cvt_scalef32_pk_f32_fp4 v[158:159], v4, 1.0 op_sel:[0,1,0]
	v_cvt_scalef32_pk_f32_fp4 v[160:161], v4, 1.0 op_sel:[1,1,0]
	v_cvt_scalef32_pk_f32_fp4 v[162:163], v5, 1.0
	v_cvt_scalef32_pk_f32_fp4 v[164:165], v5, 1.0 op_sel:[1,0,0]
	v_cvt_scalef32_pk_f32_fp4 v[166:167], v5, 1.0 op_sel:[0,1,0]
	v_cvt_scalef32_pk_f32_fp4 v[168:169], v5, 1.0 op_sel:[1,1,0]
	ds_read2_b32 v[2:3], v47 offset0:64 offset1:80
	buffer_load_dwordx2 v[186:187], v192, s[4:7], s25 offen
	buffer_load_dwordx2 v[188:189], v192, s[4:7], s27 offen
	buffer_load_dwordx2 v[6:7], v192, s[4:7], s29 offen
	buffer_load_dwordx2 v[4:5], v192, s[4:7], s31 offen
	v_cvt_scalef32_pk_f32_fp4 v[38:39], v107, 1.0 op_sel:[1,0,0]
	v_pk_fma_f32 v[16:17], v[38:39], s[20:21], v[16:17] op_sel_hi:[1,0,1]
	v_cvt_scalef32_pk_f32_fp4 v[98:99], v111, 1.0 op_sel:[1,0,0]
	v_pk_fma_f32 v[16:17], v[86:87], s[22:23], v[16:17] op_sel_hi:[1,0,1]
	v_cvt_scalef32_pk_f32_fp4 v[114:115], v35, 1.0 op_sel:[1,0,0]
	v_pk_fma_f32 v[16:17], v[98:99], s[24:25], v[16:17] op_sel_hi:[1,0,1]
	v_cvt_scalef32_pk_f32_fp4 v[130:131], v27, 1.0 op_sel:[1,0,0]
	v_pk_fma_f32 v[16:17], v[114:115], s[26:27], v[16:17] op_sel_hi:[1,0,1]
	v_cvt_scalef32_pk_f32_fp4 v[92:93], v93, 1.0 op_sel:[1,1,0]
	v_pk_fma_f32 v[16:17], v[130:131], s[28:29], v[16:17] op_sel_hi:[1,0,1]
	v_cvt_scalef32_pk_f32_fp4 v[200:201], v100, 1.0 op_sel:[1,0,0]
	v_cvt_scalef32_pk_f32_fp4 v[204:205], v100, 1.0 op_sel:[1,1,0]
	v_pk_fma_f32 v[16:17], v[148:149], s[30:31], v[16:17] op_sel_hi:[1,0,1]
	v_cvt_scalef32_pk_f32_fp4 v[202:203], v100, 1.0 op_sel:[0,1,0]
	v_cvt_scalef32_pk_f32_fp4 v[100:101], v101, 1.0 op_sel:[1,1,0]
	v_cvt_scalef32_pk_f32_fp4 v[216:217], v102, 1.0 op_sel:[1,0,0]
	v_cvt_scalef32_pk_f32_fp4 v[230:231], v102, 1.0 op_sel:[1,1,0]
	v_pk_fma_f32 v[8:9], v[200:201], s[38:39], v[8:9] op_sel_hi:[1,0,1]
	v_pk_fma_f32 v[12:13], v[204:205], s[38:39], v[12:13] op_sel_hi:[1,0,1]
	v_pk_fma_f32 v[20:21], v[92:93], s[36:37], v[20:21] op_sel_hi:[1,0,1]
	s_waitcnt lgkmcnt(0)
	v_readlane_b32 s36, v2, 0
	s_waitcnt vmcnt(15)
	v_cvt_scalef32_pk_f32_fp4 v[204:205], v109, 1.0 op_sel:[1,0,0]
	v_pk_fma_f32 v[16:17], v[164:165], s[34:35], v[16:17] op_sel_hi:[1,0,1]
	v_cvt_scalef32_pk_f32_fp4 v[228:229], v102, 1.0 op_sel:[0,1,0]
	v_cvt_scalef32_pk_f32_fp4 v[102:103], v103, 1.0 op_sel:[1,1,0]
	v_cvt_scalef32_pk_f32_fp4 v[240:241], v104, 1.0 op_sel:[1,0,0]
	v_cvt_scalef32_pk_f32_fp4 v[244:245], v104, 1.0 op_sel:[1,1,0]
	v_pk_fma_f32 v[8:9], v[216:217], s[56:57], v[8:9] op_sel_hi:[1,0,1]
	v_pk_fma_f32 v[10:11], v[202:203], s[38:39], v[10:11] op_sel_hi:[1,0,1]
	v_pk_fma_f32 v[12:13], v[230:231], s[56:57], v[12:13] op_sel_hi:[1,0,1]
	v_pk_fma_f32 v[20:21], v[100:101], s[38:39], v[20:21] op_sel_hi:[1,0,1]
	v_readlane_b32 s38, v2, 1
	s_waitcnt vmcnt(14)
	v_cvt_scalef32_pk_f32_fp4 v[230:231], v119, 1.0 op_sel:[1,0,0]
	v_pk_fma_f32 v[16:17], v[204:205], s[36:37], v[16:17] op_sel_hi:[1,0,1]
	v_cvt_scalef32_pk_f32_fp4 v[242:243], v104, 1.0 op_sel:[0,1,0]
	v_pk_fma_f32 v[8:9], v[240:241], s[60:61], v[8:9] op_sel_hi:[1,0,1]
	v_pk_fma_f32 v[10:11], v[228:229], s[56:57], v[10:11] op_sel_hi:[1,0,1]
	v_pk_fma_f32 v[12:13], v[244:245], s[60:61], v[12:13] op_sel_hi:[1,0,1]
	v_cvt_scalef32_pk_f32_fp4 v[40:41], v105, 1.0 op_sel:[1,1,0]
	v_pk_fma_f32 v[20:21], v[102:103], s[56:57], v[20:21] op_sel_hi:[1,0,1]
	v_cvt_scalef32_pk_f32_fp4 v[42:43], v106, 1.0 op_sel:[1,0,0]
	v_readlane_b32 s56, v2, 2
	s_waitcnt vmcnt(13)
	v_cvt_scalef32_pk_f32_fp4 v[244:245], v133, 1.0 op_sel:[1,0,0]
	v_pk_fma_f32 v[16:17], v[230:231], s[38:39], v[16:17] op_sel_hi:[1,0,1]
	v_pk_fma_f32 v[10:11], v[242:243], s[60:61], v[10:11] op_sel_hi:[1,0,1]
	v_pk_fma_f32 v[20:21], v[40:41], s[60:61], v[20:21] op_sel_hi:[1,0,1]
	v_cvt_scalef32_pk_f32_fp4 v[30:31], v107, 1.0 op_sel:[0,1,0]
	v_readlane_b32 s60, v2, 3
	v_pk_fma_f32 v[8:9], v[42:43], s[20:21], v[8:9] op_sel_hi:[1,0,1]
	s_waitcnt vmcnt(12)
	v_cvt_scalef32_pk_f32_fp4 v[42:43], v143, 1.0 op_sel:[1,0,0]
	v_pk_fma_f32 v[16:17], v[244:245], s[56:57], v[16:17] op_sel_hi:[1,0,1]
	v_cvt_scalef32_pk_f32_fp4 v[100:101], v111, 1.0 op_sel:[0,1,0]
	v_pk_fma_f32 v[38:39], v[42:43], s[60:61], v[16:17] op_sel_hi:[1,0,1]
	v_pk_fma_f32 v[16:17], v[30:31], s[20:21], v[18:19] op_sel_hi:[1,0,1]
	v_cvt_scalef32_pk_f32_fp4 v[52:53], v107, 1.0
	v_pk_fma_f32 v[16:17], v[36:37], s[22:23], v[16:17] op_sel_hi:[1,0,1]
	v_cvt_scalef32_pk_f32_fp4 v[116:117], v35, 1.0 op_sel:[0,1,0]
	v_pk_fma_f32 v[16:17], v[100:101], s[24:25], v[16:17] op_sel_hi:[1,0,1]
	v_cvt_scalef32_pk_f32_fp4 v[90:91], v110, 1.0 op_sel:[1,0,0]
	v_cvt_scalef32_pk_f32_fp4 v[134:135], v27, 1.0 op_sel:[0,1,0]
	v_pk_fma_f32 v[8:9], v[56:57], s[22:23], v[8:9] op_sel_hi:[1,0,1]
	v_pk_fma_f32 v[14:15], v[52:53], s[20:21], v[14:15] op_sel_hi:[1,0,1]
	v_pk_fma_f32 v[16:17], v[116:117], s[26:27], v[16:17] op_sel_hi:[1,0,1]
	v_cvt_scalef32_pk_f32_fp4 v[96:97], v111, 1.0
	v_cvt_scalef32_pk_f32_fp4 v[104:105], v34, 1.0 op_sel:[1,0,0]
	v_pk_fma_f32 v[8:9], v[90:91], s[24:25], v[8:9] op_sel_hi:[1,0,1]
	v_pk_fma_f32 v[14:15], v[84:85], s[22:23], v[14:15] op_sel_hi:[1,0,1]
	v_pk_fma_f32 v[16:17], v[134:135], s[28:29], v[16:17] op_sel_hi:[1,0,1]
	v_cvt_scalef32_pk_f32_fp4 v[112:113], v35, 1.0
	v_cvt_scalef32_pk_f32_fp4 v[122:123], v26, 1.0 op_sel:[1,0,0]
	v_pk_fma_f32 v[8:9], v[104:105], s[26:27], v[8:9] op_sel_hi:[1,0,1]
	v_pk_fma_f32 v[14:15], v[96:97], s[24:25], v[14:15] op_sel_hi:[1,0,1]
	v_pk_fma_f32 v[16:17], v[150:151], s[30:31], v[16:17] op_sel_hi:[1,0,1]
	v_cvt_scalef32_pk_f32_fp4 v[128:129], v27, 1.0
	v_cvt_scalef32_pk_f32_fp4 v[206:207], v109, 1.0 op_sel:[0,1,0]
	v_pk_fma_f32 v[8:9], v[122:123], s[28:29], v[8:9] op_sel_hi:[1,0,1]
	v_pk_fma_f32 v[14:15], v[112:113], s[26:27], v[14:15] op_sel_hi:[1,0,1]
	v_pk_fma_f32 v[16:17], v[166:167], s[34:35], v[16:17] op_sel_hi:[1,0,1]
	v_cvt_scalef32_pk_f32_fp4 v[232:233], v119, 1.0 op_sel:[0,1,0]
	v_pk_fma_f32 v[8:9], v[138:139], s[30:31], v[8:9] op_sel_hi:[1,0,1]
	v_pk_fma_f32 v[14:15], v[128:129], s[28:29], v[14:15] op_sel_hi:[1,0,1]
	v_pk_fma_f32 v[16:17], v[206:207], s[36:37], v[16:17] op_sel_hi:[1,0,1]
	v_cvt_scalef32_pk_f32_fp4 v[44:45], v106, 1.0 op_sel:[0,1,0]
	v_cvt_scalef32_pk_f32_fp4 v[196:197], v108, 1.0 op_sel:[1,0,0]
	v_cvt_scalef32_pk_f32_fp4 v[246:247], v133, 1.0 op_sel:[0,1,0]
	v_pk_fma_f32 v[8:9], v[156:157], s[34:35], v[8:9] op_sel_hi:[1,0,1]
	v_pk_fma_f32 v[14:15], v[146:147], s[30:31], v[14:15] op_sel_hi:[1,0,1]
	v_pk_fma_f32 v[16:17], v[232:233], s[38:39], v[16:17] op_sel_hi:[1,0,1]
	v_cvt_scalef32_pk_f32_fp4 v[22:23], v107, 1.0 op_sel:[1,1,0]
	v_cvt_scalef32_pk_f32_fp4 v[202:203], v109, 1.0
	v_cvt_scalef32_pk_f32_fp4 v[210:211], v118, 1.0 op_sel:[1,0,0]
	v_pk_fma_f32 v[8:9], v[196:197], s[36:37], v[8:9] op_sel_hi:[1,0,1]
	v_pk_fma_f32 v[10:11], v[44:45], s[20:21], v[10:11] op_sel_hi:[1,0,1]
	v_cvt_scalef32_pk_f32_fp4 v[44:45], v143, 1.0 op_sel:[0,1,0]
	v_pk_fma_f32 v[14:15], v[162:163], s[34:35], v[14:15] op_sel_hi:[1,0,1]
	v_pk_fma_f32 v[16:17], v[246:247], s[56:57], v[16:17] op_sel_hi:[1,0,1]
	v_cvt_scalef32_pk_f32_fp4 v[40:41], v106, 1.0
	v_cvt_scalef32_pk_f32_fp4 v[228:229], v119, 1.0
	v_cvt_scalef32_pk_f32_fp4 v[236:237], v132, 1.0 op_sel:[1,0,0]
	v_pk_fma_f32 v[8:9], v[210:211], s[38:39], v[8:9] op_sel_hi:[1,0,1]
	v_pk_fma_f32 v[14:15], v[202:203], s[36:37], v[14:15] op_sel_hi:[1,0,1]
	v_pk_fma_f32 v[18:19], v[44:45], s[60:61], v[16:17] op_sel_hi:[1,0,1]
	v_pk_fma_f32 v[16:17], v[22:23], s[20:21], v[20:21] op_sel_hi:[1,0,1]
	v_cvt_scalef32_pk_f32_fp4 v[32:33], v111, 1.0 op_sel:[1,1,0]
	v_cvt_scalef32_pk_f32_fp4 v[242:243], v133, 1.0
	v_pk_fma_f32 v[24:25], v[40:41], s[20:21], v[24:25] op_sel_hi:[1,0,1]
	v_cvt_scalef32_pk_f32_fp4 v[40:41], v142, 1.0 op_sel:[1,0,0]
	v_pk_fma_f32 v[8:9], v[236:237], s[56:57], v[8:9] op_sel_hi:[1,0,1]
	v_pk_fma_f32 v[14:15], v[228:229], s[38:39], v[14:15] op_sel_hi:[1,0,1]
	v_pk_fma_f32 v[16:17], v[28:29], s[22:23], v[16:17] op_sel_hi:[1,0,1]
	v_cvt_scalef32_pk_f32_fp4 v[50:51], v106, 1.0 op_sel:[1,1,0]
	v_cvt_scalef32_pk_f32_fp4 v[88:89], v110, 1.0
	v_cvt_scalef32_pk_f32_fp4 v[92:93], v110, 1.0 op_sel:[0,1,0]
	v_cvt_scalef32_pk_f32_fp4 v[94:95], v110, 1.0 op_sel:[1,1,0]
	v_cvt_scalef32_pk_f32_fp4 v[102:103], v34, 1.0
	v_cvt_scalef32_pk_f32_fp4 v[106:107], v34, 1.0 op_sel:[0,1,0]
	v_cvt_scalef32_pk_f32_fp4 v[110:111], v34, 1.0 op_sel:[1,1,0]
	v_cvt_scalef32_pk_f32_fp4 v[34:35], v35, 1.0 op_sel:[1,1,0]
	v_pk_fma_f32 v[8:9], v[40:41], s[60:61], v[8:9] op_sel_hi:[1,0,1]
	v_cvt_scalef32_pk_f32_fp4 v[40:41], v143, 1.0
	v_pk_fma_f32 v[14:15], v[242:243], s[56:57], v[14:15] op_sel_hi:[1,0,1]
	v_pk_fma_f32 v[16:17], v[32:33], s[24:25], v[16:17] op_sel_hi:[1,0,1]
	v_cvt_scalef32_pk_f32_fp4 v[120:121], v26, 1.0
	v_cvt_scalef32_pk_f32_fp4 v[124:125], v26, 1.0 op_sel:[0,1,0]
	v_cvt_scalef32_pk_f32_fp4 v[126:127], v26, 1.0 op_sel:[1,1,0]
	v_cvt_scalef32_pk_f32_fp4 v[26:27], v27, 1.0 op_sel:[1,1,0]
	v_pk_fma_f32 v[12:13], v[50:51], s[20:21], v[12:13] op_sel_hi:[1,0,1]
	v_pk_fma_f32 v[14:15], v[40:41], s[60:61], v[14:15] op_sel_hi:[1,0,1]
	v_pk_fma_f32 v[16:17], v[34:35], s[26:27], v[16:17] op_sel_hi:[1,0,1]
	v_readlane_b32 s20, v2, 4
	s_waitcnt vmcnt(11)
	v_cvt_scalef32_pk_f32_fp4 v[30:31], v171, 1.0
	v_pk_fma_f32 v[24:25], v[54:55], s[22:23], v[24:25] op_sel_hi:[1,0,1]
	v_pk_fma_f32 v[10:11], v[80:81], s[22:23], v[10:11] op_sel_hi:[1,0,1]
	v_pk_fma_f32 v[12:13], v[82:83], s[22:23], v[12:13] op_sel_hi:[1,0,1]
	v_pk_fma_f32 v[16:17], v[26:27], s[28:29], v[16:17] op_sel_hi:[1,0,1]
	v_readlane_b32 s22, v2, 5
	s_waitcnt vmcnt(10)
	v_cvt_scalef32_pk_f32_fp4 v[52:53], v173, 1.0
	v_pk_fma_f32 v[14:15], v[30:31], s[20:21], v[14:15] op_sel_hi:[1,0,1]
	v_pk_fma_f32 v[24:25], v[88:89], s[24:25], v[24:25] op_sel_hi:[1,0,1]
	v_pk_fma_f32 v[10:11], v[92:93], s[24:25], v[10:11] op_sel_hi:[1,0,1]
	v_pk_fma_f32 v[12:13], v[94:95], s[24:25], v[12:13] op_sel_hi:[1,0,1]
	v_pk_fma_f32 v[16:17], v[152:153], s[30:31], v[16:17] op_sel_hi:[1,0,1]
	v_readlane_b32 s24, v2, 6
	s_waitcnt vmcnt(9)
	v_cvt_scalef32_pk_f32_fp4 v[90:91], v175, 1.0
	v_pk_fma_f32 v[14:15], v[52:53], s[22:23], v[14:15] op_sel_hi:[1,0,1]
	v_cvt_scalef32_pk_f32_fp4 v[190:191], v108, 1.0
	v_cvt_scalef32_pk_f32_fp4 v[198:199], v108, 1.0 op_sel:[0,1,0]
	v_cvt_scalef32_pk_f32_fp4 v[200:201], v108, 1.0 op_sel:[1,1,0]
	v_cvt_scalef32_pk_f32_fp4 v[108:109], v109, 1.0 op_sel:[1,1,0]
	v_pk_fma_f32 v[24:25], v[102:103], s[26:27], v[24:25] op_sel_hi:[1,0,1]
	v_pk_fma_f32 v[10:11], v[106:107], s[26:27], v[10:11] op_sel_hi:[1,0,1]
	v_pk_fma_f32 v[12:13], v[110:111], s[26:27], v[12:13] op_sel_hi:[1,0,1]
	v_pk_fma_f32 v[16:17], v[168:169], s[34:35], v[16:17] op_sel_hi:[1,0,1]
	v_readlane_b32 s26, v2, 7
	s_waitcnt vmcnt(8)
	v_cvt_scalef32_pk_f32_fp4 v[106:107], v177, 1.0
	v_pk_fma_f32 v[14:15], v[90:91], s[24:25], v[14:15] op_sel_hi:[1,0,1]
	v_cvt_scalef32_pk_f32_fp4 v[208:209], v118, 1.0
	v_cvt_scalef32_pk_f32_fp4 v[214:215], v118, 1.0 op_sel:[0,1,0]
	v_cvt_scalef32_pk_f32_fp4 v[216:217], v118, 1.0 op_sel:[1,1,0]
	v_cvt_scalef32_pk_f32_fp4 v[118:119], v119, 1.0 op_sel:[1,1,0]
	v_pk_fma_f32 v[24:25], v[120:121], s[28:29], v[24:25] op_sel_hi:[1,0,1]
	v_pk_fma_f32 v[10:11], v[124:125], s[28:29], v[10:11] op_sel_hi:[1,0,1]
	v_pk_fma_f32 v[12:13], v[126:127], s[28:29], v[12:13] op_sel_hi:[1,0,1]
	v_pk_fma_f32 v[16:17], v[108:109], s[36:37], v[16:17] op_sel_hi:[1,0,1]
	v_readlane_b32 s28, v2, 8
	s_waitcnt vmcnt(7)
	v_cvt_scalef32_pk_f32_fp4 v[122:123], v179, 1.0
	v_pk_fma_f32 v[14:15], v[106:107], s[26:27], v[14:15] op_sel_hi:[1,0,1]
	v_cvt_scalef32_pk_f32_fp4 v[234:235], v132, 1.0
	v_cvt_scalef32_pk_f32_fp4 v[238:239], v132, 1.0 op_sel:[0,1,0]
	v_cvt_scalef32_pk_f32_fp4 v[240:241], v132, 1.0 op_sel:[1,1,0]
	v_cvt_scalef32_pk_f32_fp4 v[132:133], v133, 1.0 op_sel:[1,1,0]
	v_pk_fma_f32 v[24:25], v[136:137], s[30:31], v[24:25] op_sel_hi:[1,0,1]
	v_pk_fma_f32 v[10:11], v[140:141], s[30:31], v[10:11] op_sel_hi:[1,0,1]
	v_pk_fma_f32 v[12:13], v[144:145], s[30:31], v[12:13] op_sel_hi:[1,0,1]
	v_pk_fma_f32 v[16:17], v[118:119], s[38:39], v[16:17] op_sel_hi:[1,0,1]
	v_readlane_b32 s30, v2, 9
	s_waitcnt vmcnt(6)
	v_cvt_scalef32_pk_f32_fp4 v[138:139], v181, 1.0
	v_pk_fma_f32 v[14:15], v[122:123], s[28:29], v[14:15] op_sel_hi:[1,0,1]
	v_pk_fma_f32 v[24:25], v[154:155], s[34:35], v[24:25] op_sel_hi:[1,0,1]
	v_pk_fma_f32 v[10:11], v[158:159], s[34:35], v[10:11] op_sel_hi:[1,0,1]
	v_pk_fma_f32 v[12:13], v[160:161], s[34:35], v[12:13] op_sel_hi:[1,0,1]
	v_cvt_scalef32_pk_f32_fp4 v[50:51], v143, 1.0 op_sel:[1,1,0]
	v_pk_fma_f32 v[16:17], v[132:133], s[56:57], v[16:17] op_sel_hi:[1,0,1]
	v_readlane_b32 s34, v2, 10
	s_waitcnt vmcnt(5)
	v_cvt_scalef32_pk_f32_fp4 v[154:155], v183, 1.0
	v_pk_fma_f32 v[14:15], v[138:139], s[30:31], v[14:15] op_sel_hi:[1,0,1]
	v_pk_fma_f32 v[24:25], v[190:191], s[36:37], v[24:25] op_sel_hi:[1,0,1]
	v_pk_fma_f32 v[10:11], v[198:199], s[36:37], v[10:11] op_sel_hi:[1,0,1]
	v_pk_fma_f32 v[12:13], v[200:201], s[36:37], v[12:13] op_sel_hi:[1,0,1]
	v_pk_fma_f32 v[20:21], v[50:51], s[60:61], v[16:17] op_sel_hi:[1,0,1]
	v_cvt_scalef32_pk_f32_fp4 v[16:17], v170, 1.0
	v_cvt_scalef32_pk_f32_fp4 v[22:23], v170, 1.0 op_sel:[1,0,0]
	v_cvt_scalef32_pk_f32_fp4 v[26:27], v170, 1.0 op_sel:[0,1,0]
	v_cvt_scalef32_pk_f32_fp4 v[28:29], v170, 1.0 op_sel:[1,1,0]
	v_cvt_scalef32_pk_f32_fp4 v[32:33], v171, 1.0 op_sel:[1,0,0]
	v_cvt_scalef32_pk_f32_fp4 v[34:35], v171, 1.0 op_sel:[0,1,0]
	v_cvt_scalef32_pk_f32_fp4 v[36:37], v171, 1.0 op_sel:[1,1,0]
	v_readlane_b32 s36, v2, 11
	s_waitcnt vmcnt(4)
	v_cvt_scalef32_pk_f32_fp4 v[170:171], v185, 1.0
	v_pk_fma_f32 v[14:15], v[154:155], s[34:35], v[14:15] op_sel_hi:[1,0,1]
	v_pk_fma_f32 v[24:25], v[208:209], s[38:39], v[24:25] op_sel_hi:[1,0,1]
	v_pk_fma_f32 v[10:11], v[214:215], s[38:39], v[10:11] op_sel_hi:[1,0,1]
	v_pk_fma_f32 v[12:13], v[216:217], s[38:39], v[12:13] op_sel_hi:[1,0,1]
	v_readlane_b32 s38, v2, 12
	s_waitcnt vmcnt(3)
	v_cvt_scalef32_pk_f32_fp4 v[190:191], v187, 1.0
	v_pk_fma_f32 v[14:15], v[170:171], s[36:37], v[14:15] op_sel_hi:[1,0,1]
	v_cvt_scalef32_pk_f32_fp4 v[248:249], v142, 1.0
	v_cvt_scalef32_pk_f32_fp4 v[54:55], v142, 1.0 op_sel:[0,1,0]
	v_cvt_scalef32_pk_f32_fp4 v[88:89], v142, 1.0 op_sel:[1,1,0]
	v_pk_fma_f32 v[24:25], v[234:235], s[56:57], v[24:25] op_sel_hi:[1,0,1]
	v_pk_fma_f32 v[10:11], v[238:239], s[56:57], v[10:11] op_sel_hi:[1,0,1]
	v_pk_fma_f32 v[12:13], v[240:241], s[56:57], v[12:13] op_sel_hi:[1,0,1]
	v_readlane_b32 s56, v2, 13
	s_waitcnt vmcnt(2)
	v_cvt_scalef32_pk_f32_fp4 v[208:209], v189, 1.0
	v_pk_fma_f32 v[14:15], v[190:191], s[38:39], v[14:15] op_sel_hi:[1,0,1]
	v_pk_fma_f32 v[24:25], v[248:249], s[60:61], v[24:25] op_sel_hi:[1,0,1]
	v_pk_fma_f32 v[10:11], v[54:55], s[60:61], v[10:11] op_sel_hi:[1,0,1]
	v_pk_fma_f32 v[12:13], v[88:89], s[60:61], v[12:13] op_sel_hi:[1,0,1]
	v_readlane_b32 s60, v2, 14
	v_pk_fma_f32 v[8:9], v[22:23], s[20:21], v[8:9] op_sel_hi:[1,0,1]
	s_waitcnt vmcnt(1)
	v_cvt_scalef32_pk_f32_fp4 v[22:23], v7, 1.0
	v_pk_fma_f32 v[14:15], v[208:209], s[56:57], v[14:15] op_sel_hi:[1,0,1]
	v_cvt_scalef32_pk_f32_fp4 v[40:41], v172, 1.0
	v_cvt_scalef32_pk_f32_fp4 v[42:43], v172, 1.0 op_sel:[1,0,0]
	v_cvt_scalef32_pk_f32_fp4 v[44:45], v172, 1.0 op_sel:[0,1,0]
	v_cvt_scalef32_pk_f32_fp4 v[50:51], v172, 1.0 op_sel:[1,1,0]
	v_cvt_scalef32_pk_f32_fp4 v[54:55], v173, 1.0 op_sel:[1,0,0]
	v_pk_fma_f32 v[16:17], v[16:17], s[20:21], v[24:25] op_sel_hi:[1,0,1]
	v_pk_fma_f32 v[10:11], v[26:27], s[20:21], v[10:11] op_sel_hi:[1,0,1]
	v_pk_fma_f32 v[12:13], v[28:29], s[20:21], v[12:13] op_sel_hi:[1,0,1]
	v_pk_fma_f32 v[14:15], v[22:23], s[60:61], v[14:15] op_sel_hi:[1,0,1]
	v_pk_fma_f32 v[22:23], v[32:33], s[20:21], v[38:39] op_sel_hi:[1,0,1]
	v_cvt_scalef32_pk_f32_fp4 v[82:83], v174, 1.0
	v_cvt_scalef32_pk_f32_fp4 v[84:85], v174, 1.0 op_sel:[1,0,0]
	v_cvt_scalef32_pk_f32_fp4 v[86:87], v174, 1.0 op_sel:[0,1,0]
	v_cvt_scalef32_pk_f32_fp4 v[88:89], v174, 1.0 op_sel:[1,1,0]
	v_cvt_scalef32_pk_f32_fp4 v[92:93], v175, 1.0 op_sel:[1,0,0]
	v_pk_fma_f32 v[16:17], v[40:41], s[22:23], v[16:17] op_sel_hi:[1,0,1]
	v_pk_fma_f32 v[8:9], v[42:43], s[22:23], v[8:9] op_sel_hi:[1,0,1]
	v_pk_fma_f32 v[10:11], v[44:45], s[22:23], v[10:11] op_sel_hi:[1,0,1]
	v_pk_fma_f32 v[12:13], v[50:51], s[22:23], v[12:13] op_sel_hi:[1,0,1]
	v_pk_fma_f32 v[22:23], v[54:55], s[22:23], v[22:23] op_sel_hi:[1,0,1]
	v_cvt_scalef32_pk_f32_fp4 v[56:57], v173, 1.0 op_sel:[0,1,0]
	v_pk_fma_f32 v[16:17], v[82:83], s[24:25], v[16:17] op_sel_hi:[1,0,1]
	v_pk_fma_f32 v[8:9], v[84:85], s[24:25], v[8:9] op_sel_hi:[1,0,1]
	v_pk_fma_f32 v[10:11], v[86:87], s[24:25], v[10:11] op_sel_hi:[1,0,1]
	v_pk_fma_f32 v[12:13], v[88:89], s[24:25], v[12:13] op_sel_hi:[1,0,1]
	v_pk_fma_f32 v[22:23], v[92:93], s[24:25], v[22:23] op_sel_hi:[1,0,1]
	v_readlane_b32 s25, v48, 0
	v_pk_fma_f32 v[18:19], v[34:35], s[20:21], v[18:19] op_sel_hi:[1,0,1]
	v_cvt_scalef32_pk_f32_fp4 v[94:95], v175, 1.0 op_sel:[0,1,0]
	v_pk_fma_f32 v[18:19], v[56:57], s[22:23], v[18:19] op_sel_hi:[1,0,1]
	v_cvt_scalef32_pk_f32_fp4 v[110:111], v177, 1.0 op_sel:[0,1,0]
	v_pk_fma_f32 v[18:19], v[94:95], s[24:25], v[18:19] op_sel_hi:[1,0,1]
	v_cvt_scalef32_pk_f32_fp4 v[126:127], v179, 1.0 op_sel:[0,1,0]
	v_pk_fma_f32 v[18:19], v[110:111], s[26:27], v[18:19] op_sel_hi:[1,0,1]
	v_cvt_scalef32_pk_f32_fp4 v[142:143], v181, 1.0 op_sel:[0,1,0]
	v_pk_fma_f32 v[18:19], v[126:127], s[28:29], v[18:19] op_sel_hi:[1,0,1]
	v_cvt_scalef32_pk_f32_fp4 v[158:159], v183, 1.0 op_sel:[0,1,0]
	v_pk_fma_f32 v[18:19], v[142:143], s[30:31], v[18:19] op_sel_hi:[1,0,1]
	v_cvt_scalef32_pk_f32_fp4 v[96:97], v175, 1.0 op_sel:[1,1,0]
	v_cvt_scalef32_pk_f32_fp4 v[108:109], v177, 1.0 op_sel:[1,0,0]
	v_cvt_scalef32_pk_f32_fp4 v[174:175], v185, 1.0 op_sel:[0,1,0]
	v_pk_fma_f32 v[18:19], v[158:159], s[34:35], v[18:19] op_sel_hi:[1,0,1]
	v_cvt_scalef32_pk_f32_fp4 v[80:81], v173, 1.0 op_sel:[1,1,0]
	v_cvt_scalef32_pk_f32_fp4 v[124:125], v179, 1.0 op_sel:[1,0,0]
	v_cvt_scalef32_pk_f32_fp4 v[198:199], v187, 1.0 op_sel:[0,1,0]
	v_pk_fma_f32 v[22:23], v[108:109], s[26:27], v[22:23] op_sel_hi:[1,0,1]
	v_pk_fma_f32 v[18:19], v[174:175], s[36:37], v[18:19] op_sel_hi:[1,0,1]
	v_pk_fma_f32 v[20:21], v[36:37], s[20:21], v[20:21] op_sel_hi:[1,0,1]
	v_cvt_scalef32_pk_f32_fp4 v[140:141], v181, 1.0 op_sel:[1,0,0]
	v_cvt_scalef32_pk_f32_fp4 v[214:215], v189, 1.0 op_sel:[0,1,0]
	v_pk_fma_f32 v[22:23], v[124:125], s[28:29], v[22:23] op_sel_hi:[1,0,1]
	v_pk_fma_f32 v[18:19], v[198:199], s[38:39], v[18:19] op_sel_hi:[1,0,1]
	v_pk_fma_f32 v[20:21], v[80:81], s[22:23], v[20:21] op_sel_hi:[1,0,1]
	v_readlane_b32 s20, v48, 3
	v_readlane_b32 s22, v48, 5
	v_cvt_scalef32_pk_f32_fp4 v[156:157], v183, 1.0 op_sel:[1,0,0]
	v_cvt_scalef32_pk_f32_fp4 v[26:27], v7, 1.0 op_sel:[0,1,0]
	v_pk_fma_f32 v[22:23], v[140:141], s[30:31], v[22:23] op_sel_hi:[1,0,1]
	v_pk_fma_f32 v[18:19], v[214:215], s[56:57], v[18:19] op_sel_hi:[1,0,1]
	v_cvt_scalef32_pk_f32_fp4 v[172:173], v185, 1.0 op_sel:[1,0,0]
	v_pk_fma_f32 v[22:23], v[156:157], s[34:35], v[22:23] op_sel_hi:[1,0,1]
	v_pk_fma_f32 v[18:19], v[26:27], s[60:61], v[18:19] op_sel_hi:[1,0,1]
	buffer_load_dwordx2 v[26:27], v192, s[4:7], s20 offen
	buffer_load_dwordx2 v[52:53], v192, s[4:7], s22 offen
	v_readlane_b32 s20, v48, 4
	v_cvt_scalef32_pk_f32_fp4 v[196:197], v187, 1.0 op_sel:[1,0,0]
	v_pk_fma_f32 v[22:23], v[172:173], s[36:37], v[22:23] op_sel_hi:[1,0,1]
	v_cvt_scalef32_pk_f32_fp4 v[210:211], v189, 1.0 op_sel:[1,0,0]
	v_pk_fma_f32 v[22:23], v[196:197], s[38:39], v[22:23] op_sel_hi:[1,0,1]
	buffer_load_dwordx2 v[28:29], v192, s[4:7], s25 offen
	buffer_load_dwordx2 v[36:37], v192, s[4:7], s20 offen
	v_readlane_b32 s25, v48, 1
	v_cvt_scalef32_pk_f32_fp4 v[24:25], v7, 1.0 op_sel:[1,0,0]
	v_pk_fma_f32 v[22:23], v[210:211], s[56:57], v[22:23] op_sel_hi:[1,0,1]
	v_pk_fma_f32 v[30:31], v[24:25], s[60:61], v[22:23] op_sel_hi:[1,0,1]
	v_readlane_b32 s22, v48, 6
	s_nop 0
	buffer_load_dwordx2 v[24:25], v192, s[4:7], s25 offen
	v_readlane_b32 s25, v48, 2
	s_nop 1
	v_pk_fma_f32 v[20:21], v[96:97], s[24:25], v[20:21] op_sel_hi:[1,0,1]
	v_readlane_b32 s24, v48, 7
	s_nop 2
	buffer_load_dwordx2 v[34:35], v192, s[4:7], s25 offen
	buffer_load_dwordx2 v[82:83], v192, s[4:7], s22 offen
	s_nop 1
	s_nop 0
	buffer_load_dwordx2 v[84:85], v192, s[4:7], s24 offen
	v_cvt_scalef32_pk_f32_fp4 v[98:99], v176, 1.0
	v_cvt_scalef32_pk_f32_fp4 v[100:101], v176, 1.0 op_sel:[1,0,0]
	v_cvt_scalef32_pk_f32_fp4 v[102:103], v176, 1.0 op_sel:[0,1,0]
	v_cvt_scalef32_pk_f32_fp4 v[104:105], v176, 1.0 op_sel:[1,1,0]
	v_cvt_scalef32_pk_f32_fp4 v[112:113], v177, 1.0 op_sel:[1,1,0]
	v_readlane_b32 s22, v48, 8
	v_pk_fma_f32 v[16:17], v[98:99], s[26:27], v[16:17] op_sel_hi:[1,0,1]
	v_pk_fma_f32 v[8:9], v[100:101], s[26:27], v[8:9] op_sel_hi:[1,0,1]
	v_pk_fma_f32 v[10:11], v[102:103], s[26:27], v[10:11] op_sel_hi:[1,0,1]
	v_pk_fma_f32 v[12:13], v[104:105], s[26:27], v[12:13] op_sel_hi:[1,0,1]
	v_pk_fma_f32 v[20:21], v[112:113], s[26:27], v[20:21] op_sel_hi:[1,0,1]
	v_readlane_b32 s24, v48, 9
	v_readlane_b32 s25, v48, 10
	v_readlane_b32 s26, v48, 11
	buffer_load_dwordx2 v[86:87], v192, s[4:7], s22 offen
	s_nop 1
	buffer_load_dwordx2 v[88:89], v192, s[4:7], s24 offen
	buffer_load_dwordx2 v[90:91], v192, s[4:7], s25 offen
	buffer_load_dwordx2 v[92:93], v192, s[4:7], s26 offen
	v_cvt_scalef32_pk_f32_fp4 v[128:129], v179, 1.0 op_sel:[1,1,0]
	v_cvt_scalef32_pk_f32_fp4 v[144:145], v181, 1.0 op_sel:[1,1,0]
	v_pk_fma_f32 v[20:21], v[128:129], s[28:29], v[20:21] op_sel_hi:[1,0,1]
	v_cvt_scalef32_pk_f32_fp4 v[160:161], v183, 1.0 op_sel:[1,1,0]
	v_pk_fma_f32 v[20:21], v[144:145], s[30:31], v[20:21] op_sel_hi:[1,0,1]
	v_cvt_scalef32_pk_f32_fp4 v[176:177], v185, 1.0 op_sel:[1,1,0]
	v_pk_fma_f32 v[20:21], v[160:161], s[34:35], v[20:21] op_sel_hi:[1,0,1]
	v_cvt_scalef32_pk_f32_fp4 v[114:115], v178, 1.0
	v_cvt_scalef32_pk_f32_fp4 v[116:117], v178, 1.0 op_sel:[1,0,0]
	v_cvt_scalef32_pk_f32_fp4 v[118:119], v178, 1.0 op_sel:[0,1,0]
	v_cvt_scalef32_pk_f32_fp4 v[120:121], v178, 1.0 op_sel:[1,1,0]
	v_cvt_scalef32_pk_f32_fp4 v[130:131], v180, 1.0
	v_cvt_scalef32_pk_f32_fp4 v[132:133], v180, 1.0 op_sel:[1,0,0]
	v_cvt_scalef32_pk_f32_fp4 v[134:135], v180, 1.0 op_sel:[0,1,0]
	v_cvt_scalef32_pk_f32_fp4 v[136:137], v180, 1.0 op_sel:[1,1,0]
	v_cvt_scalef32_pk_f32_fp4 v[146:147], v182, 1.0
	v_cvt_scalef32_pk_f32_fp4 v[148:149], v182, 1.0 op_sel:[1,0,0]
	v_cvt_scalef32_pk_f32_fp4 v[150:151], v182, 1.0 op_sel:[0,1,0]
	v_cvt_scalef32_pk_f32_fp4 v[152:153], v182, 1.0 op_sel:[1,1,0]
	v_cvt_scalef32_pk_f32_fp4 v[162:163], v184, 1.0
	v_cvt_scalef32_pk_f32_fp4 v[164:165], v184, 1.0 op_sel:[1,0,0]
	v_cvt_scalef32_pk_f32_fp4 v[166:167], v184, 1.0 op_sel:[0,1,0]
	v_cvt_scalef32_pk_f32_fp4 v[168:169], v184, 1.0 op_sel:[1,1,0]
	v_cvt_scalef32_pk_f32_fp4 v[178:179], v186, 1.0
	v_cvt_scalef32_pk_f32_fp4 v[180:181], v186, 1.0 op_sel:[1,0,0]
	v_cvt_scalef32_pk_f32_fp4 v[182:183], v186, 1.0 op_sel:[0,1,0]
	v_cvt_scalef32_pk_f32_fp4 v[184:185], v186, 1.0 op_sel:[1,1,0]
	v_cvt_scalef32_pk_f32_fp4 v[186:187], v187, 1.0 op_sel:[1,1,0]
	v_pk_fma_f32 v[20:21], v[176:177], s[36:37], v[20:21] op_sel_hi:[1,0,1]
	v_cvt_scalef32_pk_f32_fp4 v[200:201], v188, 1.0
	v_cvt_scalef32_pk_f32_fp4 v[202:203], v188, 1.0 op_sel:[1,0,0]
	v_cvt_scalef32_pk_f32_fp4 v[204:205], v188, 1.0 op_sel:[0,1,0]
	v_cvt_scalef32_pk_f32_fp4 v[206:207], v188, 1.0 op_sel:[1,1,0]
	v_cvt_scalef32_pk_f32_fp4 v[188:189], v189, 1.0 op_sel:[1,1,0]
	v_pk_fma_f32 v[20:21], v[186:187], s[38:39], v[20:21] op_sel_hi:[1,0,1]
	v_readlane_b32 s22, v48, 12
	v_cvt_scalef32_pk_f32_fp4 v[216:217], v6, 1.0
	v_cvt_scalef32_pk_f32_fp4 v[228:229], v6, 1.0 op_sel:[1,0,0]
	v_cvt_scalef32_pk_f32_fp4 v[230:231], v6, 1.0 op_sel:[0,1,0]
	v_cvt_scalef32_pk_f32_fp4 v[232:233], v6, 1.0 op_sel:[1,1,0]
	v_cvt_scalef32_pk_f32_fp4 v[6:7], v7, 1.0 op_sel:[1,1,0]
	v_pk_fma_f32 v[20:21], v[188:189], s[56:57], v[20:21] op_sel_hi:[1,0,1]
	v_readlane_b32 s24, v48, 13
	v_readlane_b32 s25, v48, 14
	v_readlane_b32 s26, v48, 15
	v_pk_fma_f32 v[20:21], v[6:7], s[60:61], v[20:21] op_sel_hi:[1,0,1]
	s_waitcnt vmcnt(12)
	v_cvt_scalef32_pk_f32_fp4 v[38:39], v4, 1.0
	v_cvt_scalef32_pk_f32_fp4 v[40:41], v4, 1.0 op_sel:[1,0,0]
	v_cvt_scalef32_pk_f32_fp4 v[42:43], v4, 1.0 op_sel:[0,1,0]
	v_cvt_scalef32_pk_f32_fp4 v[44:45], v4, 1.0 op_sel:[1,1,0]
	v_cvt_scalef32_pk_f32_fp4 v[50:51], v5, 1.0
	v_cvt_scalef32_pk_f32_fp4 v[54:55], v5, 1.0 op_sel:[1,0,0]
	v_cvt_scalef32_pk_f32_fp4 v[56:57], v5, 1.0 op_sel:[0,1,0]
	v_cvt_scalef32_pk_f32_fp4 v[80:81], v5, 1.0 op_sel:[1,1,0]
	buffer_load_dwordx2 v[32:33], v192, s[4:7], s22 offen
	buffer_load_dwordx2 v[22:23], v192, s[4:7], s24 offen
	buffer_load_dwordx2 v[6:7], v192, s[4:7], s25 offen
	buffer_load_dwordx2 v[4:5], v192, s[4:7], s26 offen
	v_pk_fma_f32 v[16:17], v[114:115], s[28:29], v[16:17] op_sel_hi:[1,0,1]
	v_readlane_b32 s20, v2, 15
	v_pk_fma_f32 v[16:17], v[130:131], s[30:31], v[16:17] op_sel_hi:[1,0,1]
	v_readlane_b32 s22, v3, 0
	v_pk_fma_f32 v[16:17], v[146:147], s[34:35], v[16:17] op_sel_hi:[1,0,1]
	s_waitcnt vmcnt(13)
	v_cvt_scalef32_pk_f32_fp4 v[48:49], v28, 1.0
	v_pk_fma_f32 v[16:17], v[162:163], s[36:37], v[16:17] op_sel_hi:[1,0,1]
	v_cvt_scalef32_pk_f32_fp4 v[100:101], v29, 1.0
	v_pk_fma_f32 v[16:17], v[178:179], s[38:39], v[16:17] op_sel_hi:[1,0,1]
	v_readlane_b32 s24, v3, 1
	v_pk_fma_f32 v[16:17], v[200:201], s[56:57], v[16:17] op_sel_hi:[1,0,1]
	s_waitcnt vmcnt(11)
	v_cvt_scalef32_pk_f32_fp4 v[106:107], v24, 1.0
	v_pk_fma_f32 v[16:17], v[216:217], s[60:61], v[16:17] op_sel_hi:[1,0,1]
	v_pk_fma_f32 v[14:15], v[50:51], s[20:21], v[14:15] op_sel_hi:[1,0,1]
	v_pk_fma_f32 v[16:17], v[38:39], s[20:21], v[16:17] op_sel_hi:[1,0,1]
	v_pk_fma_f32 v[8:9], v[116:117], s[28:29], v[8:9] op_sel_hi:[1,0,1]
	v_pk_fma_f32 v[16:17], v[48:49], s[22:23], v[16:17] op_sel_hi:[1,0,1]
	v_pk_fma_f32 v[10:11], v[118:119], s[28:29], v[10:11] op_sel_hi:[1,0,1]
	v_pk_fma_f32 v[12:13], v[120:121], s[28:29], v[12:13] op_sel_hi:[1,0,1]
	v_cvt_scalef32_pk_f32_fp4 v[108:109], v24, 1.0 op_sel:[1,0,0]
	v_cvt_scalef32_pk_f32_fp4 v[110:111], v24, 1.0 op_sel:[0,1,0]
	v_cvt_scalef32_pk_f32_fp4 v[112:113], v24, 1.0 op_sel:[1,1,0]
	v_cvt_scalef32_pk_f32_fp4 v[114:115], v25, 1.0
	v_cvt_scalef32_pk_f32_fp4 v[116:117], v25, 1.0 op_sel:[1,0,0]
	v_cvt_scalef32_pk_f32_fp4 v[118:119], v25, 1.0 op_sel:[0,1,0]
	v_cvt_scalef32_pk_f32_fp4 v[120:121], v25, 1.0 op_sel:[1,1,0]
	v_readlane_b32 s26, v3, 2
	s_waitcnt vmcnt(10)
	v_cvt_scalef32_pk_f32_fp4 v[24:25], v34, 1.0
	v_pk_fma_f32 v[16:17], v[106:107], s[24:25], v[16:17] op_sel_hi:[1,0,1]
	v_pk_fma_f32 v[14:15], v[100:101], s[22:23], v[14:15] op_sel_hi:[1,0,1]
	v_pk_fma_f32 v[8:9], v[132:133], s[30:31], v[8:9] op_sel_hi:[1,0,1]
	v_pk_fma_f32 v[10:11], v[134:135], s[30:31], v[10:11] op_sel_hi:[1,0,1]
	v_cvt_scalef32_pk_f32_fp4 v[128:129], v35, 1.0
	v_readlane_b32 s28, v3, 3
	v_cvt_scalef32_pk_f32_fp4 v[134:135], v26, 1.0
	v_pk_fma_f32 v[16:17], v[24:25], s[26:27], v[16:17] op_sel_hi:[1,0,1]
	v_pk_fma_f32 v[14:15], v[114:115], s[24:25], v[14:15] op_sel_hi:[1,0,1]
	v_pk_fma_f32 v[8:9], v[148:149], s[34:35], v[8:9] op_sel_hi:[1,0,1]
	v_pk_fma_f32 v[12:13], v[136:137], s[30:31], v[12:13] op_sel_hi:[1,0,1]
	v_cvt_scalef32_pk_f32_fp4 v[142:143], v27, 1.0
	v_readlane_b32 s30, v3, 4
	v_cvt_scalef32_pk_f32_fp4 v[148:149], v36, 1.0
	v_pk_fma_f32 v[16:17], v[134:135], s[28:29], v[16:17] op_sel_hi:[1,0,1]
	v_pk_fma_f32 v[14:15], v[128:129], s[26:27], v[14:15] op_sel_hi:[1,0,1]
	v_pk_fma_f32 v[10:11], v[150:151], s[34:35], v[10:11] op_sel_hi:[1,0,1]
	v_pk_fma_f32 v[12:13], v[152:153], s[34:35], v[12:13] op_sel_hi:[1,0,1]
	v_cvt_scalef32_pk_f32_fp4 v[156:157], v37, 1.0
	v_readlane_b32 s34, v3, 5
	v_cvt_scalef32_pk_f32_fp4 v[162:163], v52, 1.0
	v_pk_fma_f32 v[16:17], v[148:149], s[30:31], v[16:17] op_sel_hi:[1,0,1]
	v_pk_fma_f32 v[14:15], v[142:143], s[28:29], v[14:15] op_sel_hi:[1,0,1]
	v_pk_fma_f32 v[8:9], v[164:165], s[36:37], v[8:9] op_sel_hi:[1,0,1]
	v_pk_fma_f32 v[10:11], v[166:167], s[36:37], v[10:11] op_sel_hi:[1,0,1]
	v_pk_fma_f32 v[12:13], v[168:169], s[36:37], v[12:13] op_sel_hi:[1,0,1]
	v_cvt_scalef32_pk_f32_fp4 v[170:171], v53, 1.0
	v_readlane_b32 s36, v3, 6
	s_waitcnt vmcnt(9)
	v_cvt_scalef32_pk_f32_fp4 v[176:177], v82, 1.0
	v_pk_fma_f32 v[16:17], v[162:163], s[34:35], v[16:17] op_sel_hi:[1,0,1]
	v_pk_fma_f32 v[14:15], v[156:157], s[30:31], v[14:15] op_sel_hi:[1,0,1]
	v_pk_fma_f32 v[8:9], v[180:181], s[38:39], v[8:9] op_sel_hi:[1,0,1]
	v_pk_fma_f32 v[10:11], v[182:183], s[38:39], v[10:11] op_sel_hi:[1,0,1]
	v_pk_fma_f32 v[12:13], v[184:185], s[38:39], v[12:13] op_sel_hi:[1,0,1]
	v_cvt_scalef32_pk_f32_fp4 v[184:185], v83, 1.0
	v_readlane_b32 s38, v3, 7
	s_waitcnt vmcnt(8)
	v_cvt_scalef32_pk_f32_fp4 v[190:191], v84, 1.0
	v_pk_fma_f32 v[16:17], v[176:177], s[36:37], v[16:17] op_sel_hi:[1,0,1]
	v_pk_fma_f32 v[14:15], v[170:171], s[34:35], v[14:15] op_sel_hi:[1,0,1]
	v_pk_fma_f32 v[8:9], v[202:203], s[56:57], v[8:9] op_sel_hi:[1,0,1]
	v_pk_fma_f32 v[10:11], v[204:205], s[56:57], v[10:11] op_sel_hi:[1,0,1]
	v_pk_fma_f32 v[12:13], v[206:207], s[56:57], v[12:13] op_sel_hi:[1,0,1]
	v_cvt_scalef32_pk_f32_fp4 v[202:203], v85, 1.0
	v_readlane_b32 s56, v3, 8
	s_waitcnt vmcnt(7)
	v_cvt_scalef32_pk_f32_fp4 v[208:209], v86, 1.0
	v_pk_fma_f32 v[16:17], v[190:191], s[38:39], v[16:17] op_sel_hi:[1,0,1]
	v_pk_fma_f32 v[14:15], v[184:185], s[36:37], v[14:15] op_sel_hi:[1,0,1]
	v_pk_fma_f32 v[8:9], v[228:229], s[60:61], v[8:9] op_sel_hi:[1,0,1]
	v_pk_fma_f32 v[10:11], v[230:231], s[60:61], v[10:11] op_sel_hi:[1,0,1]
	v_pk_fma_f32 v[12:13], v[232:233], s[60:61], v[12:13] op_sel_hi:[1,0,1]
	v_cvt_scalef32_pk_f32_fp4 v[228:229], v87, 1.0
	v_readlane_b32 s60, v3, 9
	s_waitcnt vmcnt(6)
	v_cvt_scalef32_pk_f32_fp4 v[234:235], v88, 1.0
	v_pk_fma_f32 v[16:17], v[208:209], s[56:57], v[16:17] op_sel_hi:[1,0,1]
	v_pk_fma_f32 v[14:15], v[202:203], s[38:39], v[14:15] op_sel_hi:[1,0,1]
	v_pk_fma_f32 v[24:25], v[234:235], s[60:61], v[16:17] op_sel_hi:[1,0,1]
	v_cvt_scalef32_pk_f32_fp4 v[16:17], v89, 1.0
	v_pk_fma_f32 v[14:15], v[228:229], s[56:57], v[14:15] op_sel_hi:[1,0,1]
	v_cvt_scalef32_pk_f32_fp4 v[94:95], v28, 1.0 op_sel:[1,0,0]
	v_cvt_scalef32_pk_f32_fp4 v[96:97], v28, 1.0 op_sel:[0,1,0]
	v_cvt_scalef32_pk_f32_fp4 v[98:99], v28, 1.0 op_sel:[1,1,0]
	v_cvt_scalef32_pk_f32_fp4 v[102:103], v29, 1.0 op_sel:[1,0,0]
	v_cvt_scalef32_pk_f32_fp4 v[104:105], v29, 1.0 op_sel:[0,1,0]
	v_cvt_scalef32_pk_f32_fp4 v[28:29], v29, 1.0 op_sel:[1,1,0]
	v_pk_fma_f32 v[14:15], v[16:17], s[60:61], v[14:15] op_sel_hi:[1,0,1]
	v_pk_fma_f32 v[16:17], v[54:55], s[20:21], v[30:31] op_sel_hi:[1,0,1]
	v_pk_fma_f32 v[18:19], v[56:57], s[20:21], v[18:19] op_sel_hi:[1,0,1]
	v_pk_fma_f32 v[20:21], v[80:81], s[20:21], v[20:21] op_sel_hi:[1,0,1]
	v_pk_fma_f32 v[16:17], v[102:103], s[22:23], v[16:17] op_sel_hi:[1,0,1]
	v_pk_fma_f32 v[18:19], v[104:105], s[22:23], v[18:19] op_sel_hi:[1,0,1]
	v_pk_fma_f32 v[20:21], v[28:29], s[22:23], v[20:21] op_sel_hi:[1,0,1]
	v_cvt_scalef32_pk_f32_fp4 v[122:123], v34, 1.0 op_sel:[1,0,0]
	v_cvt_scalef32_pk_f32_fp4 v[124:125], v34, 1.0 op_sel:[0,1,0]
	v_cvt_scalef32_pk_f32_fp4 v[126:127], v34, 1.0 op_sel:[1,1,0]
	v_cvt_scalef32_pk_f32_fp4 v[130:131], v35, 1.0 op_sel:[1,0,0]
	v_cvt_scalef32_pk_f32_fp4 v[132:133], v35, 1.0 op_sel:[0,1,0]
	v_cvt_scalef32_pk_f32_fp4 v[34:35], v35, 1.0 op_sel:[1,1,0]
	v_pk_fma_f32 v[16:17], v[116:117], s[24:25], v[16:17] op_sel_hi:[1,0,1]
	v_pk_fma_f32 v[18:19], v[118:119], s[24:25], v[18:19] op_sel_hi:[1,0,1]
	v_pk_fma_f32 v[20:21], v[120:121], s[24:25], v[20:21] op_sel_hi:[1,0,1]
	v_cvt_scalef32_pk_f32_fp4 v[136:137], v26, 1.0 op_sel:[1,0,0]
	v_cvt_scalef32_pk_f32_fp4 v[138:139], v26, 1.0 op_sel:[0,1,0]
	v_cvt_scalef32_pk_f32_fp4 v[140:141], v26, 1.0 op_sel:[1,1,0]
	v_cvt_scalef32_pk_f32_fp4 v[144:145], v27, 1.0 op_sel:[1,0,0]
	v_cvt_scalef32_pk_f32_fp4 v[146:147], v27, 1.0 op_sel:[0,1,0]
	v_cvt_scalef32_pk_f32_fp4 v[26:27], v27, 1.0 op_sel:[1,1,0]
	v_pk_fma_f32 v[16:17], v[130:131], s[26:27], v[16:17] op_sel_hi:[1,0,1]
	v_pk_fma_f32 v[18:19], v[132:133], s[26:27], v[18:19] op_sel_hi:[1,0,1]
	v_pk_fma_f32 v[20:21], v[34:35], s[26:27], v[20:21] op_sel_hi:[1,0,1]
	v_cvt_scalef32_pk_f32_fp4 v[150:151], v36, 1.0 op_sel:[1,0,0]
	v_cvt_scalef32_pk_f32_fp4 v[152:153], v36, 1.0 op_sel:[0,1,0]
	v_cvt_scalef32_pk_f32_fp4 v[154:155], v36, 1.0 op_sel:[1,1,0]
	v_cvt_scalef32_pk_f32_fp4 v[158:159], v37, 1.0 op_sel:[1,0,0]
	v_cvt_scalef32_pk_f32_fp4 v[160:161], v37, 1.0 op_sel:[0,1,0]
	v_cvt_scalef32_pk_f32_fp4 v[36:37], v37, 1.0 op_sel:[1,1,0]
	v_pk_fma_f32 v[16:17], v[144:145], s[28:29], v[16:17] op_sel_hi:[1,0,1]
	v_pk_fma_f32 v[18:19], v[146:147], s[28:29], v[18:19] op_sel_hi:[1,0,1]
	v_pk_fma_f32 v[20:21], v[26:27], s[28:29], v[20:21] op_sel_hi:[1,0,1]
	v_cvt_scalef32_pk_f32_fp4 v[164:165], v52, 1.0 op_sel:[1,0,0]
	v_cvt_scalef32_pk_f32_fp4 v[166:167], v52, 1.0 op_sel:[0,1,0]
	v_cvt_scalef32_pk_f32_fp4 v[168:169], v52, 1.0 op_sel:[1,1,0]
	v_cvt_scalef32_pk_f32_fp4 v[172:173], v53, 1.0 op_sel:[1,0,0]
	v_cvt_scalef32_pk_f32_fp4 v[174:175], v53, 1.0 op_sel:[0,1,0]
	v_cvt_scalef32_pk_f32_fp4 v[52:53], v53, 1.0 op_sel:[1,1,0]
	v_pk_fma_f32 v[16:17], v[158:159], s[30:31], v[16:17] op_sel_hi:[1,0,1]
	v_pk_fma_f32 v[18:19], v[160:161], s[30:31], v[18:19] op_sel_hi:[1,0,1]
	v_pk_fma_f32 v[20:21], v[36:37], s[30:31], v[20:21] op_sel_hi:[1,0,1]
	v_cvt_scalef32_pk_f32_fp4 v[178:179], v82, 1.0 op_sel:[1,0,0]
	v_cvt_scalef32_pk_f32_fp4 v[180:181], v82, 1.0 op_sel:[0,1,0]
	v_cvt_scalef32_pk_f32_fp4 v[182:183], v82, 1.0 op_sel:[1,1,0]
	v_cvt_scalef32_pk_f32_fp4 v[186:187], v83, 1.0 op_sel:[1,0,0]
	v_cvt_scalef32_pk_f32_fp4 v[188:189], v83, 1.0 op_sel:[0,1,0]
	v_cvt_scalef32_pk_f32_fp4 v[82:83], v83, 1.0 op_sel:[1,1,0]
	v_pk_fma_f32 v[8:9], v[40:41], s[20:21], v[8:9] op_sel_hi:[1,0,1]
	v_pk_fma_f32 v[10:11], v[42:43], s[20:21], v[10:11] op_sel_hi:[1,0,1]
	v_pk_fma_f32 v[12:13], v[44:45], s[20:21], v[12:13] op_sel_hi:[1,0,1]
	v_pk_fma_f32 v[16:17], v[172:173], s[34:35], v[16:17] op_sel_hi:[1,0,1]
	v_pk_fma_f32 v[18:19], v[174:175], s[34:35], v[18:19] op_sel_hi:[1,0,1]
	v_pk_fma_f32 v[20:21], v[52:53], s[34:35], v[20:21] op_sel_hi:[1,0,1]
	v_cvt_scalef32_pk_f32_fp4 v[196:197], v84, 1.0 op_sel:[1,0,0]
	v_cvt_scalef32_pk_f32_fp4 v[198:199], v84, 1.0 op_sel:[0,1,0]
	v_cvt_scalef32_pk_f32_fp4 v[200:201], v84, 1.0 op_sel:[1,1,0]
	v_cvt_scalef32_pk_f32_fp4 v[204:205], v85, 1.0 op_sel:[1,0,0]
	v_cvt_scalef32_pk_f32_fp4 v[206:207], v85, 1.0 op_sel:[0,1,0]
	v_cvt_scalef32_pk_f32_fp4 v[84:85], v85, 1.0 op_sel:[1,1,0]
	v_pk_fma_f32 v[8:9], v[94:95], s[22:23], v[8:9] op_sel_hi:[1,0,1]
	v_pk_fma_f32 v[10:11], v[96:97], s[22:23], v[10:11] op_sel_hi:[1,0,1]
	v_pk_fma_f32 v[12:13], v[98:99], s[22:23], v[12:13] op_sel_hi:[1,0,1]
	v_pk_fma_f32 v[16:17], v[186:187], s[36:37], v[16:17] op_sel_hi:[1,0,1]
	v_pk_fma_f32 v[18:19], v[188:189], s[36:37], v[18:19] op_sel_hi:[1,0,1]
	v_pk_fma_f32 v[20:21], v[82:83], s[36:37], v[20:21] op_sel_hi:[1,0,1]
	v_cvt_scalef32_pk_f32_fp4 v[210:211], v86, 1.0 op_sel:[1,0,0]
	v_cvt_scalef32_pk_f32_fp4 v[214:215], v86, 1.0 op_sel:[0,1,0]
	v_cvt_scalef32_pk_f32_fp4 v[216:217], v86, 1.0 op_sel:[1,1,0]
	v_cvt_scalef32_pk_f32_fp4 v[230:231], v87, 1.0 op_sel:[1,0,0]
	v_cvt_scalef32_pk_f32_fp4 v[232:233], v87, 1.0 op_sel:[0,1,0]
	v_cvt_scalef32_pk_f32_fp4 v[86:87], v87, 1.0 op_sel:[1,1,0]
	v_pk_fma_f32 v[8:9], v[108:109], s[24:25], v[8:9] op_sel_hi:[1,0,1]
	v_pk_fma_f32 v[10:11], v[110:111], s[24:25], v[10:11] op_sel_hi:[1,0,1]
	v_pk_fma_f32 v[12:13], v[112:113], s[24:25], v[12:13] op_sel_hi:[1,0,1]
	v_pk_fma_f32 v[16:17], v[204:205], s[38:39], v[16:17] op_sel_hi:[1,0,1]
	v_pk_fma_f32 v[18:19], v[206:207], s[38:39], v[18:19] op_sel_hi:[1,0,1]
	v_pk_fma_f32 v[20:21], v[84:85], s[38:39], v[20:21] op_sel_hi:[1,0,1]
	v_readlane_b32 s25, v46, 0
	v_cvt_scalef32_pk_f32_fp4 v[38:39], v89, 1.0 op_sel:[1,0,0]
	v_cvt_scalef32_pk_f32_fp4 v[40:41], v89, 1.0 op_sel:[0,1,0]
	v_cvt_scalef32_pk_f32_fp4 v[42:43], v89, 1.0 op_sel:[1,1,0]
	v_pk_fma_f32 v[16:17], v[230:231], s[56:57], v[16:17] op_sel_hi:[1,0,1]
	v_pk_fma_f32 v[18:19], v[232:233], s[56:57], v[18:19] op_sel_hi:[1,0,1]
	v_pk_fma_f32 v[20:21], v[86:87], s[56:57], v[20:21] op_sel_hi:[1,0,1]
	v_pk_fma_f32 v[16:17], v[38:39], s[60:61], v[16:17] op_sel_hi:[1,0,1]
	v_pk_fma_f32 v[18:19], v[40:41], s[60:61], v[18:19] op_sel_hi:[1,0,1]
	v_pk_fma_f32 v[20:21], v[42:43], s[60:61], v[20:21] op_sel_hi:[1,0,1]
	s_waitcnt vmcnt(5)
	v_cvt_scalef32_pk_f32_fp4 v[34:35], v90, 1.0
	v_cvt_scalef32_pk_f32_fp4 v[36:37], v90, 1.0 op_sel:[1,0,0]
	v_cvt_scalef32_pk_f32_fp4 v[38:39], v90, 1.0 op_sel:[0,1,0]
	v_cvt_scalef32_pk_f32_fp4 v[40:41], v90, 1.0 op_sel:[1,1,0]
	v_cvt_scalef32_pk_f32_fp4 v[42:43], v91, 1.0
	v_cvt_scalef32_pk_f32_fp4 v[44:45], v91, 1.0 op_sel:[1,0,0]
	v_cvt_scalef32_pk_f32_fp4 v[30:31], v91, 1.0 op_sel:[0,1,0]
	v_cvt_scalef32_pk_f32_fp4 v[26:27], v91, 1.0 op_sel:[1,1,0]
	buffer_load_dwordx2 v[90:91], v192, s[4:7], s25 offen
	v_readlane_b32 s25, v46, 1
	v_pk_fma_f32 v[10:11], v[124:125], s[26:27], v[10:11] op_sel_hi:[1,0,1]
	v_pk_fma_f32 v[8:9], v[122:123], s[26:27], v[8:9] op_sel_hi:[1,0,1]
	v_pk_fma_f32 v[12:13], v[126:127], s[26:27], v[12:13] op_sel_hi:[1,0,1]
	v_pk_fma_f32 v[8:9], v[136:137], s[28:29], v[8:9] op_sel_hi:[1,0,1]
	s_nop 0
	buffer_load_dwordx2 v[96:97], v192, s[4:7], s25 offen
	v_readlane_b32 s25, v46, 2
	v_pk_fma_f32 v[10:11], v[138:139], s[28:29], v[10:11] op_sel_hi:[1,0,1]
	v_pk_fma_f32 v[12:13], v[140:141], s[28:29], v[12:13] op_sel_hi:[1,0,1]
	v_readlane_b32 s27, v46, 6
	v_readlane_b32 s29, v46, 7
	s_nop 0
	buffer_load_dwordx2 v[114:115], v192, s[4:7], s25 offen
	v_readlane_b32 s25, v46, 3
	v_pk_fma_f32 v[10:11], v[152:153], s[30:31], v[10:11] op_sel_hi:[1,0,1]
	v_pk_fma_f32 v[12:13], v[154:155], s[30:31], v[12:13] op_sel_hi:[1,0,1]
	s_nop 2
	buffer_load_dwordx2 v[124:125], v192, s[4:7], s25 offen
	v_readlane_b32 s25, v46, 4
	v_pk_fma_f32 v[8:9], v[150:151], s[30:31], v[8:9] op_sel_hi:[1,0,1]
	v_readlane_b32 s31, v46, 11
	v_pk_fma_f32 v[8:9], v[164:165], s[34:35], v[8:9] op_sel_hi:[1,0,1]
	v_pk_fma_f32 v[10:11], v[166:167], s[34:35], v[10:11] op_sel_hi:[1,0,1]
	s_nop 0
	buffer_load_dwordx2 v[136:137], v192, s[4:7], s25 offen
	v_readlane_b32 s25, v46, 5
	s_nop 3
	s_nop 0
	buffer_load_dwordx2 v[152:153], v192, s[4:7], s25 offen
	buffer_load_dwordx2 v[154:155], v192, s[4:7], s27 offen
	buffer_load_dwordx2 v[158:159], v192, s[4:7], s29 offen
	v_readlane_b32 s25, v46, 8
	v_readlane_b32 s27, v46, 9
	v_readlane_b32 s29, v46, 10
	s_nop 2
	buffer_load_dwordx2 v[160:161], v192, s[4:7], s25 offen
	s_nop 2
	buffer_load_dwordx2 v[162:163], v192, s[4:7], s27 offen
	s_nop 2
	buffer_load_dwordx2 v[164:165], v192, s[4:7], s29 offen
	buffer_load_dwordx2 v[166:167], v192, s[4:7], s31 offen
	v_readlane_b32 s25, v46, 12
	v_readlane_b32 s27, v46, 13
	v_readlane_b32 s29, v46, 14
	v_readlane_b32 s31, v46, 15
	v_readlane_b32 s20, v3, 10
	v_readlane_b32 s22, v3, 11
	v_readlane_b32 s24, v3, 12
	v_readlane_b32 s26, v3, 13
	v_readlane_b32 s28, v3, 14
	s_waitcnt vmcnt(13)
	v_cvt_scalef32_pk_f32_fp4 v[116:117], v6, 1.0
	v_cvt_scalef32_pk_f32_fp4 v[120:121], v6, 1.0 op_sel:[1,0,0]
	v_cvt_scalef32_pk_f32_fp4 v[122:123], v6, 1.0 op_sel:[0,1,0]
	v_cvt_scalef32_pk_f32_fp4 v[126:127], v6, 1.0 op_sel:[1,1,0]
	v_cvt_scalef32_pk_f32_fp4 v[128:129], v7, 1.0
	v_cvt_scalef32_pk_f32_fp4 v[130:131], v7, 1.0 op_sel:[1,0,0]
	v_cvt_scalef32_pk_f32_fp4 v[132:133], v7, 1.0 op_sel:[0,1,0]
	v_cvt_scalef32_pk_f32_fp4 v[134:135], v7, 1.0 op_sel:[1,1,0]
	v_readlane_b32 s30, v3, 15
	ds_read2_b32 v[2:3], v47 offset0:96 offset1:112
	buffer_load_dwordx2 v[46:47], v192, s[4:7], s25 offen
	buffer_load_dwordx2 v[170:171], v192, s[4:7], s27 offen
	buffer_load_dwordx2 v[172:173], v192, s[4:7], s29 offen
	buffer_load_dwordx2 v[6:7], v192, s[4:7], s31 offen
	v_pk_fma_f32 v[8:9], v[178:179], s[36:37], v[8:9] op_sel_hi:[1,0,1]
	v_cvt_scalef32_pk_f32_fp4 v[236:237], v88, 1.0 op_sel:[1,0,0]
	v_pk_fma_f32 v[8:9], v[196:197], s[38:39], v[8:9] op_sel_hi:[1,0,1]
	v_cvt_scalef32_pk_f32_fp4 v[50:51], v92, 1.0 op_sel:[1,0,0]
	v_pk_fma_f32 v[8:9], v[210:211], s[56:57], v[8:9] op_sel_hi:[1,0,1]
	v_cvt_scalef32_pk_f32_fp4 v[56:57], v93, 1.0
	v_pk_fma_f32 v[8:9], v[236:237], s[60:61], v[8:9] op_sel_hi:[1,0,1]
	v_cvt_scalef32_pk_f32_fp4 v[86:87], v32, 1.0 op_sel:[1,0,0]
	v_pk_fma_f32 v[8:9], v[36:37], s[20:21], v[8:9] op_sel_hi:[1,0,1]
	v_pk_fma_f32 v[14:15], v[42:43], s[20:21], v[14:15] op_sel_hi:[1,0,1]
	v_pk_fma_f32 v[8:9], v[50:51], s[22:23], v[8:9] op_sel_hi:[1,0,1]
	v_cvt_scalef32_pk_f32_fp4 v[94:95], v33, 1.0
	v_cvt_scalef32_pk_f32_fp4 v[104:105], v22, 1.0 op_sel:[1,0,0]
	v_pk_fma_f32 v[8:9], v[86:87], s[24:25], v[8:9] op_sel_hi:[1,0,1]
	v_pk_fma_f32 v[14:15], v[56:57], s[22:23], v[14:15] op_sel_hi:[1,0,1]
	v_cvt_scalef32_pk_f32_fp4 v[48:49], v92, 1.0
	v_cvt_scalef32_pk_f32_fp4 v[110:111], v23, 1.0
	v_pk_fma_f32 v[24:25], v[34:35], s[20:21], v[24:25] op_sel_hi:[1,0,1]
	v_pk_fma_f32 v[8:9], v[104:105], s[26:27], v[8:9] op_sel_hi:[1,0,1]
	v_pk_fma_f32 v[14:15], v[94:95], s[24:25], v[14:15] op_sel_hi:[1,0,1]
	v_cvt_scalef32_pk_f32_fp4 v[84:85], v32, 1.0
	s_waitcnt vmcnt(16)
	v_cvt_scalef32_pk_f32_fp4 v[140:141], v4, 1.0 op_sel:[1,0,0]
	v_pk_fma_f32 v[24:25], v[48:49], s[22:23], v[24:25] op_sel_hi:[1,0,1]
	v_pk_fma_f32 v[8:9], v[120:121], s[28:29], v[8:9] op_sel_hi:[1,0,1]
	v_pk_fma_f32 v[14:15], v[110:111], s[26:27], v[14:15] op_sel_hi:[1,0,1]
	v_pk_fma_f32 v[12:13], v[168:169], s[34:35], v[12:13] op_sel_hi:[1,0,1]
	v_cvt_scalef32_pk_f32_fp4 v[102:103], v22, 1.0
	v_cvt_scalef32_pk_f32_fp4 v[146:147], v5, 1.0
	s_waitcnt lgkmcnt(0)
	v_readlane_b32 s34, v2, 0
	s_waitcnt vmcnt(15)
	v_cvt_scalef32_pk_f32_fp4 v[168:169], v90, 1.0 op_sel:[1,0,0]
	v_pk_fma_f32 v[24:25], v[84:85], s[24:25], v[24:25] op_sel_hi:[1,0,1]
	v_pk_fma_f32 v[8:9], v[140:141], s[30:31], v[8:9] op_sel_hi:[1,0,1]
	v_pk_fma_f32 v[14:15], v[128:129], s[28:29], v[14:15] op_sel_hi:[1,0,1]
	v_pk_fma_f32 v[10:11], v[180:181], s[36:37], v[10:11] op_sel_hi:[1,0,1]
	v_pk_fma_f32 v[12:13], v[182:183], s[36:37], v[12:13] op_sel_hi:[1,0,1]
	v_cvt_scalef32_pk_f32_fp4 v[178:179], v91, 1.0
	v_readlane_b32 s36, v2, 1
	s_waitcnt vmcnt(14)
	v_cvt_scalef32_pk_f32_fp4 v[186:187], v96, 1.0 op_sel:[1,0,0]
	v_pk_fma_f32 v[24:25], v[102:103], s[26:27], v[24:25] op_sel_hi:[1,0,1]
	v_pk_fma_f32 v[8:9], v[168:169], s[34:35], v[8:9] op_sel_hi:[1,0,1]
	v_pk_fma_f32 v[14:15], v[146:147], s[30:31], v[14:15] op_sel_hi:[1,0,1]
	v_pk_fma_f32 v[10:11], v[198:199], s[38:39], v[10:11] op_sel_hi:[1,0,1]
	v_pk_fma_f32 v[12:13], v[200:201], s[38:39], v[12:13] op_sel_hi:[1,0,1]
	v_cvt_scalef32_pk_f32_fp4 v[138:139], v4, 1.0
	v_cvt_scalef32_pk_f32_fp4 v[196:197], v97, 1.0
	v_readlane_b32 s38, v2, 2
	s_waitcnt vmcnt(13)
	v_cvt_scalef32_pk_f32_fp4 v[204:205], v114, 1.0 op_sel:[1,0,0]
	v_pk_fma_f32 v[24:25], v[116:117], s[28:29], v[24:25] op_sel_hi:[1,0,1]
	v_pk_fma_f32 v[8:9], v[186:187], s[36:37], v[8:9] op_sel_hi:[1,0,1]
	v_pk_fma_f32 v[14:15], v[178:179], s[34:35], v[14:15] op_sel_hi:[1,0,1]
	v_cvt_scalef32_pk_f32_fp4 v[238:239], v88, 1.0 op_sel:[0,1,0]
	v_cvt_scalef32_pk_f32_fp4 v[240:241], v88, 1.0 op_sel:[1,1,0]
	v_pk_fma_f32 v[10:11], v[214:215], s[56:57], v[10:11] op_sel_hi:[1,0,1]
	v_pk_fma_f32 v[12:13], v[216:217], s[56:57], v[12:13] op_sel_hi:[1,0,1]
	v_cvt_scalef32_pk_f32_fp4 v[156:157], v90, 1.0
	v_cvt_scalef32_pk_f32_fp4 v[210:211], v115, 1.0
	v_readlane_b32 s56, v2, 3
	s_waitcnt vmcnt(12)
	v_cvt_scalef32_pk_f32_fp4 v[230:231], v124, 1.0 op_sel:[1,0,0]
	v_pk_fma_f32 v[24:25], v[138:139], s[30:31], v[24:25] op_sel_hi:[1,0,1]
	v_pk_fma_f32 v[8:9], v[204:205], s[38:39], v[8:9] op_sel_hi:[1,0,1]
	v_pk_fma_f32 v[14:15], v[196:197], s[36:37], v[14:15] op_sel_hi:[1,0,1]
	v_pk_fma_f32 v[10:11], v[238:239], s[60:61], v[10:11] op_sel_hi:[1,0,1]
	v_pk_fma_f32 v[12:13], v[240:241], s[60:61], v[12:13] op_sel_hi:[1,0,1]
	v_cvt_scalef32_pk_f32_fp4 v[184:185], v96, 1.0
	v_cvt_scalef32_pk_f32_fp4 v[236:237], v125, 1.0
	v_readlane_b32 s60, v2, 4
	s_waitcnt vmcnt(11)
	v_cvt_scalef32_pk_f32_fp4 v[244:245], v136, 1.0 op_sel:[1,0,0]
	v_pk_fma_f32 v[24:25], v[156:157], s[34:35], v[24:25] op_sel_hi:[1,0,1]
	v_pk_fma_f32 v[8:9], v[230:231], s[56:57], v[8:9] op_sel_hi:[1,0,1]
	v_pk_fma_f32 v[14:15], v[210:211], s[38:39], v[14:15] op_sel_hi:[1,0,1]
	v_cvt_scalef32_pk_f32_fp4 v[52:53], v92, 1.0 op_sel:[0,1,0]
	v_cvt_scalef32_pk_f32_fp4 v[188:189], v96, 1.0 op_sel:[0,1,0]
	v_cvt_scalef32_pk_f32_fp4 v[190:191], v96, 1.0 op_sel:[1,1,0]
	v_cvt_scalef32_pk_f32_fp4 v[198:199], v97, 1.0 op_sel:[1,0,0]
	v_cvt_scalef32_pk_f32_fp4 v[200:201], v97, 1.0 op_sel:[0,1,0]
	v_cvt_scalef32_pk_f32_fp4 v[202:203], v97, 1.0 op_sel:[1,1,0]
	v_cvt_scalef32_pk_f32_fp4 v[96:97], v114, 1.0
	v_pk_fma_f32 v[24:25], v[184:185], s[36:37], v[24:25] op_sel_hi:[1,0,1]
	v_pk_fma_f32 v[120:121], v[244:245], s[60:61], v[8:9] op_sel_hi:[1,0,1]
	v_pk_fma_f32 v[8:9], v[38:39], s[20:21], v[10:11] op_sel_hi:[1,0,1]
	v_cvt_scalef32_pk_f32_fp4 v[10:11], v137, 1.0
	v_pk_fma_f32 v[14:15], v[236:237], s[56:57], v[14:15] op_sel_hi:[1,0,1]
	v_cvt_scalef32_pk_f32_fp4 v[80:81], v93, 1.0 op_sel:[1,0,0]
	v_cvt_scalef32_pk_f32_fp4 v[88:89], v32, 1.0 op_sel:[0,1,0]
	v_pk_fma_f32 v[24:25], v[96:97], s[38:39], v[24:25] op_sel_hi:[1,0,1]
	v_pk_fma_f32 v[8:9], v[52:53], s[22:23], v[8:9] op_sel_hi:[1,0,1]
	v_pk_fma_f32 v[96:97], v[10:11], s[60:61], v[14:15] op_sel_hi:[1,0,1]
	v_pk_fma_f32 v[10:11], v[44:45], s[20:21], v[16:17] op_sel_hi:[1,0,1]
	v_cvt_scalef32_pk_f32_fp4 v[98:99], v33, 1.0 op_sel:[1,0,0]
	v_cvt_scalef32_pk_f32_fp4 v[106:107], v22, 1.0 op_sel:[0,1,0]
	v_pk_fma_f32 v[8:9], v[88:89], s[24:25], v[8:9] op_sel_hi:[1,0,1]
	v_pk_fma_f32 v[10:11], v[80:81], s[22:23], v[10:11] op_sel_hi:[1,0,1]
	v_cvt_scalef32_pk_f32_fp4 v[112:113], v23, 1.0 op_sel:[1,0,0]
	v_pk_fma_f32 v[8:9], v[106:107], s[26:27], v[8:9] op_sel_hi:[1,0,1]
	v_pk_fma_f32 v[10:11], v[98:99], s[24:25], v[10:11] op_sel_hi:[1,0,1]
	v_cvt_scalef32_pk_f32_fp4 v[28:29], v93, 1.0 op_sel:[1,1,0]
	v_cvt_scalef32_pk_f32_fp4 v[142:143], v4, 1.0 op_sel:[0,1,0]
	v_pk_fma_f32 v[8:9], v[122:123], s[28:29], v[8:9] op_sel_hi:[1,0,1]
	v_pk_fma_f32 v[10:11], v[112:113], s[26:27], v[10:11] op_sel_hi:[1,0,1]
	v_pk_fma_f32 v[14:15], v[26:27], s[20:21], v[20:21] op_sel_hi:[1,0,1]
	v_cvt_scalef32_pk_f32_fp4 v[54:55], v92, 1.0 op_sel:[1,1,0]
	v_cvt_scalef32_pk_f32_fp4 v[82:83], v93, 1.0 op_sel:[0,1,0]
	v_cvt_scalef32_pk_f32_fp4 v[92:93], v32, 1.0 op_sel:[1,1,0]
	v_cvt_scalef32_pk_f32_fp4 v[100:101], v33, 1.0 op_sel:[0,1,0]
	v_cvt_scalef32_pk_f32_fp4 v[32:33], v33, 1.0 op_sel:[1,1,0]
	v_cvt_scalef32_pk_f32_fp4 v[148:149], v5, 1.0 op_sel:[1,0,0]
	v_cvt_scalef32_pk_f32_fp4 v[174:175], v90, 1.0 op_sel:[0,1,0]
	v_pk_fma_f32 v[8:9], v[142:143], s[30:31], v[8:9] op_sel_hi:[1,0,1]
	v_pk_fma_f32 v[10:11], v[130:131], s[28:29], v[10:11] op_sel_hi:[1,0,1]
	v_pk_fma_f32 v[14:15], v[28:29], s[22:23], v[14:15] op_sel_hi:[1,0,1]
	v_cvt_scalef32_pk_f32_fp4 v[108:109], v22, 1.0 op_sel:[1,1,0]
	v_cvt_scalef32_pk_f32_fp4 v[118:119], v23, 1.0 op_sel:[0,1,0]
	v_cvt_scalef32_pk_f32_fp4 v[22:23], v23, 1.0 op_sel:[1,1,0]
	v_cvt_scalef32_pk_f32_fp4 v[180:181], v91, 1.0 op_sel:[1,0,0]
	v_pk_fma_f32 v[8:9], v[174:175], s[34:35], v[8:9] op_sel_hi:[1,0,1]
	v_pk_fma_f32 v[10:11], v[148:149], s[30:31], v[10:11] op_sel_hi:[1,0,1]
	v_pk_fma_f32 v[14:15], v[32:33], s[24:25], v[14:15] op_sel_hi:[1,0,1]
	v_cvt_scalef32_pk_f32_fp4 v[206:207], v114, 1.0 op_sel:[0,1,0]
	v_pk_fma_f32 v[8:9], v[188:189], s[36:37], v[8:9] op_sel_hi:[1,0,1]
	v_pk_fma_f32 v[10:11], v[180:181], s[34:35], v[10:11] op_sel_hi:[1,0,1]
	v_pk_fma_f32 v[14:15], v[22:23], s[26:27], v[14:15] op_sel_hi:[1,0,1]
	v_cvt_scalef32_pk_f32_fp4 v[144:145], v4, 1.0 op_sel:[1,1,0]
	v_cvt_scalef32_pk_f32_fp4 v[150:151], v5, 1.0 op_sel:[0,1,0]
	v_cvt_scalef32_pk_f32_fp4 v[4:5], v5, 1.0 op_sel:[1,1,0]
	v_cvt_scalef32_pk_f32_fp4 v[214:215], v115, 1.0 op_sel:[1,0,0]
	v_cvt_scalef32_pk_f32_fp4 v[232:233], v124, 1.0 op_sel:[0,1,0]
	v_pk_fma_f32 v[8:9], v[206:207], s[38:39], v[8:9] op_sel_hi:[1,0,1]
	v_pk_fma_f32 v[10:11], v[198:199], s[36:37], v[10:11] op_sel_hi:[1,0,1]
	v_pk_fma_f32 v[14:15], v[134:135], s[28:29], v[14:15] op_sel_hi:[1,0,1]
	v_cvt_scalef32_pk_f32_fp4 v[176:177], v90, 1.0 op_sel:[1,1,0]
	v_cvt_scalef32_pk_f32_fp4 v[182:183], v91, 1.0 op_sel:[0,1,0]
	v_cvt_scalef32_pk_f32_fp4 v[90:91], v91, 1.0 op_sel:[1,1,0]
	v_cvt_scalef32_pk_f32_fp4 v[228:229], v124, 1.0
	v_cvt_scalef32_pk_f32_fp4 v[238:239], v125, 1.0 op_sel:[1,0,0]
	v_cvt_scalef32_pk_f32_fp4 v[246:247], v136, 1.0 op_sel:[0,1,0]
	v_pk_fma_f32 v[8:9], v[232:233], s[56:57], v[8:9] op_sel_hi:[1,0,1]
	v_pk_fma_f32 v[10:11], v[214:215], s[38:39], v[10:11] op_sel_hi:[1,0,1]
	v_pk_fma_f32 v[4:5], v[4:5], s[30:31], v[14:15] op_sel_hi:[1,0,1]
	v_cvt_scalef32_pk_f32_fp4 v[242:243], v136, 1.0
	v_pk_fma_f32 v[24:25], v[228:229], s[56:57], v[24:25] op_sel_hi:[1,0,1]
	v_pk_fma_f32 v[116:117], v[246:247], s[60:61], v[8:9] op_sel_hi:[1,0,1]
	v_pk_fma_f32 v[8:9], v[40:41], s[20:21], v[12:13] op_sel_hi:[1,0,1]
	v_cvt_scalef32_pk_f32_fp4 v[12:13], v137, 1.0 op_sel:[1,0,0]
	v_pk_fma_f32 v[10:11], v[238:239], s[56:57], v[10:11] op_sel_hi:[1,0,1]
	v_pk_fma_f32 v[4:5], v[90:91], s[34:35], v[4:5] op_sel_hi:[1,0,1]
	v_cvt_scalef32_pk_f32_fp4 v[208:209], v114, 1.0 op_sel:[1,1,0]
	v_cvt_scalef32_pk_f32_fp4 v[216:217], v115, 1.0 op_sel:[0,1,0]
	v_cvt_scalef32_pk_f32_fp4 v[114:115], v115, 1.0 op_sel:[1,1,0]
	v_pk_fma_f32 v[138:139], v[242:243], s[60:61], v[24:25] op_sel_hi:[1,0,1]
	v_pk_fma_f32 v[8:9], v[54:55], s[22:23], v[8:9] op_sel_hi:[1,0,1]
	v_pk_fma_f32 v[10:11], v[12:13], s[60:61], v[10:11] op_sel_hi:[1,0,1]
	v_pk_fma_f32 v[12:13], v[30:31], s[20:21], v[18:19] op_sel_hi:[1,0,1]
	v_pk_fma_f32 v[4:5], v[202:203], s[36:37], v[4:5] op_sel_hi:[1,0,1]
	v_readlane_b32 s20, v2, 5
	s_waitcnt vmcnt(10)
	v_cvt_scalef32_pk_f32_fp4 v[110:111], v152, 1.0
	v_pk_fma_f32 v[8:9], v[92:93], s[24:25], v[8:9] op_sel_hi:[1,0,1]
	v_pk_fma_f32 v[12:13], v[82:83], s[22:23], v[12:13] op_sel_hi:[1,0,1]
	v_pk_fma_f32 v[4:5], v[114:115], s[38:39], v[4:5] op_sel_hi:[1,0,1]
	v_readlane_b32 s22, v2, 6
	s_waitcnt vmcnt(9)
	v_cvt_scalef32_pk_f32_fp4 v[114:115], v154, 1.0
	v_pk_fma_f32 v[110:111], v[110:111], s[20:21], v[138:139] op_sel_hi:[1,0,1]
	v_pk_fma_f32 v[8:9], v[108:109], s[26:27], v[8:9] op_sel_hi:[1,0,1]
	v_pk_fma_f32 v[12:13], v[100:101], s[24:25], v[12:13] op_sel_hi:[1,0,1]
	v_readlane_b32 s24, v2, 7
	s_waitcnt vmcnt(8)
	v_cvt_scalef32_pk_f32_fp4 v[122:123], v158, 1.0
	v_pk_fma_f32 v[110:111], v[114:115], s[22:23], v[110:111] op_sel_hi:[1,0,1]
	v_pk_fma_f32 v[8:9], v[126:127], s[28:29], v[8:9] op_sel_hi:[1,0,1]
	v_pk_fma_f32 v[12:13], v[118:119], s[26:27], v[12:13] op_sel_hi:[1,0,1]
	v_readlane_b32 s26, v2, 8
	s_waitcnt vmcnt(7)
	v_cvt_scalef32_pk_f32_fp4 v[126:127], v160, 1.0
	v_pk_fma_f32 v[110:111], v[122:123], s[24:25], v[110:111] op_sel_hi:[1,0,1]
	v_pk_fma_f32 v[12:13], v[132:133], s[28:29], v[12:13] op_sel_hi:[1,0,1]
	v_readlane_b32 s28, v2, 9
	s_waitcnt vmcnt(6)
	v_cvt_scalef32_pk_f32_fp4 v[132:133], v162, 1.0
	v_pk_fma_f32 v[110:111], v[126:127], s[26:27], v[110:111] op_sel_hi:[1,0,1]
	v_cvt_scalef32_pk_f32_fp4 v[248:249], v136, 1.0 op_sel:[1,1,0]
	v_pk_fma_f32 v[8:9], v[144:145], s[30:31], v[8:9] op_sel_hi:[1,0,1]
	v_cvt_scalef32_pk_f32_fp4 v[24:25], v137, 1.0 op_sel:[0,1,0]
	v_cvt_scalef32_pk_f32_fp4 v[34:35], v137, 1.0 op_sel:[1,1,0]
	v_pk_fma_f32 v[12:13], v[150:151], s[30:31], v[12:13] op_sel_hi:[1,0,1]
	v_readlane_b32 s30, v2, 10
	s_waitcnt vmcnt(5)
	v_cvt_scalef32_pk_f32_fp4 v[136:137], v164, 1.0
	v_pk_fma_f32 v[110:111], v[132:133], s[28:29], v[110:111] op_sel_hi:[1,0,1]
	v_pk_fma_f32 v[8:9], v[176:177], s[34:35], v[8:9] op_sel_hi:[1,0,1]
	v_pk_fma_f32 v[12:13], v[182:183], s[34:35], v[12:13] op_sel_hi:[1,0,1]
	v_readlane_b32 s34, v2, 11
	s_waitcnt vmcnt(4)
	v_cvt_scalef32_pk_f32_fp4 v[180:181], v166, 1.0
	v_pk_fma_f32 v[110:111], v[136:137], s[30:31], v[110:111] op_sel_hi:[1,0,1]
	v_pk_fma_f32 v[8:9], v[190:191], s[36:37], v[8:9] op_sel_hi:[1,0,1]
	v_pk_fma_f32 v[12:13], v[200:201], s[36:37], v[12:13] op_sel_hi:[1,0,1]
	v_readlane_b32 s36, v2, 12
	s_waitcnt vmcnt(3)
	v_cvt_scalef32_pk_f32_fp4 v[200:201], v46, 1.0
	v_pk_fma_f32 v[110:111], v[180:181], s[34:35], v[110:111] op_sel_hi:[1,0,1]
	v_cvt_scalef32_pk_f32_fp4 v[234:235], v124, 1.0 op_sel:[1,1,0]
	v_cvt_scalef32_pk_f32_fp4 v[240:241], v125, 1.0 op_sel:[0,1,0]
	v_cvt_scalef32_pk_f32_fp4 v[124:125], v125, 1.0 op_sel:[1,1,0]
	v_pk_fma_f32 v[8:9], v[208:209], s[38:39], v[8:9] op_sel_hi:[1,0,1]
	v_pk_fma_f32 v[12:13], v[216:217], s[38:39], v[12:13] op_sel_hi:[1,0,1]
	v_readlane_b32 s38, v2, 13
	s_waitcnt vmcnt(2)
	v_cvt_scalef32_pk_f32_fp4 v[204:205], v170, 1.0
	v_pk_fma_f32 v[110:111], v[200:201], s[36:37], v[110:111] op_sel_hi:[1,0,1]
	v_pk_fma_f32 v[8:9], v[234:235], s[56:57], v[8:9] op_sel_hi:[1,0,1]
	v_pk_fma_f32 v[12:13], v[240:241], s[56:57], v[12:13] op_sel_hi:[1,0,1]
	v_pk_fma_f32 v[4:5], v[124:125], s[56:57], v[4:5] op_sel_hi:[1,0,1]
	v_readlane_b32 s56, v2, 14
	s_waitcnt vmcnt(1)
	v_cvt_scalef32_pk_f32_fp4 v[208:209], v172, 1.0
	v_pk_fma_f32 v[110:111], v[204:205], s[38:39], v[110:111] op_sel_hi:[1,0,1]
	v_pk_fma_f32 v[8:9], v[248:249], s[60:61], v[8:9] op_sel_hi:[1,0,1]
	v_pk_fma_f32 v[12:13], v[24:25], s[60:61], v[12:13] op_sel_hi:[1,0,1]
	v_pk_fma_f32 v[14:15], v[34:35], s[60:61], v[4:5] op_sel_hi:[1,0,1]
	v_cvt_scalef32_pk_f32_fp4 v[112:113], v152, 1.0 op_sel:[1,0,0]
	v_readlane_b32 s60, v2, 15
	s_waitcnt vmcnt(0)
	v_cvt_scalef32_pk_f32_fp4 v[214:215], v6, 1.0
	v_pk_fma_f32 v[110:111], v[208:209], s[56:57], v[110:111] op_sel_hi:[1,0,1]
	v_cvt_scalef32_pk_f32_fp4 v[118:119], v154, 1.0 op_sel:[1,0,0]
	v_pk_fma_f32 v[180:181], v[214:215], s[60:61], v[110:111] op_sel_hi:[1,0,1]
	v_pk_fma_f32 v[110:111], v[112:113], s[20:21], v[120:121] op_sel_hi:[1,0,1]
	v_cvt_scalef32_pk_f32_fp4 v[124:125], v158, 1.0 op_sel:[1,0,0]
	v_pk_fma_f32 v[110:111], v[118:119], s[22:23], v[110:111] op_sel_hi:[1,0,1]
	v_cvt_scalef32_pk_f32_fp4 v[130:131], v160, 1.0 op_sel:[1,0,0]
	v_pk_fma_f32 v[110:111], v[124:125], s[24:25], v[110:111] op_sel_hi:[1,0,1]
	v_readlane_b32 s25, v0, 0
	v_pk_fma_f32 v[138:139], v[130:131], s[26:27], v[110:111] op_sel_hi:[1,0,1]
	v_cvt_scalef32_pk_f32_fp4 v[134:135], v152, 1.0 op_sel:[0,1,0]
	v_cvt_scalef32_pk_f32_fp4 v[140:141], v154, 1.0 op_sel:[0,1,0]
	v_cvt_scalef32_pk_f32_fp4 v[184:185], v162, 1.0 op_sel:[1,0,0]
	s_nop 0
	buffer_load_dwordx2 v[110:111], v192, s[4:7], s25 offen
	v_readlane_b32 s25, v0, 1
	v_pk_fma_f32 v[116:117], v[134:135], s[20:21], v[116:117] op_sel_hi:[1,0,1]
	v_cvt_scalef32_pk_f32_fp4 v[142:143], v158, 1.0 op_sel:[0,1,0]
	v_cvt_scalef32_pk_f32_fp4 v[190:191], v164, 1.0 op_sel:[1,0,0]
	v_pk_fma_f32 v[138:139], v[184:185], s[28:29], v[138:139] op_sel_hi:[1,0,1]
	s_nop 0
	buffer_load_dwordx2 v[112:113], v192, s[4:7], s25 offen
	v_readlane_b32 s25, v0, 2
	v_pk_fma_f32 v[116:117], v[140:141], s[22:23], v[116:117] op_sel_hi:[1,0,1]
	v_cvt_scalef32_pk_f32_fp4 v[186:187], v160, 1.0 op_sel:[0,1,0]
	v_cvt_scalef32_pk_f32_fp4 v[198:199], v166, 1.0 op_sel:[1,0,0]
	v_pk_fma_f32 v[138:139], v[190:191], s[30:31], v[138:139] op_sel_hi:[1,0,1]
	s_nop 0
	buffer_load_dwordx2 v[114:115], v192, s[4:7], s25 offen
	v_readlane_b32 s25, v0, 3
	v_cvt_scalef32_pk_f32_fp4 v[188:189], v162, 1.0 op_sel:[0,1,0]
	v_cvt_scalef32_pk_f32_fp4 v[202:203], v46, 1.0 op_sel:[1,0,0]
	v_pk_fma_f32 v[138:139], v[198:199], s[34:35], v[138:139] op_sel_hi:[1,0,1]
	v_cvt_scalef32_pk_f32_fp4 v[196:197], v164, 1.0 op_sel:[0,1,0]
	s_nop 0
	buffer_load_dwordx2 v[118:119], v192, s[4:7], s25 offen
	v_readlane_b32 s25, v0, 4
	v_cvt_scalef32_pk_f32_fp4 v[206:207], v170, 1.0 op_sel:[1,0,0]
	v_pk_fma_f32 v[138:139], v[202:203], s[36:37], v[138:139] op_sel_hi:[1,0,1]
	v_cvt_scalef32_pk_f32_fp4 v[210:211], v172, 1.0 op_sel:[1,0,0]
	v_pk_fma_f32 v[138:139], v[206:207], s[38:39], v[138:139] op_sel_hi:[1,0,1]
	s_nop 0
	buffer_load_dwordx2 v[120:121], v192, s[4:7], s25 offen
	v_readlane_b32 s25, v0, 5
	v_cvt_scalef32_pk_f32_fp4 v[216:217], v6, 1.0 op_sel:[1,0,0]
	v_pk_fma_f32 v[138:139], v[210:211], s[56:57], v[138:139] op_sel_hi:[1,0,1]
	v_lshlrev_b64 v[204:205], 12, v[78:79]
	v_pk_fma_f32 v[184:185], v[216:217], s[60:61], v[138:139] op_sel_hi:[1,0,1]
	s_nop 0
	buffer_load_dwordx2 v[122:123], v192, s[4:7], s25 offen
	v_readlane_b32 s25, v0, 6
	v_cvt_scalef32_pk_f32_fp4 v[4:5], v166, 1.0 op_sel:[0,1,0]
	v_cvt_scalef32_pk_f32_fp4 v[176:177], v46, 1.0 op_sel:[0,1,0]
	v_cvt_scalef32_pk_f32_fp4 v[178:179], v170, 1.0 op_sel:[0,1,0]
	v_cvt_scalef32_pk_f32_fp4 v[182:183], v172, 1.0 op_sel:[0,1,0]
	s_nop 0
	buffer_load_dwordx2 v[124:125], v192, s[4:7], s25 offen
	v_readlane_b32 s25, v0, 7
	v_readlane_b32 s62, v3, 1
	v_readlane_b32 s64, v3, 2
	v_readlane_b32 s66, v3, 3
	v_readlane_b32 s68, v3, 4
	s_nop 0
	buffer_load_dwordx2 v[126:127], v192, s[4:7], s25 offen
	v_readlane_b32 s25, v0, 8
	v_readlane_b32 s70, v3, 5
	v_readlane_b32 s72, v3, 6
	v_readlane_b32 s74, v3, 7
	v_readlane_b32 s76, v3, 8
	s_nop 0
	buffer_load_dwordx2 v[130:131], v192, s[4:7], s25 offen
	v_readlane_b32 s25, v0, 9
	v_readlane_b32 s78, v3, 9
	v_readlane_b32 s80, v3, 10
	v_readlane_b32 s82, v3, 11
	v_readlane_b32 s84, v3, 12
	s_nop 0
	buffer_load_dwordx2 v[132:133], v192, s[4:7], s25 offen
	v_readlane_b32 s25, v0, 10
	v_readlane_b32 s86, v3, 13
	s_nop 0
	v_pk_fma_f32 v[116:117], v[142:143], s[24:25], v[116:117] op_sel_hi:[1,0,1]
	v_readlane_b32 s88, v3, 14
	v_pk_fma_f32 v[116:117], v[186:187], s[26:27], v[116:117] op_sel_hi:[1,0,1]
	s_nop 0
	buffer_load_dwordx2 v[136:137], v192, s[4:7], s25 offen
	v_readlane_b32 s25, v0, 11
	v_pk_fma_f32 v[116:117], v[188:189], s[28:29], v[116:117] op_sel_hi:[1,0,1]
	v_pk_fma_f32 v[190:191], v[196:197], s[30:31], v[116:117] op_sel_hi:[1,0,1]
	v_readlane_b32 s27, v0, 13
	v_readlane_b32 s29, v0, 14
	s_nop 0
	buffer_load_dwordx2 v[116:117], v192, s[4:7], s25 offen
	v_readlane_b32 s25, v0, 12
	v_readlane_b32 s31, v0, 15
	v_add_u32_e32 v0, 0xffffe000, v78
	s_nop 2
	buffer_load_dwordx2 v[142:143], v192, s[4:7], s25 offen
	buffer_load_dwordx2 v[140:141], v192, s[4:7], s27 offen
	buffer_load_dwordx2 v[138:139], v192, s[4:7], s29 offen
	s_nop 0
	buffer_load_dwordx2 v[134:135], v192, s[4:7], s31 offen
	v_lshrrev_b32_e32 v0, 12, v0
	s_movk_i32 s6, 0x1fff
	v_add_u32_e32 v0, 1, v0
	v_cmp_lt_i32_e32 vcc, s6, v78
	v_mov_b64_e32 v[186:187], s[94:95]
	v_pk_fma_f32 v[4:5], v[4:5], s[34:35], v[190:191] op_sel_hi:[1,0,1]
	v_cndmask_b32_e32 v195, 0, v0, vcc
	v_add_u32_e32 v0, s21, v195
	v_mad_i64_i32 v[186:187], s[6:7], v0, s67, v[186:187]
	s_mov_b64 s[6:7], 0x9665000
	s_nop 0
	v_lshl_add_u64 v[188:189], v[186:187], 0, s[6:7]
	v_lshlrev_b32_e32 v0, 2, v58
	v_lshl_add_u64 v[186:187], v[68:69], 0, v[204:205]
	v_lshl_add_u64 v[200:201], v[188:189], 0, v[0:1]
	global_load_dwordx4 v[196:199], v[186:187], off
	s_nop 0
	global_load_dwordx4 v[200:203], v[200:201], off
	v_pk_fma_f32 v[4:5], v[176:177], s[36:37], v[4:5] op_sel_hi:[1,0,1]
	v_readlane_b32 s6, v3, 0
	v_pk_fma_f32 v[4:5], v[178:179], s[38:39], v[4:5] op_sel_hi:[1,0,1]
	s_waitcnt vmcnt(17)
	v_cvt_scalef32_pk_f32_fp4 v[176:177], v110, 1.0 op_sel:[1,0,0]
	v_pk_fma_f32 v[190:191], v[182:183], s[56:57], v[4:5] op_sel_hi:[1,0,1]
	v_cvt_scalef32_pk_f32_fp4 v[4:5], v110, 1.0
	s_waitcnt vmcnt(16)
	v_cvt_scalef32_pk_f32_fp4 v[178:179], v112, 1.0
	v_cvt_scalef32_pk_f32_fp4 v[182:183], v112, 1.0 op_sel:[1,0,0]
	v_pk_fma_f32 v[4:5], v[4:5], s[6:7], v[180:181] op_sel_hi:[1,0,1]
	v_pk_fma_f32 v[176:177], v[176:177], s[6:7], v[184:185] op_sel_hi:[1,0,1]
	s_waitcnt vmcnt(15)
	v_cvt_scalef32_pk_f32_fp4 v[206:207], v114, 1.0
	v_cvt_scalef32_pk_f32_fp4 v[208:209], v114, 1.0 op_sel:[1,0,0]
	v_pk_fma_f32 v[4:5], v[178:179], s[62:63], v[4:5] op_sel_hi:[1,0,1]
	v_pk_fma_f32 v[176:177], v[182:183], s[62:63], v[176:177] op_sel_hi:[1,0,1]
	s_waitcnt vmcnt(14)
	v_cvt_scalef32_pk_f32_fp4 v[210:211], v118, 1.0
	v_cvt_scalef32_pk_f32_fp4 v[214:215], v118, 1.0 op_sel:[1,0,0]
	v_pk_fma_f32 v[4:5], v[206:207], s[64:65], v[4:5] op_sel_hi:[1,0,1]
	v_pk_fma_f32 v[176:177], v[208:209], s[64:65], v[176:177] op_sel_hi:[1,0,1]
	s_waitcnt vmcnt(13)
	v_cvt_scalef32_pk_f32_fp4 v[216:217], v120, 1.0
	v_cvt_scalef32_pk_f32_fp4 v[228:229], v120, 1.0 op_sel:[1,0,0]
	v_pk_fma_f32 v[4:5], v[210:211], s[66:67], v[4:5] op_sel_hi:[1,0,1]
	v_pk_fma_f32 v[176:177], v[214:215], s[66:67], v[176:177] op_sel_hi:[1,0,1]
	s_waitcnt vmcnt(12)
	v_cvt_scalef32_pk_f32_fp4 v[230:231], v122, 1.0
	v_cvt_scalef32_pk_f32_fp4 v[232:233], v122, 1.0 op_sel:[1,0,0]
	v_pk_fma_f32 v[4:5], v[216:217], s[68:69], v[4:5] op_sel_hi:[1,0,1]
	v_pk_fma_f32 v[176:177], v[228:229], s[68:69], v[176:177] op_sel_hi:[1,0,1]
	s_waitcnt vmcnt(11)
	v_cvt_scalef32_pk_f32_fp4 v[234:235], v124, 1.0
	v_cvt_scalef32_pk_f32_fp4 v[236:237], v124, 1.0 op_sel:[1,0,0]
	v_pk_fma_f32 v[4:5], v[230:231], s[70:71], v[4:5] op_sel_hi:[1,0,1]
	v_pk_fma_f32 v[176:177], v[232:233], s[70:71], v[176:177] op_sel_hi:[1,0,1]
	s_waitcnt vmcnt(10)
	v_cvt_scalef32_pk_f32_fp4 v[238:239], v126, 1.0
	v_cvt_scalef32_pk_f32_fp4 v[240:241], v126, 1.0 op_sel:[1,0,0]
	v_pk_fma_f32 v[4:5], v[234:235], s[72:73], v[4:5] op_sel_hi:[1,0,1]
	v_pk_fma_f32 v[176:177], v[236:237], s[72:73], v[176:177] op_sel_hi:[1,0,1]
	s_waitcnt vmcnt(9)
	v_cvt_scalef32_pk_f32_fp4 v[242:243], v130, 1.0
	v_cvt_scalef32_pk_f32_fp4 v[244:245], v130, 1.0 op_sel:[1,0,0]
	v_pk_fma_f32 v[4:5], v[238:239], s[74:75], v[4:5] op_sel_hi:[1,0,1]
	v_pk_fma_f32 v[176:177], v[240:241], s[74:75], v[176:177] op_sel_hi:[1,0,1]
	v_pk_fma_f32 v[4:5], v[242:243], s[76:77], v[4:5] op_sel_hi:[1,0,1]
	v_pk_fma_f32 v[176:177], v[244:245], s[76:77], v[176:177] op_sel_hi:[1,0,1]
	v_readlane_b32 s90, v3, 15
	s_waitcnt vmcnt(8)
	v_cvt_scalef32_pk_f32_fp4 v[246:247], v132, 1.0
	v_cvt_scalef32_pk_f32_fp4 v[248:249], v132, 1.0 op_sel:[1,0,0]
	v_pk_fma_f32 v[4:5], v[246:247], s[78:79], v[4:5] op_sel_hi:[1,0,1]
	v_pk_fma_f32 v[176:177], v[248:249], s[78:79], v[176:177] op_sel_hi:[1,0,1]
	v_mov_b32_e32 v73, v1
	v_cvt_scalef32_pk_f32_fp4 v[148:149], v152, 1.0 op_sel:[1,1,0]
	v_cvt_scalef32_pk_f32_fp4 v[144:145], v153, 1.0
	s_waitcnt vmcnt(7)
	v_cvt_scalef32_pk_f32_fp4 v[180:181], v136, 1.0
	v_cvt_scalef32_pk_f32_fp4 v[178:179], v136, 1.0 op_sel:[1,0,0]
	v_pk_fma_f32 v[4:5], v[180:181], s[80:81], v[4:5] op_sel_hi:[1,0,1]
	v_pk_fma_f32 v[176:177], v[178:179], s[80:81], v[176:177] op_sel_hi:[1,0,1]
	v_cvt_scalef32_pk_f32_fp4 v[56:57], v153, 1.0 op_sel:[1,0,0]
	v_cvt_scalef32_pk_f32_fp4 v[52:53], v153, 1.0 op_sel:[0,1,0]
	v_cvt_scalef32_pk_f32_fp4 v[16:17], v153, 1.0 op_sel:[1,1,0]
	s_waitcnt vmcnt(6)
	v_cvt_scalef32_pk_f32_fp4 v[178:179], v116, 1.0
	v_pk_fma_f32 v[4:5], v[178:179], s[82:83], v[4:5] op_sel_hi:[1,0,1]
	v_cvt_scalef32_pk_f32_fp4 v[180:181], v116, 1.0 op_sel:[1,0,0]
	v_cvt_scalef32_pk_f32_fp4 v[152:153], v154, 1.0 op_sel:[1,1,0]
	v_pk_fma_f32 v[8:9], v[148:149], s[20:21], v[8:9] op_sel_hi:[1,0,1]
	s_waitcnt vmcnt(5)
	v_cvt_scalef32_pk_f32_fp4 v[182:183], v142, 1.0
	s_waitcnt vmcnt(4)
	v_cvt_scalef32_pk_f32_fp4 v[206:207], v140, 1.0
	v_pk_fma_f32 v[4:5], v[182:183], s[84:85], v[4:5] op_sel_hi:[1,0,1]
	s_waitcnt vmcnt(3)
	v_cvt_scalef32_pk_f32_fp4 v[210:211], v138, 1.0
	v_pk_fma_f32 v[4:5], v[206:207], s[86:87], v[4:5] op_sel_hi:[1,0,1]
	s_waitcnt vmcnt(2)
	v_cvt_scalef32_pk_f32_fp4 v[2:3], v134, 1.0
	v_pk_fma_f32 v[4:5], v[210:211], s[88:89], v[4:5] op_sel_hi:[1,0,1]
	v_cvt_scalef32_pk_f32_fp4 v[184:185], v142, 1.0 op_sel:[1,0,0]
	v_pk_fma_f32 v[2:3], v[2:3], s[90:91], v[4:5] op_sel_hi:[1,0,1]
	v_pk_fma_f32 v[4:5], v[180:181], s[82:83], v[176:177] op_sel_hi:[1,0,1]
	v_cvt_scalef32_pk_f32_fp4 v[208:209], v140, 1.0 op_sel:[1,0,0]
	v_pk_fma_f32 v[4:5], v[184:185], s[84:85], v[4:5] op_sel_hi:[1,0,1]
	v_cvt_scalef32_pk_f32_fp4 v[214:215], v138, 1.0 op_sel:[1,0,0]
	v_pk_fma_f32 v[4:5], v[208:209], s[86:87], v[4:5] op_sel_hi:[1,0,1]
	v_cvt_scalef32_pk_f32_fp4 v[216:217], v134, 1.0 op_sel:[1,0,0]
	v_pk_fma_f32 v[4:5], v[214:215], s[88:89], v[4:5] op_sel_hi:[1,0,1]
	v_lshl_add_u64 v[176:177], v[70:71], 0, v[204:205]
	v_pk_fma_f32 v[4:5], v[216:217], s[90:91], v[4:5] op_sel_hi:[1,0,1]
	v_lshl_add_u64 v[182:183], v[188:189], 0, v[72:73]
	s_waitcnt vmcnt(0)
	v_pk_fma_f32 v[2:3], v[2:3], v[200:201], v[196:197]
	v_pk_fma_f32 v[4:5], v[4:5], v[202:203], v[198:199]
	global_store_dwordx4 v[176:177], v[2:5], off
	global_load_dwordx4 v[178:181], v[186:187], off offset:16
	s_nop 0
	global_load_dwordx4 v[182:185], v[182:183], off
	v_cvt_scalef32_pk_f32_fp4 v[156:157], v158, 1.0 op_sel:[1,1,0]
	v_pk_fma_f32 v[8:9], v[152:153], s[22:23], v[8:9] op_sel_hi:[1,0,1]
	v_cvt_scalef32_pk_f32_fp4 v[150:151], v159, 1.0
	v_cvt_scalef32_pk_f32_fp4 v[82:83], v159, 1.0 op_sel:[1,0,0]
	v_cvt_scalef32_pk_f32_fp4 v[24:25], v159, 1.0 op_sel:[0,1,0]
	v_cvt_scalef32_pk_f32_fp4 v[20:21], v159, 1.0 op_sel:[1,1,0]
	v_cvt_scalef32_pk_f32_fp4 v[158:159], v160, 1.0 op_sel:[1,1,0]
	v_pk_fma_f32 v[8:9], v[156:157], s[24:25], v[8:9] op_sel_hi:[1,0,1]
	v_cvt_scalef32_pk_f32_fp4 v[146:147], v155, 1.0
	v_cvt_scalef32_pk_f32_fp4 v[80:81], v155, 1.0 op_sel:[1,0,0]
	v_cvt_scalef32_pk_f32_fp4 v[54:55], v155, 1.0 op_sel:[0,1,0]
	v_cvt_scalef32_pk_f32_fp4 v[18:19], v155, 1.0 op_sel:[1,1,0]
	v_cvt_scalef32_pk_f32_fp4 v[154:155], v161, 1.0
	v_cvt_scalef32_pk_f32_fp4 v[84:85], v161, 1.0 op_sel:[1,0,0]
	v_cvt_scalef32_pk_f32_fp4 v[28:29], v161, 1.0 op_sel:[0,1,0]
	v_cvt_scalef32_pk_f32_fp4 v[22:23], v161, 1.0 op_sel:[1,1,0]
	v_cvt_scalef32_pk_f32_fp4 v[160:161], v162, 1.0 op_sel:[1,1,0]
	v_pk_fma_f32 v[8:9], v[158:159], s[26:27], v[8:9] op_sel_hi:[1,0,1]
	v_cvt_scalef32_pk_f32_fp4 v[90:91], v163, 1.0
	v_cvt_scalef32_pk_f32_fp4 v[86:87], v163, 1.0 op_sel:[1,0,0]
	v_cvt_scalef32_pk_f32_fp4 v[32:33], v163, 1.0 op_sel:[0,1,0]
	v_cvt_scalef32_pk_f32_fp4 v[26:27], v163, 1.0 op_sel:[1,1,0]
	v_cvt_scalef32_pk_f32_fp4 v[162:163], v164, 1.0 op_sel:[1,1,0]
	v_pk_fma_f32 v[8:9], v[160:161], s[28:29], v[8:9] op_sel_hi:[1,0,1]
	v_cvt_scalef32_pk_f32_fp4 v[94:95], v165, 1.0
	v_cvt_scalef32_pk_f32_fp4 v[88:89], v165, 1.0 op_sel:[1,0,0]
	v_cvt_scalef32_pk_f32_fp4 v[36:37], v165, 1.0 op_sel:[0,1,0]
	v_cvt_scalef32_pk_f32_fp4 v[30:31], v165, 1.0 op_sel:[1,1,0]
	v_cvt_scalef32_pk_f32_fp4 v[164:165], v166, 1.0 op_sel:[1,1,0]
	v_pk_fma_f32 v[8:9], v[162:163], s[30:31], v[8:9] op_sel_hi:[1,0,1]
	v_cvt_scalef32_pk_f32_fp4 v[100:101], v167, 1.0
	v_cvt_scalef32_pk_f32_fp4 v[92:93], v167, 1.0 op_sel:[1,0,0]
	v_cvt_scalef32_pk_f32_fp4 v[40:41], v167, 1.0 op_sel:[0,1,0]
	v_cvt_scalef32_pk_f32_fp4 v[34:35], v167, 1.0 op_sel:[1,1,0]
	v_cvt_scalef32_pk_f32_fp4 v[166:167], v46, 1.0 op_sel:[1,1,0]
	v_pk_fma_f32 v[8:9], v[164:165], s[34:35], v[8:9] op_sel_hi:[1,0,1]
	v_cvt_scalef32_pk_f32_fp4 v[104:105], v47, 1.0
	v_cvt_scalef32_pk_f32_fp4 v[98:99], v47, 1.0 op_sel:[1,0,0]
	v_cvt_scalef32_pk_f32_fp4 v[44:45], v47, 1.0 op_sel:[0,1,0]
	v_cvt_scalef32_pk_f32_fp4 v[38:39], v47, 1.0 op_sel:[1,1,0]
	v_cvt_scalef32_pk_f32_fp4 v[168:169], v170, 1.0 op_sel:[1,1,0]
	v_cvt_scalef32_pk_f32_fp4 v[108:109], v171, 1.0
	v_cvt_scalef32_pk_f32_fp4 v[102:103], v171, 1.0 op_sel:[1,0,0]
	v_cvt_scalef32_pk_f32_fp4 v[48:49], v171, 1.0 op_sel:[0,1,0]
	v_cvt_scalef32_pk_f32_fp4 v[42:43], v171, 1.0 op_sel:[1,1,0]
	v_cvt_scalef32_pk_f32_fp4 v[170:171], v172, 1.0 op_sel:[1,1,0]
	v_cvt_scalef32_pk_f32_fp4 v[128:129], v173, 1.0
	v_cvt_scalef32_pk_f32_fp4 v[106:107], v173, 1.0 op_sel:[1,0,0]
	v_cvt_scalef32_pk_f32_fp4 v[50:51], v173, 1.0 op_sel:[0,1,0]
	v_cvt_scalef32_pk_f32_fp4 v[46:47], v173, 1.0 op_sel:[1,1,0]
	v_cvt_scalef32_pk_f32_fp4 v[174:175], v6, 1.0 op_sel:[0,1,0]
	v_cvt_scalef32_pk_f32_fp4 v[172:173], v6, 1.0 op_sel:[1,1,0]
	v_pk_fma_f32 v[8:9], v[166:167], s[36:37], v[8:9] op_sel_hi:[1,0,1]
	v_cvt_scalef32_pk_f32_fp4 v[152:153], v7, 1.0
	v_cvt_scalef32_pk_f32_fp4 v[156:157], v7, 1.0 op_sel:[1,0,0]
	v_cvt_scalef32_pk_f32_fp4 v[158:159], v7, 1.0 op_sel:[0,1,0]
	v_cvt_scalef32_pk_f32_fp4 v[160:161], v7, 1.0 op_sel:[1,1,0]
	v_pk_fma_f32 v[6:7], v[144:145], s[20:21], v[96:97] op_sel_hi:[1,0,1]
	v_pk_fma_f32 v[8:9], v[168:169], s[38:39], v[8:9] op_sel_hi:[1,0,1]
	v_pk_fma_f32 v[6:7], v[146:147], s[22:23], v[6:7] op_sel_hi:[1,0,1]
	v_pk_fma_f32 v[8:9], v[170:171], s[56:57], v[8:9] op_sel_hi:[1,0,1]
	v_pk_fma_f32 v[6:7], v[150:151], s[24:25], v[6:7] op_sel_hi:[1,0,1]
	v_pk_fma_f32 v[174:175], v[174:175], s[60:61], v[190:191] op_sel_hi:[1,0,1]
	v_pk_fma_f32 v[8:9], v[172:173], s[60:61], v[8:9] op_sel_hi:[1,0,1]
	v_pk_fma_f32 v[96:97], v[154:155], s[26:27], v[6:7] op_sel_hi:[1,0,1]
	v_cvt_scalef32_pk_f32_fp4 v[6:7], v110, 1.0 op_sel:[0,1,0]
	v_cvt_scalef32_pk_f32_fp4 v[144:145], v110, 1.0 op_sel:[1,1,0]
	v_cvt_scalef32_pk_f32_fp4 v[146:147], v112, 1.0 op_sel:[0,1,0]
	v_cvt_scalef32_pk_f32_fp4 v[148:149], v112, 1.0 op_sel:[1,1,0]
	v_pk_fma_f32 v[6:7], v[6:7], s[6:7], v[174:175] op_sel_hi:[1,0,1]
	v_pk_fma_f32 v[8:9], v[144:145], s[6:7], v[8:9] op_sel_hi:[1,0,1]
	v_cvt_scalef32_pk_f32_fp4 v[150:151], v114, 1.0 op_sel:[0,1,0]
	v_cvt_scalef32_pk_f32_fp4 v[154:155], v114, 1.0 op_sel:[1,1,0]
	v_pk_fma_f32 v[6:7], v[146:147], s[62:63], v[6:7] op_sel_hi:[1,0,1]
	v_pk_fma_f32 v[8:9], v[148:149], s[62:63], v[8:9] op_sel_hi:[1,0,1]
	v_cvt_scalef32_pk_f32_fp4 v[162:163], v118, 1.0 op_sel:[0,1,0]
	v_cvt_scalef32_pk_f32_fp4 v[164:165], v118, 1.0 op_sel:[1,1,0]
	v_pk_fma_f32 v[6:7], v[150:151], s[64:65], v[6:7] op_sel_hi:[1,0,1]
	v_pk_fma_f32 v[8:9], v[154:155], s[64:65], v[8:9] op_sel_hi:[1,0,1]
	v_cvt_scalef32_pk_f32_fp4 v[166:167], v120, 1.0 op_sel:[0,1,0]
	v_cvt_scalef32_pk_f32_fp4 v[168:169], v120, 1.0 op_sel:[1,1,0]
	v_pk_fma_f32 v[6:7], v[162:163], s[66:67], v[6:7] op_sel_hi:[1,0,1]
	v_pk_fma_f32 v[8:9], v[164:165], s[66:67], v[8:9] op_sel_hi:[1,0,1]
	v_cvt_scalef32_pk_f32_fp4 v[170:171], v122, 1.0 op_sel:[0,1,0]
	v_cvt_scalef32_pk_f32_fp4 v[172:173], v122, 1.0 op_sel:[1,1,0]
	v_pk_fma_f32 v[6:7], v[166:167], s[68:69], v[6:7] op_sel_hi:[1,0,1]
	v_pk_fma_f32 v[8:9], v[168:169], s[68:69], v[8:9] op_sel_hi:[1,0,1]
	v_cvt_scalef32_pk_f32_fp4 v[190:191], v124, 1.0 op_sel:[0,1,0]
	v_cvt_scalef32_pk_f32_fp4 v[196:197], v124, 1.0 op_sel:[1,1,0]
	v_pk_fma_f32 v[6:7], v[170:171], s[70:71], v[6:7] op_sel_hi:[1,0,1]
	v_pk_fma_f32 v[8:9], v[172:173], s[70:71], v[8:9] op_sel_hi:[1,0,1]
	v_cvt_scalef32_pk_f32_fp4 v[198:199], v126, 1.0 op_sel:[0,1,0]
	v_cvt_scalef32_pk_f32_fp4 v[200:201], v126, 1.0 op_sel:[1,1,0]
	v_pk_fma_f32 v[6:7], v[190:191], s[72:73], v[6:7] op_sel_hi:[1,0,1]
	v_pk_fma_f32 v[8:9], v[196:197], s[72:73], v[8:9] op_sel_hi:[1,0,1]
	v_cvt_scalef32_pk_f32_fp4 v[202:203], v130, 1.0 op_sel:[0,1,0]
	v_cvt_scalef32_pk_f32_fp4 v[204:205], v130, 1.0 op_sel:[1,1,0]
	v_pk_fma_f32 v[6:7], v[198:199], s[74:75], v[6:7] op_sel_hi:[1,0,1]
	v_pk_fma_f32 v[8:9], v[200:201], s[74:75], v[8:9] op_sel_hi:[1,0,1]
	v_cvt_scalef32_pk_f32_fp4 v[206:207], v132, 1.0 op_sel:[0,1,0]
	v_cvt_scalef32_pk_f32_fp4 v[208:209], v132, 1.0 op_sel:[1,1,0]
	v_pk_fma_f32 v[6:7], v[202:203], s[76:77], v[6:7] op_sel_hi:[1,0,1]
	v_pk_fma_f32 v[8:9], v[204:205], s[76:77], v[8:9] op_sel_hi:[1,0,1]
	v_cvt_scalef32_pk_f32_fp4 v[210:211], v136, 1.0 op_sel:[0,1,0]
	v_cvt_scalef32_pk_f32_fp4 v[214:215], v136, 1.0 op_sel:[1,1,0]
	v_pk_fma_f32 v[6:7], v[206:207], s[78:79], v[6:7] op_sel_hi:[1,0,1]
	v_pk_fma_f32 v[8:9], v[208:209], s[78:79], v[8:9] op_sel_hi:[1,0,1]
	v_pk_fma_f32 v[6:7], v[210:211], s[80:81], v[6:7] op_sel_hi:[1,0,1]
	v_pk_fma_f32 v[8:9], v[214:215], s[80:81], v[8:9] op_sel_hi:[1,0,1]
	v_cvt_scalef32_pk_f32_fp4 v[144:145], v116, 1.0 op_sel:[0,1,0]
	v_cvt_scalef32_pk_f32_fp4 v[146:147], v116, 1.0 op_sel:[1,1,0]
	v_cvt_scalef32_pk_f32_fp4 v[148:149], v142, 1.0 op_sel:[0,1,0]
	v_cvt_scalef32_pk_f32_fp4 v[150:151], v142, 1.0 op_sel:[1,1,0]
	v_pk_fma_f32 v[6:7], v[144:145], s[82:83], v[6:7] op_sel_hi:[1,0,1]
	v_pk_fma_f32 v[8:9], v[146:147], s[82:83], v[8:9] op_sel_hi:[1,0,1]
	v_cvt_scalef32_pk_f32_fp4 v[154:155], v140, 1.0 op_sel:[0,1,0]
	v_cvt_scalef32_pk_f32_fp4 v[162:163], v140, 1.0 op_sel:[1,1,0]
	v_pk_fma_f32 v[6:7], v[148:149], s[84:85], v[6:7] op_sel_hi:[1,0,1]
	v_pk_fma_f32 v[8:9], v[150:151], s[84:85], v[8:9] op_sel_hi:[1,0,1]
	v_cvt_scalef32_pk_f32_fp4 v[164:165], v138, 1.0 op_sel:[0,1,0]
	v_cvt_scalef32_pk_f32_fp4 v[166:167], v138, 1.0 op_sel:[1,1,0]
	v_pk_fma_f32 v[6:7], v[154:155], s[86:87], v[6:7] op_sel_hi:[1,0,1]
	v_pk_fma_f32 v[8:9], v[162:163], s[86:87], v[8:9] op_sel_hi:[1,0,1]
	v_cvt_scalef32_pk_f32_fp4 v[168:169], v134, 1.0 op_sel:[0,1,0]
	v_cvt_scalef32_pk_f32_fp4 v[170:171], v134, 1.0 op_sel:[1,1,0]
	v_pk_fma_f32 v[6:7], v[164:165], s[88:89], v[6:7] op_sel_hi:[1,0,1]
	v_pk_fma_f32 v[8:9], v[166:167], s[88:89], v[8:9] op_sel_hi:[1,0,1]
	v_pk_fma_f32 v[6:7], v[168:169], s[90:91], v[6:7] op_sel_hi:[1,0,1]
	v_pk_fma_f32 v[8:9], v[170:171], s[90:91], v[8:9] op_sel_hi:[1,0,1]
	s_waitcnt vmcnt(0)
	v_pk_fma_f32 v[6:7], v[6:7], v[182:183], v[178:179]
	v_pk_fma_f32 v[8:9], v[8:9], v[184:185], v[180:181]
	global_store_dwordx4 v[176:177], v[6:9], off offset:16
	v_lshl_add_u64 v[148:149], v[188:189], 0, v[74:75]
	global_load_dwordx4 v[144:147], v[186:187], off offset:32
	s_nop 0
	global_load_dwordx4 v[148:151], v[148:149], off
	v_pk_fma_f32 v[10:11], v[56:57], s[20:21], v[10:11] op_sel_hi:[1,0,1]
	v_pk_fma_f32 v[90:91], v[90:91], s[28:29], v[96:97] op_sel_hi:[1,0,1]
	v_pk_fma_f32 v[10:11], v[80:81], s[22:23], v[10:11] op_sel_hi:[1,0,1]
	v_pk_fma_f32 v[90:91], v[94:95], s[30:31], v[90:91] op_sel_hi:[1,0,1]
	v_pk_fma_f32 v[10:11], v[82:83], s[24:25], v[10:11] op_sel_hi:[1,0,1]
	v_pk_fma_f32 v[90:91], v[100:101], s[34:35], v[90:91] op_sel_hi:[1,0,1]
	v_pk_fma_f32 v[10:11], v[84:85], s[26:27], v[10:11] op_sel_hi:[1,0,1]
	v_pk_fma_f32 v[90:91], v[104:105], s[36:37], v[90:91] op_sel_hi:[1,0,1]
	v_pk_fma_f32 v[10:11], v[86:87], s[28:29], v[10:11] op_sel_hi:[1,0,1]
	v_pk_fma_f32 v[90:91], v[108:109], s[38:39], v[90:91] op_sel_hi:[1,0,1]
	v_pk_fma_f32 v[10:11], v[88:89], s[30:31], v[10:11] op_sel_hi:[1,0,1]
	v_pk_fma_f32 v[90:91], v[128:129], s[56:57], v[90:91] op_sel_hi:[1,0,1]
	v_pk_fma_f32 v[10:11], v[92:93], s[34:35], v[10:11] op_sel_hi:[1,0,1]
	v_pk_fma_f32 v[12:13], v[52:53], s[20:21], v[12:13] op_sel_hi:[1,0,1]
	v_pk_fma_f32 v[10:11], v[98:99], s[36:37], v[10:11] op_sel_hi:[1,0,1]
	v_pk_fma_f32 v[90:91], v[152:153], s[60:61], v[90:91] op_sel_hi:[1,0,1]
	v_pk_fma_f32 v[10:11], v[102:103], s[38:39], v[10:11] op_sel_hi:[1,0,1]
	v_pk_fma_f32 v[56:57], v[54:55], s[22:23], v[12:13] op_sel_hi:[1,0,1]
	v_pk_fma_f32 v[10:11], v[106:107], s[56:57], v[10:11] op_sel_hi:[1,0,1]
	v_cvt_scalef32_pk_f32_fp4 v[12:13], v111, 1.0
	v_pk_fma_f32 v[10:11], v[156:157], s[60:61], v[10:11] op_sel_hi:[1,0,1]
	v_cvt_scalef32_pk_f32_fp4 v[52:53], v111, 1.0 op_sel:[1,0,0]
	v_cvt_scalef32_pk_f32_fp4 v[54:55], v113, 1.0
	v_cvt_scalef32_pk_f32_fp4 v[80:81], v113, 1.0 op_sel:[1,0,0]
	v_pk_fma_f32 v[12:13], v[12:13], s[6:7], v[90:91] op_sel_hi:[1,0,1]
	v_pk_fma_f32 v[10:11], v[52:53], s[6:7], v[10:11] op_sel_hi:[1,0,1]
	v_cvt_scalef32_pk_f32_fp4 v[82:83], v115, 1.0
	v_cvt_scalef32_pk_f32_fp4 v[84:85], v115, 1.0 op_sel:[1,0,0]
	v_pk_fma_f32 v[12:13], v[54:55], s[62:63], v[12:13] op_sel_hi:[1,0,1]
	v_pk_fma_f32 v[10:11], v[80:81], s[62:63], v[10:11] op_sel_hi:[1,0,1]
	v_cvt_scalef32_pk_f32_fp4 v[86:87], v119, 1.0
	v_cvt_scalef32_pk_f32_fp4 v[88:89], v119, 1.0 op_sel:[1,0,0]
	v_pk_fma_f32 v[12:13], v[82:83], s[64:65], v[12:13] op_sel_hi:[1,0,1]
	v_pk_fma_f32 v[10:11], v[84:85], s[64:65], v[10:11] op_sel_hi:[1,0,1]
	v_cvt_scalef32_pk_f32_fp4 v[92:93], v121, 1.0
	v_cvt_scalef32_pk_f32_fp4 v[94:95], v121, 1.0 op_sel:[1,0,0]
	v_pk_fma_f32 v[12:13], v[86:87], s[66:67], v[12:13] op_sel_hi:[1,0,1]
	v_pk_fma_f32 v[10:11], v[88:89], s[66:67], v[10:11] op_sel_hi:[1,0,1]
	v_cvt_scalef32_pk_f32_fp4 v[96:97], v123, 1.0
	v_cvt_scalef32_pk_f32_fp4 v[98:99], v123, 1.0 op_sel:[1,0,0]
	v_pk_fma_f32 v[12:13], v[92:93], s[68:69], v[12:13] op_sel_hi:[1,0,1]
	v_pk_fma_f32 v[10:11], v[94:95], s[68:69], v[10:11] op_sel_hi:[1,0,1]
	v_cvt_scalef32_pk_f32_fp4 v[100:101], v125, 1.0
	v_cvt_scalef32_pk_f32_fp4 v[102:103], v125, 1.0 op_sel:[1,0,0]
	v_pk_fma_f32 v[12:13], v[96:97], s[70:71], v[12:13] op_sel_hi:[1,0,1]
	v_pk_fma_f32 v[10:11], v[98:99], s[70:71], v[10:11] op_sel_hi:[1,0,1]
	v_cvt_scalef32_pk_f32_fp4 v[104:105], v127, 1.0
	v_cvt_scalef32_pk_f32_fp4 v[106:107], v127, 1.0 op_sel:[1,0,0]
	v_pk_fma_f32 v[12:13], v[100:101], s[72:73], v[12:13] op_sel_hi:[1,0,1]
	v_pk_fma_f32 v[10:11], v[102:103], s[72:73], v[10:11] op_sel_hi:[1,0,1]
	v_cvt_scalef32_pk_f32_fp4 v[108:109], v131, 1.0
	v_cvt_scalef32_pk_f32_fp4 v[128:129], v131, 1.0 op_sel:[1,0,0]
	v_pk_fma_f32 v[12:13], v[104:105], s[74:75], v[12:13] op_sel_hi:[1,0,1]
	v_pk_fma_f32 v[10:11], v[106:107], s[74:75], v[10:11] op_sel_hi:[1,0,1]
	v_cvt_scalef32_pk_f32_fp4 v[152:153], v133, 1.0
	v_cvt_scalef32_pk_f32_fp4 v[154:155], v133, 1.0 op_sel:[1,0,0]
	v_pk_fma_f32 v[12:13], v[108:109], s[76:77], v[12:13] op_sel_hi:[1,0,1]
	v_pk_fma_f32 v[10:11], v[128:129], s[76:77], v[10:11] op_sel_hi:[1,0,1]
	v_cvt_scalef32_pk_f32_fp4 v[156:157], v137, 1.0
	v_cvt_scalef32_pk_f32_fp4 v[162:163], v137, 1.0 op_sel:[1,0,0]
	v_pk_fma_f32 v[12:13], v[152:153], s[78:79], v[12:13] op_sel_hi:[1,0,1]
	v_pk_fma_f32 v[10:11], v[154:155], s[78:79], v[10:11] op_sel_hi:[1,0,1]
	v_pk_fma_f32 v[12:13], v[156:157], s[80:81], v[12:13] op_sel_hi:[1,0,1]
	v_pk_fma_f32 v[52:53], v[162:163], s[80:81], v[10:11] op_sel_hi:[1,0,1]
	v_cvt_scalef32_pk_f32_fp4 v[10:11], v117, 1.0
	v_cvt_scalef32_pk_f32_fp4 v[54:55], v117, 1.0 op_sel:[1,0,0]
	v_cvt_scalef32_pk_f32_fp4 v[80:81], v143, 1.0
	v_cvt_scalef32_pk_f32_fp4 v[82:83], v143, 1.0 op_sel:[1,0,0]
	v_pk_fma_f32 v[10:11], v[10:11], s[82:83], v[12:13] op_sel_hi:[1,0,1]
	v_pk_fma_f32 v[12:13], v[54:55], s[82:83], v[52:53] op_sel_hi:[1,0,1]
	v_cvt_scalef32_pk_f32_fp4 v[84:85], v141, 1.0
	v_cvt_scalef32_pk_f32_fp4 v[86:87], v141, 1.0 op_sel:[1,0,0]
	v_pk_fma_f32 v[10:11], v[80:81], s[84:85], v[10:11] op_sel_hi:[1,0,1]
	v_pk_fma_f32 v[12:13], v[82:83], s[84:85], v[12:13] op_sel_hi:[1,0,1]
	v_cvt_scalef32_pk_f32_fp4 v[88:89], v139, 1.0
	v_cvt_scalef32_pk_f32_fp4 v[90:91], v139, 1.0 op_sel:[1,0,0]
	v_pk_fma_f32 v[10:11], v[84:85], s[86:87], v[10:11] op_sel_hi:[1,0,1]
	v_pk_fma_f32 v[12:13], v[86:87], s[86:87], v[12:13] op_sel_hi:[1,0,1]
	v_cvt_scalef32_pk_f32_fp4 v[92:93], v135, 1.0
	v_cvt_scalef32_pk_f32_fp4 v[94:95], v135, 1.0 op_sel:[1,0,0]
	v_pk_fma_f32 v[10:11], v[88:89], s[88:89], v[10:11] op_sel_hi:[1,0,1]
	v_pk_fma_f32 v[12:13], v[90:91], s[88:89], v[12:13] op_sel_hi:[1,0,1]
	v_pk_fma_f32 v[10:11], v[92:93], s[90:91], v[10:11] op_sel_hi:[1,0,1]
	v_pk_fma_f32 v[12:13], v[94:95], s[90:91], v[12:13] op_sel_hi:[1,0,1]
	s_waitcnt vmcnt(0)
	v_pk_fma_f32 v[10:11], v[10:11], v[148:149], v[144:145]
	v_pk_fma_f32 v[12:13], v[12:13], v[150:151], v[146:147]
	global_store_dwordx4 v[176:177], v[10:13], off offset:32
	v_lshl_add_u64 v[80:81], v[188:189], 0, v[76:77]
	global_load_dwordx4 v[52:55], v[186:187], off offset:48
	s_nop 0
	global_load_dwordx4 v[80:83], v[80:81], off
	v_pk_fma_f32 v[14:15], v[16:17], s[20:21], v[14:15] op_sel_hi:[1,0,1]
	v_pk_fma_f32 v[24:25], v[24:25], s[24:25], v[56:57] op_sel_hi:[1,0,1]
	v_pk_fma_f32 v[14:15], v[18:19], s[22:23], v[14:15] op_sel_hi:[1,0,1]
	v_pk_fma_f32 v[24:25], v[28:29], s[26:27], v[24:25] op_sel_hi:[1,0,1]
	v_pk_fma_f32 v[14:15], v[20:21], s[24:25], v[14:15] op_sel_hi:[1,0,1]
	v_pk_fma_f32 v[24:25], v[32:33], s[28:29], v[24:25] op_sel_hi:[1,0,1]
	v_pk_fma_f32 v[14:15], v[22:23], s[26:27], v[14:15] op_sel_hi:[1,0,1]
	v_pk_fma_f32 v[24:25], v[36:37], s[30:31], v[24:25] op_sel_hi:[1,0,1]
	v_pk_fma_f32 v[14:15], v[26:27], s[28:29], v[14:15] op_sel_hi:[1,0,1]
	v_pk_fma_f32 v[24:25], v[40:41], s[34:35], v[24:25] op_sel_hi:[1,0,1]
	v_pk_fma_f32 v[14:15], v[30:31], s[30:31], v[14:15] op_sel_hi:[1,0,1]
	v_pk_fma_f32 v[24:25], v[44:45], s[36:37], v[24:25] op_sel_hi:[1,0,1]
	v_pk_fma_f32 v[14:15], v[34:35], s[34:35], v[14:15] op_sel_hi:[1,0,1]
	v_pk_fma_f32 v[24:25], v[48:49], s[38:39], v[24:25] op_sel_hi:[1,0,1]
	v_pk_fma_f32 v[14:15], v[38:39], s[36:37], v[14:15] op_sel_hi:[1,0,1]
	v_pk_fma_f32 v[24:25], v[50:51], s[56:57], v[24:25] op_sel_hi:[1,0,1]
	v_pk_fma_f32 v[14:15], v[42:43], s[38:39], v[14:15] op_sel_hi:[1,0,1]
	v_pk_fma_f32 v[24:25], v[158:159], s[60:61], v[24:25] op_sel_hi:[1,0,1]
	v_pk_fma_f32 v[14:15], v[46:47], s[56:57], v[14:15] op_sel_hi:[1,0,1]
	v_cvt_scalef32_pk_f32_fp4 v[16:17], v111, 1.0 op_sel:[0,1,0]
	v_pk_fma_f32 v[14:15], v[160:161], s[60:61], v[14:15] op_sel_hi:[1,0,1]
	v_cvt_scalef32_pk_f32_fp4 v[18:19], v111, 1.0 op_sel:[1,1,0]
	v_cvt_scalef32_pk_f32_fp4 v[20:21], v113, 1.0 op_sel:[0,1,0]
	v_cvt_scalef32_pk_f32_fp4 v[22:23], v113, 1.0 op_sel:[1,1,0]
	v_pk_fma_f32 v[16:17], v[16:17], s[6:7], v[24:25] op_sel_hi:[1,0,1]
	v_pk_fma_f32 v[14:15], v[18:19], s[6:7], v[14:15] op_sel_hi:[1,0,1]
	v_cvt_scalef32_pk_f32_fp4 v[26:27], v115, 1.0 op_sel:[0,1,0]
	v_cvt_scalef32_pk_f32_fp4 v[28:29], v115, 1.0 op_sel:[1,1,0]
	v_pk_fma_f32 v[16:17], v[20:21], s[62:63], v[16:17] op_sel_hi:[1,0,1]
	v_pk_fma_f32 v[14:15], v[22:23], s[62:63], v[14:15] op_sel_hi:[1,0,1]
	v_cvt_scalef32_pk_f32_fp4 v[30:31], v119, 1.0 op_sel:[0,1,0]
	v_cvt_scalef32_pk_f32_fp4 v[32:33], v119, 1.0 op_sel:[1,1,0]
	v_pk_fma_f32 v[16:17], v[26:27], s[64:65], v[16:17] op_sel_hi:[1,0,1]
	v_pk_fma_f32 v[14:15], v[28:29], s[64:65], v[14:15] op_sel_hi:[1,0,1]
	v_cvt_scalef32_pk_f32_fp4 v[34:35], v121, 1.0 op_sel:[0,1,0]
	v_cvt_scalef32_pk_f32_fp4 v[36:37], v121, 1.0 op_sel:[1,1,0]
	v_pk_fma_f32 v[16:17], v[30:31], s[66:67], v[16:17] op_sel_hi:[1,0,1]
	v_pk_fma_f32 v[14:15], v[32:33], s[66:67], v[14:15] op_sel_hi:[1,0,1]
	v_cvt_scalef32_pk_f32_fp4 v[38:39], v123, 1.0 op_sel:[0,1,0]
	v_cvt_scalef32_pk_f32_fp4 v[40:41], v123, 1.0 op_sel:[1,1,0]
	v_pk_fma_f32 v[16:17], v[34:35], s[68:69], v[16:17] op_sel_hi:[1,0,1]
	v_pk_fma_f32 v[14:15], v[36:37], s[68:69], v[14:15] op_sel_hi:[1,0,1]
	v_cvt_scalef32_pk_f32_fp4 v[42:43], v125, 1.0 op_sel:[0,1,0]
	v_cvt_scalef32_pk_f32_fp4 v[44:45], v125, 1.0 op_sel:[1,1,0]
	v_pk_fma_f32 v[16:17], v[38:39], s[70:71], v[16:17] op_sel_hi:[1,0,1]
	v_pk_fma_f32 v[14:15], v[40:41], s[70:71], v[14:15] op_sel_hi:[1,0,1]
	v_cvt_scalef32_pk_f32_fp4 v[46:47], v127, 1.0 op_sel:[0,1,0]
	v_cvt_scalef32_pk_f32_fp4 v[48:49], v127, 1.0 op_sel:[1,1,0]
	v_pk_fma_f32 v[16:17], v[42:43], s[72:73], v[16:17] op_sel_hi:[1,0,1]
	v_pk_fma_f32 v[14:15], v[44:45], s[72:73], v[14:15] op_sel_hi:[1,0,1]
	v_cvt_scalef32_pk_f32_fp4 v[50:51], v131, 1.0 op_sel:[0,1,0]
	v_cvt_scalef32_pk_f32_fp4 v[56:57], v131, 1.0 op_sel:[1,1,0]
	v_pk_fma_f32 v[16:17], v[46:47], s[74:75], v[16:17] op_sel_hi:[1,0,1]
	v_pk_fma_f32 v[14:15], v[48:49], s[74:75], v[14:15] op_sel_hi:[1,0,1]
	v_cvt_scalef32_pk_f32_fp4 v[84:85], v133, 1.0 op_sel:[0,1,0]
	v_cvt_scalef32_pk_f32_fp4 v[86:87], v133, 1.0 op_sel:[1,1,0]
	v_pk_fma_f32 v[16:17], v[50:51], s[76:77], v[16:17] op_sel_hi:[1,0,1]
	v_pk_fma_f32 v[14:15], v[56:57], s[76:77], v[14:15] op_sel_hi:[1,0,1]
	v_cvt_scalef32_pk_f32_fp4 v[88:89], v137, 1.0 op_sel:[0,1,0]
	v_cvt_scalef32_pk_f32_fp4 v[90:91], v137, 1.0 op_sel:[1,1,0]
	v_pk_fma_f32 v[16:17], v[84:85], s[78:79], v[16:17] op_sel_hi:[1,0,1]
	v_pk_fma_f32 v[14:15], v[86:87], s[78:79], v[14:15] op_sel_hi:[1,0,1]
	v_pk_fma_f32 v[16:17], v[88:89], s[80:81], v[16:17] op_sel_hi:[1,0,1]
	v_pk_fma_f32 v[18:19], v[90:91], s[80:81], v[14:15] op_sel_hi:[1,0,1]
	v_cvt_scalef32_pk_f32_fp4 v[14:15], v117, 1.0 op_sel:[0,1,0]
	v_cvt_scalef32_pk_f32_fp4 v[20:21], v117, 1.0 op_sel:[1,1,0]
	v_cvt_scalef32_pk_f32_fp4 v[22:23], v143, 1.0 op_sel:[0,1,0]
	v_cvt_scalef32_pk_f32_fp4 v[24:25], v143, 1.0 op_sel:[1,1,0]
	v_pk_fma_f32 v[14:15], v[14:15], s[82:83], v[16:17] op_sel_hi:[1,0,1]
	v_pk_fma_f32 v[16:17], v[20:21], s[82:83], v[18:19] op_sel_hi:[1,0,1]
	v_cvt_scalef32_pk_f32_fp4 v[26:27], v141, 1.0 op_sel:[0,1,0]
	v_cvt_scalef32_pk_f32_fp4 v[28:29], v141, 1.0 op_sel:[1,1,0]
	v_pk_fma_f32 v[14:15], v[22:23], s[84:85], v[14:15] op_sel_hi:[1,0,1]
	v_pk_fma_f32 v[16:17], v[24:25], s[84:85], v[16:17] op_sel_hi:[1,0,1]
	v_cvt_scalef32_pk_f32_fp4 v[30:31], v139, 1.0 op_sel:[0,1,0]
	v_cvt_scalef32_pk_f32_fp4 v[32:33], v139, 1.0 op_sel:[1,1,0]
	v_pk_fma_f32 v[14:15], v[26:27], s[86:87], v[14:15] op_sel_hi:[1,0,1]
	v_pk_fma_f32 v[16:17], v[28:29], s[86:87], v[16:17] op_sel_hi:[1,0,1]
	v_cvt_scalef32_pk_f32_fp4 v[34:35], v135, 1.0 op_sel:[0,1,0]
	v_cvt_scalef32_pk_f32_fp4 v[36:37], v135, 1.0 op_sel:[1,1,0]
	v_pk_fma_f32 v[14:15], v[30:31], s[88:89], v[14:15] op_sel_hi:[1,0,1]
	v_pk_fma_f32 v[16:17], v[32:33], s[88:89], v[16:17] op_sel_hi:[1,0,1]
	v_pk_fma_f32 v[14:15], v[34:35], s[90:91], v[14:15] op_sel_hi:[1,0,1]
	v_pk_fma_f32 v[16:17], v[36:37], s[90:91], v[16:17] op_sel_hi:[1,0,1]
	s_waitcnt vmcnt(0)
	v_pk_fma_f32 v[14:15], v[14:15], v[80:81], v[52:53]
	v_pk_fma_f32 v[16:17], v[16:17], v[82:83], v[54:55]
	s_andn2_b64 vcc, exec, s[12:13]
	global_store_dwordx4 v[176:177], v[14:17], off offset:48
	s_cbranch_vccnz .LBB0_686
	v_mov_b32_e32 v24, v3
	v_mov_b32_e32 v25, v7
	v_mov_b32_e32 v22, v2
	v_mov_b32_e32 v23, v6
	v_pk_mul_f32 v[24:25], v[24:25], v[24:25]
	v_mov_b32_e32 v26, v11
	v_mov_b32_e32 v27, v15
	v_mov_b32_e32 v20, v4
	v_mov_b32_e32 v21, v8
	v_pk_fma_f32 v[22:23], v[22:23], v[22:23], v[24:25]
	v_mov_b32_e32 v24, v10
	v_mov_b32_e32 v25, v14
	v_pk_mul_f32 v[26:27], v[26:27], v[26:27]
	v_mov_b32_e32 v18, v5
	v_mov_b32_e32 v19, v9
	v_pk_fma_f32 v[20:21], v[20:21], v[20:21], v[22:23]
	v_mov_b32_e32 v22, v12
	v_mov_b32_e32 v23, v16
	v_pk_fma_f32 v[24:25], v[24:25], v[24:25], v[26:27]
	v_pk_fma_f32 v[18:19], v[18:19], v[18:19], v[20:21]
	v_mov_b32_e32 v20, v13
	v_mov_b32_e32 v21, v17
	v_pk_fma_f32 v[22:23], v[22:23], v[22:23], v[24:25]
	v_add_f32_e32 v18, v18, v19
	v_pk_fma_f32 v[20:21], v[20:21], v[20:21], v[22:23]
	v_and_b32_e32 v19, 64, v219
	v_add_f32_e32 v18, v18, v20
	v_add_u32_e32 v19, 64, v19
	v_xor_b32_e32 v20, 32, v219
	v_cmp_lt_i32_e32 vcc, v20, v19
	v_add_f32_e32 v18, v18, v21
	v_readlane_b32 s6, v250, 40
	v_cndmask_b32_e32 v20, v219, v20, vcc
	v_lshlrev_b32_e32 v20, 2, v20
	ds_bpermute_b32 v20, v20, v18
	v_readlane_b32 s7, v250, 41
	v_lshlrev_b64 v[80:81], 10, v[78:79]
	s_waitcnt lgkmcnt(0)
	v_add_f32_e32 v18, v18, v20
	v_xor_b32_e32 v20, 16, v219
	v_cmp_lt_i32_e32 vcc, v20, v19
	s_nop 1
	v_cndmask_b32_e32 v20, v219, v20, vcc
	v_lshlrev_b32_e32 v20, 2, v20
	ds_bpermute_b32 v20, v20, v18
	s_waitcnt lgkmcnt(0)
	v_add_f32_e32 v18, v18, v20
	v_xor_b32_e32 v20, 8, v219
	v_cmp_lt_i32_e32 vcc, v20, v19
	s_nop 1
	v_cndmask_b32_e32 v20, v219, v20, vcc
	v_lshlrev_b32_e32 v20, 2, v20
	ds_bpermute_b32 v20, v20, v18
	s_waitcnt lgkmcnt(0)
	v_add_f32_e32 v18, v18, v20
	v_xor_b32_e32 v20, 4, v219
	v_cmp_lt_i32_e32 vcc, v20, v19
	s_nop 1
	v_cndmask_b32_e32 v20, v219, v20, vcc
	v_lshlrev_b32_e32 v20, 2, v20
	ds_bpermute_b32 v20, v20, v18
	s_waitcnt lgkmcnt(0)
	v_add_f32_e32 v18, v18, v20
	v_xor_b32_e32 v20, 2, v219
	v_cmp_lt_i32_e32 vcc, v20, v19
	s_nop 1
	v_cndmask_b32_e32 v20, v219, v20, vcc
	v_lshlrev_b32_e32 v20, 2, v20
	ds_bpermute_b32 v20, v20, v18
	s_waitcnt lgkmcnt(0)
	v_add_f32_e32 v18, v18, v20
	v_xor_b32_e32 v20, 1, v219
	v_cmp_lt_i32_e32 vcc, v20, v19
	s_nop 1
	v_cndmask_b32_e32 v19, v219, v20, vcc
	v_lshlrev_b32_e32 v19, 2, v19
	ds_bpermute_b32 v19, v19, v18
	v_add_u32_e32 v20, 3, v195
	s_waitcnt lgkmcnt(0)
	v_add_f32_e32 v18, v18, v19
	v_fmamk_f32 v18, v18, 0x3a800000, v213
	v_cmp_gt_f32_e32 vcc, s54, v18
	v_mul_f32_e32 v19, 0x4b800000, v18
	s_nop 0
	v_cndmask_b32_e32 v18, v18, v19, vcc
	v_rsq_f32_e32 v18, v18
	s_nop 0
	v_mul_f32_e32 v19, 0x45800000, v18
	v_cndmask_b32_e32 v82, v18, v19, vcc
	v_mov_b64_e32 v[18:19], s[6:7]
	v_mad_u64_u32 v[18:19], s[6:7], v20, s67, v[18:19]
	v_lshl_add_u64 v[50:51], v[18:19], 0, v[0:1]
	s_mov_b64 s[6:7], 0x1000
	v_lshl_add_u64 v[88:89], v[50:51], 0, s[6:7]
	s_movk_i32 s6, 0x1000
	global_load_dwordx4 v[18:21], v[66:67], off offset:48
	global_load_dwordx4 v[22:25], v[66:67], off offset:32
	global_load_dwordx4 v[30:33], v[66:67], off offset:16
	global_load_dwordx4 v[42:45], v[66:67], off
	global_load_dwordx4 v[26:29], v[50:51], off offset:48
	global_load_dwordx4 v[34:37], v[50:51], off offset:32
	global_load_dwordx4 v[38:41], v[50:51], off offset:16
	global_load_dwordx4 v[46:49], v[50:51], off
	v_add_co_u32_e32 v50, vcc, s6, v50
	v_pk_mul_f32 v[2:3], v[2:3], v[82:83] op_sel_hi:[1,0]
	s_nop 0
	v_addc_co_u32_e32 v51, vcc, 0, v51, vcc
	global_load_dwordx4 v[84:87], v[50:51], off
	s_nop 0
	global_load_dwordx4 v[50:53], v[88:89], off offset:48
	global_load_dwordx4 v[54:57], v[88:89], off offset:32
	s_nop 0
	global_load_dwordx4 v[88:91], v[88:89], off offset:16
	v_pk_mul_f32 v[6:7], v[6:7], v[82:83] op_sel_hi:[1,0]
	v_pk_mul_f32 v[4:5], v[4:5], v[82:83] op_sel_hi:[1,0]
	v_pk_mul_f32 v[8:9], v[8:9], v[82:83] op_sel_hi:[1,0]
	v_pk_mul_f32 v[10:11], v[10:11], v[82:83] op_sel_hi:[1,0]
	v_pk_mul_f32 v[14:15], v[14:15], v[82:83] op_sel_hi:[1,0]
	v_pk_mul_f32 v[12:13], v[12:13], v[82:83] op_sel_hi:[1,0]
	v_pk_mul_f32 v[16:17], v[16:17], v[82:83] op_sel_hi:[1,0]
	s_waitcnt vmcnt(11)
	v_pk_mul_f32 v[14:15], v[14:15], v[18:19]
	s_waitcnt vmcnt(10)
	v_pk_mul_f32 v[10:11], v[10:11], v[22:23]
	s_waitcnt vmcnt(9)
	v_pk_mul_f32 v[6:7], v[6:7], v[30:31]
	s_waitcnt vmcnt(8)
	v_pk_mul_f32 v[2:3], v[42:43], v[2:3]
	v_pk_mul_f32 v[4:5], v[44:45], v[4:5]
	v_pk_mul_f32 v[8:9], v[8:9], v[32:33]
	v_pk_mul_f32 v[12:13], v[12:13], v[24:25]
	v_pk_mul_f32 v[16:17], v[16:17], v[20:21]
	s_waitcnt vmcnt(3)
	v_pk_add_f32 v[42:43], v[84:85], 1.0 op_sel_hi:[1,0]
	s_nop 0
	v_pk_fma_f32 v[2:3], v[42:43], v[2:3], v[46:47]
	v_pk_add_f32 v[42:43], v[86:87], 1.0 op_sel_hi:[1,0]
	s_waitcnt vmcnt(0)
	v_pk_add_f32 v[30:31], v[88:89], 1.0 op_sel_hi:[1,0]
	v_pk_add_f32 v[22:23], v[54:55], 1.0 op_sel_hi:[1,0]
	v_pk_fma_f32 v[6:7], v[6:7], v[30:31], v[38:39]
	v_pk_add_f32 v[30:31], v[90:91], 1.0 op_sel_hi:[1,0]
	v_pk_add_f32 v[18:19], v[50:51], 1.0 op_sel_hi:[1,0]
	v_pk_fma_f32 v[4:5], v[4:5], v[42:43], v[48:49]
	v_pk_fma_f32 v[8:9], v[8:9], v[30:31], v[40:41]
	v_pk_fma_f32 v[10:11], v[10:11], v[22:23], v[34:35]
	v_pk_add_f32 v[22:23], v[56:57], 1.0 op_sel_hi:[1,0]
	v_pk_fma_f32 v[14:15], v[14:15], v[18:19], v[26:27]
	v_pk_add_f32 v[18:19], v[52:53], 1.0 op_sel_hi:[1,0]
	v_pk_fma_f32 v[12:13], v[12:13], v[22:23], v[36:37]
	v_pk_fma_f32 v[16:17], v[16:17], v[18:19], v[28:29]
	v_lshl_add_u64 v[18:19], v[80:81], 1, v[60:61]
	v_cvt_pk_bf16_f32 v2, v2, v3
	v_cvt_pk_bf16_f32 v3, v4, v5
	v_cvt_pk_bf16_f32 v4, v6, v7
	v_cvt_pk_bf16_f32 v5, v8, v9
	global_store_dwordx4 v[18:19], v[2:5], off
	s_nop 1
	v_cvt_pk_bf16_f32 v2, v10, v11
	v_cvt_pk_bf16_f32 v3, v12, v13
	v_cvt_pk_bf16_f32 v4, v14, v15
	v_cvt_pk_bf16_f32 v5, v16, v17
	global_store_dwordx4 v[18:19], v[2:5], off offset:16
	s_branch .LBB0_686
